# norm fix + per-MFMA-block priority flips (setprio 1 around each 32-MFMA block) instead of static raise for wr=1
# speedup vs baseline: 1.0129x; 1.0129x over previous
; template <class Epi, class Sched, bool ALIGN_EPI = true, bool SP2 = true, bool FULLLINE = false, bool NOSTAGE = false, bool FP8 = false>
; __device__ __forceinline__ void gemm_phase(PG8_LAS unsigned char* lds, const Gemm g, const Sched& S, const Epi& E) {
;     const int tid = threadIdx.x, wid = __builtin_amdgcn_readfirstlane(tid >> 6), lane = tid & 63, wr = wid >> 2, wc = wid & 3, fr = lane & 15, fq = lane >> 4;
;     const int K = g.K, nt = K / BK;
;     unsigned voffA_, voffB_;
;     { int R, C; stage_rc(tid * 16, R, C); const int Rb = Epi::PERM ? ((R & ~31) + perm32(R & 31)) : R;
;       voffA_ = (unsigned)(R * g.lda + C) * 2u; voffB_ = (unsigned)(Rb * g.ldb + C) * 2u; }
;     const unsigned voffA = voffA_, voffB = voffB_;
;     const size_t pstepoffA = (size_t)64 * g.lda * 2, pstepoffB = (size_t)64 * g.ldb * 2;
;     const size_t kstep = (size_t)(BK * 2);
;     const size_t hstepA = (size_t)HALF * g.lda * 2, hstepB = (size_t)HALF * g.ldb * 2;
;     const size_t tstepA = 2 * hstepA, tstepB = 2 * hstepB;
;     const unsigned ldsw = (unsigned)wid * 1024u;
;     const int aoff = lds_byte(wr * 64 + fr, fq * 8), boff = lds_byte(wc * 32 + fr, fq * 8);
;     ...
;     if (wr == 1) __builtin_amdgcn_s_setprio(1);
.LBB0_254:
	s_waitcnt vmcnt(0)
	v_cndmask_b32_e64 v4, 0, 1, s[8:9]
	v_cmp_ne_u32_e64 s[6:7], 1, v4
	s_andn2_b64 vcc, exec, s[8:9]
	s_barrier
	s_barrier
	s_cbranch_vccnz .LBB0_256
.LBB0_256:
	s_add_u32 s14, s48, 0x500000
	s_addc_u32 s15, s49, 0
	v_and_b32_e32 v4, 48, v0
	v_lshlrev_b32_e32 v5, 6, v0
	s_movk_i32 s1, 0x3c0
	s_add_u32 s16, s48, 0xd00000
	v_and_or_b32 v4, v5, s1, v4
	v_lshlrev_b32_e32 v5, 2, v0
	s_addc_u32 s17, s49, 0
	s_lshl_b32 s0, s19, 13
	v_and_b32_e32 v5, 32, v5
	v_bitop3_b32 v6, v4, s0, v5 bitop3:0xde
	s_lshl_b32 s0, s18, 5
	s_and_b32 s96, s0, 0x60
	s_lshl_b32 s0, s96, 7
	s_lshl_b32 s95, s19, 6
	v_bitop3_b32 v4, s0, v4, v5 bitop3:0xf6
	v_lshlrev_b32_e32 v5, 9, v0
	s_cmpk_lt_u32 s3, 0x100
	v_and_b32_e32 v5, 0x30000, v5
	v_lshlrev_b32_e32 v1, 12, v1
	s_cselect_b64 s[18:19], -1, 0
	v_or3_b32 v1, v2, v5, v1
	s_add_i32 s62, 0, 0x10000
	s_add_i32 s63, 0, 0x14000
	s_add_i32 s46, 0, 0x18000
	s_add_i32 s47, 0, 0x1c000
	s_ashr_i32 s97, s86, 31
	s_ashr_i32 s54, s2, 31
	v_add_u32_e32 v144, v1, v3
	v_mov_b32_e32 v145, 0
	s_mov_b32 s55, 0
	v_mov_b64_e32 v[146:147], 0xc00
	v_mov_b64_e32 v[148:149], 0xbff
	v_add_u32_e32 v156, s62, v4
	v_add_u32_e32 v157, s63, v4
	v_add_u32_e32 v158, 0, v6
	s_mov_b64 s[20:21], 0x80080
	s_add_i32 s89, s44, 0xc000
	s_mov_b64 s[22:23], 0xc0080
	s_add_i32 s45, s44, 0xe000
	s_mov_b64 s[24:25], 0x100
	s_waitcnt lgkmcnt(0)
	s_mov_b64 s[26:27], 0x40100
	s_mov_b64 s[28:29], 0x80100
	s_mov_b64 s[30:31], 0xc0100
	v_add_u32_e32 v159, s46, v4
	v_add_u32_e32 v160, s47, v4
	s_mov_b64 s[34:35], 0x180
	s_mov_b64 s[36:37], 0x40180
	s_mov_b64 s[38:39], 0x40000
	s_mov_b64 s[60:61], 0x80000
	s_mov_b64 s[66:67], 0xc0000
	s_mov_b64 s[68:69], 0x80
	s_mov_b64 s[70:71], 0x40080
	s_mov_b32 s52, 0xc2fc0000
	v_mov_b32_e32 v161, 0x3ecc95a3
	v_mov_b32_e32 v162, 0x42800000
	v_mov_b32_e32 v163, 0x7fc00000
	v_mov_b32_e32 v164, 0xff800000
	v_not_b32_e32 v165, 63
	s_branch .LBB0_259

.LBB0_261:
	s_ashr_i32 s75, s74, 31
	s_lshl_b64 s[40:41], s[74:75], 20
	s_add_u32 s76, s58, s40
	ds_read_b128 v[2:5], v156
	ds_read_b128 v[6:9], v156 offset:1024
	ds_read_b128 v[10:13], v156 offset:2048
	ds_read_b128 v[14:17], v156 offset:3072
	ds_read_b128 v[18:21], v157
	ds_read_b128 v[22:25], v157 offset:1024
	ds_read_b128 v[26:29], v157 offset:2048
	ds_read_b128 v[30:33], v157 offset:3072
	s_addc_u32 s77, s59, s41
	s_ashr_i32 s73, s72, 31
	s_lshl_b64 s[40:41], s[72:73], 20
	s_add_u32 s78, s84, s40
	s_addc_u32 s79, s85, s41
	s_and_b64 s[40:41], s[8:9], exec
	s_cselect_b32 s3, s77, s83
	s_cselect_b32 s11, s76, s82
	s_cselect_b32 s13, s79, s81
	s_cselect_b32 s42, s78, s80
	v_lshl_add_u64 v[138:139], s[82:83], 0, v[140:141]
	s_mov_b32 m0, s89
	v_lshl_add_u64 v[66:67], v[138:139], 0, s[20:21]
	ds_read_b128 v[34:37], v158
	ds_read_b128 v[38:41], v158 offset:1024
	ds_read_b128 v[42:45], v158 offset:2048
	ds_read_b128 v[46:49], v158 offset:3072
	ds_read_b128 v[50:53], v158 offset:4096
	ds_read_b128 v[54:57], v158 offset:5120
	ds_read_b128 v[58:61], v158 offset:6144
	ds_read_b128 v[62:65], v158 offset:7168
	global_load_lds_dwordx4 v[66:67], off
	v_lshl_add_u64 v[66:67], v[138:139], 0, s[22:23]
	s_mov_b32 m0, s45
	s_nop 0
	global_load_lds_dwordx4 v[66:67], off
	s_waitcnt vmcnt(24)
	s_waitcnt lgkmcnt(0)
	s_barrier
	s_waitcnt lgkmcnt(0)
	s_setprio 1
	v_mfma_f32_16x16x32_bf16 v[86:89], v[10:13], v[50:53], 0
	v_mfma_f32_16x16x32_bf16 v[90:93], v[14:17], v[54:57], v[86:89]
	v_mfma_f32_16x16x32_bf16 v[86:89], v[2:5], v[58:61], 0
	v_mfma_f32_16x16x32_bf16 v[66:69], v[2:5], v[34:37], 0
	v_mfma_f32_16x16x32_bf16 v[70:73], v[10:13], v[34:37], 0
	v_mfma_f32_16x16x32_bf16 v[74:77], v[2:5], v[42:45], 0
	v_mfma_f32_16x16x32_bf16 v[78:81], v[10:13], v[42:45], 0
	v_mfma_f32_16x16x32_bf16 v[82:85], v[2:5], v[50:53], 0
	v_mfma_f32_16x16x32_bf16 v[94:97], v[6:9], v[62:65], v[86:89]
	v_mfma_f32_16x16x32_bf16 v[86:89], v[10:13], v[58:61], 0
	v_mfma_f32_16x16x32_bf16 v[66:69], v[6:9], v[38:41], v[66:69]
	v_mfma_f32_16x16x32_bf16 v[70:73], v[14:17], v[38:41], v[70:73]
	v_mfma_f32_16x16x32_bf16 v[74:77], v[6:9], v[46:49], v[74:77]
	v_mfma_f32_16x16x32_bf16 v[78:81], v[14:17], v[46:49], v[78:81]
	v_mfma_f32_16x16x32_bf16 v[82:85], v[6:9], v[54:57], v[82:85]
	v_mfma_f32_16x16x32_bf16 v[106:109], v[14:17], v[62:65], v[86:89]
	v_mfma_f32_16x16x32_bf16 v[86:89], v[18:21], v[34:37], 0
	v_mfma_f32_16x16x32_bf16 v[34:37], v[26:29], v[34:37], 0
	v_mfma_f32_16x16x32_bf16 v[110:113], v[22:25], v[38:41], v[86:89]
	v_mfma_f32_16x16x32_bf16 v[34:37], v[30:33], v[38:41], v[34:37]
	v_mfma_f32_16x16x32_bf16 v[38:41], v[18:21], v[42:45], 0
	v_mfma_f32_16x16x32_bf16 v[42:45], v[26:29], v[42:45], 0
	v_mfma_f32_16x16x32_bf16 v[38:41], v[22:25], v[46:49], v[38:41]
	v_mfma_f32_16x16x32_bf16 v[42:45], v[30:33], v[46:49], v[42:45]
	v_mfma_f32_16x16x32_bf16 v[46:49], v[18:21], v[50:53], 0
	v_mfma_f32_16x16x32_bf16 v[50:53], v[26:29], v[50:53], 0
	v_mfma_f32_16x16x32_bf16 v[46:49], v[22:25], v[54:57], v[46:49]
	v_mfma_f32_16x16x32_bf16 v[50:53], v[30:33], v[54:57], v[50:53]
	v_mfma_f32_16x16x32_bf16 v[54:57], v[18:21], v[58:61], 0
	v_mfma_f32_16x16x32_bf16 v[58:61], v[26:29], v[58:61], 0
	v_mfma_f32_16x16x32_bf16 v[54:57], v[22:25], v[62:65], v[54:57]
	v_mfma_f32_16x16x32_bf16 v[58:61], v[30:33], v[62:65], v[58:61]
	s_setprio 0
	s_barrier
	v_lshl_add_u64 v[154:155], s[80:81], 0, v[142:143]
	s_add_i32 s43, s62, s88
	v_lshl_add_u64 v[130:131], v[154:155], 0, s[24:25]
	s_mov_b32 m0, s43
	s_add_i32 s53, s43, 0x2000
	ds_read_b128 v[62:65], v158 offset:16384
	ds_read_b128 v[86:89], v158 offset:17408
	ds_read_b128 v[98:101], v158 offset:18432
	ds_read_b128 v[102:105], v158 offset:19456
	ds_read_b128 v[114:117], v158 offset:20480
	ds_read_b128 v[118:121], v158 offset:21504
	ds_read_b128 v[122:125], v158 offset:22528
	ds_read_b128 v[126:129], v158 offset:23552
	global_load_lds_dwordx4 v[130:131], off
	v_lshl_add_u64 v[130:131], v[154:155], 0, s[26:27]
	s_mov_b32 m0, s53
	s_add_i32 s73, s63, s88
	global_load_lds_dwordx4 v[130:131], off
	v_lshl_add_u64 v[130:131], v[154:155], 0, s[28:29]
	s_mov_b32 m0, s73
	s_add_i32 s40, s73, 0x2000
	global_load_lds_dwordx4 v[130:131], off
	v_lshl_add_u64 v[130:131], v[154:155], 0, s[30:31]
	s_mov_b32 m0, s40
	s_nop 0
	global_load_lds_dwordx4 v[130:131], off
	v_lshl_add_u64 v[130:131], v[138:139], 0, s[24:25]
	s_mov_b32 m0, s44
	s_nop 0
	global_load_lds_dwordx4 v[130:131], off
	v_lshl_add_u64 v[130:131], v[138:139], 0, s[26:27]
	s_mov_b32 m0, s90
	s_nop 0
	global_load_lds_dwordx4 v[130:131], off
	s_waitcnt vmcnt(24)
	s_waitcnt lgkmcnt(0)
	s_barrier
	s_waitcnt lgkmcnt(0)
	s_setprio 1
	v_mfma_f32_16x16x32_bf16 v[130:133], v[2:5], v[62:65], 0
	v_mfma_f32_16x16x32_bf16 v[150:153], v[2:5], v[98:101], 0
	v_mfma_f32_16x16x32_bf16 v[170:173], v[2:5], v[114:117], 0
	v_mfma_f32_16x16x32_bf16 v[2:5], v[2:5], v[122:125], 0
	v_mfma_f32_16x16x32_bf16 v[130:133], v[6:9], v[86:89], v[130:133]
	v_mfma_f32_16x16x32_bf16 v[150:153], v[6:9], v[102:105], v[150:153]
	v_mfma_f32_16x16x32_bf16 v[170:173], v[6:9], v[118:121], v[170:173]
	v_mfma_f32_16x16x32_bf16 v[2:5], v[6:9], v[126:129], v[2:5]
	v_mfma_f32_16x16x32_bf16 v[6:9], v[10:13], v[122:125], 0
	v_mfma_f32_16x16x32_bf16 v[134:137], v[10:13], v[62:65], 0
	v_mfma_f32_16x16x32_bf16 v[166:169], v[10:13], v[98:101], 0
	v_mfma_f32_16x16x32_bf16 v[174:177], v[10:13], v[114:117], 0
	v_mfma_f32_16x16x32_bf16 v[6:9], v[14:17], v[126:129], v[6:9]
	v_mfma_f32_16x16x32_bf16 v[134:137], v[14:17], v[86:89], v[134:137]
	v_mfma_f32_16x16x32_bf16 v[166:169], v[14:17], v[102:105], v[166:169]
	v_mfma_f32_16x16x32_bf16 v[174:177], v[14:17], v[118:121], v[174:177]
	v_mfma_f32_16x16x32_bf16 v[10:13], v[18:21], v[62:65], 0
	v_mfma_f32_16x16x32_bf16 v[14:17], v[26:29], v[62:65], 0
	v_mfma_f32_16x16x32_bf16 v[62:65], v[18:21], v[98:101], 0
	v_mfma_f32_16x16x32_bf16 v[178:181], v[22:25], v[102:105], v[62:65]
	v_mfma_f32_16x16x32_bf16 v[62:65], v[26:29], v[98:101], 0
	v_mfma_f32_16x16x32_bf16 v[182:185], v[30:33], v[102:105], v[62:65]
	v_mfma_f32_16x16x32_bf16 v[62:65], v[18:21], v[114:117], 0
	v_mfma_f32_16x16x32_bf16 v[18:21], v[18:21], v[122:125], 0
	v_mfma_f32_16x16x32_bf16 v[10:13], v[22:25], v[86:89], v[10:13]
	v_mfma_f32_16x16x32_bf16 v[14:17], v[30:33], v[86:89], v[14:17]
	v_mfma_f32_16x16x32_bf16 v[186:189], v[22:25], v[118:121], v[62:65]
	v_mfma_f32_16x16x32_bf16 v[62:65], v[26:29], v[114:117], 0
	v_mfma_f32_16x16x32_bf16 v[194:197], v[22:25], v[126:129], v[18:21]
	v_mfma_f32_16x16x32_bf16 v[18:21], v[26:29], v[122:125], 0
	v_mfma_f32_16x16x32_bf16 v[190:193], v[30:33], v[118:121], v[62:65]
	v_mfma_f32_16x16x32_bf16 v[198:201], v[30:33], v[126:129], v[18:21]
	s_setprio 0
	s_barrier
	ds_read_b128 v[26:29], v159
	ds_read_b128 v[30:33], v159 offset:1024
	s_nop 0
	ds_read_b128 v[62:65], v159 offset:2048
	ds_read_b128 v[202:205], v159 offset:3072
	ds_read_b128 v[206:209], v160
	ds_read_b128 v[210:213], v160 offset:1024
	ds_read_b128 v[214:217], v160 offset:2048
	ds_read_b128 v[218:221], v160 offset:3072
	s_mov_b32 m0, s91
	v_lshl_add_u64 v[86:87], v[138:139], 0, s[28:29]
	ds_read_b128 v[18:21], v158 offset:32768
	ds_read_b128 v[22:25], v158 offset:33792
	ds_read_b128 v[222:225], v158 offset:34816
	ds_read_b128 v[226:229], v158 offset:35840
	ds_read_b128 v[230:233], v158 offset:36864
	ds_read_b128 v[234:237], v158 offset:37888
	ds_read_b128 v[238:241], v158 offset:38912
	ds_read_b128 v[242:245], v158 offset:39936
	global_load_lds_dwordx4 v[86:87], off
	v_lshl_add_u64 v[86:87], v[138:139], 0, s[30:31]
	s_mov_b32 m0, s92
	s_nop 0
	global_load_lds_dwordx4 v[86:87], off
	s_waitcnt vmcnt(8)
	s_waitcnt lgkmcnt(0)
	s_barrier
	s_waitcnt lgkmcnt(0)
	s_setprio 1
	v_mfma_f32_16x16x32_bf16 v[66:69], v[26:29], v[18:21], v[66:69]
	v_mfma_f32_16x16x32_bf16 v[118:121], v[30:33], v[22:25], v[66:69]
	v_mfma_f32_16x16x32_bf16 v[66:69], v[62:65], v[18:21], v[70:73]
	v_mfma_f32_16x16x32_bf16 v[114:117], v[202:205], v[22:25], v[66:69]
	v_mfma_f32_16x16x32_bf16 v[66:69], v[26:29], v[222:225], v[74:77]
	v_mfma_f32_16x16x32_bf16 v[102:105], v[30:33], v[226:229], v[66:69]
	v_mfma_f32_16x16x32_bf16 v[66:69], v[62:65], v[222:225], v[78:81]
	v_mfma_f32_16x16x32_bf16 v[98:101], v[202:205], v[226:229], v[66:69]
	v_mfma_f32_16x16x32_bf16 v[66:69], v[26:29], v[230:233], v[82:85]
	v_mfma_f32_16x16x32_bf16 v[86:89], v[30:33], v[234:237], v[66:69]
	v_mfma_f32_16x16x32_bf16 v[66:69], v[62:65], v[230:233], v[90:93]
	v_mfma_f32_16x16x32_bf16 v[82:85], v[202:205], v[234:237], v[66:69]
	v_mfma_f32_16x16x32_bf16 v[66:69], v[26:29], v[238:241], v[94:97]
	v_mfma_f32_16x16x32_bf16 v[70:73], v[62:65], v[238:241], v[106:109]
	v_mfma_f32_16x16x32_bf16 v[66:69], v[30:33], v[242:245], v[66:69]
	v_mfma_f32_16x16x32_bf16 v[70:73], v[202:205], v[242:245], v[70:73]
	v_mfma_f32_16x16x32_bf16 v[74:77], v[206:209], v[18:21], v[110:113]
	v_mfma_f32_16x16x32_bf16 v[18:21], v[214:217], v[18:21], v[34:37]
	v_mfma_f32_16x16x32_bf16 v[122:125], v[218:221], v[22:25], v[18:21]
	v_mfma_f32_16x16x32_bf16 v[18:21], v[206:209], v[222:225], v[38:41]
	v_mfma_f32_16x16x32_bf16 v[110:113], v[210:213], v[226:229], v[18:21]
	v_mfma_f32_16x16x32_bf16 v[18:21], v[214:217], v[222:225], v[42:45]
	v_mfma_f32_16x16x32_bf16 v[106:109], v[218:221], v[226:229], v[18:21]
	v_mfma_f32_16x16x32_bf16 v[18:21], v[206:209], v[230:233], v[46:49]
	v_mfma_f32_16x16x32_bf16 v[94:97], v[210:213], v[234:237], v[18:21]
	v_mfma_f32_16x16x32_bf16 v[18:21], v[214:217], v[230:233], v[50:53]
	v_mfma_f32_16x16x32_bf16 v[90:93], v[218:221], v[234:237], v[18:21]
	v_mfma_f32_16x16x32_bf16 v[18:21], v[206:209], v[238:241], v[54:57]
	v_mfma_f32_16x16x32_bf16 v[126:129], v[210:213], v[22:25], v[74:77]
	v_mfma_f32_16x16x32_bf16 v[74:77], v[210:213], v[242:245], v[18:21]
	v_mfma_f32_16x16x32_bf16 v[18:21], v[214:217], v[238:241], v[58:61]
	v_mfma_f32_16x16x32_bf16 v[78:81], v[218:221], v[242:245], v[18:21]
	s_setprio 0
	s_barrier
; #define PG8_WAIT_V(n) asm volatile("s_waitcnt vmcnt(" #n ")" ::: "memory")
; template <class Epi, class Sched, bool ALIGN_EPI = true, bool SP2 = true, bool FULLLINE = false, bool NOSTAGE = false, bool FP8 = false>
; __device__ __forceinline__ void gemm_phase(PG8_LAS unsigned char* lds, const Gemm g, const Sched& S, const Epi& E) {
;     ...
;         static_assert(SP2, "only the SP2 loop is kept");
;         { const int t = 0; if constexpr (Epi::NST == 16) PG8_ITER(PG8_WAIT_V(24)); else if constexpr (Epi::NST == 8) PG8_ITER(PG8_WAIT_V(16)); else PG8_ITER(PG8_WAIT_V(8)); }
;         for (int t = 2; t < nt; t += 2) PG8_ITER(PG8_WAIT_V(8));
	s_add_i32 s41, s46, s88
	s_nop 4
	v_lshl_add_u64 v[18:19], v[154:155], 0, s[34:35]
	s_mov_b32 m0, s41
	s_add_i32 s50, s41, 0x2000
	ds_read_b128 v[42:45], v158 offset:49152
	ds_read_b128 v[46:49], v158 offset:50176
	ds_read_b128 v[222:225], v158 offset:51200
	ds_read_b128 v[226:229], v158 offset:52224
	ds_read_b128 v[230:233], v158 offset:53248
	ds_read_b128 v[234:237], v158 offset:54272
	ds_read_b128 v[238:241], v158 offset:55296
	ds_read_b128 v[242:245], v158 offset:56320
	global_load_lds_dwordx4 v[18:19], off
	v_lshl_add_u64 v[18:19], v[154:155], 0, s[36:37]
	s_mov_b32 m0, s50
	s_mov_b64 s[56:57], 0x80180
	s_add_i32 s51, s47, s88
	global_load_lds_dwordx4 v[18:19], off
	v_lshl_add_u64 v[18:19], v[154:155], 0, s[56:57]
	s_mov_b32 m0, s51
	s_mov_b64 s[56:57], 0xc0180
	s_add_i32 s33, s51, 0x2000
	global_load_lds_dwordx4 v[18:19], off
	v_lshl_add_u64 v[18:19], v[154:155], 0, s[56:57]
	s_mov_b32 m0, s33
	s_nop 0
	global_load_lds_dwordx4 v[18:19], off
	v_lshl_add_u64 v[18:19], v[138:139], 0, s[34:35]
	s_mov_b32 m0, s93
	s_nop 0
	global_load_lds_dwordx4 v[18:19], off
	v_lshl_add_u64 v[18:19], v[138:139], 0, s[36:37]
	s_mov_b32 m0, s94
	s_nop 0
	global_load_lds_dwordx4 v[18:19], off
	s_waitcnt vmcnt(8)
	s_waitcnt lgkmcnt(0)
	s_barrier
	s_waitcnt lgkmcnt(0)
	s_setprio 1
	v_mfma_f32_16x16x32_bf16 v[18:21], v[26:29], v[42:45], v[130:133]
	v_mfma_f32_16x16x32_bf16 v[50:53], v[30:33], v[46:49], v[18:21]
	v_mfma_f32_16x16x32_bf16 v[18:21], v[62:65], v[42:45], v[134:137]
	v_mfma_f32_16x16x32_bf16 v[54:57], v[202:205], v[46:49], v[18:21]
	v_mfma_f32_16x16x32_bf16 v[18:21], v[26:29], v[222:225], v[150:153]
	v_mfma_f32_16x16x32_bf16 v[34:37], v[30:33], v[226:229], v[18:21]
	v_mfma_f32_16x16x32_bf16 v[18:21], v[62:65], v[222:225], v[166:169]
	v_mfma_f32_16x16x32_bf16 v[38:41], v[202:205], v[226:229], v[18:21]
	v_mfma_f32_16x16x32_bf16 v[18:21], v[26:29], v[230:233], v[170:173]
	v_mfma_f32_16x16x32_bf16 v[22:25], v[62:65], v[230:233], v[174:177]
	v_mfma_f32_16x16x32_bf16 v[2:5], v[26:29], v[238:241], v[2:5]
	v_mfma_f32_16x16x32_bf16 v[6:9], v[62:65], v[238:241], v[6:9]
	v_mfma_f32_16x16x32_bf16 v[18:21], v[30:33], v[234:237], v[18:21]
	v_mfma_f32_16x16x32_bf16 v[22:25], v[202:205], v[234:237], v[22:25]
	v_mfma_f32_16x16x32_bf16 v[2:5], v[30:33], v[242:245], v[2:5]
	v_mfma_f32_16x16x32_bf16 v[6:9], v[202:205], v[242:245], v[6:9]
	v_mfma_f32_16x16x32_bf16 v[10:13], v[206:209], v[42:45], v[10:13]
	v_mfma_f32_16x16x32_bf16 v[58:61], v[210:213], v[46:49], v[10:13]
	v_mfma_f32_16x16x32_bf16 v[10:13], v[214:217], v[42:45], v[14:17]
	v_mfma_f32_16x16x32_bf16 v[62:65], v[218:221], v[46:49], v[10:13]
	v_mfma_f32_16x16x32_bf16 v[10:13], v[206:209], v[222:225], v[178:181]
	v_mfma_f32_16x16x32_bf16 v[42:45], v[210:213], v[226:229], v[10:13]
	v_mfma_f32_16x16x32_bf16 v[10:13], v[214:217], v[222:225], v[182:185]
	v_mfma_f32_16x16x32_bf16 v[46:49], v[218:221], v[226:229], v[10:13]
	v_mfma_f32_16x16x32_bf16 v[10:13], v[206:209], v[230:233], v[186:189]
	v_mfma_f32_16x16x32_bf16 v[26:29], v[210:213], v[234:237], v[10:13]
	v_mfma_f32_16x16x32_bf16 v[10:13], v[214:217], v[230:233], v[190:193]
	v_mfma_f32_16x16x32_bf16 v[30:33], v[218:221], v[234:237], v[10:13]
	v_mfma_f32_16x16x32_bf16 v[10:13], v[206:209], v[238:241], v[194:197]
	v_mfma_f32_16x16x32_bf16 v[14:17], v[214:217], v[238:241], v[198:201]
	v_mfma_f32_16x16x32_bf16 v[10:13], v[210:213], v[242:245], v[10:13]
	v_mfma_f32_16x16x32_bf16 v[14:17], v[218:221], v[242:245], v[14:17]
	s_setprio 0
	s_barrier
	s_add_u32 s82, s82, 0x80180
	s_addc_u32 s83, s83, 0
	s_add_u32 s56, s80, 0x200
	s_addc_u32 s57, s81, 0
	s_mov_b32 s75, 0
.LBB0_262:
	ds_read_b128 v[130:133], v156
	ds_read_b128 v[134:137], v156 offset:1024
	ds_read_b128 v[150:153], v156 offset:2048
	ds_read_b128 v[166:169], v156 offset:3072
	ds_read_b128 v[170:173], v157
	ds_read_b128 v[174:177], v157 offset:1024
	ds_read_b128 v[178:181], v157 offset:2048
	ds_read_b128 v[182:185], v157 offset:3072
	s_add_u32 s0, s82, 0xfff80080
	s_addc_u32 s1, s83, -1
	s_cmp_eq_u32 s75, 28
	s_cselect_b32 s81, s3, s1
	s_cselect_b32 s80, s11, s0
	s_cselect_b32 vcc_hi, s13, s57
	s_cselect_b32 vcc_lo, s42, s56
	s_mov_b32 m0, s89
	v_lshl_add_u64 v[138:139], s[82:83], 0, v[144:145]
	ds_read_b128 v[186:189], v158
	ds_read_b128 v[190:193], v158 offset:1024
	ds_read_b128 v[194:197], v158 offset:2048
	ds_read_b128 v[198:201], v158 offset:3072
	ds_read_b128 v[202:205], v158 offset:4096
	ds_read_b128 v[206:209], v158 offset:5120
	ds_read_b128 v[210:213], v158 offset:6144
	ds_read_b128 v[214:217], v158 offset:7168
	global_load_lds_dwordx4 v[138:139], off
	v_lshl_add_u64 v[138:139], v[138:139], 0, s[38:39]
	s_mov_b32 m0, s45
	s_nop 0
	global_load_lds_dwordx4 v[138:139], off
	s_waitcnt vmcnt(8)
	s_waitcnt lgkmcnt(0)
	s_barrier
	s_waitcnt lgkmcnt(0)
	s_setprio 1
	v_mfma_f32_16x16x32_bf16 v[118:121], v[130:133], v[186:189], v[118:121]
	v_mfma_f32_16x16x32_bf16 v[114:117], v[150:153], v[186:189], v[114:117]
	v_mfma_f32_16x16x32_bf16 v[102:105], v[130:133], v[194:197], v[102:105]
	v_mfma_f32_16x16x32_bf16 v[98:101], v[150:153], v[194:197], v[98:101]
	v_mfma_f32_16x16x32_bf16 v[86:89], v[130:133], v[202:205], v[86:89]
	v_mfma_f32_16x16x32_bf16 v[82:85], v[150:153], v[202:205], v[82:85]
	v_mfma_f32_16x16x32_bf16 v[66:69], v[130:133], v[210:213], v[66:69]
	v_mfma_f32_16x16x32_bf16 v[70:73], v[150:153], v[210:213], v[70:73]
	v_mfma_f32_16x16x32_bf16 v[118:121], v[134:137], v[190:193], v[118:121]
	v_mfma_f32_16x16x32_bf16 v[114:117], v[166:169], v[190:193], v[114:117]
	v_mfma_f32_16x16x32_bf16 v[102:105], v[134:137], v[198:201], v[102:105]
	v_mfma_f32_16x16x32_bf16 v[98:101], v[166:169], v[198:201], v[98:101]
	v_mfma_f32_16x16x32_bf16 v[86:89], v[134:137], v[206:209], v[86:89]
	v_mfma_f32_16x16x32_bf16 v[82:85], v[166:169], v[206:209], v[82:85]
	v_mfma_f32_16x16x32_bf16 v[66:69], v[134:137], v[214:217], v[66:69]
	v_mfma_f32_16x16x32_bf16 v[70:73], v[166:169], v[214:217], v[70:73]
	v_mfma_f32_16x16x32_bf16 v[126:129], v[170:173], v[186:189], v[126:129]
	v_mfma_f32_16x16x32_bf16 v[122:125], v[178:181], v[186:189], v[122:125]
	v_mfma_f32_16x16x32_bf16 v[110:113], v[170:173], v[194:197], v[110:113]
	v_mfma_f32_16x16x32_bf16 v[106:109], v[178:181], v[194:197], v[106:109]
	v_mfma_f32_16x16x32_bf16 v[94:97], v[170:173], v[202:205], v[94:97]
	v_mfma_f32_16x16x32_bf16 v[90:93], v[178:181], v[202:205], v[90:93]
	v_mfma_f32_16x16x32_bf16 v[74:77], v[170:173], v[210:213], v[74:77]
	v_mfma_f32_16x16x32_bf16 v[78:81], v[178:181], v[210:213], v[78:81]
	v_mfma_f32_16x16x32_bf16 v[126:129], v[174:177], v[190:193], v[126:129]
	v_mfma_f32_16x16x32_bf16 v[122:125], v[182:185], v[190:193], v[122:125]
	v_mfma_f32_16x16x32_bf16 v[110:113], v[174:177], v[198:201], v[110:113]
	v_mfma_f32_16x16x32_bf16 v[106:109], v[182:185], v[198:201], v[106:109]
	v_mfma_f32_16x16x32_bf16 v[94:97], v[174:177], v[206:209], v[94:97]
	v_mfma_f32_16x16x32_bf16 v[90:93], v[182:185], v[206:209], v[90:93]
	v_mfma_f32_16x16x32_bf16 v[74:77], v[174:177], v[214:217], v[74:77]
	v_mfma_f32_16x16x32_bf16 v[78:81], v[182:185], v[214:217], v[78:81]
	s_setprio 0
	s_barrier
	s_mov_b32 m0, s43
	v_lshl_add_u64 v[138:139], vcc, 0, v[142:143]
	ds_read_b128 v[186:189], v158 offset:16384
	ds_read_b128 v[190:193], v158 offset:17408
	ds_read_b128 v[194:197], v158 offset:18432
	ds_read_b128 v[198:201], v158 offset:19456
	ds_read_b128 v[202:205], v158 offset:20480
	ds_read_b128 v[206:209], v158 offset:21504
	ds_read_b128 v[210:213], v158 offset:22528
	ds_read_b128 v[214:217], v158 offset:23552
	global_load_lds_dwordx4 v[138:139], off
	v_lshl_add_u64 v[154:155], v[138:139], 0, s[38:39]
	s_mov_b32 m0, s53
	s_nop 0
	global_load_lds_dwordx4 v[154:155], off
	v_lshl_add_u64 v[154:155], v[138:139], 0, s[60:61]
	s_mov_b32 m0, s73
	s_nop 0
	global_load_lds_dwordx4 v[154:155], off
	v_lshl_add_u64 v[154:155], v[138:139], 0, s[66:67]
	s_mov_b32 m0, s40
	s_nop 0
	global_load_lds_dwordx4 v[154:155], off
	v_lshl_add_u64 v[154:155], s[80:81], 0, v[140:141]
	s_mov_b32 m0, s44
	v_lshl_add_u64 v[218:219], v[154:155], 0, s[38:39]
	global_load_lds_dwordx4 v[154:155], off
	s_mov_b32 m0, s90
	s_nop 0
	global_load_lds_dwordx4 v[218:219], off
	s_waitcnt vmcnt(8)
	s_waitcnt lgkmcnt(0)
	s_barrier
	s_waitcnt lgkmcnt(0)
	s_setprio 1
	v_mfma_f32_16x16x32_bf16 v[50:53], v[130:133], v[186:189], v[50:53]
	v_mfma_f32_16x16x32_bf16 v[54:57], v[150:153], v[186:189], v[54:57]
	v_mfma_f32_16x16x32_bf16 v[34:37], v[130:133], v[194:197], v[34:37]
	v_mfma_f32_16x16x32_bf16 v[38:41], v[150:153], v[194:197], v[38:41]
	v_mfma_f32_16x16x32_bf16 v[18:21], v[130:133], v[202:205], v[18:21]
	v_mfma_f32_16x16x32_bf16 v[22:25], v[150:153], v[202:205], v[22:25]
	v_mfma_f32_16x16x32_bf16 v[2:5], v[130:133], v[210:213], v[2:5]
	v_mfma_f32_16x16x32_bf16 v[6:9], v[150:153], v[210:213], v[6:9]
	v_mfma_f32_16x16x32_bf16 v[50:53], v[134:137], v[190:193], v[50:53]
	v_mfma_f32_16x16x32_bf16 v[54:57], v[166:169], v[190:193], v[54:57]
	v_mfma_f32_16x16x32_bf16 v[34:37], v[134:137], v[198:201], v[34:37]
	v_mfma_f32_16x16x32_bf16 v[38:41], v[166:169], v[198:201], v[38:41]
	v_mfma_f32_16x16x32_bf16 v[18:21], v[134:137], v[206:209], v[18:21]
	v_mfma_f32_16x16x32_bf16 v[22:25], v[166:169], v[206:209], v[22:25]
	v_mfma_f32_16x16x32_bf16 v[2:5], v[134:137], v[214:217], v[2:5]
	v_mfma_f32_16x16x32_bf16 v[6:9], v[166:169], v[214:217], v[6:9]
	v_mfma_f32_16x16x32_bf16 v[58:61], v[170:173], v[186:189], v[58:61]
	v_mfma_f32_16x16x32_bf16 v[62:65], v[178:181], v[186:189], v[62:65]
	v_mfma_f32_16x16x32_bf16 v[42:45], v[170:173], v[194:197], v[42:45]
	v_mfma_f32_16x16x32_bf16 v[46:49], v[178:181], v[194:197], v[46:49]
	v_mfma_f32_16x16x32_bf16 v[26:29], v[170:173], v[202:205], v[26:29]
	v_mfma_f32_16x16x32_bf16 v[30:33], v[178:181], v[202:205], v[30:33]
	v_mfma_f32_16x16x32_bf16 v[10:13], v[170:173], v[210:213], v[10:13]
	v_mfma_f32_16x16x32_bf16 v[14:17], v[178:181], v[210:213], v[14:17]
	v_mfma_f32_16x16x32_bf16 v[58:61], v[174:177], v[190:193], v[58:61]
	v_mfma_f32_16x16x32_bf16 v[62:65], v[182:185], v[190:193], v[62:65]
	v_mfma_f32_16x16x32_bf16 v[42:45], v[174:177], v[198:201], v[42:45]
	v_mfma_f32_16x16x32_bf16 v[46:49], v[182:185], v[198:201], v[46:49]
	v_mfma_f32_16x16x32_bf16 v[26:29], v[174:177], v[206:209], v[26:29]
	v_mfma_f32_16x16x32_bf16 v[30:33], v[182:185], v[206:209], v[30:33]
	v_mfma_f32_16x16x32_bf16 v[10:13], v[174:177], v[214:217], v[10:13]
	v_mfma_f32_16x16x32_bf16 v[14:17], v[182:185], v[214:217], v[14:17]
	s_setprio 0
	s_barrier
; #define PG8_WAIT_V(n) asm volatile("s_waitcnt vmcnt(" #n ")" ::: "memory")
; template <class Epi, class Sched, bool ALIGN_EPI = true, bool SP2 = true, bool FULLLINE = false, bool NOSTAGE = false, bool FP8 = false>
; __device__ __forceinline__ void gemm_phase(PG8_LAS unsigned char* lds, const Gemm g, const Sched& S, const Epi& E) {
;     ...
;         for (int t = 2; t < nt; t += 2) PG8_ITER(PG8_WAIT_V(8));
	ds_read_b128 v[130:133], v159
	ds_read_b128 v[134:137], v159 offset:1024
	ds_read_b128 v[150:153], v159 offset:2048
	ds_read_b128 v[166:169], v159 offset:3072
	ds_read_b128 v[170:173], v160
	ds_read_b128 v[174:177], v160 offset:1024
	ds_read_b128 v[178:181], v160 offset:2048
	ds_read_b128 v[182:185], v160 offset:3072
	s_mov_b32 m0, s91
	v_lshl_add_u64 v[218:219], v[154:155], 0, s[60:61]
	ds_read_b128 v[186:189], v158 offset:32768
	ds_read_b128 v[190:193], v158 offset:33792
	ds_read_b128 v[194:197], v158 offset:34816
	ds_read_b128 v[198:201], v158 offset:35840
	ds_read_b128 v[202:205], v158 offset:36864
	ds_read_b128 v[206:209], v158 offset:37888
	ds_read_b128 v[210:213], v158 offset:38912
	ds_read_b128 v[214:217], v158 offset:39936
	global_load_lds_dwordx4 v[218:219], off
	v_lshl_add_u64 v[218:219], v[154:155], 0, s[66:67]
	s_mov_b32 m0, s92
	s_nop 0
	global_load_lds_dwordx4 v[218:219], off
	s_waitcnt vmcnt(8)
	s_waitcnt lgkmcnt(0)
	s_barrier
	s_waitcnt lgkmcnt(0)
	s_setprio 1
	v_mfma_f32_16x16x32_bf16 v[118:121], v[130:133], v[186:189], v[118:121]
	v_mfma_f32_16x16x32_bf16 v[114:117], v[150:153], v[186:189], v[114:117]
	v_mfma_f32_16x16x32_bf16 v[102:105], v[130:133], v[194:197], v[102:105]
	v_mfma_f32_16x16x32_bf16 v[98:101], v[150:153], v[194:197], v[98:101]
	v_mfma_f32_16x16x32_bf16 v[86:89], v[130:133], v[202:205], v[86:89]
	v_mfma_f32_16x16x32_bf16 v[82:85], v[150:153], v[202:205], v[82:85]
	v_mfma_f32_16x16x32_bf16 v[66:69], v[130:133], v[210:213], v[66:69]
	v_mfma_f32_16x16x32_bf16 v[70:73], v[150:153], v[210:213], v[70:73]
	v_mfma_f32_16x16x32_bf16 v[118:121], v[134:137], v[190:193], v[118:121]
	v_mfma_f32_16x16x32_bf16 v[114:117], v[166:169], v[190:193], v[114:117]
	v_mfma_f32_16x16x32_bf16 v[102:105], v[134:137], v[198:201], v[102:105]
	v_mfma_f32_16x16x32_bf16 v[98:101], v[166:169], v[198:201], v[98:101]
	v_mfma_f32_16x16x32_bf16 v[86:89], v[134:137], v[206:209], v[86:89]
	v_mfma_f32_16x16x32_bf16 v[82:85], v[166:169], v[206:209], v[82:85]
	v_mfma_f32_16x16x32_bf16 v[66:69], v[134:137], v[214:217], v[66:69]
	v_mfma_f32_16x16x32_bf16 v[70:73], v[166:169], v[214:217], v[70:73]
	v_mfma_f32_16x16x32_bf16 v[126:129], v[170:173], v[186:189], v[126:129]
	v_mfma_f32_16x16x32_bf16 v[122:125], v[178:181], v[186:189], v[122:125]
	v_mfma_f32_16x16x32_bf16 v[110:113], v[170:173], v[194:197], v[110:113]
	v_mfma_f32_16x16x32_bf16 v[106:109], v[178:181], v[194:197], v[106:109]
	v_mfma_f32_16x16x32_bf16 v[94:97], v[170:173], v[202:205], v[94:97]
	v_mfma_f32_16x16x32_bf16 v[90:93], v[178:181], v[202:205], v[90:93]
	v_mfma_f32_16x16x32_bf16 v[74:77], v[170:173], v[210:213], v[74:77]
	v_mfma_f32_16x16x32_bf16 v[78:81], v[178:181], v[210:213], v[78:81]
	v_mfma_f32_16x16x32_bf16 v[126:129], v[174:177], v[190:193], v[126:129]
	v_mfma_f32_16x16x32_bf16 v[122:125], v[182:185], v[190:193], v[122:125]
	v_mfma_f32_16x16x32_bf16 v[110:113], v[174:177], v[198:201], v[110:113]
	v_mfma_f32_16x16x32_bf16 v[106:109], v[182:185], v[198:201], v[106:109]
	v_mfma_f32_16x16x32_bf16 v[94:97], v[174:177], v[206:209], v[94:97]
	v_mfma_f32_16x16x32_bf16 v[90:93], v[182:185], v[206:209], v[90:93]
	v_mfma_f32_16x16x32_bf16 v[74:77], v[174:177], v[214:217], v[74:77]
	v_mfma_f32_16x16x32_bf16 v[78:81], v[182:185], v[214:217], v[78:81]
	s_setprio 0
	s_barrier
	s_mov_b32 m0, s41
	v_lshl_add_u64 v[218:219], v[138:139], 0, s[68:69]
	ds_read_b128 v[186:189], v158 offset:49152
	ds_read_b128 v[190:193], v158 offset:50176
	ds_read_b128 v[194:197], v158 offset:51200
	ds_read_b128 v[198:201], v158 offset:52224
	ds_read_b128 v[202:205], v158 offset:53248
	ds_read_b128 v[206:209], v158 offset:54272
	ds_read_b128 v[210:213], v158 offset:55296
	ds_read_b128 v[214:217], v158 offset:56320
	global_load_lds_dwordx4 v[218:219], off
	v_lshl_add_u64 v[218:219], v[138:139], 0, s[70:71]
	s_mov_b32 m0, s50
	s_nop 0
	global_load_lds_dwordx4 v[218:219], off
	v_lshl_add_u64 v[218:219], v[138:139], 0, s[20:21]
	s_mov_b32 m0, s51
	v_lshl_add_u64 v[138:139], v[138:139], 0, s[22:23]
	global_load_lds_dwordx4 v[218:219], off
	s_mov_b32 m0, s33
	s_nop 0
	global_load_lds_dwordx4 v[138:139], off
	v_lshl_add_u64 v[138:139], v[154:155], 0, s[68:69]
	s_mov_b32 m0, s93
	s_nop 0
	global_load_lds_dwordx4 v[138:139], off
	v_lshl_add_u64 v[138:139], v[154:155], 0, s[70:71]
	s_mov_b32 m0, s94
	s_nop 0
	global_load_lds_dwordx4 v[138:139], off
	s_waitcnt vmcnt(8)
	s_waitcnt lgkmcnt(0)
	s_barrier
	s_waitcnt lgkmcnt(0)
	s_setprio 1
	v_mfma_f32_16x16x32_bf16 v[50:53], v[130:133], v[186:189], v[50:53]
	v_mfma_f32_16x16x32_bf16 v[54:57], v[150:153], v[186:189], v[54:57]
	v_mfma_f32_16x16x32_bf16 v[34:37], v[130:133], v[194:197], v[34:37]
	v_mfma_f32_16x16x32_bf16 v[38:41], v[150:153], v[194:197], v[38:41]
	v_mfma_f32_16x16x32_bf16 v[18:21], v[130:133], v[202:205], v[18:21]
	v_mfma_f32_16x16x32_bf16 v[22:25], v[150:153], v[202:205], v[22:25]
	v_mfma_f32_16x16x32_bf16 v[2:5], v[130:133], v[210:213], v[2:5]
	v_mfma_f32_16x16x32_bf16 v[6:9], v[150:153], v[210:213], v[6:9]
	v_mfma_f32_16x16x32_bf16 v[50:53], v[134:137], v[190:193], v[50:53]
	v_mfma_f32_16x16x32_bf16 v[54:57], v[166:169], v[190:193], v[54:57]
	v_mfma_f32_16x16x32_bf16 v[34:37], v[134:137], v[198:201], v[34:37]
	v_mfma_f32_16x16x32_bf16 v[38:41], v[166:169], v[198:201], v[38:41]
	v_mfma_f32_16x16x32_bf16 v[18:21], v[134:137], v[206:209], v[18:21]
	v_mfma_f32_16x16x32_bf16 v[22:25], v[166:169], v[206:209], v[22:25]
	v_mfma_f32_16x16x32_bf16 v[2:5], v[134:137], v[214:217], v[2:5]
	v_mfma_f32_16x16x32_bf16 v[6:9], v[166:169], v[214:217], v[6:9]
	v_mfma_f32_16x16x32_bf16 v[58:61], v[170:173], v[186:189], v[58:61]
	v_mfma_f32_16x16x32_bf16 v[62:65], v[178:181], v[186:189], v[62:65]
	v_mfma_f32_16x16x32_bf16 v[42:45], v[170:173], v[194:197], v[42:45]
	v_mfma_f32_16x16x32_bf16 v[46:49], v[178:181], v[194:197], v[46:49]
	v_mfma_f32_16x16x32_bf16 v[26:29], v[170:173], v[202:205], v[26:29]
	v_mfma_f32_16x16x32_bf16 v[30:33], v[178:181], v[202:205], v[30:33]
	v_mfma_f32_16x16x32_bf16 v[10:13], v[170:173], v[210:213], v[10:13]
	v_mfma_f32_16x16x32_bf16 v[14:17], v[178:181], v[210:213], v[14:17]
	v_mfma_f32_16x16x32_bf16 v[58:61], v[174:177], v[190:193], v[58:61]
	v_mfma_f32_16x16x32_bf16 v[62:65], v[182:185], v[190:193], v[62:65]
	v_mfma_f32_16x16x32_bf16 v[42:45], v[174:177], v[198:201], v[42:45]
	v_mfma_f32_16x16x32_bf16 v[46:49], v[182:185], v[198:201], v[46:49]
	v_mfma_f32_16x16x32_bf16 v[26:29], v[174:177], v[206:209], v[26:29]
	v_mfma_f32_16x16x32_bf16 v[30:33], v[182:185], v[206:209], v[30:33]
	v_mfma_f32_16x16x32_bf16 v[10:13], v[174:177], v[214:217], v[10:13]
	v_mfma_f32_16x16x32_bf16 v[14:17], v[182:185], v[214:217], v[14:17]
	s_setprio 0
	s_barrier
	s_add_i32 s75, s75, 2
	s_add_u32 s82, s82, 0x100
	s_addc_u32 s83, s83, 0
	s_add_u32 s56, s56, 0x100
	s_addc_u32 s57, s57, 0
	s_cmp_gt_u32 s75, 29
	s_cbranch_scc0 .LBB0_262
	s_and_b64 vcc, exec, s[18:19]
	s_cbranch_vccz .LBB0_265
	s_barrier

; template <class Epi, class Sched, bool ALIGN_EPI = true, bool SP2 = true, bool FULLLINE = false, bool NOSTAGE = false, bool FP8 = false>
; __device__ __forceinline__ void gemm_phase(PG8_LAS unsigned char* lds, const Gemm g, const Sched& S, const Epi& E) {
;     const int tid = threadIdx.x, wid = __builtin_amdgcn_readfirstlane(tid >> 6), lane = tid & 63, wr = wid >> 2, wc = wid & 3, fr = lane & 15, fq = lane >> 4;
;     const int K = g.K, nt = K / BK;
;     unsigned voffA_, voffB_;
;     { int R, C; stage_rc(tid * 16, R, C); const int Rb = Epi::PERM ? ((R & ~31) + perm32(R & 31)) : R;
;       voffA_ = (unsigned)(R * g.lda + C) * 2u; voffB_ = (unsigned)(Rb * g.ldb + C) * 2u; }
;     const unsigned voffA = voffA_, voffB = voffB_;
;     const size_t pstepoffA = (size_t)64 * g.lda * 2, pstepoffB = (size_t)64 * g.ldb * 2;
;     const size_t kstep = (size_t)(BK * 2);
;     const size_t hstepA = (size_t)HALF * g.lda * 2, hstepB = (size_t)HALF * g.ldb * 2;
;     const size_t tstepA = 2 * hstepA, tstepB = 2 * hstepB;
;     const unsigned ldsw = (unsigned)wid * 1024u;
;     const int aoff = lds_byte(wr * 64 + fr, fq * 8), boff = lds_byte(wc * 32 + fr, fq * 8);
;     ...
;     if (wr == 1) __builtin_amdgcn_s_setprio(1);
.LBB0_582:
	s_waitcnt vmcnt(0)
	v_cndmask_b32_e64 v4, 0, 1, s[10:11]
	v_cmp_ne_u32_e64 s[6:7], 1, v4
	s_andn2_b64 vcc, exec, s[10:11]
	s_barrier
	s_barrier
	s_cbranch_vccnz .LBB0_584
.LBB0_584:
	v_and_b32_e32 v4, 48, v0
	v_lshlrev_b32_e32 v5, 6, v0
	s_movk_i32 s1, 0x3c0
	s_add_u32 s63, s48, 0x104000
	v_and_or_b32 v4, v5, s1, v4
	v_lshlrev_b32_e32 v5, 2, v0
	s_addc_u32 s80, s49, 0
	s_lshl_b32 s0, s13, 13
	v_and_b32_e32 v5, 32, v5
	v_bitop3_b32 v6, v4, s0, v5 bitop3:0xde
	s_lshl_b32 s0, s12, 5
	s_and_b32 s82, s0, 0x60
	s_lshl_b32 s0, s82, 7
	s_lshl_b32 s81, s13, 6
	v_bitop3_b32 v4, s0, v4, v5 bitop3:0xf6
	v_lshlrev_b32_e32 v5, 10, v0
	s_cmpk_lt_u32 s9, 0x100
	v_and_b32_e32 v5, 0x60000, v5
	v_lshlrev_b32_e32 v1, 13, v1
	s_cselect_b64 s[10:11], -1, 0
	v_or3_b32 v1, v2, v5, v1
	s_add_i32 s85, 0, 0x10000
	s_add_i32 s87, 0, 0x14000
	s_add_i32 s90, 0, 0x18000
	s_add_i32 s91, 0, 0x1c000
	s_sext_i32_i8 s75, s8
	s_ashr_i32 s83, s86, 31
	v_add_u32_e32 v150, v1, v3
	v_mov_b32_e32 v151, 0
	s_mov_b32 s84, 0
	v_mov_b64_e32 v[152:153], 0x200
	v_mov_b64_e32 v[154:155], 0x1ff
	v_add_u32_e32 v160, s85, v4
	v_add_u32_e32 v161, s87, v4
	v_add_u32_e32 v162, 0, v6
	s_mov_b64 s[12:13], 0x100080
	s_add_i32 s88, s47, 0xc000
	s_mov_b64 s[14:15], 0x180080
	s_add_i32 s89, s47, 0xe000
	s_mov_b64 s[16:17], 0x100
	s_mov_b64 s[18:19], 0x80100
	s_mov_b64 s[20:21], 0x100100
	s_mov_b64 s[22:23], 0x180100
	v_add_u32_e32 v163, s90, v4
	v_add_u32_e32 v164, s91, v4
	s_mov_b64 s[24:25], 0x180
	s_waitcnt lgkmcnt(0)
	s_mov_b64 s[26:27], 0x80180
	s_mov_b64 s[28:29], 0x80000
	s_mov_b64 s[30:31], 0x100000
	s_mov_b64 s[34:35], 0x180000
	s_mov_b64 s[36:37], 0x80
	s_mov_b64 s[38:39], 0x80080
	s_branch .LBB0_587

.LBB0_593:
	s_ashr_i32 s69, s68, 31
	s_lshl_b64 s[40:41], s[68:69], 21
	s_add_u32 s70, s42, s40
	ds_read_b128 v[2:5], v160
	ds_read_b128 v[6:9], v160 offset:1024
	ds_read_b128 v[10:13], v160 offset:2048
	ds_read_b128 v[14:17], v160 offset:3072
	ds_read_b128 v[18:21], v161
	ds_read_b128 v[22:25], v161 offset:1024
	ds_read_b128 v[26:29], v161 offset:2048
	ds_read_b128 v[30:33], v161 offset:3072
	s_addc_u32 s71, s43, s41
	s_ashr_i32 s67, s66, 31
	s_lshl_b64 s[40:41], s[66:67], 21
	s_add_u32 s72, s44, s40
	s_addc_u32 s73, s45, s41
	s_and_b64 s[40:41], s[8:9], exec
	s_cselect_b32 s67, s71, s79
	s_cselect_b32 s69, s70, s78
	s_cselect_b32 s92, s73, s77
	s_cselect_b32 s93, s72, s76
	v_lshl_add_u64 v[246:247], s[78:79], 0, v[146:147]
	s_mov_b32 m0, s88
	v_lshl_add_u64 v[66:67], v[246:247], 0, s[12:13]
	ds_read_b128 v[34:37], v162
	ds_read_b128 v[38:41], v162 offset:1024
	ds_read_b128 v[42:45], v162 offset:2048
	ds_read_b128 v[46:49], v162 offset:3072
	ds_read_b128 v[50:53], v162 offset:4096
	ds_read_b128 v[54:57], v162 offset:5120
	ds_read_b128 v[58:61], v162 offset:6144
	ds_read_b128 v[62:65], v162 offset:7168
	global_load_lds_dwordx4 v[66:67], off
	v_lshl_add_u64 v[66:67], v[246:247], 0, s[14:15]
	s_mov_b32 m0, s89
	s_nop 0
	global_load_lds_dwordx4 v[66:67], off
	s_waitcnt vmcnt(24)
	s_waitcnt lgkmcnt(0)
	s_barrier
	s_waitcnt lgkmcnt(0)
	s_setprio 1
	v_mfma_f32_16x16x32_bf16 v[66:69], v[2:5], v[34:37], 0
	v_mfma_f32_16x16x32_bf16 v[70:73], v[10:13], v[34:37], 0
	v_mfma_f32_16x16x32_bf16 v[74:77], v[2:5], v[42:45], 0
	v_mfma_f32_16x16x32_bf16 v[78:81], v[10:13], v[42:45], 0
	v_mfma_f32_16x16x32_bf16 v[82:85], v[2:5], v[50:53], 0
	v_mfma_f32_16x16x32_bf16 v[86:89], v[10:13], v[50:53], 0
	v_mfma_f32_16x16x32_bf16 v[90:93], v[2:5], v[58:61], 0
	v_mfma_f32_16x16x32_bf16 v[94:97], v[10:13], v[58:61], 0
	v_mfma_f32_16x16x32_bf16 v[66:69], v[6:9], v[38:41], v[66:69]
	v_mfma_f32_16x16x32_bf16 v[70:73], v[14:17], v[38:41], v[70:73]
	v_mfma_f32_16x16x32_bf16 v[74:77], v[6:9], v[46:49], v[74:77]
	v_mfma_f32_16x16x32_bf16 v[78:81], v[14:17], v[46:49], v[78:81]
	v_mfma_f32_16x16x32_bf16 v[82:85], v[6:9], v[54:57], v[82:85]
	v_mfma_f32_16x16x32_bf16 v[86:89], v[14:17], v[54:57], v[86:89]
	v_mfma_f32_16x16x32_bf16 v[90:93], v[6:9], v[62:65], v[90:93]
	v_mfma_f32_16x16x32_bf16 v[94:97], v[14:17], v[62:65], v[94:97]
	v_mfma_f32_16x16x32_bf16 v[98:101], v[18:21], v[34:37], 0
	v_mfma_f32_16x16x32_bf16 v[34:37], v[26:29], v[34:37], 0
	v_mfma_f32_16x16x32_bf16 v[106:109], v[22:25], v[38:41], v[98:101]
	v_mfma_f32_16x16x32_bf16 v[34:37], v[30:33], v[38:41], v[34:37]
	v_mfma_f32_16x16x32_bf16 v[38:41], v[18:21], v[42:45], 0
	v_mfma_f32_16x16x32_bf16 v[42:45], v[26:29], v[42:45], 0
	v_mfma_f32_16x16x32_bf16 v[38:41], v[22:25], v[46:49], v[38:41]
	v_mfma_f32_16x16x32_bf16 v[42:45], v[30:33], v[46:49], v[42:45]
	v_mfma_f32_16x16x32_bf16 v[46:49], v[18:21], v[50:53], 0
	v_mfma_f32_16x16x32_bf16 v[50:53], v[26:29], v[50:53], 0
	v_mfma_f32_16x16x32_bf16 v[46:49], v[22:25], v[54:57], v[46:49]
	v_mfma_f32_16x16x32_bf16 v[50:53], v[30:33], v[54:57], v[50:53]
	v_mfma_f32_16x16x32_bf16 v[54:57], v[18:21], v[58:61], 0
	v_mfma_f32_16x16x32_bf16 v[58:61], v[26:29], v[58:61], 0
	v_mfma_f32_16x16x32_bf16 v[54:57], v[22:25], v[62:65], v[54:57]
	v_mfma_f32_16x16x32_bf16 v[58:61], v[30:33], v[62:65], v[58:61]
	s_setprio 0
	s_barrier
	v_lshl_add_u64 v[248:249], s[76:77], 0, v[148:149]
	s_add_i32 s94, s85, s46
	v_lshl_add_u64 v[130:131], v[248:249], 0, s[16:17]
	s_mov_b32 m0, s94
	s_add_i32 s95, s94, 0x2000
	ds_read_b128 v[62:65], v162 offset:16384
	ds_read_b128 v[98:101], v162 offset:17408
	ds_read_b128 v[102:105], v162 offset:18432
	ds_read_b128 v[110:113], v162 offset:19456
	ds_read_b128 v[114:117], v162 offset:20480
	ds_read_b128 v[118:121], v162 offset:21504
	ds_read_b128 v[122:125], v162 offset:22528
	ds_read_b128 v[126:129], v162 offset:23552
	global_load_lds_dwordx4 v[130:131], off
	v_lshl_add_u64 v[130:131], v[248:249], 0, s[18:19]
	s_mov_b32 m0, s95
	s_add_i32 s96, s87, s46
	global_load_lds_dwordx4 v[130:131], off
	v_lshl_add_u64 v[130:131], v[248:249], 0, s[20:21]
	s_mov_b32 m0, s96
	s_add_i32 s40, s96, 0x2000
	global_load_lds_dwordx4 v[130:131], off
	v_lshl_add_u64 v[130:131], v[248:249], 0, s[22:23]
	s_mov_b32 m0, s40
	s_nop 0
	global_load_lds_dwordx4 v[130:131], off
	v_lshl_add_u64 v[130:131], v[246:247], 0, s[16:17]
	s_mov_b32 m0, s47
	s_nop 0
	global_load_lds_dwordx4 v[130:131], off
	v_lshl_add_u64 v[130:131], v[246:247], 0, s[18:19]
	s_mov_b32 m0, s52
	s_nop 0
	global_load_lds_dwordx4 v[130:131], off
	s_waitcnt vmcnt(24)
	s_waitcnt lgkmcnt(0)
	s_barrier
	s_waitcnt lgkmcnt(0)
	s_setprio 1
	v_mfma_f32_16x16x32_bf16 v[130:133], v[2:5], v[62:65], 0
	v_mfma_f32_16x16x32_bf16 v[156:159], v[6:9], v[98:101], v[130:133]
	v_mfma_f32_16x16x32_bf16 v[130:133], v[10:13], v[62:65], 0
	v_mfma_f32_16x16x32_bf16 v[166:169], v[14:17], v[98:101], v[130:133]
	v_mfma_f32_16x16x32_bf16 v[130:133], v[2:5], v[102:105], 0
	v_mfma_f32_16x16x32_bf16 v[170:173], v[6:9], v[110:113], v[130:133]
	v_mfma_f32_16x16x32_bf16 v[130:133], v[10:13], v[102:105], 0
	v_mfma_f32_16x16x32_bf16 v[174:177], v[14:17], v[110:113], v[130:133]
	v_mfma_f32_16x16x32_bf16 v[130:133], v[2:5], v[114:117], 0
	v_mfma_f32_16x16x32_bf16 v[2:5], v[2:5], v[122:125], 0
	v_mfma_f32_16x16x32_bf16 v[178:181], v[6:9], v[118:121], v[130:133]
	v_mfma_f32_16x16x32_bf16 v[2:5], v[6:9], v[126:129], v[2:5]
	v_mfma_f32_16x16x32_bf16 v[6:9], v[10:13], v[122:125], 0
	v_mfma_f32_16x16x32_bf16 v[130:133], v[10:13], v[114:117], 0
	v_mfma_f32_16x16x32_bf16 v[6:9], v[14:17], v[126:129], v[6:9]
	v_mfma_f32_16x16x32_bf16 v[182:185], v[14:17], v[118:121], v[130:133]
	v_mfma_f32_16x16x32_bf16 v[10:13], v[18:21], v[62:65], 0
	v_mfma_f32_16x16x32_bf16 v[186:189], v[22:25], v[98:101], v[10:13]
	v_mfma_f32_16x16x32_bf16 v[10:13], v[26:29], v[62:65], 0
	v_mfma_f32_16x16x32_bf16 v[62:65], v[30:33], v[98:101], v[10:13]
	v_mfma_f32_16x16x32_bf16 v[10:13], v[18:21], v[102:105], 0
	v_mfma_f32_16x16x32_bf16 v[190:193], v[22:25], v[110:113], v[10:13]
	v_mfma_f32_16x16x32_bf16 v[10:13], v[26:29], v[102:105], 0
	v_mfma_f32_16x16x32_bf16 v[194:197], v[30:33], v[110:113], v[10:13]
	v_mfma_f32_16x16x32_bf16 v[10:13], v[18:21], v[114:117], 0
	v_mfma_f32_16x16x32_bf16 v[198:201], v[22:25], v[118:121], v[10:13]
	v_mfma_f32_16x16x32_bf16 v[10:13], v[26:29], v[114:117], 0
	v_mfma_f32_16x16x32_bf16 v[202:205], v[30:33], v[118:121], v[10:13]
	v_mfma_f32_16x16x32_bf16 v[10:13], v[18:21], v[122:125], 0
	v_mfma_f32_16x16x32_bf16 v[206:209], v[22:25], v[126:129], v[10:13]
	v_mfma_f32_16x16x32_bf16 v[10:13], v[26:29], v[122:125], 0
	v_mfma_f32_16x16x32_bf16 v[210:213], v[30:33], v[126:129], v[10:13]
	s_setprio 0
	s_barrier
	s_nop 5
	ds_read_b128 v[10:13], v163
	ds_read_b128 v[14:17], v163 offset:1024
	ds_read_b128 v[26:29], v163 offset:2048
	ds_read_b128 v[30:33], v163 offset:3072
	ds_read_b128 v[214:217], v164
	ds_read_b128 v[218:221], v164 offset:1024
	ds_read_b128 v[222:225], v164 offset:2048
	ds_read_b128 v[226:229], v164 offset:3072
	s_mov_b32 m0, s53
	v_lshl_add_u64 v[98:99], v[246:247], 0, s[20:21]
	ds_read_b128 v[18:21], v162 offset:32768
	ds_read_b128 v[22:25], v162 offset:33792
	ds_read_b128 v[110:113], v162 offset:34816
	ds_read_b128 v[122:125], v162 offset:35840
	ds_read_b128 v[230:233], v162 offset:36864
	ds_read_b128 v[234:237], v162 offset:37888
	ds_read_b128 v[238:241], v162 offset:38912
	ds_read_b128 v[242:245], v162 offset:39936
	global_load_lds_dwordx4 v[98:99], off
	v_lshl_add_u64 v[98:99], v[246:247], 0, s[22:23]
	s_mov_b32 m0, s54
	s_nop 0
	global_load_lds_dwordx4 v[98:99], off
	s_waitcnt vmcnt(8)
	s_waitcnt lgkmcnt(0)
	s_barrier
	s_waitcnt lgkmcnt(0)
	s_setprio 1
	v_mfma_f32_16x16x32_bf16 v[66:69], v[10:13], v[18:21], v[66:69]
	v_mfma_f32_16x16x32_bf16 v[142:145], v[14:17], v[22:25], v[66:69]
	v_mfma_f32_16x16x32_bf16 v[66:69], v[26:29], v[18:21], v[70:73]
	v_mfma_f32_16x16x32_bf16 v[138:141], v[30:33], v[22:25], v[66:69]
	v_mfma_f32_16x16x32_bf16 v[66:69], v[10:13], v[110:113], v[74:77]
	v_mfma_f32_16x16x32_bf16 v[118:121], v[14:17], v[122:125], v[66:69]
	v_mfma_f32_16x16x32_bf16 v[66:69], v[26:29], v[110:113], v[78:81]
	v_mfma_f32_16x16x32_bf16 v[114:117], v[30:33], v[122:125], v[66:69]
	v_mfma_f32_16x16x32_bf16 v[66:69], v[10:13], v[230:233], v[82:85]
	v_mfma_f32_16x16x32_bf16 v[102:105], v[14:17], v[234:237], v[66:69]
	v_mfma_f32_16x16x32_bf16 v[66:69], v[26:29], v[230:233], v[86:89]
	v_mfma_f32_16x16x32_bf16 v[98:101], v[30:33], v[234:237], v[66:69]
	v_mfma_f32_16x16x32_bf16 v[66:69], v[10:13], v[238:241], v[90:93]
	v_mfma_f32_16x16x32_bf16 v[86:89], v[14:17], v[242:245], v[66:69]
	v_mfma_f32_16x16x32_bf16 v[66:69], v[26:29], v[238:241], v[94:97]
	v_mfma_f32_16x16x32_bf16 v[82:85], v[30:33], v[242:245], v[66:69]
	v_mfma_f32_16x16x32_bf16 v[66:69], v[214:217], v[18:21], v[106:109]
	v_mfma_f32_16x16x32_bf16 v[18:21], v[222:225], v[18:21], v[34:37]
	v_mfma_f32_16x16x32_bf16 v[130:133], v[226:229], v[22:25], v[18:21]
	v_mfma_f32_16x16x32_bf16 v[18:21], v[214:217], v[110:113], v[38:41]
	v_mfma_f32_16x16x32_bf16 v[126:129], v[218:221], v[122:125], v[18:21]
	v_mfma_f32_16x16x32_bf16 v[18:21], v[222:225], v[110:113], v[42:45]
	v_mfma_f32_16x16x32_bf16 v[122:125], v[226:229], v[122:125], v[18:21]
	v_mfma_f32_16x16x32_bf16 v[18:21], v[214:217], v[230:233], v[46:49]
	v_mfma_f32_16x16x32_bf16 v[110:113], v[218:221], v[234:237], v[18:21]
	v_mfma_f32_16x16x32_bf16 v[18:21], v[222:225], v[230:233], v[50:53]
	v_mfma_f32_16x16x32_bf16 v[106:109], v[226:229], v[234:237], v[18:21]
	v_mfma_f32_16x16x32_bf16 v[18:21], v[214:217], v[238:241], v[54:57]
	v_mfma_f32_16x16x32_bf16 v[94:97], v[218:221], v[242:245], v[18:21]
	v_mfma_f32_16x16x32_bf16 v[18:21], v[222:225], v[238:241], v[58:61]
	v_mfma_f32_16x16x32_bf16 v[134:137], v[218:221], v[22:25], v[66:69]
	v_mfma_f32_16x16x32_bf16 v[90:93], v[226:229], v[242:245], v[18:21]
	s_setprio 0
	s_barrier
; #define PG8_WAIT_V(n) asm volatile("s_waitcnt vmcnt(" #n ")" ::: "memory")
; template <class Epi, class Sched, bool ALIGN_EPI = true, bool SP2 = true, bool FULLLINE = false, bool NOSTAGE = false, bool FP8 = false>
; __device__ __forceinline__ void gemm_phase(PG8_LAS unsigned char* lds, const Gemm g, const Sched& S, const Epi& E) {
;     ...
;         static_assert(SP2, "only the SP2 loop is kept");
;         { const int t = 0; if constexpr (Epi::NST == 16) PG8_ITER(PG8_WAIT_V(24)); else if constexpr (Epi::NST == 8) PG8_ITER(PG8_WAIT_V(16)); else PG8_ITER(PG8_WAIT_V(8)); }
;         for (int t = 2; t < nt; t += 2) PG8_ITER(PG8_WAIT_V(8));
	s_add_i32 s41, s90, s46
	s_nop 3
	v_lshl_add_u64 v[18:19], v[248:249], 0, s[24:25]
	s_mov_b32 m0, s41
	s_add_i32 s50, s41, 0x2000
	ds_read_b128 v[34:37], v162 offset:49152
	ds_read_b128 v[38:41], v162 offset:50176
	ds_read_b128 v[42:45], v162 offset:51200
	ds_read_b128 v[46:49], v162 offset:52224
	ds_read_b128 v[230:233], v162 offset:53248
	ds_read_b128 v[234:237], v162 offset:54272
	ds_read_b128 v[238:241], v162 offset:55296
	ds_read_b128 v[242:245], v162 offset:56320
	global_load_lds_dwordx4 v[18:19], off
	v_lshl_add_u64 v[18:19], v[248:249], 0, s[26:27]
	s_mov_b32 m0, s50
	s_mov_b64 s[56:57], 0x100180
	s_add_i32 s51, s91, s46
	global_load_lds_dwordx4 v[18:19], off
	v_lshl_add_u64 v[18:19], v[248:249], 0, s[56:57]
	s_mov_b32 m0, s51
	s_mov_b64 s[56:57], 0x180180
	s_add_i32 s33, s51, 0x2000
	global_load_lds_dwordx4 v[18:19], off
	v_lshl_add_u64 v[18:19], v[248:249], 0, s[56:57]
	s_mov_b32 m0, s33
	s_nop 0
	global_load_lds_dwordx4 v[18:19], off
	v_lshl_add_u64 v[18:19], v[246:247], 0, s[24:25]
	s_mov_b32 m0, s55
	s_nop 0
	global_load_lds_dwordx4 v[18:19], off
	v_lshl_add_u64 v[18:19], v[246:247], 0, s[26:27]
	s_mov_b32 m0, s62
	s_nop 0
	global_load_lds_dwordx4 v[18:19], off
	s_waitcnt vmcnt(8)
	s_waitcnt lgkmcnt(0)
	s_barrier
	s_waitcnt lgkmcnt(0)
	s_setprio 1
	v_mfma_f32_16x16x32_bf16 v[18:21], v[10:13], v[34:37], v[156:159]
	v_mfma_f32_16x16x32_bf16 v[70:73], v[14:17], v[38:41], v[18:21]
	v_mfma_f32_16x16x32_bf16 v[18:21], v[26:29], v[34:37], v[166:169]
	v_mfma_f32_16x16x32_bf16 v[66:69], v[30:33], v[38:41], v[18:21]
	v_mfma_f32_16x16x32_bf16 v[18:21], v[10:13], v[42:45], v[170:173]
	v_mfma_f32_16x16x32_bf16 v[54:57], v[14:17], v[46:49], v[18:21]
	v_mfma_f32_16x16x32_bf16 v[18:21], v[26:29], v[42:45], v[174:177]
	v_mfma_f32_16x16x32_bf16 v[50:53], v[30:33], v[46:49], v[18:21]
	v_mfma_f32_16x16x32_bf16 v[18:21], v[10:13], v[230:233], v[178:181]
	v_mfma_f32_16x16x32_bf16 v[2:5], v[10:13], v[238:241], v[2:5]
	v_mfma_f32_16x16x32_bf16 v[22:25], v[14:17], v[234:237], v[18:21]
	v_mfma_f32_16x16x32_bf16 v[18:21], v[26:29], v[230:233], v[182:185]
	v_mfma_f32_16x16x32_bf16 v[14:17], v[14:17], v[242:245], v[2:5]
	v_mfma_f32_16x16x32_bf16 v[2:5], v[26:29], v[238:241], v[6:9]
	v_mfma_f32_16x16x32_bf16 v[18:21], v[30:33], v[234:237], v[18:21]
	v_mfma_f32_16x16x32_bf16 v[10:13], v[30:33], v[242:245], v[2:5]
	v_mfma_f32_16x16x32_bf16 v[2:5], v[214:217], v[34:37], v[186:189]
	v_mfma_f32_16x16x32_bf16 v[78:81], v[218:221], v[38:41], v[2:5]
	v_mfma_f32_16x16x32_bf16 v[2:5], v[222:225], v[34:37], v[62:65]
	v_mfma_f32_16x16x32_bf16 v[74:77], v[226:229], v[38:41], v[2:5]
	v_mfma_f32_16x16x32_bf16 v[2:5], v[214:217], v[42:45], v[190:193]
	v_mfma_f32_16x16x32_bf16 v[62:65], v[218:221], v[46:49], v[2:5]
	v_mfma_f32_16x16x32_bf16 v[2:5], v[222:225], v[42:45], v[194:197]
	v_mfma_f32_16x16x32_bf16 v[58:61], v[226:229], v[46:49], v[2:5]
	v_mfma_f32_16x16x32_bf16 v[2:5], v[214:217], v[230:233], v[198:201]
	v_mfma_f32_16x16x32_bf16 v[30:33], v[218:221], v[234:237], v[2:5]
	v_mfma_f32_16x16x32_bf16 v[2:5], v[222:225], v[230:233], v[202:205]
	v_mfma_f32_16x16x32_bf16 v[26:29], v[226:229], v[234:237], v[2:5]
	v_mfma_f32_16x16x32_bf16 v[2:5], v[214:217], v[238:241], v[206:209]
	v_mfma_f32_16x16x32_bf16 v[6:9], v[218:221], v[242:245], v[2:5]
	v_mfma_f32_16x16x32_bf16 v[2:5], v[222:225], v[238:241], v[210:213]
	v_mfma_f32_16x16x32_bf16 v[2:5], v[226:229], v[242:245], v[2:5]
	s_setprio 0
	s_barrier
	s_add_u32 s78, s78, 0x100180
	s_addc_u32 s79, s79, 0
	s_add_u32 s56, s76, 0x200
	s_addc_u32 s57, s77, 0
	s_mov_b32 s76, 0
.LBB0_594:
	ds_read_b128 v[34:37], v160
	ds_read_b128 v[38:41], v160 offset:1024
	ds_read_b128 v[42:45], v160 offset:2048
	ds_read_b128 v[46:49], v160 offset:3072
	ds_read_b128 v[156:159], v161
	ds_read_b128 v[166:169], v161 offset:1024
	ds_read_b128 v[170:173], v161 offset:2048
	ds_read_b128 v[174:177], v161 offset:3072
	s_add_u32 s0, s78, 0xfff00080
	s_addc_u32 s1, s79, -1
	s_cmp_eq_u32 s76, 60
	s_cselect_b32 vcc_hi, s67, s1
	s_cselect_b32 vcc_lo, s69, s0
	s_cselect_b32 s65, s92, s57
	s_cselect_b32 s64, s93, s56
	s_mov_b32 m0, s88
	v_lshl_add_u64 v[210:211], s[78:79], 0, v[150:151]
	ds_read_b128 v[178:181], v162
	ds_read_b128 v[182:185], v162 offset:1024
	ds_read_b128 v[186:189], v162 offset:2048
	ds_read_b128 v[190:193], v162 offset:3072
	ds_read_b128 v[194:197], v162 offset:4096
	ds_read_b128 v[198:201], v162 offset:5120
	ds_read_b128 v[202:205], v162 offset:6144
	ds_read_b128 v[206:209], v162 offset:7168
	global_load_lds_dwordx4 v[210:211], off
	v_lshl_add_u64 v[210:211], v[210:211], 0, s[28:29]
	s_mov_b32 m0, s89
	s_nop 0
	global_load_lds_dwordx4 v[210:211], off
	s_waitcnt vmcnt(8)
	s_waitcnt lgkmcnt(0)
	s_barrier
	s_waitcnt lgkmcnt(0)
	s_setprio 1
	v_mfma_f32_16x16x32_bf16 v[142:145], v[34:37], v[178:181], v[142:145]
	v_mfma_f32_16x16x32_bf16 v[138:141], v[42:45], v[178:181], v[138:141]
	v_mfma_f32_16x16x32_bf16 v[118:121], v[34:37], v[186:189], v[118:121]
	v_mfma_f32_16x16x32_bf16 v[114:117], v[42:45], v[186:189], v[114:117]
	v_mfma_f32_16x16x32_bf16 v[102:105], v[34:37], v[194:197], v[102:105]
	v_mfma_f32_16x16x32_bf16 v[98:101], v[42:45], v[194:197], v[98:101]
	v_mfma_f32_16x16x32_bf16 v[86:89], v[34:37], v[202:205], v[86:89]
	v_mfma_f32_16x16x32_bf16 v[82:85], v[42:45], v[202:205], v[82:85]
	v_mfma_f32_16x16x32_bf16 v[142:145], v[38:41], v[182:185], v[142:145]
	v_mfma_f32_16x16x32_bf16 v[138:141], v[46:49], v[182:185], v[138:141]
	v_mfma_f32_16x16x32_bf16 v[118:121], v[38:41], v[190:193], v[118:121]
	v_mfma_f32_16x16x32_bf16 v[114:117], v[46:49], v[190:193], v[114:117]
	v_mfma_f32_16x16x32_bf16 v[102:105], v[38:41], v[198:201], v[102:105]
	v_mfma_f32_16x16x32_bf16 v[98:101], v[46:49], v[198:201], v[98:101]
	v_mfma_f32_16x16x32_bf16 v[86:89], v[38:41], v[206:209], v[86:89]
	v_mfma_f32_16x16x32_bf16 v[82:85], v[46:49], v[206:209], v[82:85]
	v_mfma_f32_16x16x32_bf16 v[134:137], v[156:159], v[178:181], v[134:137]
	v_mfma_f32_16x16x32_bf16 v[130:133], v[170:173], v[178:181], v[130:133]
	v_mfma_f32_16x16x32_bf16 v[126:129], v[156:159], v[186:189], v[126:129]
	v_mfma_f32_16x16x32_bf16 v[122:125], v[170:173], v[186:189], v[122:125]
	v_mfma_f32_16x16x32_bf16 v[110:113], v[156:159], v[194:197], v[110:113]
	v_mfma_f32_16x16x32_bf16 v[106:109], v[170:173], v[194:197], v[106:109]
	v_mfma_f32_16x16x32_bf16 v[94:97], v[156:159], v[202:205], v[94:97]
	v_mfma_f32_16x16x32_bf16 v[90:93], v[170:173], v[202:205], v[90:93]
	v_mfma_f32_16x16x32_bf16 v[134:137], v[166:169], v[182:185], v[134:137]
	v_mfma_f32_16x16x32_bf16 v[130:133], v[174:177], v[182:185], v[130:133]
	v_mfma_f32_16x16x32_bf16 v[126:129], v[166:169], v[190:193], v[126:129]
	v_mfma_f32_16x16x32_bf16 v[122:125], v[174:177], v[190:193], v[122:125]
	v_mfma_f32_16x16x32_bf16 v[110:113], v[166:169], v[198:201], v[110:113]
	v_mfma_f32_16x16x32_bf16 v[106:109], v[174:177], v[198:201], v[106:109]
	v_mfma_f32_16x16x32_bf16 v[94:97], v[166:169], v[206:209], v[94:97]
	v_mfma_f32_16x16x32_bf16 v[90:93], v[174:177], v[206:209], v[90:93]
	s_setprio 0
	s_barrier
	s_mov_b32 m0, s94
	v_lshl_add_u64 v[210:211], s[64:65], 0, v[148:149]
	ds_read_b128 v[178:181], v162 offset:16384
	ds_read_b128 v[182:185], v162 offset:17408
	ds_read_b128 v[186:189], v162 offset:18432
	ds_read_b128 v[190:193], v162 offset:19456
	ds_read_b128 v[194:197], v162 offset:20480
	ds_read_b128 v[198:201], v162 offset:21504
	ds_read_b128 v[202:205], v162 offset:22528
	ds_read_b128 v[206:209], v162 offset:23552
	global_load_lds_dwordx4 v[210:211], off
	v_lshl_add_u64 v[212:213], v[210:211], 0, s[28:29]
	s_mov_b32 m0, s95
	s_nop 0
	global_load_lds_dwordx4 v[212:213], off
	v_lshl_add_u64 v[212:213], v[210:211], 0, s[30:31]
	s_mov_b32 m0, s96
	s_nop 0
	global_load_lds_dwordx4 v[212:213], off
	v_lshl_add_u64 v[212:213], v[210:211], 0, s[34:35]
	s_mov_b32 m0, s40
	s_nop 0
	global_load_lds_dwordx4 v[212:213], off
	v_lshl_add_u64 v[212:213], vcc, 0, v[146:147]
	s_mov_b32 m0, s47
	v_lshl_add_u64 v[214:215], v[212:213], 0, s[28:29]
	global_load_lds_dwordx4 v[212:213], off
	s_mov_b32 m0, s52
	s_nop 0
	global_load_lds_dwordx4 v[214:215], off
	s_waitcnt vmcnt(8)
	s_waitcnt lgkmcnt(0)
	s_barrier
	s_waitcnt lgkmcnt(0)
	s_setprio 1
	v_mfma_f32_16x16x32_bf16 v[70:73], v[34:37], v[178:181], v[70:73]
	v_mfma_f32_16x16x32_bf16 v[66:69], v[42:45], v[178:181], v[66:69]
	v_mfma_f32_16x16x32_bf16 v[54:57], v[34:37], v[186:189], v[54:57]
	v_mfma_f32_16x16x32_bf16 v[50:53], v[42:45], v[186:189], v[50:53]
	v_mfma_f32_16x16x32_bf16 v[22:25], v[34:37], v[194:197], v[22:25]
	v_mfma_f32_16x16x32_bf16 v[18:21], v[42:45], v[194:197], v[18:21]
	v_mfma_f32_16x16x32_bf16 v[14:17], v[34:37], v[202:205], v[14:17]
	v_mfma_f32_16x16x32_bf16 v[10:13], v[42:45], v[202:205], v[10:13]
	v_mfma_f32_16x16x32_bf16 v[70:73], v[38:41], v[182:185], v[70:73]
	v_mfma_f32_16x16x32_bf16 v[66:69], v[46:49], v[182:185], v[66:69]
	v_mfma_f32_16x16x32_bf16 v[54:57], v[38:41], v[190:193], v[54:57]
	v_mfma_f32_16x16x32_bf16 v[50:53], v[46:49], v[190:193], v[50:53]
	v_mfma_f32_16x16x32_bf16 v[22:25], v[38:41], v[198:201], v[22:25]
	v_mfma_f32_16x16x32_bf16 v[18:21], v[46:49], v[198:201], v[18:21]
	v_mfma_f32_16x16x32_bf16 v[14:17], v[38:41], v[206:209], v[14:17]
	v_mfma_f32_16x16x32_bf16 v[10:13], v[46:49], v[206:209], v[10:13]
	v_mfma_f32_16x16x32_bf16 v[30:33], v[156:159], v[194:197], v[30:33]
	v_mfma_f32_16x16x32_bf16 v[26:29], v[170:173], v[194:197], v[26:29]
	v_mfma_f32_16x16x32_bf16 v[6:9], v[156:159], v[202:205], v[6:9]
	v_mfma_f32_16x16x32_bf16 v[2:5], v[170:173], v[202:205], v[2:5]
	v_mfma_f32_16x16x32_bf16 v[34:37], v[156:159], v[178:181], v[78:81]
	v_mfma_f32_16x16x32_bf16 v[38:41], v[170:173], v[178:181], v[74:77]
	v_mfma_f32_16x16x32_bf16 v[42:45], v[156:159], v[186:189], v[62:65]
	v_mfma_f32_16x16x32_bf16 v[46:49], v[170:173], v[186:189], v[58:61]
	v_mfma_f32_16x16x32_bf16 v[30:33], v[166:169], v[198:201], v[30:33]
	v_mfma_f32_16x16x32_bf16 v[26:29], v[174:177], v[198:201], v[26:29]
	v_mfma_f32_16x16x32_bf16 v[6:9], v[166:169], v[206:209], v[6:9]
	v_mfma_f32_16x16x32_bf16 v[2:5], v[174:177], v[206:209], v[2:5]
	v_mfma_f32_16x16x32_bf16 v[34:37], v[166:169], v[182:185], v[34:37]
	v_mfma_f32_16x16x32_bf16 v[38:41], v[174:177], v[182:185], v[38:41]
	v_mfma_f32_16x16x32_bf16 v[42:45], v[166:169], v[190:193], v[42:45]
	v_mfma_f32_16x16x32_bf16 v[46:49], v[174:177], v[190:193], v[46:49]
	s_setprio 0
	s_barrier
; #define PG8_WAIT_V(n) asm volatile("s_waitcnt vmcnt(" #n ")" ::: "memory")
; #define PG8_BAR __builtin_amdgcn_s_barrier()
; template <class Epi, class Sched, bool ALIGN_EPI = true, bool SP2 = true, bool FULLLINE = false, bool NOSTAGE = false, bool FP8 = false>
; __device__ __forceinline__ void gemm_phase(PG8_LAS unsigned char* lds, const Gemm g, const Sched& S, const Epi& E) {
;     ...
;         static_assert(SP2, "only the SP2 loop is kept");
;         { const int t = 0; if constexpr (Epi::NST == 16) PG8_ITER(PG8_WAIT_V(24)); else if constexpr (Epi::NST == 8) PG8_ITER(PG8_WAIT_V(16)); else PG8_ITER(PG8_WAIT_V(8)); }
;         for (int t = 2; t < nt; t += 2) PG8_ITER(PG8_WAIT_V(8));
;     ...
;         if constexpr (ALIGN_EPI) { if (wr == 0) PG8_BAR; }
	ds_read_b128 v[58:61], v163
	ds_read_b128 v[62:65], v163 offset:1024
	ds_read_b128 v[74:77], v163 offset:2048
	ds_read_b128 v[78:81], v163 offset:3072
	ds_read_b128 v[156:159], v164
	ds_read_b128 v[166:169], v164 offset:1024
	ds_read_b128 v[170:173], v164 offset:2048
	ds_read_b128 v[174:177], v164 offset:3072
	s_mov_b32 m0, s53
	v_lshl_add_u64 v[214:215], v[212:213], 0, s[30:31]
	ds_read_b128 v[178:181], v162 offset:32768
	ds_read_b128 v[182:185], v162 offset:33792
	ds_read_b128 v[186:189], v162 offset:34816
	ds_read_b128 v[190:193], v162 offset:35840
	ds_read_b128 v[194:197], v162 offset:36864
	ds_read_b128 v[198:201], v162 offset:37888
	ds_read_b128 v[202:205], v162 offset:38912
	ds_read_b128 v[206:209], v162 offset:39936
	global_load_lds_dwordx4 v[214:215], off
	v_lshl_add_u64 v[214:215], v[212:213], 0, s[34:35]
	s_mov_b32 m0, s54
	s_nop 0
	global_load_lds_dwordx4 v[214:215], off
	s_waitcnt vmcnt(8)
	s_waitcnt lgkmcnt(0)
	s_barrier
	s_waitcnt lgkmcnt(0)
	s_setprio 1
	v_mfma_f32_16x16x32_bf16 v[142:145], v[58:61], v[178:181], v[142:145]
	v_mfma_f32_16x16x32_bf16 v[138:141], v[74:77], v[178:181], v[138:141]
	v_mfma_f32_16x16x32_bf16 v[118:121], v[58:61], v[186:189], v[118:121]
	v_mfma_f32_16x16x32_bf16 v[114:117], v[74:77], v[186:189], v[114:117]
	v_mfma_f32_16x16x32_bf16 v[102:105], v[58:61], v[194:197], v[102:105]
	v_mfma_f32_16x16x32_bf16 v[98:101], v[74:77], v[194:197], v[98:101]
	v_mfma_f32_16x16x32_bf16 v[86:89], v[58:61], v[202:205], v[86:89]
	v_mfma_f32_16x16x32_bf16 v[82:85], v[74:77], v[202:205], v[82:85]
	v_mfma_f32_16x16x32_bf16 v[142:145], v[62:65], v[182:185], v[142:145]
	v_mfma_f32_16x16x32_bf16 v[138:141], v[78:81], v[182:185], v[138:141]
	v_mfma_f32_16x16x32_bf16 v[118:121], v[62:65], v[190:193], v[118:121]
	v_mfma_f32_16x16x32_bf16 v[114:117], v[78:81], v[190:193], v[114:117]
	v_mfma_f32_16x16x32_bf16 v[102:105], v[62:65], v[198:201], v[102:105]
	v_mfma_f32_16x16x32_bf16 v[98:101], v[78:81], v[198:201], v[98:101]
	v_mfma_f32_16x16x32_bf16 v[86:89], v[62:65], v[206:209], v[86:89]
	v_mfma_f32_16x16x32_bf16 v[82:85], v[78:81], v[206:209], v[82:85]
	v_mfma_f32_16x16x32_bf16 v[134:137], v[156:159], v[178:181], v[134:137]
	v_mfma_f32_16x16x32_bf16 v[130:133], v[170:173], v[178:181], v[130:133]
	v_mfma_f32_16x16x32_bf16 v[126:129], v[156:159], v[186:189], v[126:129]
	v_mfma_f32_16x16x32_bf16 v[122:125], v[170:173], v[186:189], v[122:125]
	v_mfma_f32_16x16x32_bf16 v[110:113], v[156:159], v[194:197], v[110:113]
	v_mfma_f32_16x16x32_bf16 v[106:109], v[170:173], v[194:197], v[106:109]
	v_mfma_f32_16x16x32_bf16 v[94:97], v[156:159], v[202:205], v[94:97]
	v_mfma_f32_16x16x32_bf16 v[90:93], v[170:173], v[202:205], v[90:93]
	v_mfma_f32_16x16x32_bf16 v[134:137], v[166:169], v[182:185], v[134:137]
	v_mfma_f32_16x16x32_bf16 v[130:133], v[174:177], v[182:185], v[130:133]
	v_mfma_f32_16x16x32_bf16 v[126:129], v[166:169], v[190:193], v[126:129]
	v_mfma_f32_16x16x32_bf16 v[122:125], v[174:177], v[190:193], v[122:125]
	v_mfma_f32_16x16x32_bf16 v[110:113], v[166:169], v[198:201], v[110:113]
	v_mfma_f32_16x16x32_bf16 v[106:109], v[174:177], v[198:201], v[106:109]
	v_mfma_f32_16x16x32_bf16 v[94:97], v[166:169], v[206:209], v[94:97]
	v_mfma_f32_16x16x32_bf16 v[90:93], v[174:177], v[206:209], v[90:93]
	s_setprio 0
	s_barrier
	s_mov_b32 m0, s41
	v_lshl_add_u64 v[214:215], v[210:211], 0, s[36:37]
	ds_read_b128 v[178:181], v162 offset:49152
	ds_read_b128 v[182:185], v162 offset:50176
	ds_read_b128 v[186:189], v162 offset:51200
	ds_read_b128 v[190:193], v162 offset:52224
	ds_read_b128 v[194:197], v162 offset:53248
	ds_read_b128 v[198:201], v162 offset:54272
	ds_read_b128 v[202:205], v162 offset:55296
	ds_read_b128 v[206:209], v162 offset:56320
	global_load_lds_dwordx4 v[214:215], off
	v_lshl_add_u64 v[214:215], v[210:211], 0, s[38:39]
	s_mov_b32 m0, s50
	s_nop 0
	global_load_lds_dwordx4 v[214:215], off
	v_lshl_add_u64 v[214:215], v[210:211], 0, s[12:13]
	s_mov_b32 m0, s51
	v_lshl_add_u64 v[210:211], v[210:211], 0, s[14:15]
	global_load_lds_dwordx4 v[214:215], off
	s_mov_b32 m0, s33
	s_nop 0
	global_load_lds_dwordx4 v[210:211], off
	v_lshl_add_u64 v[210:211], v[212:213], 0, s[36:37]
	s_mov_b32 m0, s55
	s_nop 0
	global_load_lds_dwordx4 v[210:211], off
	v_lshl_add_u64 v[210:211], v[212:213], 0, s[38:39]
	s_mov_b32 m0, s62
	s_nop 0
	global_load_lds_dwordx4 v[210:211], off
	s_waitcnt vmcnt(8)
	s_waitcnt lgkmcnt(0)
	s_barrier
	s_waitcnt lgkmcnt(0)
	s_setprio 1
	v_mfma_f32_16x16x32_bf16 v[70:73], v[58:61], v[178:181], v[70:73]
	v_mfma_f32_16x16x32_bf16 v[66:69], v[74:77], v[178:181], v[66:69]
	v_mfma_f32_16x16x32_bf16 v[54:57], v[58:61], v[186:189], v[54:57]
	v_mfma_f32_16x16x32_bf16 v[50:53], v[74:77], v[186:189], v[50:53]
	v_mfma_f32_16x16x32_bf16 v[22:25], v[58:61], v[194:197], v[22:25]
	v_mfma_f32_16x16x32_bf16 v[18:21], v[74:77], v[194:197], v[18:21]
	v_mfma_f32_16x16x32_bf16 v[14:17], v[58:61], v[202:205], v[14:17]
	v_mfma_f32_16x16x32_bf16 v[10:13], v[74:77], v[202:205], v[10:13]
	v_mfma_f32_16x16x32_bf16 v[70:73], v[62:65], v[182:185], v[70:73]
	v_mfma_f32_16x16x32_bf16 v[66:69], v[78:81], v[182:185], v[66:69]
	v_mfma_f32_16x16x32_bf16 v[54:57], v[62:65], v[190:193], v[54:57]
	v_mfma_f32_16x16x32_bf16 v[50:53], v[78:81], v[190:193], v[50:53]
	v_mfma_f32_16x16x32_bf16 v[22:25], v[62:65], v[198:201], v[22:25]
	v_mfma_f32_16x16x32_bf16 v[18:21], v[78:81], v[198:201], v[18:21]
	v_mfma_f32_16x16x32_bf16 v[14:17], v[62:65], v[206:209], v[14:17]
	v_mfma_f32_16x16x32_bf16 v[10:13], v[78:81], v[206:209], v[10:13]
	v_mfma_f32_16x16x32_bf16 v[34:37], v[156:159], v[178:181], v[34:37]
	v_mfma_f32_16x16x32_bf16 v[78:81], v[166:169], v[182:185], v[34:37]
	v_mfma_f32_16x16x32_bf16 v[34:37], v[170:173], v[178:181], v[38:41]
	v_mfma_f32_16x16x32_bf16 v[74:77], v[174:177], v[182:185], v[34:37]
	v_mfma_f32_16x16x32_bf16 v[34:37], v[156:159], v[186:189], v[42:45]
	v_mfma_f32_16x16x32_bf16 v[62:65], v[166:169], v[190:193], v[34:37]
	v_mfma_f32_16x16x32_bf16 v[34:37], v[170:173], v[186:189], v[46:49]
	v_mfma_f32_16x16x32_bf16 v[30:33], v[156:159], v[194:197], v[30:33]
	v_mfma_f32_16x16x32_bf16 v[26:29], v[170:173], v[194:197], v[26:29]
	v_mfma_f32_16x16x32_bf16 v[6:9], v[156:159], v[202:205], v[6:9]
	v_mfma_f32_16x16x32_bf16 v[2:5], v[170:173], v[202:205], v[2:5]
	v_mfma_f32_16x16x32_bf16 v[58:61], v[174:177], v[190:193], v[34:37]
	v_mfma_f32_16x16x32_bf16 v[30:33], v[166:169], v[198:201], v[30:33]
	v_mfma_f32_16x16x32_bf16 v[26:29], v[174:177], v[198:201], v[26:29]
	v_mfma_f32_16x16x32_bf16 v[6:9], v[166:169], v[206:209], v[6:9]
	v_mfma_f32_16x16x32_bf16 v[2:5], v[174:177], v[206:209], v[2:5]
	s_setprio 0
	s_barrier
	s_add_i32 s76, s76, 2
	s_add_u32 s78, s78, 0x100
	s_addc_u32 s79, s79, 0
	s_add_u32 s56, s56, 0x100
	s_addc_u32 s57, s57, 0
	s_cmp_gt_u32 s76, 61
	s_cbranch_scc0 .LBB0_594
	s_and_b64 vcc, exec, s[10:11]
	s_cbranch_vccz .LBB0_597
	s_barrier

; template <class Epi, class Sched, bool ALIGN_EPI = true, bool SP2 = true, bool FULLLINE = false, bool NOSTAGE = false, bool FP8 = false>
; __device__ __forceinline__ void gemm_phase(PG8_LAS unsigned char* lds, const Gemm g, const Sched& S, const Epi& E) {
;     const int tid = threadIdx.x, wid = __builtin_amdgcn_readfirstlane(tid >> 6), lane = tid & 63, wr = wid >> 2, wc = wid & 3, fr = lane & 15, fq = lane >> 4;
;     const int K = g.K, nt = K / BK;
;     unsigned voffA_, voffB_;
;     { int R, C; stage_rc(tid * 16, R, C); const int Rb = Epi::PERM ? ((R & ~31) + perm32(R & 31)) : R;
;       voffA_ = (unsigned)(R * g.lda + C) * 2u; voffB_ = (unsigned)(Rb * g.ldb + C) * 2u; }
;     const unsigned voffA = voffA_, voffB = voffB_;
;     const size_t pstepoffA = (size_t)64 * g.lda * 2, pstepoffB = (size_t)64 * g.ldb * 2;
;     const size_t kstep = (size_t)(BK * 2);
;     const size_t hstepA = (size_t)HALF * g.lda * 2, hstepB = (size_t)HALF * g.ldb * 2;
;     const size_t tstepA = 2 * hstepA, tstepB = 2 * hstepB;
;     const unsigned ldsw = (unsigned)wid * 1024u;
;     const int aoff = lds_byte(wr * 64 + fr, fq * 8), boff = lds_byte(wc * 32 + fr, fq * 8);
;     ...
;     if (wr == 1) __builtin_amdgcn_s_setprio(1);
.LBB0_759:
	s_waitcnt vmcnt(0)
	v_cndmask_b32_e64 v4, 0, 1, s[10:11]
	v_cmp_ne_u32_e64 s[6:7], 1, v4
	s_andn2_b64 vcc, exec, s[10:11]
	s_barrier
	s_barrier
	s_cbranch_vccnz .LBB0_761
.LBB0_761:
	v_and_b32_e32 v4, 48, v0
	v_lshlrev_b32_e32 v5, 6, v0
	s_movk_i32 s1, 0x3c0
	v_and_or_b32 v4, v5, s1, v4
	v_lshlrev_b32_e32 v5, 2, v0
	s_lshl_b32 s0, s13, 13
	v_and_b32_e32 v5, 32, v5
	v_bitop3_b32 v6, v4, s0, v5 bitop3:0xde
	s_lshl_b32 s0, s12, 5
	s_and_b32 s62, s0, 0x60
	s_lshl_b32 s0, s62, 7
	s_lshl_b32 s55, s13, 6
	v_bitop3_b32 v4, s0, v4, v5 bitop3:0xf6
	v_lshlrev_b32_e32 v5, 9, v0
	s_cmpk_lt_u32 s9, 0x100
	v_and_b32_e32 v5, 0x30000, v5
	v_lshlrev_b32_e32 v3, 12, v3
	s_cselect_b64 s[10:11], -1, 0
	v_or3_b32 v1, v1, v5, v3
	s_add_i32 s83, 0, 0x10000
	s_add_i32 s80, 0, 0x14000
	s_add_i32 s84, 0, 0x18000
	s_add_i32 s85, 0, 0x1c000
	s_sext_i32_i16 s88, s8
	s_ashr_i32 s63, s86, 31
	v_add_u32_e32 v134, v1, v2
	v_mov_b32_e32 v135, 0
	s_mov_b32 s75, 0
	v_mov_b64_e32 v[136:137], 0xb00
	v_mov_b64_e32 v[138:139], 0xaff
	v_add_u32_e32 v1, s83, v4
	v_add_u32_e32 v142, s80, v4
	v_add_u32_e32 v143, 0, v6
	s_mov_b64 s[12:13], 0x80080
	s_add_i32 s81, s45, 0xc000
	s_mov_b64 s[14:15], 0xc0080
	s_add_i32 s82, s45, 0xe000
	s_mov_b64 s[16:17], 0x100
	s_add_i32 s83, s83, s43
	s_mov_b64 s[18:19], 0x40100
	s_mov_b64 s[20:21], 0x80100
	s_mov_b64 s[22:23], 0xc0100
	v_add_u32_e32 v144, s84, v4
	v_add_u32_e32 v145, s85, v4
	s_mov_b64 s[24:25], 0x180
	s_waitcnt lgkmcnt(0)
	s_mov_b64 s[26:27], 0x40180
	s_mov_b64 s[28:29], 0x40000
	s_mov_b64 s[30:31], 0x80000
	s_mov_b64 s[34:35], 0xc0000
	s_mov_b64 s[36:37], 0x80
	s_mov_b64 s[38:39], 0x40080
	s_movk_i32 s87, 0x2c00
	s_branch .LBB0_764

.LBB0_766:
	s_ashr_i32 s69, s68, 31
	s_lshl_b64 s[40:41], s[68:69], 20
	s_add_u32 s70, s58, s40
	ds_read_b128 v[2:5], v1
	ds_read_b128 v[6:9], v1 offset:1024
	ds_read_b128 v[10:13], v1 offset:2048
	ds_read_b128 v[14:17], v1 offset:3072
	ds_read_b128 v[18:21], v142
	ds_read_b128 v[22:25], v142 offset:1024
	ds_read_b128 v[26:29], v142 offset:2048
	ds_read_b128 v[30:33], v142 offset:3072
	s_addc_u32 s71, s59, s41
	s_ashr_i32 s67, s66, 31
	s_lshl_b64 s[40:41], s[66:67], 20
	s_add_u32 s72, s3, s40
	s_addc_u32 s73, s42, s41
	s_and_b64 s[40:41], s[8:9], exec
	s_cselect_b32 s67, s71, s79
	s_cselect_b32 s69, s70, s78
	s_cselect_b32 s89, s73, s77
	s_cselect_b32 s90, s72, s76
	v_lshl_add_u64 v[140:141], s[78:79], 0, v[132:133]
	s_mov_b32 m0, s81
	v_lshl_add_u64 v[66:67], v[140:141], 0, s[12:13]
	ds_read_b128 v[34:37], v143
	ds_read_b128 v[38:41], v143 offset:1024
	ds_read_b128 v[42:45], v143 offset:2048
	ds_read_b128 v[46:49], v143 offset:3072
	ds_read_b128 v[50:53], v143 offset:4096
	ds_read_b128 v[54:57], v143 offset:5120
	ds_read_b128 v[58:61], v143 offset:6144
	ds_read_b128 v[62:65], v143 offset:7168
	global_load_lds_dwordx4 v[66:67], off
	v_lshl_add_u64 v[66:67], v[140:141], 0, s[14:15]
	s_mov_b32 m0, s82
	s_nop 0
	global_load_lds_dwordx4 v[66:67], off
	s_waitcnt vmcnt(16)
	s_waitcnt lgkmcnt(0)
	s_barrier
	s_waitcnt lgkmcnt(0)
	s_setprio 1
	v_mfma_f32_16x16x32_bf16 v[86:89], v[10:13], v[50:53], 0
	v_mfma_f32_16x16x32_bf16 v[90:93], v[14:17], v[54:57], v[86:89]
	v_mfma_f32_16x16x32_bf16 v[86:89], v[2:5], v[58:61], 0
	v_mfma_f32_16x16x32_bf16 v[66:69], v[2:5], v[34:37], 0
	v_mfma_f32_16x16x32_bf16 v[70:73], v[10:13], v[34:37], 0
	v_mfma_f32_16x16x32_bf16 v[74:77], v[2:5], v[42:45], 0
	v_mfma_f32_16x16x32_bf16 v[78:81], v[10:13], v[42:45], 0
	v_mfma_f32_16x16x32_bf16 v[82:85], v[2:5], v[50:53], 0
	v_mfma_f32_16x16x32_bf16 v[94:97], v[6:9], v[62:65], v[86:89]
	v_mfma_f32_16x16x32_bf16 v[86:89], v[10:13], v[58:61], 0
	v_mfma_f32_16x16x32_bf16 v[66:69], v[6:9], v[38:41], v[66:69]
	v_mfma_f32_16x16x32_bf16 v[70:73], v[14:17], v[38:41], v[70:73]
	v_mfma_f32_16x16x32_bf16 v[74:77], v[6:9], v[46:49], v[74:77]
	v_mfma_f32_16x16x32_bf16 v[78:81], v[14:17], v[46:49], v[78:81]
	v_mfma_f32_16x16x32_bf16 v[82:85], v[6:9], v[54:57], v[82:85]
	v_mfma_f32_16x16x32_bf16 v[106:109], v[14:17], v[62:65], v[86:89]
	v_mfma_f32_16x16x32_bf16 v[86:89], v[18:21], v[34:37], 0
	v_mfma_f32_16x16x32_bf16 v[34:37], v[26:29], v[34:37], 0
	v_mfma_f32_16x16x32_bf16 v[110:113], v[22:25], v[38:41], v[86:89]
	v_mfma_f32_16x16x32_bf16 v[34:37], v[30:33], v[38:41], v[34:37]
	v_mfma_f32_16x16x32_bf16 v[38:41], v[18:21], v[42:45], 0
	v_mfma_f32_16x16x32_bf16 v[42:45], v[26:29], v[42:45], 0
	v_mfma_f32_16x16x32_bf16 v[38:41], v[22:25], v[46:49], v[38:41]
	v_mfma_f32_16x16x32_bf16 v[42:45], v[30:33], v[46:49], v[42:45]
	v_mfma_f32_16x16x32_bf16 v[46:49], v[18:21], v[50:53], 0
	v_mfma_f32_16x16x32_bf16 v[50:53], v[26:29], v[50:53], 0
	v_mfma_f32_16x16x32_bf16 v[46:49], v[22:25], v[54:57], v[46:49]
	v_mfma_f32_16x16x32_bf16 v[50:53], v[30:33], v[54:57], v[50:53]
	v_mfma_f32_16x16x32_bf16 v[54:57], v[18:21], v[58:61], 0
	v_mfma_f32_16x16x32_bf16 v[58:61], v[26:29], v[58:61], 0
	v_mfma_f32_16x16x32_bf16 v[54:57], v[22:25], v[62:65], v[54:57]
	v_mfma_f32_16x16x32_bf16 v[58:61], v[30:33], v[62:65], v[58:61]
	s_setprio 0
	s_barrier
	v_lshl_add_u64 v[238:239], s[76:77], 0, v[130:131]
	s_mov_b32 m0, s83
	v_lshl_add_u64 v[146:147], v[238:239], 0, s[16:17]
	s_add_i32 s91, s83, 0x2000
	ds_read_b128 v[62:65], v143 offset:16384
	ds_read_b128 v[86:89], v143 offset:17408
	ds_read_b128 v[98:101], v143 offset:18432
	ds_read_b128 v[102:105], v143 offset:19456
	ds_read_b128 v[114:117], v143 offset:20480
	ds_read_b128 v[118:121], v143 offset:21504
	ds_read_b128 v[122:125], v143 offset:22528
	ds_read_b128 v[126:129], v143 offset:23552
	global_load_lds_dwordx4 v[146:147], off
	v_lshl_add_u64 v[146:147], v[238:239], 0, s[18:19]
	s_mov_b32 m0, s91
	s_add_i32 s92, s80, s43
	global_load_lds_dwordx4 v[146:147], off
	v_lshl_add_u64 v[146:147], v[238:239], 0, s[20:21]
	s_mov_b32 m0, s92
	s_add_i32 s40, s92, 0x2000
	global_load_lds_dwordx4 v[146:147], off
	v_lshl_add_u64 v[146:147], v[238:239], 0, s[22:23]
	s_mov_b32 m0, s40
	s_nop 0
	global_load_lds_dwordx4 v[146:147], off
	v_lshl_add_u64 v[146:147], v[140:141], 0, s[16:17]
	s_mov_b32 m0, s45
	s_nop 0
	global_load_lds_dwordx4 v[146:147], off
	v_lshl_add_u64 v[146:147], v[140:141], 0, s[18:19]
	s_mov_b32 m0, s46
	s_nop 0
	global_load_lds_dwordx4 v[146:147], off
	s_waitcnt vmcnt(16)
	s_waitcnt lgkmcnt(0)
	s_barrier
	s_waitcnt lgkmcnt(0)
	s_setprio 1
	v_mfma_f32_16x16x32_bf16 v[146:149], v[2:5], v[62:65], 0
	v_mfma_f32_16x16x32_bf16 v[154:157], v[2:5], v[98:101], 0
	v_mfma_f32_16x16x32_bf16 v[162:165], v[2:5], v[114:117], 0
	v_mfma_f32_16x16x32_bf16 v[2:5], v[2:5], v[122:125], 0
	v_mfma_f32_16x16x32_bf16 v[146:149], v[6:9], v[86:89], v[146:149]
	v_mfma_f32_16x16x32_bf16 v[154:157], v[6:9], v[102:105], v[154:157]
	v_mfma_f32_16x16x32_bf16 v[162:165], v[6:9], v[118:121], v[162:165]
	v_mfma_f32_16x16x32_bf16 v[2:5], v[6:9], v[126:129], v[2:5]
	v_mfma_f32_16x16x32_bf16 v[6:9], v[10:13], v[122:125], 0
	v_mfma_f32_16x16x32_bf16 v[150:153], v[10:13], v[62:65], 0
	v_mfma_f32_16x16x32_bf16 v[158:161], v[10:13], v[98:101], 0
	v_mfma_f32_16x16x32_bf16 v[166:169], v[10:13], v[114:117], 0
	v_mfma_f32_16x16x32_bf16 v[10:13], v[14:17], v[126:129], v[6:9]
	v_mfma_f32_16x16x32_bf16 v[150:153], v[14:17], v[86:89], v[150:153]
	v_mfma_f32_16x16x32_bf16 v[158:161], v[14:17], v[102:105], v[158:161]
	v_mfma_f32_16x16x32_bf16 v[166:169], v[14:17], v[118:121], v[166:169]
	v_mfma_f32_16x16x32_bf16 v[6:9], v[18:21], v[62:65], 0
	v_mfma_f32_16x16x32_bf16 v[14:17], v[22:25], v[86:89], v[6:9]
	v_mfma_f32_16x16x32_bf16 v[6:9], v[26:29], v[62:65], 0
	v_mfma_f32_16x16x32_bf16 v[170:173], v[30:33], v[86:89], v[6:9]
	v_mfma_f32_16x16x32_bf16 v[6:9], v[18:21], v[98:101], 0
	v_mfma_f32_16x16x32_bf16 v[174:177], v[22:25], v[102:105], v[6:9]
	v_mfma_f32_16x16x32_bf16 v[6:9], v[26:29], v[98:101], 0
	v_mfma_f32_16x16x32_bf16 v[178:181], v[30:33], v[102:105], v[6:9]
	v_mfma_f32_16x16x32_bf16 v[6:9], v[18:21], v[114:117], 0
	v_mfma_f32_16x16x32_bf16 v[182:185], v[22:25], v[118:121], v[6:9]
	v_mfma_f32_16x16x32_bf16 v[6:9], v[26:29], v[114:117], 0
	v_mfma_f32_16x16x32_bf16 v[186:189], v[30:33], v[118:121], v[6:9]
	v_mfma_f32_16x16x32_bf16 v[6:9], v[18:21], v[122:125], 0
	v_mfma_f32_16x16x32_bf16 v[190:193], v[22:25], v[126:129], v[6:9]
	v_mfma_f32_16x16x32_bf16 v[6:9], v[26:29], v[122:125], 0
	v_mfma_f32_16x16x32_bf16 v[194:197], v[30:33], v[126:129], v[6:9]
	s_setprio 0
	s_barrier
	s_nop 5
	ds_read_b128 v[6:9], v144
	ds_read_b128 v[26:29], v144 offset:1024
	ds_read_b128 v[30:33], v144 offset:2048
	ds_read_b128 v[62:65], v144 offset:3072
	ds_read_b128 v[198:201], v145
	ds_read_b128 v[202:205], v145 offset:1024
	ds_read_b128 v[206:209], v145 offset:2048
	ds_read_b128 v[210:213], v145 offset:3072
	s_mov_b32 m0, s47
	v_lshl_add_u64 v[86:87], v[140:141], 0, s[20:21]
	ds_read_b128 v[18:21], v143 offset:32768
	ds_read_b128 v[22:25], v143 offset:33792
	ds_read_b128 v[214:217], v143 offset:34816
	ds_read_b128 v[218:221], v143 offset:35840
	ds_read_b128 v[222:225], v143 offset:36864
	ds_read_b128 v[226:229], v143 offset:37888
	ds_read_b128 v[230:233], v143 offset:38912
	ds_read_b128 v[234:237], v143 offset:39936
	global_load_lds_dwordx4 v[86:87], off
	v_lshl_add_u64 v[86:87], v[140:141], 0, s[22:23]
	s_mov_b32 m0, s52
	s_nop 0
	global_load_lds_dwordx4 v[86:87], off
	s_waitcnt vmcnt(8)
	s_waitcnt lgkmcnt(0)
	s_barrier
	s_waitcnt lgkmcnt(0)
	s_setprio 1
	v_mfma_f32_16x16x32_bf16 v[66:69], v[6:9], v[18:21], v[66:69]
	v_mfma_f32_16x16x32_bf16 v[118:121], v[26:29], v[22:25], v[66:69]
	v_mfma_f32_16x16x32_bf16 v[66:69], v[30:33], v[18:21], v[70:73]
	v_mfma_f32_16x16x32_bf16 v[114:117], v[62:65], v[22:25], v[66:69]
	v_mfma_f32_16x16x32_bf16 v[66:69], v[6:9], v[214:217], v[74:77]
	v_mfma_f32_16x16x32_bf16 v[102:105], v[26:29], v[218:221], v[66:69]
	v_mfma_f32_16x16x32_bf16 v[66:69], v[30:33], v[214:217], v[78:81]
	v_mfma_f32_16x16x32_bf16 v[98:101], v[62:65], v[218:221], v[66:69]
	v_mfma_f32_16x16x32_bf16 v[66:69], v[6:9], v[222:225], v[82:85]
	v_mfma_f32_16x16x32_bf16 v[86:89], v[26:29], v[226:229], v[66:69]
	v_mfma_f32_16x16x32_bf16 v[66:69], v[30:33], v[222:225], v[90:93]
	v_mfma_f32_16x16x32_bf16 v[82:85], v[62:65], v[226:229], v[66:69]
	v_mfma_f32_16x16x32_bf16 v[66:69], v[6:9], v[230:233], v[94:97]
	v_mfma_f32_16x16x32_bf16 v[70:73], v[26:29], v[234:237], v[66:69]
	v_mfma_f32_16x16x32_bf16 v[66:69], v[30:33], v[230:233], v[106:109]
	v_mfma_f32_16x16x32_bf16 v[66:69], v[62:65], v[234:237], v[66:69]
	v_mfma_f32_16x16x32_bf16 v[74:77], v[198:201], v[18:21], v[110:113]
	v_mfma_f32_16x16x32_bf16 v[18:21], v[206:209], v[18:21], v[34:37]
	v_mfma_f32_16x16x32_bf16 v[122:125], v[210:213], v[22:25], v[18:21]
	v_mfma_f32_16x16x32_bf16 v[18:21], v[198:201], v[214:217], v[38:41]
	v_mfma_f32_16x16x32_bf16 v[110:113], v[202:205], v[218:221], v[18:21]
	v_mfma_f32_16x16x32_bf16 v[18:21], v[206:209], v[214:217], v[42:45]
	v_mfma_f32_16x16x32_bf16 v[106:109], v[210:213], v[218:221], v[18:21]
	v_mfma_f32_16x16x32_bf16 v[18:21], v[198:201], v[222:225], v[46:49]
	v_mfma_f32_16x16x32_bf16 v[94:97], v[202:205], v[226:229], v[18:21]
	v_mfma_f32_16x16x32_bf16 v[18:21], v[206:209], v[222:225], v[50:53]
	v_mfma_f32_16x16x32_bf16 v[90:93], v[210:213], v[226:229], v[18:21]
	v_mfma_f32_16x16x32_bf16 v[18:21], v[198:201], v[230:233], v[54:57]
	v_mfma_f32_16x16x32_bf16 v[78:81], v[202:205], v[234:237], v[18:21]
	v_mfma_f32_16x16x32_bf16 v[18:21], v[206:209], v[230:233], v[58:61]
	v_mfma_f32_16x16x32_bf16 v[126:129], v[202:205], v[22:25], v[74:77]
	v_mfma_f32_16x16x32_bf16 v[74:77], v[210:213], v[234:237], v[18:21]
	s_setprio 0
	s_barrier
	s_add_i32 s41, s84, s43
	s_nop 3
	v_lshl_add_u64 v[18:19], v[238:239], 0, s[24:25]
	s_mov_b32 m0, s41
	s_add_i32 s50, s41, 0x2000
	ds_read_b128 v[42:45], v143 offset:49152
	ds_read_b128 v[46:49], v143 offset:50176
	ds_read_b128 v[214:217], v143 offset:51200
	ds_read_b128 v[218:221], v143 offset:52224
	ds_read_b128 v[222:225], v143 offset:53248
	ds_read_b128 v[226:229], v143 offset:54272
	ds_read_b128 v[230:233], v143 offset:55296
	ds_read_b128 v[234:237], v143 offset:56320
	global_load_lds_dwordx4 v[18:19], off
	v_lshl_add_u64 v[18:19], v[238:239], 0, s[26:27]
	s_mov_b32 m0, s50
	s_mov_b64 s[56:57], 0x80180
	s_add_i32 s51, s85, s43
	global_load_lds_dwordx4 v[18:19], off
	v_lshl_add_u64 v[18:19], v[238:239], 0, s[56:57]
	s_mov_b32 m0, s51
	s_mov_b64 s[56:57], 0xc0180
	s_add_i32 s33, s51, 0x2000
	global_load_lds_dwordx4 v[18:19], off
	v_lshl_add_u64 v[18:19], v[238:239], 0, s[56:57]
	s_mov_b32 m0, s33
	s_nop 0
	global_load_lds_dwordx4 v[18:19], off
	v_lshl_add_u64 v[18:19], v[140:141], 0, s[24:25]
	s_mov_b32 m0, s53
	s_nop 0
	global_load_lds_dwordx4 v[18:19], off
	v_lshl_add_u64 v[18:19], v[140:141], 0, s[26:27]
	s_mov_b32 m0, s54
	s_nop 0
	global_load_lds_dwordx4 v[18:19], off
	s_waitcnt vmcnt(8)
	s_waitcnt lgkmcnt(0)
	s_barrier
	s_waitcnt lgkmcnt(0)
	s_setprio 1
	v_mfma_f32_16x16x32_bf16 v[18:21], v[6:9], v[42:45], v[146:149]
	v_mfma_f32_16x16x32_bf16 v[54:57], v[26:29], v[46:49], v[18:21]
	v_mfma_f32_16x16x32_bf16 v[18:21], v[30:33], v[42:45], v[150:153]
	v_mfma_f32_16x16x32_bf16 v[50:53], v[62:65], v[46:49], v[18:21]
	v_mfma_f32_16x16x32_bf16 v[18:21], v[6:9], v[214:217], v[154:157]
	v_mfma_f32_16x16x32_bf16 v[38:41], v[26:29], v[218:221], v[18:21]
	v_mfma_f32_16x16x32_bf16 v[18:21], v[30:33], v[214:217], v[158:161]
	v_mfma_f32_16x16x32_bf16 v[34:37], v[62:65], v[218:221], v[18:21]
	v_mfma_f32_16x16x32_bf16 v[18:21], v[6:9], v[222:225], v[162:165]
	v_mfma_f32_16x16x32_bf16 v[2:5], v[6:9], v[230:233], v[2:5]
	v_mfma_f32_16x16x32_bf16 v[22:25], v[26:29], v[226:229], v[18:21]
	v_mfma_f32_16x16x32_bf16 v[18:21], v[30:33], v[222:225], v[166:169]
	v_mfma_f32_16x16x32_bf16 v[6:9], v[26:29], v[234:237], v[2:5]
	v_mfma_f32_16x16x32_bf16 v[2:5], v[30:33], v[230:233], v[10:13]
	v_mfma_f32_16x16x32_bf16 v[18:21], v[62:65], v[226:229], v[18:21]
	v_mfma_f32_16x16x32_bf16 v[2:5], v[62:65], v[234:237], v[2:5]
	v_mfma_f32_16x16x32_bf16 v[10:13], v[198:201], v[42:45], v[14:17]
	v_mfma_f32_16x16x32_bf16 v[62:65], v[202:205], v[46:49], v[10:13]
	v_mfma_f32_16x16x32_bf16 v[10:13], v[206:209], v[42:45], v[170:173]
	v_mfma_f32_16x16x32_bf16 v[58:61], v[210:213], v[46:49], v[10:13]
	v_mfma_f32_16x16x32_bf16 v[10:13], v[198:201], v[214:217], v[174:177]
	v_mfma_f32_16x16x32_bf16 v[46:49], v[202:205], v[218:221], v[10:13]
	v_mfma_f32_16x16x32_bf16 v[10:13], v[206:209], v[214:217], v[178:181]
	v_mfma_f32_16x16x32_bf16 v[42:45], v[210:213], v[218:221], v[10:13]
	v_mfma_f32_16x16x32_bf16 v[10:13], v[198:201], v[222:225], v[182:185]
	v_mfma_f32_16x16x32_bf16 v[30:33], v[202:205], v[226:229], v[10:13]
	v_mfma_f32_16x16x32_bf16 v[10:13], v[206:209], v[222:225], v[186:189]
	v_mfma_f32_16x16x32_bf16 v[26:29], v[210:213], v[226:229], v[10:13]
	v_mfma_f32_16x16x32_bf16 v[10:13], v[198:201], v[230:233], v[190:193]
	v_mfma_f32_16x16x32_bf16 v[14:17], v[202:205], v[234:237], v[10:13]
	v_mfma_f32_16x16x32_bf16 v[10:13], v[206:209], v[230:233], v[194:197]
	v_mfma_f32_16x16x32_bf16 v[10:13], v[210:213], v[234:237], v[10:13]
	s_setprio 0
	s_barrier
	s_add_u32 s78, s78, 0x80180
	s_addc_u32 s79, s79, 0
	s_add_u32 s56, s76, 0x200
	s_addc_u32 s57, s77, 0
	s_mov_b32 s76, 0
.LBB0_767:
	ds_read_b128 v[146:149], v1
	ds_read_b128 v[150:153], v1 offset:1024
	ds_read_b128 v[154:157], v1 offset:2048
	ds_read_b128 v[158:161], v1 offset:3072
	ds_read_b128 v[162:165], v142
	ds_read_b128 v[166:169], v142 offset:1024
	ds_read_b128 v[170:173], v142 offset:2048
	ds_read_b128 v[174:177], v142 offset:3072
	s_add_u32 s0, s78, 0xfff80080
	s_addc_u32 s1, s79, -1
	s_cmp_eq_u32 s76, 28
	s_cselect_b32 s95, s67, s1
	s_cselect_b32 s94, s69, s0
	s_cselect_b32 s97, s89, s57
	s_cselect_b32 s96, s90, s56
	s_mov_b32 m0, s81
	v_lshl_add_u64 v[140:141], s[78:79], 0, v[134:135]
	ds_read_b128 v[178:181], v143
	ds_read_b128 v[182:185], v143 offset:1024
	ds_read_b128 v[186:189], v143 offset:2048
	ds_read_b128 v[190:193], v143 offset:3072
	ds_read_b128 v[194:197], v143 offset:4096
	ds_read_b128 v[198:201], v143 offset:5120
	ds_read_b128 v[202:205], v143 offset:6144
	ds_read_b128 v[206:209], v143 offset:7168
	global_load_lds_dwordx4 v[140:141], off
	v_lshl_add_u64 v[140:141], v[140:141], 0, s[28:29]
	s_mov_b32 m0, s82
	s_nop 0
	global_load_lds_dwordx4 v[140:141], off
	s_waitcnt vmcnt(8)
	s_waitcnt lgkmcnt(0)
	s_barrier
	s_waitcnt lgkmcnt(0)
	s_setprio 1
	v_mfma_f32_16x16x32_bf16 v[118:121], v[146:149], v[178:181], v[118:121]
	v_mfma_f32_16x16x32_bf16 v[114:117], v[154:157], v[178:181], v[114:117]
	v_mfma_f32_16x16x32_bf16 v[102:105], v[146:149], v[186:189], v[102:105]
	v_mfma_f32_16x16x32_bf16 v[98:101], v[154:157], v[186:189], v[98:101]
	v_mfma_f32_16x16x32_bf16 v[86:89], v[146:149], v[194:197], v[86:89]
	v_mfma_f32_16x16x32_bf16 v[82:85], v[154:157], v[194:197], v[82:85]
	v_mfma_f32_16x16x32_bf16 v[70:73], v[146:149], v[202:205], v[70:73]
	v_mfma_f32_16x16x32_bf16 v[66:69], v[154:157], v[202:205], v[66:69]
	v_mfma_f32_16x16x32_bf16 v[118:121], v[150:153], v[182:185], v[118:121]
	v_mfma_f32_16x16x32_bf16 v[114:117], v[158:161], v[182:185], v[114:117]
	v_mfma_f32_16x16x32_bf16 v[102:105], v[150:153], v[190:193], v[102:105]
	v_mfma_f32_16x16x32_bf16 v[98:101], v[158:161], v[190:193], v[98:101]
	v_mfma_f32_16x16x32_bf16 v[86:89], v[150:153], v[198:201], v[86:89]
	v_mfma_f32_16x16x32_bf16 v[82:85], v[158:161], v[198:201], v[82:85]
	v_mfma_f32_16x16x32_bf16 v[70:73], v[150:153], v[206:209], v[70:73]
	v_mfma_f32_16x16x32_bf16 v[66:69], v[158:161], v[206:209], v[66:69]
	v_mfma_f32_16x16x32_bf16 v[126:129], v[162:165], v[178:181], v[126:129]
	v_mfma_f32_16x16x32_bf16 v[122:125], v[170:173], v[178:181], v[122:125]
	v_mfma_f32_16x16x32_bf16 v[110:113], v[162:165], v[186:189], v[110:113]
	v_mfma_f32_16x16x32_bf16 v[106:109], v[170:173], v[186:189], v[106:109]
	v_mfma_f32_16x16x32_bf16 v[94:97], v[162:165], v[194:197], v[94:97]
	v_mfma_f32_16x16x32_bf16 v[90:93], v[170:173], v[194:197], v[90:93]
	v_mfma_f32_16x16x32_bf16 v[78:81], v[162:165], v[202:205], v[78:81]
	v_mfma_f32_16x16x32_bf16 v[74:77], v[170:173], v[202:205], v[74:77]
	v_mfma_f32_16x16x32_bf16 v[126:129], v[166:169], v[182:185], v[126:129]
	v_mfma_f32_16x16x32_bf16 v[122:125], v[174:177], v[182:185], v[122:125]
	v_mfma_f32_16x16x32_bf16 v[110:113], v[166:169], v[190:193], v[110:113]
	v_mfma_f32_16x16x32_bf16 v[106:109], v[174:177], v[190:193], v[106:109]
	v_mfma_f32_16x16x32_bf16 v[94:97], v[166:169], v[198:201], v[94:97]
	v_mfma_f32_16x16x32_bf16 v[90:93], v[174:177], v[198:201], v[90:93]
	v_mfma_f32_16x16x32_bf16 v[78:81], v[166:169], v[206:209], v[78:81]
	v_mfma_f32_16x16x32_bf16 v[74:77], v[174:177], v[206:209], v[74:77]
	s_setprio 0
	s_barrier
	s_mov_b32 m0, s83
	v_lshl_add_u64 v[140:141], s[96:97], 0, v[130:131]
	ds_read_b128 v[178:181], v143 offset:16384
	ds_read_b128 v[182:185], v143 offset:17408
	ds_read_b128 v[186:189], v143 offset:18432
	ds_read_b128 v[190:193], v143 offset:19456
	ds_read_b128 v[194:197], v143 offset:20480
	ds_read_b128 v[198:201], v143 offset:21504
	ds_read_b128 v[202:205], v143 offset:22528
	ds_read_b128 v[206:209], v143 offset:23552
	global_load_lds_dwordx4 v[140:141], off
	v_lshl_add_u64 v[210:211], v[140:141], 0, s[28:29]
	s_mov_b32 m0, s91
	s_nop 0
	global_load_lds_dwordx4 v[210:211], off
	v_lshl_add_u64 v[210:211], v[140:141], 0, s[30:31]
	s_mov_b32 m0, s92
	s_nop 0
	global_load_lds_dwordx4 v[210:211], off
	v_lshl_add_u64 v[210:211], v[140:141], 0, s[34:35]
	s_mov_b32 m0, s40
	s_nop 0
	global_load_lds_dwordx4 v[210:211], off
	v_lshl_add_u64 v[210:211], s[94:95], 0, v[132:133]
	s_mov_b32 m0, s45
	v_lshl_add_u64 v[212:213], v[210:211], 0, s[28:29]
	global_load_lds_dwordx4 v[210:211], off
	s_mov_b32 m0, s46
	s_nop 0
	global_load_lds_dwordx4 v[212:213], off
	s_waitcnt vmcnt(8)
	s_waitcnt lgkmcnt(0)
	s_barrier
	s_waitcnt lgkmcnt(0)
	s_setprio 1
	v_mfma_f32_16x16x32_bf16 v[54:57], v[146:149], v[178:181], v[54:57]
	v_mfma_f32_16x16x32_bf16 v[50:53], v[154:157], v[178:181], v[50:53]
	v_mfma_f32_16x16x32_bf16 v[38:41], v[146:149], v[186:189], v[38:41]
	v_mfma_f32_16x16x32_bf16 v[34:37], v[154:157], v[186:189], v[34:37]
	v_mfma_f32_16x16x32_bf16 v[22:25], v[146:149], v[194:197], v[22:25]
	v_mfma_f32_16x16x32_bf16 v[18:21], v[154:157], v[194:197], v[18:21]
	v_mfma_f32_16x16x32_bf16 v[6:9], v[146:149], v[202:205], v[6:9]
	v_mfma_f32_16x16x32_bf16 v[2:5], v[154:157], v[202:205], v[2:5]
	v_mfma_f32_16x16x32_bf16 v[54:57], v[150:153], v[182:185], v[54:57]
	v_mfma_f32_16x16x32_bf16 v[50:53], v[158:161], v[182:185], v[50:53]
	v_mfma_f32_16x16x32_bf16 v[38:41], v[150:153], v[190:193], v[38:41]
	v_mfma_f32_16x16x32_bf16 v[34:37], v[158:161], v[190:193], v[34:37]
	v_mfma_f32_16x16x32_bf16 v[22:25], v[150:153], v[198:201], v[22:25]
	v_mfma_f32_16x16x32_bf16 v[18:21], v[158:161], v[198:201], v[18:21]
	v_mfma_f32_16x16x32_bf16 v[6:9], v[150:153], v[206:209], v[6:9]
	v_mfma_f32_16x16x32_bf16 v[2:5], v[158:161], v[206:209], v[2:5]
	v_mfma_f32_16x16x32_bf16 v[62:65], v[162:165], v[178:181], v[62:65]
	v_mfma_f32_16x16x32_bf16 v[58:61], v[170:173], v[178:181], v[58:61]
	v_mfma_f32_16x16x32_bf16 v[46:49], v[162:165], v[186:189], v[46:49]
	v_mfma_f32_16x16x32_bf16 v[42:45], v[170:173], v[186:189], v[42:45]
	v_mfma_f32_16x16x32_bf16 v[30:33], v[162:165], v[194:197], v[30:33]
	v_mfma_f32_16x16x32_bf16 v[26:29], v[170:173], v[194:197], v[26:29]
	v_mfma_f32_16x16x32_bf16 v[14:17], v[162:165], v[202:205], v[14:17]
	v_mfma_f32_16x16x32_bf16 v[10:13], v[170:173], v[202:205], v[10:13]
	v_mfma_f32_16x16x32_bf16 v[62:65], v[166:169], v[182:185], v[62:65]
	v_mfma_f32_16x16x32_bf16 v[58:61], v[174:177], v[182:185], v[58:61]
	v_mfma_f32_16x16x32_bf16 v[46:49], v[166:169], v[190:193], v[46:49]
	v_mfma_f32_16x16x32_bf16 v[42:45], v[174:177], v[190:193], v[42:45]
	v_mfma_f32_16x16x32_bf16 v[30:33], v[166:169], v[198:201], v[30:33]
	v_mfma_f32_16x16x32_bf16 v[26:29], v[174:177], v[198:201], v[26:29]
	v_mfma_f32_16x16x32_bf16 v[14:17], v[166:169], v[206:209], v[14:17]
	v_mfma_f32_16x16x32_bf16 v[10:13], v[174:177], v[206:209], v[10:13]
	s_setprio 0
	s_barrier
	ds_read_b128 v[146:149], v144
	ds_read_b128 v[150:153], v144 offset:1024
	ds_read_b128 v[154:157], v144 offset:2048
	ds_read_b128 v[158:161], v144 offset:3072
	ds_read_b128 v[162:165], v145
	ds_read_b128 v[166:169], v145 offset:1024
	ds_read_b128 v[170:173], v145 offset:2048
	ds_read_b128 v[174:177], v145 offset:3072
	s_mov_b32 m0, s47
	v_lshl_add_u64 v[212:213], v[210:211], 0, s[30:31]
	ds_read_b128 v[178:181], v143 offset:32768
	ds_read_b128 v[182:185], v143 offset:33792
	ds_read_b128 v[186:189], v143 offset:34816
	ds_read_b128 v[190:193], v143 offset:35840
	ds_read_b128 v[194:197], v143 offset:36864
	ds_read_b128 v[198:201], v143 offset:37888
	ds_read_b128 v[202:205], v143 offset:38912
	ds_read_b128 v[206:209], v143 offset:39936
	global_load_lds_dwordx4 v[212:213], off
	v_lshl_add_u64 v[212:213], v[210:211], 0, s[34:35]
	s_mov_b32 m0, s52
	s_nop 0
	global_load_lds_dwordx4 v[212:213], off
	s_waitcnt vmcnt(8)
	s_waitcnt lgkmcnt(0)
	s_barrier
	s_waitcnt lgkmcnt(0)
	s_setprio 1
	v_mfma_f32_16x16x32_bf16 v[118:121], v[146:149], v[178:181], v[118:121]
	v_mfma_f32_16x16x32_bf16 v[114:117], v[154:157], v[178:181], v[114:117]
	v_mfma_f32_16x16x32_bf16 v[102:105], v[146:149], v[186:189], v[102:105]
	v_mfma_f32_16x16x32_bf16 v[98:101], v[154:157], v[186:189], v[98:101]
	v_mfma_f32_16x16x32_bf16 v[86:89], v[146:149], v[194:197], v[86:89]
	v_mfma_f32_16x16x32_bf16 v[82:85], v[154:157], v[194:197], v[82:85]
	v_mfma_f32_16x16x32_bf16 v[70:73], v[146:149], v[202:205], v[70:73]
	v_mfma_f32_16x16x32_bf16 v[66:69], v[154:157], v[202:205], v[66:69]
	v_mfma_f32_16x16x32_bf16 v[118:121], v[150:153], v[182:185], v[118:121]
	v_mfma_f32_16x16x32_bf16 v[114:117], v[158:161], v[182:185], v[114:117]
	v_mfma_f32_16x16x32_bf16 v[102:105], v[150:153], v[190:193], v[102:105]
	v_mfma_f32_16x16x32_bf16 v[98:101], v[158:161], v[190:193], v[98:101]
	v_mfma_f32_16x16x32_bf16 v[86:89], v[150:153], v[198:201], v[86:89]
	v_mfma_f32_16x16x32_bf16 v[82:85], v[158:161], v[198:201], v[82:85]
	v_mfma_f32_16x16x32_bf16 v[70:73], v[150:153], v[206:209], v[70:73]
	v_mfma_f32_16x16x32_bf16 v[66:69], v[158:161], v[206:209], v[66:69]
	v_mfma_f32_16x16x32_bf16 v[126:129], v[162:165], v[178:181], v[126:129]
	v_mfma_f32_16x16x32_bf16 v[122:125], v[170:173], v[178:181], v[122:125]
	v_mfma_f32_16x16x32_bf16 v[110:113], v[162:165], v[186:189], v[110:113]
	v_mfma_f32_16x16x32_bf16 v[106:109], v[170:173], v[186:189], v[106:109]
	v_mfma_f32_16x16x32_bf16 v[94:97], v[162:165], v[194:197], v[94:97]
	v_mfma_f32_16x16x32_bf16 v[90:93], v[170:173], v[194:197], v[90:93]
	v_mfma_f32_16x16x32_bf16 v[78:81], v[162:165], v[202:205], v[78:81]
	v_mfma_f32_16x16x32_bf16 v[74:77], v[170:173], v[202:205], v[74:77]
	v_mfma_f32_16x16x32_bf16 v[126:129], v[166:169], v[182:185], v[126:129]
	v_mfma_f32_16x16x32_bf16 v[122:125], v[174:177], v[182:185], v[122:125]
	v_mfma_f32_16x16x32_bf16 v[110:113], v[166:169], v[190:193], v[110:113]
	v_mfma_f32_16x16x32_bf16 v[106:109], v[174:177], v[190:193], v[106:109]
	v_mfma_f32_16x16x32_bf16 v[94:97], v[166:169], v[198:201], v[94:97]
	v_mfma_f32_16x16x32_bf16 v[90:93], v[174:177], v[198:201], v[90:93]
	v_mfma_f32_16x16x32_bf16 v[78:81], v[166:169], v[206:209], v[78:81]
	v_mfma_f32_16x16x32_bf16 v[74:77], v[174:177], v[206:209], v[74:77]
	s_setprio 0
	s_barrier
; #define PG8_WAIT_V(n) asm volatile("s_waitcnt vmcnt(" #n ")" ::: "memory")
; #define PG8_BAR __builtin_amdgcn_s_barrier()
; template <class Epi, class Sched, bool ALIGN_EPI = true, bool SP2 = true, bool FULLLINE = false, bool NOSTAGE = false, bool FP8 = false>
; __device__ __forceinline__ void gemm_phase(PG8_LAS unsigned char* lds, const Gemm g, const Sched& S, const Epi& E) {
;     ...
;         static_assert(SP2, "only the SP2 loop is kept");
;         { const int t = 0; if constexpr (Epi::NST == 16) PG8_ITER(PG8_WAIT_V(24)); else if constexpr (Epi::NST == 8) PG8_ITER(PG8_WAIT_V(16)); else PG8_ITER(PG8_WAIT_V(8)); }
;         for (int t = 2; t < nt; t += 2) PG8_ITER(PG8_WAIT_V(8));
;     ...
;         if constexpr (ALIGN_EPI) { if (wr == 0) PG8_BAR; }
	s_mov_b32 m0, s41
	v_lshl_add_u64 v[212:213], v[140:141], 0, s[36:37]
	ds_read_b128 v[178:181], v143 offset:49152
	ds_read_b128 v[182:185], v143 offset:50176
	ds_read_b128 v[186:189], v143 offset:51200
	ds_read_b128 v[190:193], v143 offset:52224
	ds_read_b128 v[194:197], v143 offset:53248
	ds_read_b128 v[198:201], v143 offset:54272
	ds_read_b128 v[202:205], v143 offset:55296
	ds_read_b128 v[206:209], v143 offset:56320
	global_load_lds_dwordx4 v[212:213], off
	v_lshl_add_u64 v[212:213], v[140:141], 0, s[38:39]
	s_mov_b32 m0, s50
	s_nop 0
	global_load_lds_dwordx4 v[212:213], off
	v_lshl_add_u64 v[212:213], v[140:141], 0, s[12:13]
	s_mov_b32 m0, s51
	v_lshl_add_u64 v[140:141], v[140:141], 0, s[14:15]
	global_load_lds_dwordx4 v[212:213], off
	s_mov_b32 m0, s33
	s_nop 0
	global_load_lds_dwordx4 v[140:141], off
	v_lshl_add_u64 v[140:141], v[210:211], 0, s[36:37]
	s_mov_b32 m0, s53
	s_nop 0
	global_load_lds_dwordx4 v[140:141], off
	v_lshl_add_u64 v[140:141], v[210:211], 0, s[38:39]
	s_mov_b32 m0, s54
	s_nop 0
	global_load_lds_dwordx4 v[140:141], off
	s_waitcnt vmcnt(8)
	s_waitcnt lgkmcnt(0)
	s_barrier
	s_waitcnt lgkmcnt(0)
	s_setprio 1
	v_mfma_f32_16x16x32_bf16 v[54:57], v[146:149], v[178:181], v[54:57]
	v_mfma_f32_16x16x32_bf16 v[50:53], v[154:157], v[178:181], v[50:53]
	v_mfma_f32_16x16x32_bf16 v[38:41], v[146:149], v[186:189], v[38:41]
	v_mfma_f32_16x16x32_bf16 v[34:37], v[154:157], v[186:189], v[34:37]
	v_mfma_f32_16x16x32_bf16 v[22:25], v[146:149], v[194:197], v[22:25]
	v_mfma_f32_16x16x32_bf16 v[18:21], v[154:157], v[194:197], v[18:21]
	v_mfma_f32_16x16x32_bf16 v[6:9], v[146:149], v[202:205], v[6:9]
	v_mfma_f32_16x16x32_bf16 v[2:5], v[154:157], v[202:205], v[2:5]
	v_mfma_f32_16x16x32_bf16 v[54:57], v[150:153], v[182:185], v[54:57]
	v_mfma_f32_16x16x32_bf16 v[50:53], v[158:161], v[182:185], v[50:53]
	v_mfma_f32_16x16x32_bf16 v[38:41], v[150:153], v[190:193], v[38:41]
	v_mfma_f32_16x16x32_bf16 v[34:37], v[158:161], v[190:193], v[34:37]
	v_mfma_f32_16x16x32_bf16 v[22:25], v[150:153], v[198:201], v[22:25]
	v_mfma_f32_16x16x32_bf16 v[18:21], v[158:161], v[198:201], v[18:21]
	v_mfma_f32_16x16x32_bf16 v[6:9], v[150:153], v[206:209], v[6:9]
	v_mfma_f32_16x16x32_bf16 v[2:5], v[158:161], v[206:209], v[2:5]
	v_mfma_f32_16x16x32_bf16 v[62:65], v[162:165], v[178:181], v[62:65]
	v_mfma_f32_16x16x32_bf16 v[58:61], v[170:173], v[178:181], v[58:61]
	v_mfma_f32_16x16x32_bf16 v[46:49], v[162:165], v[186:189], v[46:49]
	v_mfma_f32_16x16x32_bf16 v[42:45], v[170:173], v[186:189], v[42:45]
	v_mfma_f32_16x16x32_bf16 v[30:33], v[162:165], v[194:197], v[30:33]
	v_mfma_f32_16x16x32_bf16 v[26:29], v[170:173], v[194:197], v[26:29]
	v_mfma_f32_16x16x32_bf16 v[14:17], v[162:165], v[202:205], v[14:17]
	v_mfma_f32_16x16x32_bf16 v[10:13], v[170:173], v[202:205], v[10:13]
	v_mfma_f32_16x16x32_bf16 v[62:65], v[166:169], v[182:185], v[62:65]
	v_mfma_f32_16x16x32_bf16 v[58:61], v[174:177], v[182:185], v[58:61]
	v_mfma_f32_16x16x32_bf16 v[46:49], v[166:169], v[190:193], v[46:49]
	v_mfma_f32_16x16x32_bf16 v[42:45], v[174:177], v[190:193], v[42:45]
	v_mfma_f32_16x16x32_bf16 v[30:33], v[166:169], v[198:201], v[30:33]
	v_mfma_f32_16x16x32_bf16 v[26:29], v[174:177], v[198:201], v[26:29]
	v_mfma_f32_16x16x32_bf16 v[14:17], v[166:169], v[206:209], v[14:17]
	v_mfma_f32_16x16x32_bf16 v[10:13], v[174:177], v[206:209], v[10:13]
	s_setprio 0
	s_barrier
	s_add_i32 s76, s76, 2
	s_add_u32 s78, s78, 0x100
	s_addc_u32 s79, s79, 0
	s_add_u32 s56, s56, 0x100
	s_addc_u32 s57, s57, 0
	s_cmp_gt_u32 s76, 29
	s_cbranch_scc0 .LBB0_767
	s_and_b64 vcc, exec, s[10:11]
	s_cbranch_vccz .LBB0_770
	s_barrier

; #define PG8_STAGE(bufoff, gbase, voff) do { if constexpr (!NOSTAGE) _Pragma("unroll") for (int _i = 0; _i < 2; ++_i) \
;         __builtin_amdgcn_global_load_lds((const unsigned*)((const char*)(gbase) + (size_t)_i * pstep##voff + v##voff), (PG8_LAS unsigned*)(lds + (bufoff) + ldsw + _i * 8192), 16, 0, 0); } while (0)
; #define PG8_WAIT_V(n) asm volatile("s_waitcnt vmcnt(" #n ")" ::: "memory")
; #define PG8_BAR __builtin_amdgcn_s_barrier()
; template <class Epi, class Sched, bool ALIGN_EPI = true, bool SP2 = true, bool FULLLINE = false, bool NOSTAGE = false, bool FP8 = false>
; __device__ __forceinline__ void gemm_phase(PG8_LAS unsigned char* lds, const Gemm g, const Sched& S, const Epi& E) {
;     ...
;     const int aoff = lds_byte(wr * 64 + fr, fq * 8), boff = lds_byte(wc * 32 + fr, fq * 8);
;     ...
;     PG8_STAGE(PG8_SB(0, 0), cB, offB); PG8_STAGE(PG8_SB(0, 1), cB + hstepB, offB); PG8_STAGE(PG8_SA(0, 0), cA, offA); PG8_STAGE(PG8_SA(0, 1), cA + hstepA, offA);
;     PG8_STAGE(PG8_SB(1, 0), cB + kstep, offB); PG8_STAGE(PG8_SA(1, 0), cA + kstep, offA); PG8_STAGE(PG8_SB(1, 1), cB + hstepB + kstep, offB);
;     if (wr == 1) PG8_BAR;
;     PG8_WAIT_V(0); PG8_BAR;
;     PG8_BAR;
;     } else {
;     PG8_STAGE(PG8_SB(0, 0), cB, offB); PG8_STAGE(PG8_SA(0, 0), cA, offA); PG8_STAGE(PG8_SB(0, 1), cB + hstepB, offB); PG8_STAGE(PG8_SA(0, 1), cA + hstepA, offA);
;     if (wr == 1) PG8_BAR;
;     PG8_WAIT_V(4); PG8_BAR;
;     PG8_STAGE(PG8_SB(1, 0), cB + kstep, offB); PG8_STAGE(PG8_SA(1, 0), cA + kstep, offA); PG8_STAGE(PG8_SB(1, 1), cB + hstepB + kstep, offB);
;     PG8_WAIT_V(6); PG8_BAR;
;     }
;     if (wr == 1) __builtin_amdgcn_s_setprio(1);
;     for (;;) {
;         const bool has_next = S.next(ui + 1, nxt);
;         const char* nA = has_next ? PG8_ABASE(nxt) : cA; const char* nB = has_next ? PG8_BBASE(nxt) : cB;
.LBB0_854:
	s_waitcnt vmcnt(0)
	v_cndmask_b32_e64 v4, 0, 1, s[8:9]
	s_lshr_b32 s13, s6, 3
	v_cmp_ne_u32_e64 s[6:7], 1, v4
	s_andn2_b64 vcc, exec, s[8:9]
	s_barrier
	s_barrier
	s_cbranch_vccnz .LBB0_856
.LBB0_856:
	v_and_b32_e32 v4, 48, v0
	v_lshlrev_b32_e32 v5, 6, v0
	s_movk_i32 s1, 0x3c0
	s_add_u32 s55, s48, 0x10a000
	v_and_or_b32 v4, v5, s1, v4
	v_lshlrev_b32_e32 v5, 2, v0
	s_addc_u32 s62, s49, 0
	s_lshl_b32 s0, s12, 13
	v_and_b32_e32 v5, 32, v5
	v_bitop3_b32 v6, v4, s0, v5 bitop3:0xde
	s_lshl_b32 s0, s11, 5
	s_and_b32 s74, s0, 0x60
	s_lshl_b32 s63, s12, 6
	s_lshl_b32 s0, s74, 7
	s_cmpk_lt_u32 s10, 0x100
	v_add_u16_e32 v1, v1, v2
	s_sext_i32_i8 s84, s13
	v_bitop3_b32 v4, s0, v4, v5 bitop3:0xf6
	s_cselect_b64 s[12:13], -1, 0
	v_lshrrev_b16_e32 v1, 1, v1
	s_add_i32 s77, 0, 0x10000
	s_add_i32 s78, 0, 0x14000
	s_add_i32 s79, 0, 0x18000
	s_add_i32 s80, 0, 0x1c000
	s_ashr_i32 s75, s86, 31
	v_add_lshl_u32 v174, v3, v1, 1
	v_mov_b32_e32 v175, 0
	s_mov_b32 s76, 0
	v_mov_b64_e32 v[176:177], 0x200
	v_mov_b64_e32 v[178:179], 0x1ff
	v_add_u32_e32 v1, s77, v4
	v_add_u32_e32 v192, s78, v4
	v_add_u32_e32 v193, 0, v6
	s_mov_b64 s[14:15], 0x160080
	s_mov_b64 s[16:17], 0x210080
	s_mov_b64 s[18:19], 0x100
	s_mov_b64 s[20:21], 0xb0100
	s_mov_b64 s[22:23], 0x160100
	s_mov_b64 s[24:25], 0x210100
	v_add_u32_e32 v194, s79, v4
	v_add_u32_e32 v195, s80, v4
	s_waitcnt lgkmcnt(0)
	s_mov_b64 s[26:27], 0x180
	s_mov_b64 s[28:29], 0xb0180
	s_mov_b64 s[30:31], 0xb0000
	s_mov_b64 s[34:35], 0x160000
	s_mov_b64 s[36:37], 0x210000
	s_mov_b64 s[38:39], 0x80
	s_mov_b64 s[66:67], 0xb0080
	s_branch .LBB0_859

.LBB0_869:
	ds_read_b128 v[2:5], v1
	ds_read_b128 v[6:9], v1 offset:1024
	ds_read_b128 v[10:13], v1 offset:2048
	ds_read_b128 v[14:17], v1 offset:3072
	ds_read_b128 v[18:21], v192
	ds_read_b128 v[22:25], v192 offset:1024
	ds_read_b128 v[26:29], v192 offset:2048
	ds_read_b128 v[30:33], v192 offset:3072
	v_lshl_add_u64 v[248:249], s[70:71], 0, v[170:171]
	s_add_i32 s85, s45, 0xc000
	v_lshl_add_u64 v[66:67], v[248:249], 0, s[14:15]
	s_mov_b32 m0, s85
	s_add_i32 s87, s45, 0xe000
	ds_read_b128 v[34:37], v193
	ds_read_b128 v[38:41], v193 offset:1024
	ds_read_b128 v[42:45], v193 offset:2048
	ds_read_b128 v[46:49], v193 offset:3072
	ds_read_b128 v[50:53], v193 offset:4096
	ds_read_b128 v[54:57], v193 offset:5120
	ds_read_b128 v[58:61], v193 offset:6144
	ds_read_b128 v[62:65], v193 offset:7168
	global_load_lds_dwordx4 v[66:67], off
	v_lshl_add_u64 v[66:67], v[248:249], 0, s[16:17]
	s_mov_b32 m0, s87
	s_nop 0
	global_load_lds_dwordx4 v[66:67], off
	s_waitcnt vmcnt(24)
	s_waitcnt lgkmcnt(0)
	s_barrier
	s_waitcnt lgkmcnt(0)
	s_setprio 1
	v_mfma_f32_16x16x32_bf16 v[66:69], v[2:5], v[34:37], 0
	v_mfma_f32_16x16x32_bf16 v[70:73], v[10:13], v[34:37], 0
	v_mfma_f32_16x16x32_bf16 v[78:81], v[10:13], v[42:45], 0
	v_mfma_f32_16x16x32_bf16 v[86:89], v[10:13], v[50:53], 0
	v_mfma_f32_16x16x32_bf16 v[66:69], v[6:9], v[38:41], v[66:69]
	v_mfma_f32_16x16x32_bf16 v[70:73], v[14:17], v[38:41], v[70:73]
	v_mfma_f32_16x16x32_bf16 v[74:77], v[2:5], v[42:45], 0
	v_mfma_f32_16x16x32_bf16 v[78:81], v[14:17], v[46:49], v[78:81]
	v_mfma_f32_16x16x32_bf16 v[82:85], v[2:5], v[50:53], 0
	v_mfma_f32_16x16x32_bf16 v[86:89], v[14:17], v[54:57], v[86:89]
	v_mfma_f32_16x16x32_bf16 v[90:93], v[2:5], v[58:61], 0
	v_mfma_f32_16x16x32_bf16 v[94:97], v[10:13], v[58:61], 0
	v_mfma_f32_16x16x32_bf16 v[74:77], v[6:9], v[46:49], v[74:77]
	v_mfma_f32_16x16x32_bf16 v[82:85], v[6:9], v[54:57], v[82:85]
	v_mfma_f32_16x16x32_bf16 v[90:93], v[6:9], v[62:65], v[90:93]
	v_mfma_f32_16x16x32_bf16 v[94:97], v[14:17], v[62:65], v[94:97]
	v_mfma_f32_16x16x32_bf16 v[98:101], v[18:21], v[34:37], 0
	v_mfma_f32_16x16x32_bf16 v[34:37], v[26:29], v[34:37], 0
	v_mfma_f32_16x16x32_bf16 v[98:101], v[22:25], v[38:41], v[98:101]
	v_mfma_f32_16x16x32_bf16 v[34:37], v[30:33], v[38:41], v[34:37]
	v_mfma_f32_16x16x32_bf16 v[38:41], v[18:21], v[42:45], 0
	v_mfma_f32_16x16x32_bf16 v[42:45], v[26:29], v[42:45], 0
	v_mfma_f32_16x16x32_bf16 v[38:41], v[22:25], v[46:49], v[38:41]
	v_mfma_f32_16x16x32_bf16 v[42:45], v[30:33], v[46:49], v[42:45]
	v_mfma_f32_16x16x32_bf16 v[46:49], v[18:21], v[50:53], 0
	v_mfma_f32_16x16x32_bf16 v[50:53], v[26:29], v[50:53], 0
	v_mfma_f32_16x16x32_bf16 v[46:49], v[22:25], v[54:57], v[46:49]
	v_mfma_f32_16x16x32_bf16 v[50:53], v[30:33], v[54:57], v[50:53]
	v_mfma_f32_16x16x32_bf16 v[54:57], v[18:21], v[58:61], 0
	v_mfma_f32_16x16x32_bf16 v[58:61], v[26:29], v[58:61], 0
	v_mfma_f32_16x16x32_bf16 v[54:57], v[22:25], v[62:65], v[54:57]
	v_mfma_f32_16x16x32_bf16 v[58:61], v[30:33], v[62:65], v[58:61]
	s_setprio 0
	s_barrier
	v_lshl_add_u64 v[250:251], s[72:73], 0, v[172:173]
	s_add_i32 s88, s77, s44
	v_lshl_add_u64 v[130:131], v[250:251], 0, s[18:19]
	s_mov_b32 m0, s88
	s_add_i32 s89, s88, 0x2000
	ds_read_b128 v[62:65], v193 offset:16384
	ds_read_b128 v[102:105], v193 offset:17408
	ds_read_b128 v[106:109], v193 offset:18432
	ds_read_b128 v[110:113], v193 offset:19456
	ds_read_b128 v[114:117], v193 offset:20480
	ds_read_b128 v[118:121], v193 offset:21504
	ds_read_b128 v[122:125], v193 offset:22528
	ds_read_b128 v[126:129], v193 offset:23552
	global_load_lds_dwordx4 v[130:131], off
	v_lshl_add_u64 v[130:131], v[250:251], 0, s[20:21]
	s_mov_b32 m0, s89
	s_add_i32 s90, s78, s44
	global_load_lds_dwordx4 v[130:131], off
	v_lshl_add_u64 v[130:131], v[250:251], 0, s[22:23]
	s_mov_b32 m0, s90
	s_add_i32 s40, s90, 0x2000
	global_load_lds_dwordx4 v[130:131], off
	v_lshl_add_u64 v[130:131], v[250:251], 0, s[24:25]
	s_mov_b32 m0, s40
	s_nop 0
	global_load_lds_dwordx4 v[130:131], off
	v_lshl_add_u64 v[130:131], v[248:249], 0, s[18:19]
	s_mov_b32 m0, s45
	s_nop 0
	global_load_lds_dwordx4 v[130:131], off
	v_lshl_add_u64 v[130:131], v[248:249], 0, s[20:21]
	s_mov_b32 m0, s46
	s_nop 0
	global_load_lds_dwordx4 v[130:131], off
	s_waitcnt vmcnt(24)
	s_waitcnt lgkmcnt(0)
	s_barrier
	s_waitcnt lgkmcnt(0)
	s_setprio 1
	v_mfma_f32_16x16x32_bf16 v[130:133], v[2:5], v[62:65], 0
	v_mfma_f32_16x16x32_bf16 v[138:141], v[6:9], v[102:105], v[130:133]
	v_mfma_f32_16x16x32_bf16 v[130:133], v[10:13], v[62:65], 0
	v_mfma_f32_16x16x32_bf16 v[150:153], v[14:17], v[102:105], v[130:133]
	v_mfma_f32_16x16x32_bf16 v[130:133], v[2:5], v[106:109], 0
	v_mfma_f32_16x16x32_bf16 v[154:157], v[6:9], v[110:113], v[130:133]
	v_mfma_f32_16x16x32_bf16 v[130:133], v[10:13], v[106:109], 0
	v_mfma_f32_16x16x32_bf16 v[158:161], v[14:17], v[110:113], v[130:133]
	v_mfma_f32_16x16x32_bf16 v[130:133], v[2:5], v[114:117], 0
	v_mfma_f32_16x16x32_bf16 v[2:5], v[2:5], v[122:125], 0
	v_mfma_f32_16x16x32_bf16 v[162:165], v[6:9], v[118:121], v[130:133]
	v_mfma_f32_16x16x32_bf16 v[2:5], v[6:9], v[126:129], v[2:5]
	v_mfma_f32_16x16x32_bf16 v[6:9], v[10:13], v[122:125], 0
	v_mfma_f32_16x16x32_bf16 v[130:133], v[10:13], v[114:117], 0
	v_mfma_f32_16x16x32_bf16 v[6:9], v[14:17], v[126:129], v[6:9]
	v_mfma_f32_16x16x32_bf16 v[166:169], v[14:17], v[118:121], v[130:133]
	v_mfma_f32_16x16x32_bf16 v[10:13], v[18:21], v[62:65], 0
	v_mfma_f32_16x16x32_bf16 v[180:183], v[22:25], v[102:105], v[10:13]
	v_mfma_f32_16x16x32_bf16 v[10:13], v[26:29], v[62:65], 0
	v_mfma_f32_16x16x32_bf16 v[184:187], v[30:33], v[102:105], v[10:13]
	v_mfma_f32_16x16x32_bf16 v[10:13], v[18:21], v[106:109], 0
	v_mfma_f32_16x16x32_bf16 v[188:191], v[22:25], v[110:113], v[10:13]
	v_mfma_f32_16x16x32_bf16 v[10:13], v[26:29], v[106:109], 0
	v_mfma_f32_16x16x32_bf16 v[196:199], v[30:33], v[110:113], v[10:13]
	v_mfma_f32_16x16x32_bf16 v[10:13], v[18:21], v[114:117], 0
	v_mfma_f32_16x16x32_bf16 v[200:203], v[22:25], v[118:121], v[10:13]
	v_mfma_f32_16x16x32_bf16 v[10:13], v[26:29], v[114:117], 0
	v_mfma_f32_16x16x32_bf16 v[204:207], v[30:33], v[118:121], v[10:13]
	v_mfma_f32_16x16x32_bf16 v[10:13], v[18:21], v[122:125], 0
	v_mfma_f32_16x16x32_bf16 v[208:211], v[22:25], v[126:129], v[10:13]
	v_mfma_f32_16x16x32_bf16 v[10:13], v[26:29], v[122:125], 0
	v_mfma_f32_16x16x32_bf16 v[212:215], v[30:33], v[126:129], v[10:13]
	s_setprio 0
	s_barrier
; #define PG8_WAIT_V(n) asm volatile("s_waitcnt vmcnt(" #n ")" ::: "memory")
; template <class Epi, class Sched, bool ALIGN_EPI = true, bool SP2 = true, bool FULLLINE = false, bool NOSTAGE = false, bool FP8 = false>
; __device__ __forceinline__ void gemm_phase(PG8_LAS unsigned char* lds, const Gemm g, const Sched& S, const Epi& E) {
;     ...
;         static_assert(SP2, "only the SP2 loop is kept");
;         { const int t = 0; if constexpr (Epi::NST == 16) PG8_ITER(PG8_WAIT_V(24)); else if constexpr (Epi::NST == 8) PG8_ITER(PG8_WAIT_V(16)); else PG8_ITER(PG8_WAIT_V(8)); }
;         for (int t = 2; t < nt; t += 2) PG8_ITER(PG8_WAIT_V(8));
	s_nop 5
	ds_read_b128 v[10:13], v194
	ds_read_b128 v[14:17], v194 offset:1024
	ds_read_b128 v[18:21], v194 offset:2048
	ds_read_b128 v[22:25], v194 offset:3072
	ds_read_b128 v[216:219], v195
	ds_read_b128 v[220:223], v195 offset:1024
	ds_read_b128 v[224:227], v195 offset:2048
	ds_read_b128 v[228:231], v195 offset:3072
	s_mov_b32 m0, s47
	v_lshl_add_u64 v[106:107], v[248:249], 0, s[22:23]
	ds_read_b128 v[26:29], v193 offset:32768
	ds_read_b128 v[30:33], v193 offset:33792
	ds_read_b128 v[62:65], v193 offset:34816
	ds_read_b128 v[102:105], v193 offset:35840
	ds_read_b128 v[232:235], v193 offset:36864
	ds_read_b128 v[236:239], v193 offset:37888
	ds_read_b128 v[240:243], v193 offset:38912
	ds_read_b128 v[244:247], v193 offset:39936
	global_load_lds_dwordx4 v[106:107], off
	v_lshl_add_u64 v[106:107], v[248:249], 0, s[24:25]
	s_mov_b32 m0, s52
	s_nop 0
	global_load_lds_dwordx4 v[106:107], off
	s_waitcnt vmcnt(8)
	s_waitcnt lgkmcnt(0)
	s_barrier
	s_waitcnt lgkmcnt(0)
	s_setprio 1
	v_mfma_f32_16x16x32_bf16 v[66:69], v[10:13], v[26:29], v[66:69]
	v_mfma_f32_16x16x32_bf16 v[146:149], v[14:17], v[30:33], v[66:69]
	v_mfma_f32_16x16x32_bf16 v[66:69], v[18:21], v[26:29], v[70:73]
	v_mfma_f32_16x16x32_bf16 v[142:145], v[22:25], v[30:33], v[66:69]
	v_mfma_f32_16x16x32_bf16 v[66:69], v[10:13], v[62:65], v[74:77]
	v_mfma_f32_16x16x32_bf16 v[126:129], v[14:17], v[102:105], v[66:69]
	v_mfma_f32_16x16x32_bf16 v[66:69], v[18:21], v[62:65], v[78:81]
	v_mfma_f32_16x16x32_bf16 v[122:125], v[22:25], v[102:105], v[66:69]
	v_mfma_f32_16x16x32_bf16 v[66:69], v[10:13], v[232:235], v[82:85]
	v_mfma_f32_16x16x32_bf16 v[110:113], v[14:17], v[236:239], v[66:69]
	v_mfma_f32_16x16x32_bf16 v[66:69], v[18:21], v[232:235], v[86:89]
	v_mfma_f32_16x16x32_bf16 v[106:109], v[22:25], v[236:239], v[66:69]
	v_mfma_f32_16x16x32_bf16 v[66:69], v[10:13], v[240:243], v[90:93]
	v_mfma_f32_16x16x32_bf16 v[86:89], v[14:17], v[244:247], v[66:69]
	v_mfma_f32_16x16x32_bf16 v[66:69], v[18:21], v[240:243], v[94:97]
	v_mfma_f32_16x16x32_bf16 v[78:81], v[22:25], v[244:247], v[66:69]
	v_mfma_f32_16x16x32_bf16 v[66:69], v[216:219], v[26:29], v[98:101]
	v_mfma_f32_16x16x32_bf16 v[26:29], v[224:227], v[26:29], v[34:37]
	v_mfma_f32_16x16x32_bf16 v[130:133], v[228:231], v[30:33], v[26:29]
	v_mfma_f32_16x16x32_bf16 v[26:29], v[216:219], v[62:65], v[38:41]
	v_mfma_f32_16x16x32_bf16 v[118:121], v[220:223], v[102:105], v[26:29]
	v_mfma_f32_16x16x32_bf16 v[26:29], v[224:227], v[62:65], v[42:45]
	v_mfma_f32_16x16x32_bf16 v[114:117], v[228:231], v[102:105], v[26:29]
	v_mfma_f32_16x16x32_bf16 v[26:29], v[216:219], v[232:235], v[46:49]
	v_mfma_f32_16x16x32_bf16 v[102:105], v[220:223], v[236:239], v[26:29]
	v_mfma_f32_16x16x32_bf16 v[26:29], v[224:227], v[232:235], v[50:53]
	v_mfma_f32_16x16x32_bf16 v[98:101], v[228:231], v[236:239], v[26:29]
	v_mfma_f32_16x16x32_bf16 v[26:29], v[216:219], v[240:243], v[54:57]
	v_mfma_f32_16x16x32_bf16 v[70:73], v[220:223], v[244:247], v[26:29]
	v_mfma_f32_16x16x32_bf16 v[26:29], v[224:227], v[240:243], v[58:61]
	v_mfma_f32_16x16x32_bf16 v[134:137], v[220:223], v[30:33], v[66:69]
	v_mfma_f32_16x16x32_bf16 v[66:69], v[228:231], v[244:247], v[26:29]
	s_setprio 0
	s_barrier
	s_add_i32 s41, s79, s44
	s_nop 3
	v_lshl_add_u64 v[26:27], v[250:251], 0, s[26:27]
	s_mov_b32 m0, s41
	s_add_i32 s50, s41, 0x2000
	ds_read_b128 v[34:37], v193 offset:49152
	ds_read_b128 v[38:41], v193 offset:50176
	ds_read_b128 v[74:77], v193 offset:51200
	ds_read_b128 v[82:85], v193 offset:52224
	ds_read_b128 v[90:93], v193 offset:53248
	ds_read_b128 v[94:97], v193 offset:54272
	ds_read_b128 v[232:235], v193 offset:55296
	ds_read_b128 v[236:239], v193 offset:56320
	global_load_lds_dwordx4 v[26:27], off
	v_lshl_add_u64 v[26:27], v[250:251], 0, s[28:29]
	s_mov_b32 m0, s50
	s_mov_b64 s[56:57], 0x160180
	s_add_i32 s51, s80, s44
	global_load_lds_dwordx4 v[26:27], off
	v_lshl_add_u64 v[26:27], v[250:251], 0, s[56:57]
	s_mov_b32 m0, s51
	s_mov_b64 s[56:57], 0x210180
	s_add_i32 s33, s51, 0x2000
	global_load_lds_dwordx4 v[26:27], off
	v_lshl_add_u64 v[26:27], v[250:251], 0, s[56:57]
	s_mov_b32 m0, s33
	s_nop 0
	global_load_lds_dwordx4 v[26:27], off
	v_lshl_add_u64 v[26:27], v[248:249], 0, s[26:27]
	s_mov_b32 m0, s53
	s_nop 0
	global_load_lds_dwordx4 v[26:27], off
	v_lshl_add_u64 v[26:27], v[248:249], 0, s[28:29]
	s_mov_b32 m0, s54
	s_nop 0
	global_load_lds_dwordx4 v[26:27], off
	s_waitcnt vmcnt(8)
	s_waitcnt lgkmcnt(0)
	s_barrier
	s_waitcnt lgkmcnt(0)
	s_setprio 1
	v_mfma_f32_16x16x32_bf16 v[26:29], v[10:13], v[34:37], v[138:141]
	v_mfma_f32_16x16x32_bf16 v[62:65], v[14:17], v[38:41], v[26:29]
	v_mfma_f32_16x16x32_bf16 v[26:29], v[18:21], v[34:37], v[150:153]
	v_mfma_f32_16x16x32_bf16 v[58:61], v[22:25], v[38:41], v[26:29]
	v_mfma_f32_16x16x32_bf16 v[26:29], v[10:13], v[74:77], v[154:157]
	v_mfma_f32_16x16x32_bf16 v[46:49], v[14:17], v[82:85], v[26:29]
	v_mfma_f32_16x16x32_bf16 v[26:29], v[18:21], v[74:77], v[158:161]
	v_mfma_f32_16x16x32_bf16 v[42:45], v[22:25], v[82:85], v[26:29]
	v_mfma_f32_16x16x32_bf16 v[26:29], v[10:13], v[90:93], v[162:165]
	v_mfma_f32_16x16x32_bf16 v[2:5], v[10:13], v[232:235], v[2:5]
	v_mfma_f32_16x16x32_bf16 v[30:33], v[14:17], v[94:97], v[26:29]
	v_mfma_f32_16x16x32_bf16 v[26:29], v[18:21], v[90:93], v[166:169]
	v_mfma_f32_16x16x32_bf16 v[14:17], v[14:17], v[236:239], v[2:5]
	v_mfma_f32_16x16x32_bf16 v[2:5], v[18:21], v[232:235], v[6:9]
	v_mfma_f32_16x16x32_bf16 v[26:29], v[22:25], v[94:97], v[26:29]
	v_mfma_f32_16x16x32_bf16 v[10:13], v[22:25], v[236:239], v[2:5]
	v_mfma_f32_16x16x32_bf16 v[2:5], v[216:219], v[34:37], v[180:183]
	v_mfma_f32_16x16x32_bf16 v[54:57], v[220:223], v[38:41], v[2:5]
	v_mfma_f32_16x16x32_bf16 v[2:5], v[224:227], v[34:37], v[184:187]
	v_mfma_f32_16x16x32_bf16 v[50:53], v[228:231], v[38:41], v[2:5]
	v_mfma_f32_16x16x32_bf16 v[2:5], v[216:219], v[74:77], v[188:191]
	v_mfma_f32_16x16x32_bf16 v[38:41], v[220:223], v[82:85], v[2:5]
	v_mfma_f32_16x16x32_bf16 v[2:5], v[224:227], v[74:77], v[196:199]
	v_mfma_f32_16x16x32_bf16 v[34:37], v[228:231], v[82:85], v[2:5]
	v_mfma_f32_16x16x32_bf16 v[2:5], v[216:219], v[90:93], v[200:203]
	v_mfma_f32_16x16x32_bf16 v[22:25], v[220:223], v[94:97], v[2:5]
	v_mfma_f32_16x16x32_bf16 v[2:5], v[224:227], v[90:93], v[204:207]
	v_mfma_f32_16x16x32_bf16 v[18:21], v[228:231], v[94:97], v[2:5]
	v_mfma_f32_16x16x32_bf16 v[2:5], v[216:219], v[232:235], v[208:211]
	v_mfma_f32_16x16x32_bf16 v[6:9], v[220:223], v[236:239], v[2:5]
	v_mfma_f32_16x16x32_bf16 v[2:5], v[224:227], v[232:235], v[212:215]
	v_mfma_f32_16x16x32_bf16 v[2:5], v[228:231], v[236:239], v[2:5]
	s_setprio 0
	s_barrier
	s_add_u32 s70, s70, 0x160180
	s_addc_u32 s71, s71, 0
	s_add_u32 s56, s72, 0x200
	s_addc_u32 s57, s73, 0
	s_mov_b32 s72, 0
.LBB0_870:
	ds_read_b128 v[74:77], v1
	ds_read_b128 v[82:85], v1 offset:1024
	ds_read_b128 v[90:93], v1 offset:2048
	ds_read_b128 v[94:97], v1 offset:3072
	ds_read_b128 v[138:141], v192
	ds_read_b128 v[150:153], v192 offset:1024
	ds_read_b128 v[154:157], v192 offset:2048
	ds_read_b128 v[158:161], v192 offset:3072
	s_add_u32 s0, s70, 0xffea0080
	s_addc_u32 s1, s71, -1
	s_cmpk_eq_i32 s72, 0x54
	s_cselect_b32 s93, s11, s1
	s_cselect_b32 s92, s10, s0
	s_cselect_b32 s95, s69, s57
	s_cselect_b32 s94, s68, s56
	s_mov_b32 m0, s85
	v_lshl_add_u64 v[208:209], s[70:71], 0, v[174:175]
	ds_read_b128 v[162:165], v193
	ds_read_b128 v[166:169], v193 offset:1024
	ds_read_b128 v[180:183], v193 offset:2048
	ds_read_b128 v[184:187], v193 offset:3072
	ds_read_b128 v[188:191], v193 offset:4096
	ds_read_b128 v[196:199], v193 offset:5120
	ds_read_b128 v[200:203], v193 offset:6144
	ds_read_b128 v[204:207], v193 offset:7168
	global_load_lds_dwordx4 v[208:209], off
	v_lshl_add_u64 v[208:209], v[208:209], 0, s[30:31]
	s_mov_b32 m0, s87
	s_nop 0
	global_load_lds_dwordx4 v[208:209], off
	s_waitcnt vmcnt(8)
	s_waitcnt lgkmcnt(0)
	s_barrier
	s_waitcnt lgkmcnt(0)
	s_setprio 1
	v_mfma_f32_16x16x32_bf16 v[146:149], v[74:77], v[162:165], v[146:149]
	v_mfma_f32_16x16x32_bf16 v[142:145], v[90:93], v[162:165], v[142:145]
	v_mfma_f32_16x16x32_bf16 v[126:129], v[74:77], v[180:183], v[126:129]
	v_mfma_f32_16x16x32_bf16 v[122:125], v[90:93], v[180:183], v[122:125]
	v_mfma_f32_16x16x32_bf16 v[110:113], v[74:77], v[188:191], v[110:113]
	v_mfma_f32_16x16x32_bf16 v[106:109], v[90:93], v[188:191], v[106:109]
	v_mfma_f32_16x16x32_bf16 v[86:89], v[74:77], v[200:203], v[86:89]
	v_mfma_f32_16x16x32_bf16 v[78:81], v[90:93], v[200:203], v[78:81]
	v_mfma_f32_16x16x32_bf16 v[146:149], v[82:85], v[166:169], v[146:149]
	v_mfma_f32_16x16x32_bf16 v[142:145], v[94:97], v[166:169], v[142:145]
	v_mfma_f32_16x16x32_bf16 v[126:129], v[82:85], v[184:187], v[126:129]
	v_mfma_f32_16x16x32_bf16 v[122:125], v[94:97], v[184:187], v[122:125]
	v_mfma_f32_16x16x32_bf16 v[110:113], v[82:85], v[196:199], v[110:113]
	v_mfma_f32_16x16x32_bf16 v[106:109], v[94:97], v[196:199], v[106:109]
	v_mfma_f32_16x16x32_bf16 v[86:89], v[82:85], v[204:207], v[86:89]
	v_mfma_f32_16x16x32_bf16 v[78:81], v[94:97], v[204:207], v[78:81]
	v_mfma_f32_16x16x32_bf16 v[134:137], v[138:141], v[162:165], v[134:137]
	v_mfma_f32_16x16x32_bf16 v[130:133], v[154:157], v[162:165], v[130:133]
	v_mfma_f32_16x16x32_bf16 v[118:121], v[138:141], v[180:183], v[118:121]
	v_mfma_f32_16x16x32_bf16 v[114:117], v[154:157], v[180:183], v[114:117]
	v_mfma_f32_16x16x32_bf16 v[102:105], v[138:141], v[188:191], v[102:105]
	v_mfma_f32_16x16x32_bf16 v[98:101], v[154:157], v[188:191], v[98:101]
	v_mfma_f32_16x16x32_bf16 v[70:73], v[138:141], v[200:203], v[70:73]
	v_mfma_f32_16x16x32_bf16 v[66:69], v[154:157], v[200:203], v[66:69]
	v_mfma_f32_16x16x32_bf16 v[134:137], v[150:153], v[166:169], v[134:137]
	v_mfma_f32_16x16x32_bf16 v[130:133], v[158:161], v[166:169], v[130:133]
	v_mfma_f32_16x16x32_bf16 v[118:121], v[150:153], v[184:187], v[118:121]
	v_mfma_f32_16x16x32_bf16 v[114:117], v[158:161], v[184:187], v[114:117]
	v_mfma_f32_16x16x32_bf16 v[102:105], v[150:153], v[196:199], v[102:105]
	v_mfma_f32_16x16x32_bf16 v[98:101], v[158:161], v[196:199], v[98:101]
	v_mfma_f32_16x16x32_bf16 v[70:73], v[150:153], v[204:207], v[70:73]
	v_mfma_f32_16x16x32_bf16 v[66:69], v[158:161], v[204:207], v[66:69]
	s_setprio 0
	s_barrier
	s_mov_b32 m0, s88
	v_lshl_add_u64 v[208:209], s[94:95], 0, v[172:173]
	ds_read_b128 v[162:165], v193 offset:16384
	ds_read_b128 v[166:169], v193 offset:17408
	ds_read_b128 v[180:183], v193 offset:18432
	ds_read_b128 v[184:187], v193 offset:19456
	ds_read_b128 v[188:191], v193 offset:20480
	ds_read_b128 v[196:199], v193 offset:21504
	ds_read_b128 v[200:203], v193 offset:22528
	ds_read_b128 v[204:207], v193 offset:23552
	global_load_lds_dwordx4 v[208:209], off
	v_lshl_add_u64 v[210:211], v[208:209], 0, s[30:31]
	s_mov_b32 m0, s89
	s_nop 0
	global_load_lds_dwordx4 v[210:211], off
	v_lshl_add_u64 v[210:211], v[208:209], 0, s[34:35]
	s_mov_b32 m0, s90
	s_nop 0
	global_load_lds_dwordx4 v[210:211], off
	v_lshl_add_u64 v[210:211], v[208:209], 0, s[36:37]
	s_mov_b32 m0, s40
	s_nop 0
	global_load_lds_dwordx4 v[210:211], off
	v_lshl_add_u64 v[210:211], s[92:93], 0, v[170:171]
	s_mov_b32 m0, s45
	v_lshl_add_u64 v[212:213], v[210:211], 0, s[30:31]
	global_load_lds_dwordx4 v[210:211], off
	s_mov_b32 m0, s46
	s_nop 0
	global_load_lds_dwordx4 v[212:213], off
	s_waitcnt vmcnt(8)
	s_waitcnt lgkmcnt(0)
	s_barrier
	s_waitcnt lgkmcnt(0)
	s_setprio 1
	v_mfma_f32_16x16x32_bf16 v[62:65], v[74:77], v[162:165], v[62:65]
	v_mfma_f32_16x16x32_bf16 v[58:61], v[90:93], v[162:165], v[58:61]
	v_mfma_f32_16x16x32_bf16 v[46:49], v[74:77], v[180:183], v[46:49]
	v_mfma_f32_16x16x32_bf16 v[42:45], v[90:93], v[180:183], v[42:45]
	v_mfma_f32_16x16x32_bf16 v[30:33], v[74:77], v[188:191], v[30:33]
	v_mfma_f32_16x16x32_bf16 v[26:29], v[90:93], v[188:191], v[26:29]
	v_mfma_f32_16x16x32_bf16 v[14:17], v[74:77], v[200:203], v[14:17]
	v_mfma_f32_16x16x32_bf16 v[10:13], v[90:93], v[200:203], v[10:13]
	v_mfma_f32_16x16x32_bf16 v[62:65], v[82:85], v[166:169], v[62:65]
	v_mfma_f32_16x16x32_bf16 v[58:61], v[94:97], v[166:169], v[58:61]
	v_mfma_f32_16x16x32_bf16 v[46:49], v[82:85], v[184:187], v[46:49]
	v_mfma_f32_16x16x32_bf16 v[42:45], v[94:97], v[184:187], v[42:45]
	v_mfma_f32_16x16x32_bf16 v[30:33], v[82:85], v[196:199], v[30:33]
	v_mfma_f32_16x16x32_bf16 v[26:29], v[94:97], v[196:199], v[26:29]
	v_mfma_f32_16x16x32_bf16 v[14:17], v[82:85], v[204:207], v[14:17]
	v_mfma_f32_16x16x32_bf16 v[10:13], v[94:97], v[204:207], v[10:13]
	v_mfma_f32_16x16x32_bf16 v[54:57], v[138:141], v[162:165], v[54:57]
	v_mfma_f32_16x16x32_bf16 v[50:53], v[154:157], v[162:165], v[50:53]
	v_mfma_f32_16x16x32_bf16 v[38:41], v[138:141], v[180:183], v[38:41]
	v_mfma_f32_16x16x32_bf16 v[34:37], v[154:157], v[180:183], v[34:37]
	v_mfma_f32_16x16x32_bf16 v[22:25], v[138:141], v[188:191], v[22:25]
	v_mfma_f32_16x16x32_bf16 v[18:21], v[154:157], v[188:191], v[18:21]
	v_mfma_f32_16x16x32_bf16 v[6:9], v[138:141], v[200:203], v[6:9]
	v_mfma_f32_16x16x32_bf16 v[2:5], v[154:157], v[200:203], v[2:5]
	v_mfma_f32_16x16x32_bf16 v[54:57], v[150:153], v[166:169], v[54:57]
	v_mfma_f32_16x16x32_bf16 v[50:53], v[158:161], v[166:169], v[50:53]
	v_mfma_f32_16x16x32_bf16 v[38:41], v[150:153], v[184:187], v[38:41]
	v_mfma_f32_16x16x32_bf16 v[34:37], v[158:161], v[184:187], v[34:37]
	v_mfma_f32_16x16x32_bf16 v[22:25], v[150:153], v[196:199], v[22:25]
	v_mfma_f32_16x16x32_bf16 v[18:21], v[158:161], v[196:199], v[18:21]
	v_mfma_f32_16x16x32_bf16 v[6:9], v[150:153], v[204:207], v[6:9]
	v_mfma_f32_16x16x32_bf16 v[2:5], v[158:161], v[204:207], v[2:5]
	s_setprio 0
	s_barrier
	ds_read_b128 v[74:77], v194
	ds_read_b128 v[82:85], v194 offset:1024
	ds_read_b128 v[90:93], v194 offset:2048
	ds_read_b128 v[94:97], v194 offset:3072
	ds_read_b128 v[138:141], v195
	ds_read_b128 v[150:153], v195 offset:1024
	ds_read_b128 v[154:157], v195 offset:2048
	ds_read_b128 v[158:161], v195 offset:3072
	s_mov_b32 m0, s47
	v_lshl_add_u64 v[212:213], v[210:211], 0, s[34:35]
	ds_read_b128 v[162:165], v193 offset:32768
	ds_read_b128 v[166:169], v193 offset:33792
	ds_read_b128 v[180:183], v193 offset:34816
	ds_read_b128 v[184:187], v193 offset:35840
	ds_read_b128 v[188:191], v193 offset:36864
	ds_read_b128 v[196:199], v193 offset:37888
	ds_read_b128 v[200:203], v193 offset:38912
	ds_read_b128 v[204:207], v193 offset:39936
	global_load_lds_dwordx4 v[212:213], off
	v_lshl_add_u64 v[212:213], v[210:211], 0, s[36:37]
	s_mov_b32 m0, s52
	s_nop 0
	global_load_lds_dwordx4 v[212:213], off
	s_waitcnt vmcnt(8)
	s_waitcnt lgkmcnt(0)
	s_barrier
	s_waitcnt lgkmcnt(0)
	s_setprio 1
	v_mfma_f32_16x16x32_bf16 v[146:149], v[74:77], v[162:165], v[146:149]
	v_mfma_f32_16x16x32_bf16 v[142:145], v[90:93], v[162:165], v[142:145]
	v_mfma_f32_16x16x32_bf16 v[126:129], v[74:77], v[180:183], v[126:129]
	v_mfma_f32_16x16x32_bf16 v[122:125], v[90:93], v[180:183], v[122:125]
	v_mfma_f32_16x16x32_bf16 v[110:113], v[74:77], v[188:191], v[110:113]
	v_mfma_f32_16x16x32_bf16 v[106:109], v[90:93], v[188:191], v[106:109]
	v_mfma_f32_16x16x32_bf16 v[86:89], v[74:77], v[200:203], v[86:89]
	v_mfma_f32_16x16x32_bf16 v[78:81], v[90:93], v[200:203], v[78:81]
	v_mfma_f32_16x16x32_bf16 v[146:149], v[82:85], v[166:169], v[146:149]
	v_mfma_f32_16x16x32_bf16 v[142:145], v[94:97], v[166:169], v[142:145]
	v_mfma_f32_16x16x32_bf16 v[126:129], v[82:85], v[184:187], v[126:129]
	v_mfma_f32_16x16x32_bf16 v[122:125], v[94:97], v[184:187], v[122:125]
	v_mfma_f32_16x16x32_bf16 v[110:113], v[82:85], v[196:199], v[110:113]
	v_mfma_f32_16x16x32_bf16 v[106:109], v[94:97], v[196:199], v[106:109]
	v_mfma_f32_16x16x32_bf16 v[86:89], v[82:85], v[204:207], v[86:89]
	v_mfma_f32_16x16x32_bf16 v[78:81], v[94:97], v[204:207], v[78:81]
	v_mfma_f32_16x16x32_bf16 v[134:137], v[138:141], v[162:165], v[134:137]
	v_mfma_f32_16x16x32_bf16 v[130:133], v[154:157], v[162:165], v[130:133]
	v_mfma_f32_16x16x32_bf16 v[118:121], v[138:141], v[180:183], v[118:121]
	v_mfma_f32_16x16x32_bf16 v[114:117], v[154:157], v[180:183], v[114:117]
	v_mfma_f32_16x16x32_bf16 v[102:105], v[138:141], v[188:191], v[102:105]
	v_mfma_f32_16x16x32_bf16 v[98:101], v[154:157], v[188:191], v[98:101]
	v_mfma_f32_16x16x32_bf16 v[70:73], v[138:141], v[200:203], v[70:73]
	v_mfma_f32_16x16x32_bf16 v[66:69], v[154:157], v[200:203], v[66:69]
	v_mfma_f32_16x16x32_bf16 v[134:137], v[150:153], v[166:169], v[134:137]
	v_mfma_f32_16x16x32_bf16 v[130:133], v[158:161], v[166:169], v[130:133]
	v_mfma_f32_16x16x32_bf16 v[118:121], v[150:153], v[184:187], v[118:121]
	v_mfma_f32_16x16x32_bf16 v[114:117], v[158:161], v[184:187], v[114:117]
	v_mfma_f32_16x16x32_bf16 v[102:105], v[150:153], v[196:199], v[102:105]
	v_mfma_f32_16x16x32_bf16 v[98:101], v[158:161], v[196:199], v[98:101]
	v_mfma_f32_16x16x32_bf16 v[70:73], v[150:153], v[204:207], v[70:73]
	v_mfma_f32_16x16x32_bf16 v[66:69], v[158:161], v[204:207], v[66:69]
	s_setprio 0
	s_barrier
; #define PG8_WAIT_V(n) asm volatile("s_waitcnt vmcnt(" #n ")" ::: "memory")
; #define PG8_BAR __builtin_amdgcn_s_barrier()
; template <class Epi, class Sched, bool ALIGN_EPI = true, bool SP2 = true, bool FULLLINE = false, bool NOSTAGE = false, bool FP8 = false>
; __device__ __forceinline__ void gemm_phase(PG8_LAS unsigned char* lds, const Gemm g, const Sched& S, const Epi& E) {
;     ...
;         static_assert(SP2, "only the SP2 loop is kept");
;         { const int t = 0; if constexpr (Epi::NST == 16) PG8_ITER(PG8_WAIT_V(24)); else if constexpr (Epi::NST == 8) PG8_ITER(PG8_WAIT_V(16)); else PG8_ITER(PG8_WAIT_V(8)); }
;         for (int t = 2; t < nt; t += 2) PG8_ITER(PG8_WAIT_V(8));
;     ...
;         if constexpr (ALIGN_EPI) { if (wr == 0) PG8_BAR; }
	s_mov_b32 m0, s41
	v_lshl_add_u64 v[212:213], v[208:209], 0, s[38:39]
	ds_read_b128 v[162:165], v193 offset:49152
	ds_read_b128 v[166:169], v193 offset:50176
	ds_read_b128 v[180:183], v193 offset:51200
	ds_read_b128 v[184:187], v193 offset:52224
	ds_read_b128 v[188:191], v193 offset:53248
	ds_read_b128 v[196:199], v193 offset:54272
	ds_read_b128 v[200:203], v193 offset:55296
	ds_read_b128 v[204:207], v193 offset:56320
	global_load_lds_dwordx4 v[212:213], off
	v_lshl_add_u64 v[212:213], v[208:209], 0, s[66:67]
	s_mov_b32 m0, s50
	s_nop 0
	global_load_lds_dwordx4 v[212:213], off
	v_lshl_add_u64 v[212:213], v[208:209], 0, s[14:15]
	s_mov_b32 m0, s51
	v_lshl_add_u64 v[208:209], v[208:209], 0, s[16:17]
	global_load_lds_dwordx4 v[212:213], off
	s_mov_b32 m0, s33
	s_nop 0
	global_load_lds_dwordx4 v[208:209], off
	v_lshl_add_u64 v[208:209], v[210:211], 0, s[38:39]
	s_mov_b32 m0, s53
	s_nop 0
	global_load_lds_dwordx4 v[208:209], off
	v_lshl_add_u64 v[208:209], v[210:211], 0, s[66:67]
	s_mov_b32 m0, s54
	s_nop 0
	global_load_lds_dwordx4 v[208:209], off
	s_waitcnt vmcnt(8)
	s_waitcnt lgkmcnt(0)
	s_barrier
	s_waitcnt lgkmcnt(0)
	s_setprio 1
	v_mfma_f32_16x16x32_bf16 v[62:65], v[74:77], v[162:165], v[62:65]
	v_mfma_f32_16x16x32_bf16 v[58:61], v[90:93], v[162:165], v[58:61]
	v_mfma_f32_16x16x32_bf16 v[46:49], v[74:77], v[180:183], v[46:49]
	v_mfma_f32_16x16x32_bf16 v[42:45], v[90:93], v[180:183], v[42:45]
	v_mfma_f32_16x16x32_bf16 v[30:33], v[74:77], v[188:191], v[30:33]
	v_mfma_f32_16x16x32_bf16 v[26:29], v[90:93], v[188:191], v[26:29]
	v_mfma_f32_16x16x32_bf16 v[14:17], v[74:77], v[200:203], v[14:17]
	v_mfma_f32_16x16x32_bf16 v[10:13], v[90:93], v[200:203], v[10:13]
	v_mfma_f32_16x16x32_bf16 v[62:65], v[82:85], v[166:169], v[62:65]
	v_mfma_f32_16x16x32_bf16 v[58:61], v[94:97], v[166:169], v[58:61]
	v_mfma_f32_16x16x32_bf16 v[46:49], v[82:85], v[184:187], v[46:49]
	v_mfma_f32_16x16x32_bf16 v[42:45], v[94:97], v[184:187], v[42:45]
	v_mfma_f32_16x16x32_bf16 v[30:33], v[82:85], v[196:199], v[30:33]
	v_mfma_f32_16x16x32_bf16 v[26:29], v[94:97], v[196:199], v[26:29]
	v_mfma_f32_16x16x32_bf16 v[14:17], v[82:85], v[204:207], v[14:17]
	v_mfma_f32_16x16x32_bf16 v[10:13], v[94:97], v[204:207], v[10:13]
	v_mfma_f32_16x16x32_bf16 v[54:57], v[138:141], v[162:165], v[54:57]
	v_mfma_f32_16x16x32_bf16 v[50:53], v[154:157], v[162:165], v[50:53]
	v_mfma_f32_16x16x32_bf16 v[38:41], v[138:141], v[180:183], v[38:41]
	v_mfma_f32_16x16x32_bf16 v[34:37], v[154:157], v[180:183], v[34:37]
	v_mfma_f32_16x16x32_bf16 v[22:25], v[138:141], v[188:191], v[22:25]
	v_mfma_f32_16x16x32_bf16 v[18:21], v[154:157], v[188:191], v[18:21]
	v_mfma_f32_16x16x32_bf16 v[6:9], v[138:141], v[200:203], v[6:9]
	v_mfma_f32_16x16x32_bf16 v[2:5], v[154:157], v[200:203], v[2:5]
	v_mfma_f32_16x16x32_bf16 v[54:57], v[150:153], v[166:169], v[54:57]
	v_mfma_f32_16x16x32_bf16 v[50:53], v[158:161], v[166:169], v[50:53]
	v_mfma_f32_16x16x32_bf16 v[38:41], v[150:153], v[184:187], v[38:41]
	v_mfma_f32_16x16x32_bf16 v[34:37], v[158:161], v[184:187], v[34:37]
	v_mfma_f32_16x16x32_bf16 v[22:25], v[150:153], v[196:199], v[22:25]
	v_mfma_f32_16x16x32_bf16 v[18:21], v[158:161], v[196:199], v[18:21]
	v_mfma_f32_16x16x32_bf16 v[6:9], v[150:153], v[204:207], v[6:9]
	v_mfma_f32_16x16x32_bf16 v[2:5], v[158:161], v[204:207], v[2:5]
	s_setprio 0
	s_barrier
	s_add_i32 s72, s72, 2
	s_add_u32 s70, s70, 0x100
	s_addc_u32 s71, s71, 0
	s_add_u32 s56, s56, 0x100
	s_addc_u32 s57, s57, 0
	s_cmpk_gt_u32 s72, 0x55
	s_cbranch_scc0 .LBB0_870
	s_and_b64 vcc, exec, s[12:13]
	s_cbranch_vccz .LBB0_873
	s_barrier

; #define PG8_STAGE(bufoff, gbase, voff) do { if constexpr (!NOSTAGE) _Pragma("unroll") for (int _i = 0; _i < 2; ++_i) \
;         __builtin_amdgcn_global_load_lds((const unsigned*)((const char*)(gbase) + (size_t)_i * pstep##voff + v##voff), (PG8_LAS unsigned*)(lds + (bufoff) + ldsw + _i * 8192), 16, 0, 0); } while (0)
; #define PG8_WAIT_V(n) asm volatile("s_waitcnt vmcnt(" #n ")" ::: "memory")
; #define PG8_BAR __builtin_amdgcn_s_barrier()
; template <class Epi, class Sched, bool ALIGN_EPI = true, bool SP2 = true, bool FULLLINE = false, bool NOSTAGE = false, bool FP8 = false>
; __device__ __forceinline__ void gemm_phase(PG8_LAS unsigned char* lds, const Gemm g, const Sched& S, const Epi& E) {
;     ...
;     const int aoff = lds_byte(wr * 64 + fr, fq * 8), boff = lds_byte(wc * 32 + fr, fq * 8);
;     ...
;     PG8_STAGE(PG8_SB(0, 0), cB, offB); PG8_STAGE(PG8_SB(0, 1), cB + hstepB, offB); PG8_STAGE(PG8_SA(0, 0), cA, offA); PG8_STAGE(PG8_SA(0, 1), cA + hstepA, offA);
;     PG8_STAGE(PG8_SB(1, 0), cB + kstep, offB); PG8_STAGE(PG8_SA(1, 0), cA + kstep, offA); PG8_STAGE(PG8_SB(1, 1), cB + hstepB + kstep, offB);
;     if (wr == 1) PG8_BAR;
;     PG8_WAIT_V(0); PG8_BAR;
;     PG8_BAR;
;     } else {
;     PG8_STAGE(PG8_SB(0, 0), cB, offB); PG8_STAGE(PG8_SA(0, 0), cA, offA); PG8_STAGE(PG8_SB(0, 1), cB + hstepB, offB); PG8_STAGE(PG8_SA(0, 1), cA + hstepA, offA);
;     if (wr == 1) PG8_BAR;
;     PG8_WAIT_V(4); PG8_BAR;
;     PG8_STAGE(PG8_SB(1, 0), cB + kstep, offB); PG8_STAGE(PG8_SA(1, 0), cA + kstep, offA); PG8_STAGE(PG8_SB(1, 1), cB + hstepB + kstep, offB);
;     PG8_WAIT_V(6); PG8_BAR;
;     }
;     if (wr == 1) __builtin_amdgcn_s_setprio(1);
;     for (;;) {
;         const bool has_next = S.next(ui + 1, nxt);
;         const char* nA = has_next ? PG8_ABASE(nxt) : cA; const char* nB = has_next ? PG8_BBASE(nxt) : cB;
.LBB0_1017:
	s_waitcnt vmcnt(0)
	v_cndmask_b32_e64 v4, 0, 1, s[10:11]
	v_cmp_ne_u32_e64 s[6:7], 1, v4
	s_andn2_b64 vcc, exec, s[10:11]
	s_barrier
	s_barrier
	s_cbranch_vccnz .LBB0_1019
.LBB0_1019:
	s_add_u32 s10, s48, 0x21f00000
	s_addc_u32 s11, s49, 0
	v_and_b32_e32 v4, 48, v0
	v_lshlrev_b32_e32 v5, 6, v0
	s_movk_i32 s1, 0x3c0
	s_add_u32 s12, s48, 0x25f00000
	v_and_or_b32 v4, v5, s1, v4
	v_lshlrev_b32_e32 v5, 2, v0
	s_addc_u32 s13, s49, 0
	s_lshl_b32 s0, s15, 13
	v_and_b32_e32 v5, 32, v5
	v_bitop3_b32 v6, v4, s0, v5 bitop3:0xde
	s_lshl_b32 s0, s14, 5
	s_and_b32 s62, s0, 0x60
	s_lshl_b32 s0, s62, 7
	s_lshl_b32 s55, s15, 6
	v_bitop3_b32 v4, s0, v4, v5 bitop3:0xf6
	v_lshlrev_b32_e32 v5, 9, v0
	s_cmpk_lt_u32 s9, 0x100
	v_and_b32_e32 v5, 0x30000, v5
	v_lshlrev_b32_e32 v3, 12, v3
	s_cselect_b64 s[14:15], -1, 0
	v_or3_b32 v1, v1, v5, v3
	s_add_i32 s84, 0, 0x10000
	s_add_i32 s85, 0, 0x14000
	s_add_i32 s89, 0, 0x18000
	s_add_i32 s90, 0, 0x1c000
	s_sext_i32_i16 s95, s8
	s_ashr_i32 s63, s86, 31
	v_add_u32_e32 v134, v1, v2
	v_mov_b32_e32 v135, 0
	s_mov_b32 s17, 0
	v_mov_b64_e32 v[136:137], 0x600
	v_mov_b64_e32 v[138:139], 0x5ff
	v_add_u32_e32 v1, s84, v4
	v_add_u32_e32 v152, s85, v4
	v_add_u32_e32 v153, 0, v6
	s_mov_b64 s[18:19], 0x80080
	s_add_i32 s87, s45, 0xc000
	s_mov_b64 s[20:21], 0xc0080
	s_add_i32 s88, s45, 0xe000
	s_mov_b64 s[22:23], 0x100
	s_mov_b64 s[24:25], 0x40100
	s_waitcnt lgkmcnt(0)
	s_mov_b64 s[26:27], 0x80100
	s_mov_b64 s[28:29], 0xc0100
	v_add_u32_e32 v154, s89, v4
	v_add_u32_e32 v155, s90, v4
	s_mov_b64 s[30:31], 0x180
	s_mov_b64 s[34:35], 0x40180
	s_mov_b64 s[36:37], 0x40000
	s_mov_b64 s[38:39], 0x80000
	s_mov_b64 s[66:67], 0xc0000
	s_mov_b64 s[68:69], 0x80
	s_mov_b64 s[70:71], 0x40080
	s_mov_b32 s91, 0x80000
	s_mov_b32 s92, 0x90000
	s_mov_b32 s93, 0xa0000
	s_mov_b32 s94, 0
	s_branch .LBB0_1022

; template <class Epi, class Sched, bool ALIGN_EPI = true, bool SP2 = true, bool FULLLINE = false, bool NOSTAGE = false, bool FP8 = false>
; __device__ __forceinline__ void gemm_phase(PG8_LAS unsigned char* lds, const Gemm g, const Sched& S, const Epi& E) {
;     ...
;         const bool has_next = S.next(ui + 1, nxt);
;         const char* nA = has_next ? PG8_ABASE(nxt) : cA; const char* nB = has_next ? PG8_BBASE(nxt) : cB;
.LBB0_1024:
	s_ashr_i32 s75, s74, 31
	s_lshl_b64 s[40:41], s[74:75], 20
	s_add_u32 s76, s58, s40
	ds_read_b128 v[2:5], v1
	ds_read_b128 v[6:9], v1 offset:1024
	ds_read_b128 v[10:13], v1 offset:2048
	ds_read_b128 v[14:17], v1 offset:3072
	ds_read_b128 v[18:21], v152
	ds_read_b128 v[22:25], v152 offset:1024
	ds_read_b128 v[26:29], v152 offset:2048
	ds_read_b128 v[30:33], v152 offset:3072
	s_addc_u32 s77, s59, s41
	s_ashr_i32 s73, s72, 31
	s_lshl_b64 s[40:41], s[72:73], 20
	s_add_u32 s78, s3, s40
	s_addc_u32 s79, s42, s41
	s_and_b64 s[40:41], s[8:9], exec
	s_cselect_b32 s73, s77, s83
	s_cselect_b32 s75, s76, s82
	s_cselect_b32 s96, s79, s81
	s_cselect_b32 s97, s78, s80
	v_lshl_add_u64 v[244:245], s[82:83], 0, v[132:133]
	s_mov_b32 m0, s87
	v_lshl_add_u64 v[66:67], v[244:245], 0, s[18:19]
	ds_read_b128 v[34:37], v153
	ds_read_b128 v[38:41], v153 offset:1024
	ds_read_b128 v[42:45], v153 offset:2048
	ds_read_b128 v[46:49], v153 offset:3072
	ds_read_b128 v[50:53], v153 offset:4096
	ds_read_b128 v[54:57], v153 offset:5120
	ds_read_b128 v[58:61], v153 offset:6144
	ds_read_b128 v[62:65], v153 offset:7168
	global_load_lds_dwordx4 v[66:67], off
	v_lshl_add_u64 v[66:67], v[244:245], 0, s[20:21]
	s_mov_b32 m0, s88
	s_nop 0
	global_load_lds_dwordx4 v[66:67], off
	s_waitcnt vmcnt(16)
	s_waitcnt lgkmcnt(0)
	s_barrier
	s_waitcnt lgkmcnt(0)
	s_setprio 1
	v_mfma_f32_16x16x32_bf16 v[90:93], v[2:5], v[58:61], 0
	v_mfma_f32_16x16x32_bf16 v[66:69], v[2:5], v[34:37], 0
	v_mfma_f32_16x16x32_bf16 v[70:73], v[10:13], v[34:37], 0
	v_mfma_f32_16x16x32_bf16 v[74:77], v[2:5], v[42:45], 0
	v_mfma_f32_16x16x32_bf16 v[78:81], v[10:13], v[42:45], 0
	v_mfma_f32_16x16x32_bf16 v[82:85], v[2:5], v[50:53], 0
	v_mfma_f32_16x16x32_bf16 v[86:89], v[10:13], v[50:53], 0
	v_mfma_f32_16x16x32_bf16 v[94:97], v[6:9], v[62:65], v[90:93]
	v_mfma_f32_16x16x32_bf16 v[90:93], v[10:13], v[58:61], 0
	v_mfma_f32_16x16x32_bf16 v[66:69], v[6:9], v[38:41], v[66:69]
	v_mfma_f32_16x16x32_bf16 v[70:73], v[14:17], v[38:41], v[70:73]
	v_mfma_f32_16x16x32_bf16 v[74:77], v[6:9], v[46:49], v[74:77]
	v_mfma_f32_16x16x32_bf16 v[78:81], v[14:17], v[46:49], v[78:81]
	v_mfma_f32_16x16x32_bf16 v[82:85], v[6:9], v[54:57], v[82:85]
	v_mfma_f32_16x16x32_bf16 v[86:89], v[14:17], v[54:57], v[86:89]
	v_mfma_f32_16x16x32_bf16 v[102:105], v[14:17], v[62:65], v[90:93]
	v_mfma_f32_16x16x32_bf16 v[90:93], v[18:21], v[34:37], 0
	v_mfma_f32_16x16x32_bf16 v[34:37], v[26:29], v[34:37], 0
	v_mfma_f32_16x16x32_bf16 v[110:113], v[22:25], v[38:41], v[90:93]
	v_mfma_f32_16x16x32_bf16 v[34:37], v[30:33], v[38:41], v[34:37]
	v_mfma_f32_16x16x32_bf16 v[38:41], v[18:21], v[42:45], 0
	v_mfma_f32_16x16x32_bf16 v[42:45], v[26:29], v[42:45], 0
	v_mfma_f32_16x16x32_bf16 v[38:41], v[22:25], v[46:49], v[38:41]
	v_mfma_f32_16x16x32_bf16 v[42:45], v[30:33], v[46:49], v[42:45]
	v_mfma_f32_16x16x32_bf16 v[46:49], v[18:21], v[50:53], 0
	v_mfma_f32_16x16x32_bf16 v[50:53], v[26:29], v[50:53], 0
	v_mfma_f32_16x16x32_bf16 v[46:49], v[22:25], v[54:57], v[46:49]
	v_mfma_f32_16x16x32_bf16 v[54:57], v[30:33], v[54:57], v[50:53]
	v_mfma_f32_16x16x32_bf16 v[50:53], v[18:21], v[58:61], 0
	v_mfma_f32_16x16x32_bf16 v[140:143], v[22:25], v[62:65], v[50:53]
	v_mfma_f32_16x16x32_bf16 v[50:53], v[26:29], v[58:61], 0
	v_mfma_f32_16x16x32_bf16 v[144:147], v[30:33], v[62:65], v[50:53]
	s_setprio 0
	s_barrier
	v_lshl_add_u64 v[246:247], s[80:81], 0, v[130:131]
	s_add_i32 vcc_lo, s84, s43
	v_lshl_add_u64 v[122:123], v[246:247], 0, s[22:23]
	s_mov_b32 m0, vcc_lo
	s_add_i32 vcc_hi, vcc_lo, 0x2000
	s_nop 0
	ds_read_b128 v[50:53], v153 offset:16384
	ds_read_b128 v[58:61], v153 offset:17408
	ds_read_b128 v[62:65], v153 offset:18432
	ds_read_b128 v[90:93], v153 offset:19456
	ds_read_b128 v[98:101], v153 offset:20480
	ds_read_b128 v[106:109], v153 offset:21504
	ds_read_b128 v[114:117], v153 offset:22528
	ds_read_b128 v[118:121], v153 offset:23552
	global_load_lds_dwordx4 v[122:123], off
	v_lshl_add_u64 v[122:123], v[246:247], 0, s[24:25]
	s_mov_b32 m0, vcc_hi
	s_add_i32 s40, s85, s43
	global_load_lds_dwordx4 v[122:123], off
	v_lshl_add_u64 v[122:123], v[246:247], 0, s[26:27]
	s_mov_b32 m0, s40
	s_add_i32 s41, s40, 0x2000
	global_load_lds_dwordx4 v[122:123], off
	v_lshl_add_u64 v[122:123], v[246:247], 0, s[28:29]
	s_mov_b32 m0, s41
	s_nop 0
	global_load_lds_dwordx4 v[122:123], off
	v_lshl_add_u64 v[122:123], v[244:245], 0, s[22:23]
	s_mov_b32 m0, s45
	s_nop 0
	global_load_lds_dwordx4 v[122:123], off
	v_lshl_add_u64 v[122:123], v[244:245], 0, s[24:25]
	s_mov_b32 m0, s46
	s_nop 0
	global_load_lds_dwordx4 v[122:123], off
	s_waitcnt vmcnt(16)
	s_waitcnt lgkmcnt(0)
	s_barrier
	s_waitcnt lgkmcnt(0)
	s_setprio 1
	v_mfma_f32_16x16x32_bf16 v[122:125], v[2:5], v[50:53], 0
	v_mfma_f32_16x16x32_bf16 v[148:151], v[6:9], v[58:61], v[122:125]
	v_mfma_f32_16x16x32_bf16 v[122:125], v[10:13], v[50:53], 0
	v_mfma_f32_16x16x32_bf16 v[156:159], v[14:17], v[58:61], v[122:125]
	v_mfma_f32_16x16x32_bf16 v[122:125], v[2:5], v[62:65], 0
	v_mfma_f32_16x16x32_bf16 v[160:163], v[6:9], v[90:93], v[122:125]
	v_mfma_f32_16x16x32_bf16 v[122:125], v[10:13], v[62:65], 0
	v_mfma_f32_16x16x32_bf16 v[164:167], v[14:17], v[90:93], v[122:125]
	v_mfma_f32_16x16x32_bf16 v[122:125], v[2:5], v[98:101], 0
	v_mfma_f32_16x16x32_bf16 v[2:5], v[2:5], v[114:117], 0
	v_mfma_f32_16x16x32_bf16 v[168:171], v[6:9], v[106:109], v[122:125]
	v_mfma_f32_16x16x32_bf16 v[2:5], v[6:9], v[118:121], v[2:5]
	v_mfma_f32_16x16x32_bf16 v[6:9], v[10:13], v[114:117], 0
	v_mfma_f32_16x16x32_bf16 v[122:125], v[10:13], v[98:101], 0
	v_mfma_f32_16x16x32_bf16 v[6:9], v[14:17], v[118:121], v[6:9]
	v_mfma_f32_16x16x32_bf16 v[172:175], v[14:17], v[106:109], v[122:125]
	v_mfma_f32_16x16x32_bf16 v[10:13], v[18:21], v[50:53], 0
	v_mfma_f32_16x16x32_bf16 v[176:179], v[22:25], v[58:61], v[10:13]
	v_mfma_f32_16x16x32_bf16 v[10:13], v[26:29], v[50:53], 0
	v_mfma_f32_16x16x32_bf16 v[180:183], v[30:33], v[58:61], v[10:13]
	v_mfma_f32_16x16x32_bf16 v[10:13], v[18:21], v[62:65], 0
	v_mfma_f32_16x16x32_bf16 v[184:187], v[22:25], v[90:93], v[10:13]
	v_mfma_f32_16x16x32_bf16 v[10:13], v[26:29], v[62:65], 0
	v_mfma_f32_16x16x32_bf16 v[188:191], v[30:33], v[90:93], v[10:13]
	v_mfma_f32_16x16x32_bf16 v[10:13], v[18:21], v[98:101], 0
	v_mfma_f32_16x16x32_bf16 v[192:195], v[22:25], v[106:109], v[10:13]
	v_mfma_f32_16x16x32_bf16 v[10:13], v[26:29], v[98:101], 0
	v_mfma_f32_16x16x32_bf16 v[196:199], v[30:33], v[106:109], v[10:13]
	v_mfma_f32_16x16x32_bf16 v[10:13], v[18:21], v[114:117], 0
	v_mfma_f32_16x16x32_bf16 v[200:203], v[22:25], v[118:121], v[10:13]
	v_mfma_f32_16x16x32_bf16 v[10:13], v[26:29], v[114:117], 0
	v_mfma_f32_16x16x32_bf16 v[204:207], v[30:33], v[118:121], v[10:13]
	s_setprio 0
	s_barrier
	s_nop 5
	ds_read_b128 v[10:13], v154
	ds_read_b128 v[14:17], v154 offset:1024
	ds_read_b128 v[18:21], v154 offset:2048
	ds_read_b128 v[26:29], v154 offset:3072
	ds_read_b128 v[208:211], v155
	ds_read_b128 v[212:215], v155 offset:1024
	ds_read_b128 v[216:219], v155 offset:2048
	ds_read_b128 v[220:223], v155 offset:3072
	s_mov_b32 m0, s47
	v_lshl_add_u64 v[50:51], v[244:245], 0, s[26:27]
	ds_read_b128 v[22:25], v153 offset:32768
	ds_read_b128 v[30:33], v153 offset:33792
	ds_read_b128 v[62:65], v153 offset:34816
	ds_read_b128 v[224:227], v153 offset:35840
	ds_read_b128 v[228:231], v153 offset:36864
	ds_read_b128 v[232:235], v153 offset:37888
	ds_read_b128 v[236:239], v153 offset:38912
	ds_read_b128 v[240:243], v153 offset:39936
	global_load_lds_dwordx4 v[50:51], off
	v_lshl_add_u64 v[50:51], v[244:245], 0, s[28:29]
	s_mov_b32 m0, s52
	s_nop 0
	global_load_lds_dwordx4 v[50:51], off
	s_waitcnt vmcnt(8)
	s_waitcnt lgkmcnt(0)
	s_barrier
	s_waitcnt lgkmcnt(0)
	s_setprio 1
	v_mfma_f32_16x16x32_bf16 v[50:53], v[10:13], v[22:25], v[66:69]
	v_mfma_f32_16x16x32_bf16 v[122:125], v[14:17], v[30:33], v[50:53]
	v_mfma_f32_16x16x32_bf16 v[50:53], v[18:21], v[22:25], v[70:73]
	v_mfma_f32_16x16x32_bf16 v[114:117], v[26:29], v[30:33], v[50:53]
	v_mfma_f32_16x16x32_bf16 v[50:53], v[10:13], v[62:65], v[74:77]
	v_mfma_f32_16x16x32_bf16 v[106:109], v[14:17], v[224:227], v[50:53]
	v_mfma_f32_16x16x32_bf16 v[50:53], v[18:21], v[62:65], v[78:81]
	v_mfma_f32_16x16x32_bf16 v[98:101], v[26:29], v[224:227], v[50:53]
	v_mfma_f32_16x16x32_bf16 v[50:53], v[10:13], v[228:231], v[82:85]
	v_mfma_f32_16x16x32_bf16 v[90:93], v[14:17], v[232:235], v[50:53]
	v_mfma_f32_16x16x32_bf16 v[50:53], v[18:21], v[228:231], v[86:89]
	v_mfma_f32_16x16x32_bf16 v[82:85], v[26:29], v[232:235], v[50:53]
	v_mfma_f32_16x16x32_bf16 v[50:53], v[10:13], v[236:239], v[94:97]
	v_mfma_f32_16x16x32_bf16 v[58:61], v[14:17], v[240:243], v[50:53]
	v_mfma_f32_16x16x32_bf16 v[50:53], v[18:21], v[236:239], v[102:105]
	v_mfma_f32_16x16x32_bf16 v[50:53], v[26:29], v[240:243], v[50:53]
	v_mfma_f32_16x16x32_bf16 v[66:69], v[208:211], v[22:25], v[110:113]
	v_mfma_f32_16x16x32_bf16 v[22:25], v[216:219], v[22:25], v[34:37]
	v_mfma_f32_16x16x32_bf16 v[118:121], v[220:223], v[30:33], v[22:25]
	v_mfma_f32_16x16x32_bf16 v[22:25], v[208:211], v[62:65], v[38:41]
	v_mfma_f32_16x16x32_bf16 v[110:113], v[212:215], v[224:227], v[22:25]
	v_mfma_f32_16x16x32_bf16 v[22:25], v[216:219], v[62:65], v[42:45]
	v_mfma_f32_16x16x32_bf16 v[102:105], v[220:223], v[224:227], v[22:25]
	v_mfma_f32_16x16x32_bf16 v[22:25], v[208:211], v[228:231], v[46:49]
	v_mfma_f32_16x16x32_bf16 v[94:97], v[212:215], v[232:235], v[22:25]
	v_mfma_f32_16x16x32_bf16 v[22:25], v[216:219], v[228:231], v[54:57]
	v_mfma_f32_16x16x32_bf16 v[86:89], v[220:223], v[232:235], v[22:25]
	v_mfma_f32_16x16x32_bf16 v[22:25], v[208:211], v[236:239], v[140:143]
	v_mfma_f32_16x16x32_bf16 v[62:65], v[212:215], v[240:243], v[22:25]
	v_mfma_f32_16x16x32_bf16 v[22:25], v[216:219], v[236:239], v[144:147]
	v_mfma_f32_16x16x32_bf16 v[126:129], v[212:215], v[30:33], v[66:69]
	v_mfma_f32_16x16x32_bf16 v[54:57], v[220:223], v[240:243], v[22:25]
	s_setprio 0
	s_barrier
	s_add_i32 s50, s89, s43
	s_nop 3
	v_lshl_add_u64 v[22:23], v[246:247], 0, s[30:31]
	s_mov_b32 m0, s50
	s_add_i32 s51, s50, 0x2000
	ds_read_b128 v[34:37], v153 offset:49152
	ds_read_b128 v[42:45], v153 offset:50176
	ds_read_b128 v[140:143], v153 offset:51200
	ds_read_b128 v[144:147], v153 offset:52224
	ds_read_b128 v[224:227], v153 offset:53248
	ds_read_b128 v[228:231], v153 offset:54272
	ds_read_b128 v[232:235], v153 offset:55296
	ds_read_b128 v[236:239], v153 offset:56320
	global_load_lds_dwordx4 v[22:23], off
	v_lshl_add_u64 v[22:23], v[246:247], 0, s[34:35]
	s_mov_b32 m0, s51
	s_mov_b64 s[56:57], 0x80180
	s_add_i32 s33, s90, s43
	global_load_lds_dwordx4 v[22:23], off
	v_lshl_add_u64 v[22:23], v[246:247], 0, s[56:57]
	s_mov_b32 m0, s33
	s_mov_b64 s[56:57], 0xc0180
	global_load_lds_dwordx4 v[22:23], off
	v_lshl_add_u64 v[22:23], v[246:247], 0, s[56:57]
	s_add_i32 s56, s33, 0x2000
	s_mov_b32 m0, s56
	s_nop 0
	global_load_lds_dwordx4 v[22:23], off
	v_lshl_add_u64 v[22:23], v[244:245], 0, s[30:31]
	s_mov_b32 m0, s53
	s_nop 0
	global_load_lds_dwordx4 v[22:23], off
	v_lshl_add_u64 v[22:23], v[244:245], 0, s[34:35]
	s_mov_b32 m0, s54
	s_nop 0
	global_load_lds_dwordx4 v[22:23], off
	s_waitcnt vmcnt(8)
	s_waitcnt lgkmcnt(0)
	s_barrier
	s_waitcnt lgkmcnt(0)
	s_setprio 1
	v_mfma_f32_16x16x32_bf16 v[22:25], v[10:13], v[34:37], v[148:151]
	v_mfma_f32_16x16x32_bf16 v[78:81], v[14:17], v[42:45], v[22:25]
	v_mfma_f32_16x16x32_bf16 v[22:25], v[18:21], v[34:37], v[156:159]
	v_mfma_f32_16x16x32_bf16 v[70:73], v[26:29], v[42:45], v[22:25]
	v_mfma_f32_16x16x32_bf16 v[22:25], v[10:13], v[140:143], v[160:163]
	v_mfma_f32_16x16x32_bf16 v[46:49], v[14:17], v[144:147], v[22:25]
	v_mfma_f32_16x16x32_bf16 v[22:25], v[18:21], v[140:143], v[164:167]
	v_mfma_f32_16x16x32_bf16 v[38:41], v[26:29], v[144:147], v[22:25]
	v_mfma_f32_16x16x32_bf16 v[22:25], v[10:13], v[224:227], v[168:171]
	v_mfma_f32_16x16x32_bf16 v[2:5], v[10:13], v[232:235], v[2:5]
	v_mfma_f32_16x16x32_bf16 v[30:33], v[14:17], v[228:231], v[22:25]
	v_mfma_f32_16x16x32_bf16 v[22:25], v[18:21], v[224:227], v[172:175]
	v_mfma_f32_16x16x32_bf16 v[14:17], v[14:17], v[236:239], v[2:5]
	v_mfma_f32_16x16x32_bf16 v[2:5], v[18:21], v[232:235], v[6:9]
	v_mfma_f32_16x16x32_bf16 v[22:25], v[26:29], v[228:231], v[22:25]
	v_mfma_f32_16x16x32_bf16 v[10:13], v[26:29], v[236:239], v[2:5]
	v_mfma_f32_16x16x32_bf16 v[2:5], v[208:211], v[34:37], v[176:179]
	v_mfma_f32_16x16x32_bf16 v[74:77], v[212:215], v[42:45], v[2:5]
	v_mfma_f32_16x16x32_bf16 v[2:5], v[216:219], v[34:37], v[180:183]
	v_mfma_f32_16x16x32_bf16 v[66:69], v[220:223], v[42:45], v[2:5]
	v_mfma_f32_16x16x32_bf16 v[2:5], v[208:211], v[140:143], v[184:187]
	v_mfma_f32_16x16x32_bf16 v[42:45], v[212:215], v[144:147], v[2:5]
	v_mfma_f32_16x16x32_bf16 v[2:5], v[216:219], v[140:143], v[188:191]
	v_mfma_f32_16x16x32_bf16 v[34:37], v[220:223], v[144:147], v[2:5]
	v_mfma_f32_16x16x32_bf16 v[2:5], v[208:211], v[224:227], v[192:195]
	v_mfma_f32_16x16x32_bf16 v[26:29], v[212:215], v[228:231], v[2:5]
	v_mfma_f32_16x16x32_bf16 v[2:5], v[216:219], v[224:227], v[196:199]
	v_mfma_f32_16x16x32_bf16 v[18:21], v[220:223], v[228:231], v[2:5]
	v_mfma_f32_16x16x32_bf16 v[2:5], v[208:211], v[232:235], v[200:203]
	v_mfma_f32_16x16x32_bf16 v[6:9], v[212:215], v[236:239], v[2:5]
	v_mfma_f32_16x16x32_bf16 v[2:5], v[216:219], v[232:235], v[204:207]
	v_mfma_f32_16x16x32_bf16 v[2:5], v[220:223], v[236:239], v[2:5]
	s_setprio 0
	s_barrier
	s_add_u32 s82, s82, 0x80180
	s_addc_u32 s83, s83, 0
	s_add_u32 s57, s80, 0x200
	s_addc_u32 s80, s81, 0
	s_mov_b32 s81, 0
.LBB0_1025:
	ds_read_b128 v[140:143], v1
	ds_read_b128 v[144:147], v1 offset:1024
	ds_read_b128 v[148:151], v1 offset:2048
	ds_read_b128 v[156:159], v1 offset:3072
	ds_read_b128 v[160:163], v152
	ds_read_b128 v[164:167], v152 offset:1024
	ds_read_b128 v[168:171], v152 offset:2048
	ds_read_b128 v[172:175], v152 offset:3072
	s_add_u32 s0, s82, 0xfff80080
	s_addc_u32 s1, s83, -1
	s_cmp_eq_u32 s81, 28
	s_cselect_b32 s1, s73, s1
	s_cselect_b32 s0, s75, s0
	s_cselect_b32 s65, s96, s80
	s_cselect_b32 s64, s97, s57
	s_mov_b32 m0, s87
	v_lshl_add_u64 v[208:209], s[82:83], 0, v[134:135]
	ds_read_b128 v[176:179], v153
	ds_read_b128 v[180:183], v153 offset:1024
	ds_read_b128 v[184:187], v153 offset:2048
	ds_read_b128 v[188:191], v153 offset:3072
	ds_read_b128 v[192:195], v153 offset:4096
	ds_read_b128 v[196:199], v153 offset:5120
	ds_read_b128 v[200:203], v153 offset:6144
	ds_read_b128 v[204:207], v153 offset:7168
	global_load_lds_dwordx4 v[208:209], off
	v_lshl_add_u64 v[208:209], v[208:209], 0, s[36:37]
	s_mov_b32 m0, s88
	s_nop 0
	global_load_lds_dwordx4 v[208:209], off
	s_waitcnt vmcnt(8)
	s_waitcnt lgkmcnt(0)
	s_barrier
	s_waitcnt lgkmcnt(0)
	s_setprio 1
	v_mfma_f32_16x16x32_bf16 v[122:125], v[140:143], v[176:179], v[122:125]
	v_mfma_f32_16x16x32_bf16 v[114:117], v[148:151], v[176:179], v[114:117]
	v_mfma_f32_16x16x32_bf16 v[106:109], v[140:143], v[184:187], v[106:109]
	v_mfma_f32_16x16x32_bf16 v[98:101], v[148:151], v[184:187], v[98:101]
	v_mfma_f32_16x16x32_bf16 v[90:93], v[140:143], v[192:195], v[90:93]
	v_mfma_f32_16x16x32_bf16 v[82:85], v[148:151], v[192:195], v[82:85]
	v_mfma_f32_16x16x32_bf16 v[58:61], v[140:143], v[200:203], v[58:61]
	v_mfma_f32_16x16x32_bf16 v[50:53], v[148:151], v[200:203], v[50:53]
	v_mfma_f32_16x16x32_bf16 v[122:125], v[144:147], v[180:183], v[122:125]
	v_mfma_f32_16x16x32_bf16 v[114:117], v[156:159], v[180:183], v[114:117]
	v_mfma_f32_16x16x32_bf16 v[106:109], v[144:147], v[188:191], v[106:109]
	v_mfma_f32_16x16x32_bf16 v[98:101], v[156:159], v[188:191], v[98:101]
	v_mfma_f32_16x16x32_bf16 v[90:93], v[144:147], v[196:199], v[90:93]
	v_mfma_f32_16x16x32_bf16 v[82:85], v[156:159], v[196:199], v[82:85]
	v_mfma_f32_16x16x32_bf16 v[58:61], v[144:147], v[204:207], v[58:61]
	v_mfma_f32_16x16x32_bf16 v[50:53], v[156:159], v[204:207], v[50:53]
	v_mfma_f32_16x16x32_bf16 v[126:129], v[160:163], v[176:179], v[126:129]
	v_mfma_f32_16x16x32_bf16 v[118:121], v[168:171], v[176:179], v[118:121]
	v_mfma_f32_16x16x32_bf16 v[110:113], v[160:163], v[184:187], v[110:113]
	v_mfma_f32_16x16x32_bf16 v[102:105], v[168:171], v[184:187], v[102:105]
	v_mfma_f32_16x16x32_bf16 v[94:97], v[160:163], v[192:195], v[94:97]
	v_mfma_f32_16x16x32_bf16 v[86:89], v[168:171], v[192:195], v[86:89]
	v_mfma_f32_16x16x32_bf16 v[62:65], v[160:163], v[200:203], v[62:65]
	v_mfma_f32_16x16x32_bf16 v[54:57], v[168:171], v[200:203], v[54:57]
	v_mfma_f32_16x16x32_bf16 v[126:129], v[164:167], v[180:183], v[126:129]
	v_mfma_f32_16x16x32_bf16 v[118:121], v[172:175], v[180:183], v[118:121]
	v_mfma_f32_16x16x32_bf16 v[110:113], v[164:167], v[188:191], v[110:113]
	v_mfma_f32_16x16x32_bf16 v[102:105], v[172:175], v[188:191], v[102:105]
	v_mfma_f32_16x16x32_bf16 v[94:97], v[164:167], v[196:199], v[94:97]
	v_mfma_f32_16x16x32_bf16 v[86:89], v[172:175], v[196:199], v[86:89]
	v_mfma_f32_16x16x32_bf16 v[62:65], v[164:167], v[204:207], v[62:65]
	v_mfma_f32_16x16x32_bf16 v[54:57], v[172:175], v[204:207], v[54:57]
	s_setprio 0
	s_barrier
	s_mov_b32 m0, vcc_lo
	v_lshl_add_u64 v[208:209], s[64:65], 0, v[130:131]
	ds_read_b128 v[176:179], v153 offset:16384
	ds_read_b128 v[180:183], v153 offset:17408
	ds_read_b128 v[184:187], v153 offset:18432
	ds_read_b128 v[188:191], v153 offset:19456
	ds_read_b128 v[192:195], v153 offset:20480
	ds_read_b128 v[196:199], v153 offset:21504
	ds_read_b128 v[200:203], v153 offset:22528
	ds_read_b128 v[204:207], v153 offset:23552
	global_load_lds_dwordx4 v[208:209], off
	v_lshl_add_u64 v[210:211], v[208:209], 0, s[36:37]
	s_mov_b32 m0, vcc_hi
	s_nop 0
	global_load_lds_dwordx4 v[210:211], off
	v_lshl_add_u64 v[210:211], v[208:209], 0, s[38:39]
	s_mov_b32 m0, s40
	s_nop 0
	global_load_lds_dwordx4 v[210:211], off
	v_lshl_add_u64 v[210:211], v[208:209], 0, s[66:67]
	s_mov_b32 m0, s41
	s_nop 0
	global_load_lds_dwordx4 v[210:211], off
	v_lshl_add_u64 v[210:211], s[0:1], 0, v[132:133]
	s_mov_b32 m0, s45
	v_lshl_add_u64 v[212:213], v[210:211], 0, s[36:37]
	global_load_lds_dwordx4 v[210:211], off
	s_mov_b32 m0, s46
	s_nop 0
	global_load_lds_dwordx4 v[212:213], off
	s_waitcnt vmcnt(8)
	s_waitcnt lgkmcnt(0)
	s_barrier
	s_waitcnt lgkmcnt(0)
	s_setprio 1
	v_mfma_f32_16x16x32_bf16 v[78:81], v[140:143], v[176:179], v[78:81]
	v_mfma_f32_16x16x32_bf16 v[70:73], v[148:151], v[176:179], v[70:73]
	v_mfma_f32_16x16x32_bf16 v[46:49], v[140:143], v[184:187], v[46:49]
	v_mfma_f32_16x16x32_bf16 v[38:41], v[148:151], v[184:187], v[38:41]
	v_mfma_f32_16x16x32_bf16 v[30:33], v[140:143], v[192:195], v[30:33]
	v_mfma_f32_16x16x32_bf16 v[22:25], v[148:151], v[192:195], v[22:25]
	v_mfma_f32_16x16x32_bf16 v[14:17], v[140:143], v[200:203], v[14:17]
	v_mfma_f32_16x16x32_bf16 v[10:13], v[148:151], v[200:203], v[10:13]
	v_mfma_f32_16x16x32_bf16 v[78:81], v[144:147], v[180:183], v[78:81]
	v_mfma_f32_16x16x32_bf16 v[70:73], v[156:159], v[180:183], v[70:73]
	v_mfma_f32_16x16x32_bf16 v[46:49], v[144:147], v[188:191], v[46:49]
	v_mfma_f32_16x16x32_bf16 v[38:41], v[156:159], v[188:191], v[38:41]
	v_mfma_f32_16x16x32_bf16 v[30:33], v[144:147], v[196:199], v[30:33]
	v_mfma_f32_16x16x32_bf16 v[22:25], v[156:159], v[196:199], v[22:25]
	v_mfma_f32_16x16x32_bf16 v[14:17], v[144:147], v[204:207], v[14:17]
	v_mfma_f32_16x16x32_bf16 v[10:13], v[156:159], v[204:207], v[10:13]
	v_mfma_f32_16x16x32_bf16 v[74:77], v[160:163], v[176:179], v[74:77]
	v_mfma_f32_16x16x32_bf16 v[66:69], v[168:171], v[176:179], v[66:69]
	v_mfma_f32_16x16x32_bf16 v[42:45], v[160:163], v[184:187], v[42:45]
	v_mfma_f32_16x16x32_bf16 v[34:37], v[168:171], v[184:187], v[34:37]
	v_mfma_f32_16x16x32_bf16 v[26:29], v[160:163], v[192:195], v[26:29]
	v_mfma_f32_16x16x32_bf16 v[18:21], v[168:171], v[192:195], v[18:21]
	v_mfma_f32_16x16x32_bf16 v[6:9], v[160:163], v[200:203], v[6:9]
	v_mfma_f32_16x16x32_bf16 v[2:5], v[168:171], v[200:203], v[2:5]
	v_mfma_f32_16x16x32_bf16 v[74:77], v[164:167], v[180:183], v[74:77]
	v_mfma_f32_16x16x32_bf16 v[66:69], v[172:175], v[180:183], v[66:69]
	v_mfma_f32_16x16x32_bf16 v[42:45], v[164:167], v[188:191], v[42:45]
	v_mfma_f32_16x16x32_bf16 v[34:37], v[172:175], v[188:191], v[34:37]
	v_mfma_f32_16x16x32_bf16 v[26:29], v[164:167], v[196:199], v[26:29]
	v_mfma_f32_16x16x32_bf16 v[18:21], v[172:175], v[196:199], v[18:21]
	v_mfma_f32_16x16x32_bf16 v[6:9], v[164:167], v[204:207], v[6:9]
	v_mfma_f32_16x16x32_bf16 v[2:5], v[172:175], v[204:207], v[2:5]
	s_setprio 0
	s_barrier
; #define PG8_WAIT_V(n) asm volatile("s_waitcnt vmcnt(" #n ")" ::: "memory")
; #define PG8_BAR __builtin_amdgcn_s_barrier()
; template <class Epi, class Sched, bool ALIGN_EPI = true, bool SP2 = true, bool FULLLINE = false, bool NOSTAGE = false, bool FP8 = false>
; __device__ __forceinline__ void gemm_phase(PG8_LAS unsigned char* lds, const Gemm g, const Sched& S, const Epi& E) {
;     ...
;         static_assert(SP2, "only the SP2 loop is kept");
;         { const int t = 0; if constexpr (Epi::NST == 16) PG8_ITER(PG8_WAIT_V(24)); else if constexpr (Epi::NST == 8) PG8_ITER(PG8_WAIT_V(16)); else PG8_ITER(PG8_WAIT_V(8)); }
;         for (int t = 2; t < nt; t += 2) PG8_ITER(PG8_WAIT_V(8));
;     ...
;         if constexpr (ALIGN_EPI) { if (wr == 0) PG8_BAR; }
	ds_read_b128 v[140:143], v154
	ds_read_b128 v[144:147], v154 offset:1024
	ds_read_b128 v[148:151], v154 offset:2048
	ds_read_b128 v[156:159], v154 offset:3072
	ds_read_b128 v[160:163], v155
	ds_read_b128 v[164:167], v155 offset:1024
	ds_read_b128 v[168:171], v155 offset:2048
	ds_read_b128 v[172:175], v155 offset:3072
	s_mov_b32 m0, s47
	v_lshl_add_u64 v[212:213], v[210:211], 0, s[38:39]
	ds_read_b128 v[176:179], v153 offset:32768
	ds_read_b128 v[180:183], v153 offset:33792
	ds_read_b128 v[184:187], v153 offset:34816
	ds_read_b128 v[188:191], v153 offset:35840
	ds_read_b128 v[192:195], v153 offset:36864
	ds_read_b128 v[196:199], v153 offset:37888
	ds_read_b128 v[200:203], v153 offset:38912
	ds_read_b128 v[204:207], v153 offset:39936
	global_load_lds_dwordx4 v[212:213], off
	v_lshl_add_u64 v[212:213], v[210:211], 0, s[66:67]
	s_mov_b32 m0, s52
	s_nop 0
	global_load_lds_dwordx4 v[212:213], off
	s_waitcnt vmcnt(8)
	s_waitcnt lgkmcnt(0)
	s_barrier
	s_waitcnt lgkmcnt(0)
	s_setprio 1
	v_mfma_f32_16x16x32_bf16 v[122:125], v[140:143], v[176:179], v[122:125]
	v_mfma_f32_16x16x32_bf16 v[114:117], v[148:151], v[176:179], v[114:117]
	v_mfma_f32_16x16x32_bf16 v[106:109], v[140:143], v[184:187], v[106:109]
	v_mfma_f32_16x16x32_bf16 v[98:101], v[148:151], v[184:187], v[98:101]
	v_mfma_f32_16x16x32_bf16 v[90:93], v[140:143], v[192:195], v[90:93]
	v_mfma_f32_16x16x32_bf16 v[82:85], v[148:151], v[192:195], v[82:85]
	v_mfma_f32_16x16x32_bf16 v[58:61], v[140:143], v[200:203], v[58:61]
	v_mfma_f32_16x16x32_bf16 v[50:53], v[148:151], v[200:203], v[50:53]
	v_mfma_f32_16x16x32_bf16 v[122:125], v[144:147], v[180:183], v[122:125]
	v_mfma_f32_16x16x32_bf16 v[114:117], v[156:159], v[180:183], v[114:117]
	v_mfma_f32_16x16x32_bf16 v[106:109], v[144:147], v[188:191], v[106:109]
	v_mfma_f32_16x16x32_bf16 v[98:101], v[156:159], v[188:191], v[98:101]
	v_mfma_f32_16x16x32_bf16 v[90:93], v[144:147], v[196:199], v[90:93]
	v_mfma_f32_16x16x32_bf16 v[82:85], v[156:159], v[196:199], v[82:85]
	v_mfma_f32_16x16x32_bf16 v[58:61], v[144:147], v[204:207], v[58:61]
	v_mfma_f32_16x16x32_bf16 v[50:53], v[156:159], v[204:207], v[50:53]
	v_mfma_f32_16x16x32_bf16 v[126:129], v[160:163], v[176:179], v[126:129]
	v_mfma_f32_16x16x32_bf16 v[118:121], v[168:171], v[176:179], v[118:121]
	v_mfma_f32_16x16x32_bf16 v[110:113], v[160:163], v[184:187], v[110:113]
	v_mfma_f32_16x16x32_bf16 v[102:105], v[168:171], v[184:187], v[102:105]
	v_mfma_f32_16x16x32_bf16 v[94:97], v[160:163], v[192:195], v[94:97]
	v_mfma_f32_16x16x32_bf16 v[86:89], v[168:171], v[192:195], v[86:89]
	v_mfma_f32_16x16x32_bf16 v[62:65], v[160:163], v[200:203], v[62:65]
	v_mfma_f32_16x16x32_bf16 v[54:57], v[168:171], v[200:203], v[54:57]
	v_mfma_f32_16x16x32_bf16 v[126:129], v[164:167], v[180:183], v[126:129]
	v_mfma_f32_16x16x32_bf16 v[118:121], v[172:175], v[180:183], v[118:121]
	v_mfma_f32_16x16x32_bf16 v[110:113], v[164:167], v[188:191], v[110:113]
	v_mfma_f32_16x16x32_bf16 v[102:105], v[172:175], v[188:191], v[102:105]
	v_mfma_f32_16x16x32_bf16 v[94:97], v[164:167], v[196:199], v[94:97]
	v_mfma_f32_16x16x32_bf16 v[86:89], v[172:175], v[196:199], v[86:89]
	v_mfma_f32_16x16x32_bf16 v[62:65], v[164:167], v[204:207], v[62:65]
	v_mfma_f32_16x16x32_bf16 v[54:57], v[172:175], v[204:207], v[54:57]
	s_setprio 0
	s_barrier
	s_mov_b32 m0, s50
	v_lshl_add_u64 v[212:213], v[208:209], 0, s[68:69]
	ds_read_b128 v[176:179], v153 offset:49152
	ds_read_b128 v[180:183], v153 offset:50176
	ds_read_b128 v[184:187], v153 offset:51200
	ds_read_b128 v[188:191], v153 offset:52224
	ds_read_b128 v[192:195], v153 offset:53248
	ds_read_b128 v[196:199], v153 offset:54272
	ds_read_b128 v[200:203], v153 offset:55296
	ds_read_b128 v[204:207], v153 offset:56320
	global_load_lds_dwordx4 v[212:213], off
	v_lshl_add_u64 v[212:213], v[208:209], 0, s[70:71]
	s_mov_b32 m0, s51
	s_nop 0
	global_load_lds_dwordx4 v[212:213], off
	v_lshl_add_u64 v[212:213], v[208:209], 0, s[18:19]
	s_mov_b32 m0, s33
	v_lshl_add_u64 v[208:209], v[208:209], 0, s[20:21]
	global_load_lds_dwordx4 v[212:213], off
	s_mov_b32 m0, s56
	s_nop 0
	global_load_lds_dwordx4 v[208:209], off
	v_lshl_add_u64 v[208:209], v[210:211], 0, s[68:69]
	s_mov_b32 m0, s53
	s_nop 0
	global_load_lds_dwordx4 v[208:209], off
	v_lshl_add_u64 v[208:209], v[210:211], 0, s[70:71]
	s_mov_b32 m0, s54
	s_nop 0
	global_load_lds_dwordx4 v[208:209], off
	s_waitcnt vmcnt(8)
	s_waitcnt lgkmcnt(0)
	s_barrier
	s_waitcnt lgkmcnt(0)
	s_setprio 1
	v_mfma_f32_16x16x32_bf16 v[78:81], v[140:143], v[176:179], v[78:81]
	v_mfma_f32_16x16x32_bf16 v[70:73], v[148:151], v[176:179], v[70:73]
	v_mfma_f32_16x16x32_bf16 v[46:49], v[140:143], v[184:187], v[46:49]
	v_mfma_f32_16x16x32_bf16 v[38:41], v[148:151], v[184:187], v[38:41]
	v_mfma_f32_16x16x32_bf16 v[30:33], v[140:143], v[192:195], v[30:33]
	v_mfma_f32_16x16x32_bf16 v[22:25], v[148:151], v[192:195], v[22:25]
	v_mfma_f32_16x16x32_bf16 v[14:17], v[140:143], v[200:203], v[14:17]
	v_mfma_f32_16x16x32_bf16 v[10:13], v[148:151], v[200:203], v[10:13]
	v_mfma_f32_16x16x32_bf16 v[78:81], v[144:147], v[180:183], v[78:81]
	v_mfma_f32_16x16x32_bf16 v[70:73], v[156:159], v[180:183], v[70:73]
	v_mfma_f32_16x16x32_bf16 v[46:49], v[144:147], v[188:191], v[46:49]
	v_mfma_f32_16x16x32_bf16 v[38:41], v[156:159], v[188:191], v[38:41]
	v_mfma_f32_16x16x32_bf16 v[30:33], v[144:147], v[196:199], v[30:33]
	v_mfma_f32_16x16x32_bf16 v[22:25], v[156:159], v[196:199], v[22:25]
	v_mfma_f32_16x16x32_bf16 v[14:17], v[144:147], v[204:207], v[14:17]
	v_mfma_f32_16x16x32_bf16 v[10:13], v[156:159], v[204:207], v[10:13]
	v_mfma_f32_16x16x32_bf16 v[74:77], v[160:163], v[176:179], v[74:77]
	v_mfma_f32_16x16x32_bf16 v[66:69], v[168:171], v[176:179], v[66:69]
	v_mfma_f32_16x16x32_bf16 v[42:45], v[160:163], v[184:187], v[42:45]
	v_mfma_f32_16x16x32_bf16 v[34:37], v[168:171], v[184:187], v[34:37]
	v_mfma_f32_16x16x32_bf16 v[26:29], v[160:163], v[192:195], v[26:29]
	v_mfma_f32_16x16x32_bf16 v[18:21], v[168:171], v[192:195], v[18:21]
	v_mfma_f32_16x16x32_bf16 v[6:9], v[160:163], v[200:203], v[6:9]
	v_mfma_f32_16x16x32_bf16 v[2:5], v[168:171], v[200:203], v[2:5]
	v_mfma_f32_16x16x32_bf16 v[74:77], v[164:167], v[180:183], v[74:77]
	v_mfma_f32_16x16x32_bf16 v[66:69], v[172:175], v[180:183], v[66:69]
	v_mfma_f32_16x16x32_bf16 v[42:45], v[164:167], v[188:191], v[42:45]
	v_mfma_f32_16x16x32_bf16 v[34:37], v[172:175], v[188:191], v[34:37]
	v_mfma_f32_16x16x32_bf16 v[26:29], v[164:167], v[196:199], v[26:29]
	v_mfma_f32_16x16x32_bf16 v[18:21], v[172:175], v[196:199], v[18:21]
	v_mfma_f32_16x16x32_bf16 v[6:9], v[164:167], v[204:207], v[6:9]
	v_mfma_f32_16x16x32_bf16 v[2:5], v[172:175], v[204:207], v[2:5]
	s_setprio 0
	s_barrier
	s_add_i32 s81, s81, 2
	s_add_u32 s82, s82, 0x100
	s_addc_u32 s83, s83, 0
	s_add_u32 s57, s57, 0x100
	s_addc_u32 s80, s80, 0
	s_cmp_gt_u32 s81, 29
	s_cbranch_scc0 .LBB0_1025
	s_and_b64 vcc, exec, s[14:15]
	s_cbranch_vccz .LBB0_1028
	s_barrier

; #define PG8_STAGE(bufoff, gbase, voff) do { if constexpr (!NOSTAGE) _Pragma("unroll") for (int _i = 0; _i < 2; ++_i) \
;         __builtin_amdgcn_global_load_lds((const unsigned*)((const char*)(gbase) + (size_t)_i * pstep##voff + v##voff), (PG8_LAS unsigned*)(lds + (bufoff) + ldsw + _i * 8192), 16, 0, 0); } while (0)
; #define PG8_WAIT_V(n) asm volatile("s_waitcnt vmcnt(" #n ")" ::: "memory")
; #define PG8_BAR __builtin_amdgcn_s_barrier()
; template <class Epi, class Sched, bool ALIGN_EPI = true, bool SP2 = true, bool FULLLINE = false, bool NOSTAGE = false, bool FP8 = false>
; __device__ __forceinline__ void gemm_phase(PG8_LAS unsigned char* lds, const Gemm g, const Sched& S, const Epi& E) {
;     ...
;     const int aoff = lds_byte(wr * 64 + fr, fq * 8), boff = lds_byte(wc * 32 + fr, fq * 8);
;     ...
;     PG8_STAGE(PG8_SB(0, 0), cB, offB); PG8_STAGE(PG8_SB(0, 1), cB + hstepB, offB); PG8_STAGE(PG8_SA(0, 0), cA, offA); PG8_STAGE(PG8_SA(0, 1), cA + hstepA, offA);
;     PG8_STAGE(PG8_SB(1, 0), cB + kstep, offB); PG8_STAGE(PG8_SA(1, 0), cA + kstep, offA); PG8_STAGE(PG8_SB(1, 1), cB + hstepB + kstep, offB);
;     if (wr == 1) PG8_BAR;
;     PG8_WAIT_V(0); PG8_BAR;
;     PG8_BAR;
;     } else {
;     PG8_STAGE(PG8_SB(0, 0), cB, offB); PG8_STAGE(PG8_SA(0, 0), cA, offA); PG8_STAGE(PG8_SB(0, 1), cB + hstepB, offB); PG8_STAGE(PG8_SA(0, 1), cA + hstepA, offA);
;     if (wr == 1) PG8_BAR;
;     PG8_WAIT_V(4); PG8_BAR;
;     PG8_STAGE(PG8_SB(1, 0), cB + kstep, offB); PG8_STAGE(PG8_SA(1, 0), cA + kstep, offA); PG8_STAGE(PG8_SB(1, 1), cB + hstepB + kstep, offB);
;     PG8_WAIT_V(6); PG8_BAR;
;     }
;     if (wr == 1) __builtin_amdgcn_s_setprio(1);
;     for (;;) {
;         const bool has_next = S.next(ui + 1, nxt);
;         const char* nA = has_next ? PG8_ABASE(nxt) : cA; const char* nB = has_next ? PG8_BBASE(nxt) : cB;
.LBB0_1196:
	s_waitcnt vmcnt(0)
	v_cndmask_b32_e64 v4, 0, 1, s[10:11]
	v_cmp_ne_u32_e64 s[6:7], 1, v4
	s_andn2_b64 vcc, exec, s[10:11]
	s_barrier
	s_barrier
	s_cbranch_vccnz .LBB0_1198
.LBB0_1198:
	v_and_b32_e32 v4, 48, v0
	v_lshlrev_b32_e32 v5, 6, v0
	s_movk_i32 s1, 0x3c0
	s_add_u32 s63, s48, 0x164000
	v_and_or_b32 v4, v5, s1, v4
	v_lshlrev_b32_e32 v5, 2, v0
	s_addc_u32 s80, s49, 0
	s_lshl_b32 s0, s13, 13
	v_and_b32_e32 v5, 32, v5
	v_bitop3_b32 v6, v4, s0, v5 bitop3:0xde
	s_lshl_b32 s0, s12, 5
	s_and_b32 s82, s0, 0x60
	s_lshl_b32 s0, s82, 7
	s_lshl_b32 s81, s13, 6
	v_bitop3_b32 v4, s0, v4, v5 bitop3:0xf6
	v_lshlrev_b32_e32 v5, 9, v0
	s_cmpk_lt_u32 s9, 0x100
	v_and_b32_e32 v5, 0x30000, v5
	v_lshlrev_b32_e32 v1, 12, v1
	s_cselect_b64 s[10:11], -1, 0
	v_or3_b32 v1, v2, v5, v1
	s_add_i32 s85, 0, 0x10000
	s_add_i32 s87, 0, 0x14000
	s_add_i32 s90, 0, 0x18000
	s_add_i32 s91, 0, 0x1c000
	s_sext_i32_i8 s75, s8
	s_ashr_i32 s83, s86, 31
	v_add_u32_e32 v174, v1, v3
	v_mov_b32_e32 v175, 0
	s_mov_b32 s84, 0
	v_mov_b64_e32 v[176:177], 0x200
	v_mov_b64_e32 v[178:179], 0x1ff
	v_add_u32_e32 v1, s85, v4
	v_add_u32_e32 v192, s87, v4
	v_add_u32_e32 v193, 0, v6
	s_mov_b64 s[12:13], 0x80080
	s_add_i32 s88, s47, 0xc000
	s_mov_b64 s[14:15], 0xc0080
	s_add_i32 s89, s47, 0xe000
	s_mov_b64 s[16:17], 0x100
	s_mov_b64 s[18:19], 0x40100
	s_mov_b64 s[20:21], 0x80100
	s_mov_b64 s[22:23], 0xc0100
	v_add_u32_e32 v194, s90, v4
	v_add_u32_e32 v195, s91, v4
	s_mov_b64 s[24:25], 0x180
	s_waitcnt lgkmcnt(0)
	s_mov_b64 s[26:27], 0x40180
	s_mov_b64 s[28:29], 0x40000
	s_mov_b64 s[30:31], 0x80000
	s_mov_b64 s[34:35], 0xc0000
	s_mov_b64 s[36:37], 0x80
	s_mov_b64 s[38:39], 0x40080
	s_branch .LBB0_1201

; template <class Epi, class Sched, bool ALIGN_EPI = true, bool SP2 = true, bool FULLLINE = false, bool NOSTAGE = false, bool FP8 = false>
; __device__ __forceinline__ void gemm_phase(PG8_LAS unsigned char* lds, const Gemm g, const Sched& S, const Epi& E) {
;     ...
;         const bool has_next = S.next(ui + 1, nxt);
;         const char* nA = has_next ? PG8_ABASE(nxt) : cA; const char* nB = has_next ? PG8_BBASE(nxt) : cB;
.LBB0_1207:
	s_ashr_i32 s69, s68, 31
	ds_read_b128 v[2:5], v1
	ds_read_b128 v[6:9], v1 offset:1024
	ds_read_b128 v[10:13], v1 offset:2048
	ds_read_b128 v[14:17], v1 offset:3072
	ds_read_b128 v[18:21], v192
	ds_read_b128 v[22:25], v192 offset:1024
	ds_read_b128 v[26:29], v192 offset:2048
	ds_read_b128 v[30:33], v192 offset:3072
	s_lshl_b64 s[0:1], s[68:69], 20
	s_add_u32 s70, s42, s0
	s_addc_u32 s71, s43, s1
	s_and_b64 s[0:1], s[8:9], exec
	s_cselect_b32 s69, s71, s77
	s_cselect_b32 s92, s70, s76
	s_ashr_i32 s67, s66, 31
	s_lshl_b64 s[0:1], s[66:67], 20
	s_add_u32 s72, s44, s0
	s_addc_u32 s73, s45, s1
	s_and_b64 s[0:1], s[8:9], exec
	s_cselect_b32 s67, s73, s79
	s_cselect_b32 s93, s72, s78
	v_lshl_add_u64 v[248:249], s[76:77], 0, v[170:171]
	s_mov_b32 m0, s88
	v_lshl_add_u64 v[66:67], v[248:249], 0, s[12:13]
	ds_read_b128 v[34:37], v193
	ds_read_b128 v[38:41], v193 offset:1024
	ds_read_b128 v[42:45], v193 offset:2048
	ds_read_b128 v[46:49], v193 offset:3072
	ds_read_b128 v[50:53], v193 offset:4096
	ds_read_b128 v[54:57], v193 offset:5120
	ds_read_b128 v[58:61], v193 offset:6144
	ds_read_b128 v[62:65], v193 offset:7168
	global_load_lds_dwordx4 v[66:67], off
	v_lshl_add_u64 v[66:67], v[248:249], 0, s[14:15]
	s_mov_b32 m0, s89
	s_nop 0
	global_load_lds_dwordx4 v[66:67], off
	s_waitcnt vmcnt(24)
	s_waitcnt lgkmcnt(0)
	s_barrier
	s_waitcnt lgkmcnt(0)
	s_setprio 1
	v_mfma_f32_16x16x32_bf16 v[66:69], v[2:5], v[34:37], 0
	v_mfma_f32_16x16x32_bf16 v[70:73], v[10:13], v[34:37], 0
	v_mfma_f32_16x16x32_bf16 v[78:81], v[10:13], v[42:45], 0
	v_mfma_f32_16x16x32_bf16 v[86:89], v[10:13], v[50:53], 0
	v_mfma_f32_16x16x32_bf16 v[66:69], v[6:9], v[38:41], v[66:69]
	v_mfma_f32_16x16x32_bf16 v[70:73], v[14:17], v[38:41], v[70:73]
	v_mfma_f32_16x16x32_bf16 v[74:77], v[2:5], v[42:45], 0
	v_mfma_f32_16x16x32_bf16 v[78:81], v[14:17], v[46:49], v[78:81]
	v_mfma_f32_16x16x32_bf16 v[82:85], v[2:5], v[50:53], 0
	v_mfma_f32_16x16x32_bf16 v[86:89], v[14:17], v[54:57], v[86:89]
	v_mfma_f32_16x16x32_bf16 v[90:93], v[2:5], v[58:61], 0
	v_mfma_f32_16x16x32_bf16 v[94:97], v[10:13], v[58:61], 0
	v_mfma_f32_16x16x32_bf16 v[74:77], v[6:9], v[46:49], v[74:77]
	v_mfma_f32_16x16x32_bf16 v[82:85], v[6:9], v[54:57], v[82:85]
	v_mfma_f32_16x16x32_bf16 v[90:93], v[6:9], v[62:65], v[90:93]
	v_mfma_f32_16x16x32_bf16 v[94:97], v[14:17], v[62:65], v[94:97]
	v_mfma_f32_16x16x32_bf16 v[98:101], v[18:21], v[34:37], 0
	v_mfma_f32_16x16x32_bf16 v[34:37], v[26:29], v[34:37], 0
	v_mfma_f32_16x16x32_bf16 v[98:101], v[22:25], v[38:41], v[98:101]
	v_mfma_f32_16x16x32_bf16 v[34:37], v[30:33], v[38:41], v[34:37]
	v_mfma_f32_16x16x32_bf16 v[38:41], v[18:21], v[42:45], 0
	v_mfma_f32_16x16x32_bf16 v[42:45], v[26:29], v[42:45], 0
	v_mfma_f32_16x16x32_bf16 v[38:41], v[22:25], v[46:49], v[38:41]
	v_mfma_f32_16x16x32_bf16 v[42:45], v[30:33], v[46:49], v[42:45]
	v_mfma_f32_16x16x32_bf16 v[46:49], v[18:21], v[50:53], 0
	v_mfma_f32_16x16x32_bf16 v[50:53], v[26:29], v[50:53], 0
	v_mfma_f32_16x16x32_bf16 v[46:49], v[22:25], v[54:57], v[46:49]
	v_mfma_f32_16x16x32_bf16 v[50:53], v[30:33], v[54:57], v[50:53]
	v_mfma_f32_16x16x32_bf16 v[54:57], v[18:21], v[58:61], 0
	v_mfma_f32_16x16x32_bf16 v[58:61], v[26:29], v[58:61], 0
	v_mfma_f32_16x16x32_bf16 v[54:57], v[22:25], v[62:65], v[54:57]
	v_mfma_f32_16x16x32_bf16 v[58:61], v[30:33], v[62:65], v[58:61]
	s_setprio 0
	s_barrier
	v_lshl_add_u64 v[250:251], s[78:79], 0, v[172:173]
	s_add_i32 s94, s85, s46
	v_lshl_add_u64 v[130:131], v[250:251], 0, s[16:17]
	s_mov_b32 m0, s94
	s_add_i32 s95, s94, 0x2000
	ds_read_b128 v[62:65], v193 offset:16384
	ds_read_b128 v[102:105], v193 offset:17408
	ds_read_b128 v[106:109], v193 offset:18432
	ds_read_b128 v[110:113], v193 offset:19456
	ds_read_b128 v[114:117], v193 offset:20480
	ds_read_b128 v[118:121], v193 offset:21504
	ds_read_b128 v[122:125], v193 offset:22528
	ds_read_b128 v[126:129], v193 offset:23552
	global_load_lds_dwordx4 v[130:131], off
	v_lshl_add_u64 v[130:131], v[250:251], 0, s[18:19]
	s_mov_b32 m0, s95
	s_add_i32 s40, s87, s46
	global_load_lds_dwordx4 v[130:131], off
	v_lshl_add_u64 v[130:131], v[250:251], 0, s[20:21]
	s_mov_b32 m0, s40
	s_add_i32 s41, s40, 0x2000
	global_load_lds_dwordx4 v[130:131], off
	v_lshl_add_u64 v[130:131], v[250:251], 0, s[22:23]
	s_mov_b32 m0, s41
	s_nop 0
	global_load_lds_dwordx4 v[130:131], off
	v_lshl_add_u64 v[130:131], v[248:249], 0, s[16:17]
	s_mov_b32 m0, s47
	s_nop 0
	global_load_lds_dwordx4 v[130:131], off
	v_lshl_add_u64 v[130:131], v[248:249], 0, s[18:19]
	s_mov_b32 m0, s52
	s_nop 0
	global_load_lds_dwordx4 v[130:131], off
	s_waitcnt vmcnt(24)
	s_waitcnt lgkmcnt(0)
	s_barrier
	s_waitcnt lgkmcnt(0)
	s_setprio 1
	v_mfma_f32_16x16x32_bf16 v[130:133], v[2:5], v[62:65], 0
	v_mfma_f32_16x16x32_bf16 v[138:141], v[6:9], v[102:105], v[130:133]
	v_mfma_f32_16x16x32_bf16 v[130:133], v[10:13], v[62:65], 0
	v_mfma_f32_16x16x32_bf16 v[150:153], v[14:17], v[102:105], v[130:133]
	v_mfma_f32_16x16x32_bf16 v[130:133], v[2:5], v[106:109], 0
	v_mfma_f32_16x16x32_bf16 v[154:157], v[6:9], v[110:113], v[130:133]
	v_mfma_f32_16x16x32_bf16 v[130:133], v[10:13], v[106:109], 0
	v_mfma_f32_16x16x32_bf16 v[158:161], v[14:17], v[110:113], v[130:133]
	v_mfma_f32_16x16x32_bf16 v[130:133], v[2:5], v[114:117], 0
	v_mfma_f32_16x16x32_bf16 v[2:5], v[2:5], v[122:125], 0
	v_mfma_f32_16x16x32_bf16 v[162:165], v[6:9], v[118:121], v[130:133]
	v_mfma_f32_16x16x32_bf16 v[2:5], v[6:9], v[126:129], v[2:5]
	v_mfma_f32_16x16x32_bf16 v[6:9], v[10:13], v[122:125], 0
	v_mfma_f32_16x16x32_bf16 v[130:133], v[10:13], v[114:117], 0
	v_mfma_f32_16x16x32_bf16 v[6:9], v[14:17], v[126:129], v[6:9]
	v_mfma_f32_16x16x32_bf16 v[166:169], v[14:17], v[118:121], v[130:133]
	v_mfma_f32_16x16x32_bf16 v[10:13], v[18:21], v[62:65], 0
	v_mfma_f32_16x16x32_bf16 v[180:183], v[22:25], v[102:105], v[10:13]
	v_mfma_f32_16x16x32_bf16 v[10:13], v[26:29], v[62:65], 0
	v_mfma_f32_16x16x32_bf16 v[184:187], v[30:33], v[102:105], v[10:13]
	v_mfma_f32_16x16x32_bf16 v[10:13], v[18:21], v[106:109], 0
	v_mfma_f32_16x16x32_bf16 v[188:191], v[22:25], v[110:113], v[10:13]
	v_mfma_f32_16x16x32_bf16 v[10:13], v[26:29], v[106:109], 0
	v_mfma_f32_16x16x32_bf16 v[196:199], v[30:33], v[110:113], v[10:13]
	v_mfma_f32_16x16x32_bf16 v[10:13], v[18:21], v[114:117], 0
	v_mfma_f32_16x16x32_bf16 v[200:203], v[22:25], v[118:121], v[10:13]
	v_mfma_f32_16x16x32_bf16 v[10:13], v[26:29], v[114:117], 0
	v_mfma_f32_16x16x32_bf16 v[204:207], v[30:33], v[118:121], v[10:13]
	v_mfma_f32_16x16x32_bf16 v[10:13], v[18:21], v[122:125], 0
	v_mfma_f32_16x16x32_bf16 v[208:211], v[22:25], v[126:129], v[10:13]
	v_mfma_f32_16x16x32_bf16 v[10:13], v[26:29], v[122:125], 0
	v_mfma_f32_16x16x32_bf16 v[212:215], v[30:33], v[126:129], v[10:13]
	s_setprio 0
	s_barrier
	s_nop 5
	ds_read_b128 v[10:13], v194
	ds_read_b128 v[14:17], v194 offset:1024
	ds_read_b128 v[18:21], v194 offset:2048
	ds_read_b128 v[22:25], v194 offset:3072
	ds_read_b128 v[216:219], v195
	ds_read_b128 v[220:223], v195 offset:1024
	ds_read_b128 v[224:227], v195 offset:2048
	ds_read_b128 v[228:231], v195 offset:3072
	s_mov_b32 m0, s53
	v_lshl_add_u64 v[106:107], v[248:249], 0, s[20:21]
	ds_read_b128 v[26:29], v193 offset:32768
	ds_read_b128 v[30:33], v193 offset:33792
	ds_read_b128 v[62:65], v193 offset:34816
	ds_read_b128 v[102:105], v193 offset:35840
	ds_read_b128 v[232:235], v193 offset:36864
	ds_read_b128 v[236:239], v193 offset:37888
	ds_read_b128 v[240:243], v193 offset:38912
	ds_read_b128 v[244:247], v193 offset:39936
	global_load_lds_dwordx4 v[106:107], off
	v_lshl_add_u64 v[106:107], v[248:249], 0, s[22:23]
	s_mov_b32 m0, s54
	s_nop 0
	global_load_lds_dwordx4 v[106:107], off
	s_waitcnt vmcnt(8)
	s_waitcnt lgkmcnt(0)
	s_barrier
	s_waitcnt lgkmcnt(0)
	s_setprio 1
	v_mfma_f32_16x16x32_bf16 v[66:69], v[10:13], v[26:29], v[66:69]
	v_mfma_f32_16x16x32_bf16 v[146:149], v[14:17], v[30:33], v[66:69]
	v_mfma_f32_16x16x32_bf16 v[66:69], v[18:21], v[26:29], v[70:73]
	v_mfma_f32_16x16x32_bf16 v[142:145], v[22:25], v[30:33], v[66:69]
	v_mfma_f32_16x16x32_bf16 v[66:69], v[10:13], v[62:65], v[74:77]
	v_mfma_f32_16x16x32_bf16 v[126:129], v[14:17], v[102:105], v[66:69]
	v_mfma_f32_16x16x32_bf16 v[66:69], v[18:21], v[62:65], v[78:81]
	v_mfma_f32_16x16x32_bf16 v[122:125], v[22:25], v[102:105], v[66:69]
	v_mfma_f32_16x16x32_bf16 v[66:69], v[10:13], v[232:235], v[82:85]
	v_mfma_f32_16x16x32_bf16 v[110:113], v[14:17], v[236:239], v[66:69]
	v_mfma_f32_16x16x32_bf16 v[66:69], v[18:21], v[232:235], v[86:89]
	v_mfma_f32_16x16x32_bf16 v[106:109], v[22:25], v[236:239], v[66:69]
	v_mfma_f32_16x16x32_bf16 v[66:69], v[10:13], v[240:243], v[90:93]
	v_mfma_f32_16x16x32_bf16 v[86:89], v[14:17], v[244:247], v[66:69]
	v_mfma_f32_16x16x32_bf16 v[66:69], v[18:21], v[240:243], v[94:97]
	v_mfma_f32_16x16x32_bf16 v[78:81], v[22:25], v[244:247], v[66:69]
	v_mfma_f32_16x16x32_bf16 v[66:69], v[216:219], v[26:29], v[98:101]
	v_mfma_f32_16x16x32_bf16 v[26:29], v[224:227], v[26:29], v[34:37]
	v_mfma_f32_16x16x32_bf16 v[130:133], v[228:231], v[30:33], v[26:29]
	v_mfma_f32_16x16x32_bf16 v[26:29], v[216:219], v[62:65], v[38:41]
	v_mfma_f32_16x16x32_bf16 v[118:121], v[220:223], v[102:105], v[26:29]
	v_mfma_f32_16x16x32_bf16 v[26:29], v[224:227], v[62:65], v[42:45]
	v_mfma_f32_16x16x32_bf16 v[114:117], v[228:231], v[102:105], v[26:29]
	v_mfma_f32_16x16x32_bf16 v[26:29], v[216:219], v[232:235], v[46:49]
	v_mfma_f32_16x16x32_bf16 v[102:105], v[220:223], v[236:239], v[26:29]
	v_mfma_f32_16x16x32_bf16 v[26:29], v[224:227], v[232:235], v[50:53]
	v_mfma_f32_16x16x32_bf16 v[98:101], v[228:231], v[236:239], v[26:29]
	v_mfma_f32_16x16x32_bf16 v[26:29], v[216:219], v[240:243], v[54:57]
	v_mfma_f32_16x16x32_bf16 v[70:73], v[220:223], v[244:247], v[26:29]
	v_mfma_f32_16x16x32_bf16 v[26:29], v[224:227], v[240:243], v[58:61]
	v_mfma_f32_16x16x32_bf16 v[134:137], v[220:223], v[30:33], v[66:69]
	v_mfma_f32_16x16x32_bf16 v[66:69], v[228:231], v[244:247], v[26:29]
	s_setprio 0
	s_barrier
	s_add_i32 s50, s90, s46
	s_nop 3
	v_lshl_add_u64 v[26:27], v[250:251], 0, s[24:25]
	s_mov_b32 m0, s50
	s_add_i32 s51, s50, 0x2000
	ds_read_b128 v[34:37], v193 offset:49152
	ds_read_b128 v[38:41], v193 offset:50176
	ds_read_b128 v[74:77], v193 offset:51200
	ds_read_b128 v[82:85], v193 offset:52224
	ds_read_b128 v[90:93], v193 offset:53248
	ds_read_b128 v[94:97], v193 offset:54272
	ds_read_b128 v[232:235], v193 offset:55296
	ds_read_b128 v[236:239], v193 offset:56320
	global_load_lds_dwordx4 v[26:27], off
	v_lshl_add_u64 v[26:27], v[250:251], 0, s[26:27]
	s_mov_b32 m0, s51
	s_mov_b64 s[0:1], 0x80180
	s_add_i32 s33, s91, s46
	global_load_lds_dwordx4 v[26:27], off
	v_lshl_add_u64 v[26:27], v[250:251], 0, s[0:1]
	s_mov_b32 m0, s33
	s_mov_b64 s[0:1], 0xc0180
	s_add_i32 s56, s33, 0x2000
	global_load_lds_dwordx4 v[26:27], off
	v_lshl_add_u64 v[26:27], v[250:251], 0, s[0:1]
	s_mov_b32 m0, s56
	s_nop 0
	global_load_lds_dwordx4 v[26:27], off
	v_lshl_add_u64 v[26:27], v[248:249], 0, s[24:25]
	s_mov_b32 m0, s55
	s_nop 0
	global_load_lds_dwordx4 v[26:27], off
	v_lshl_add_u64 v[26:27], v[248:249], 0, s[26:27]
	s_mov_b32 m0, s62
	s_nop 0
	global_load_lds_dwordx4 v[26:27], off
	s_waitcnt vmcnt(8)
	s_waitcnt lgkmcnt(0)
	s_barrier
	s_waitcnt lgkmcnt(0)
	s_setprio 1
	v_mfma_f32_16x16x32_bf16 v[26:29], v[10:13], v[34:37], v[138:141]
	v_mfma_f32_16x16x32_bf16 v[62:65], v[14:17], v[38:41], v[26:29]
	v_mfma_f32_16x16x32_bf16 v[26:29], v[18:21], v[34:37], v[150:153]
	v_mfma_f32_16x16x32_bf16 v[58:61], v[22:25], v[38:41], v[26:29]
	v_mfma_f32_16x16x32_bf16 v[26:29], v[10:13], v[74:77], v[154:157]
	v_mfma_f32_16x16x32_bf16 v[46:49], v[14:17], v[82:85], v[26:29]
	v_mfma_f32_16x16x32_bf16 v[26:29], v[18:21], v[74:77], v[158:161]
	v_mfma_f32_16x16x32_bf16 v[42:45], v[22:25], v[82:85], v[26:29]
	v_mfma_f32_16x16x32_bf16 v[26:29], v[10:13], v[90:93], v[162:165]
	v_mfma_f32_16x16x32_bf16 v[2:5], v[10:13], v[232:235], v[2:5]
	v_mfma_f32_16x16x32_bf16 v[30:33], v[14:17], v[94:97], v[26:29]
	v_mfma_f32_16x16x32_bf16 v[26:29], v[18:21], v[90:93], v[166:169]
	v_mfma_f32_16x16x32_bf16 v[14:17], v[14:17], v[236:239], v[2:5]
	v_mfma_f32_16x16x32_bf16 v[2:5], v[18:21], v[232:235], v[6:9]
	v_mfma_f32_16x16x32_bf16 v[26:29], v[22:25], v[94:97], v[26:29]
	v_mfma_f32_16x16x32_bf16 v[10:13], v[22:25], v[236:239], v[2:5]
	v_mfma_f32_16x16x32_bf16 v[2:5], v[216:219], v[34:37], v[180:183]
	v_mfma_f32_16x16x32_bf16 v[54:57], v[220:223], v[38:41], v[2:5]
	v_mfma_f32_16x16x32_bf16 v[2:5], v[224:227], v[34:37], v[184:187]
	v_mfma_f32_16x16x32_bf16 v[50:53], v[228:231], v[38:41], v[2:5]
	v_mfma_f32_16x16x32_bf16 v[2:5], v[216:219], v[74:77], v[188:191]
	v_mfma_f32_16x16x32_bf16 v[38:41], v[220:223], v[82:85], v[2:5]
	v_mfma_f32_16x16x32_bf16 v[2:5], v[224:227], v[74:77], v[196:199]
	v_mfma_f32_16x16x32_bf16 v[34:37], v[228:231], v[82:85], v[2:5]
	v_mfma_f32_16x16x32_bf16 v[2:5], v[216:219], v[90:93], v[200:203]
	v_mfma_f32_16x16x32_bf16 v[22:25], v[220:223], v[94:97], v[2:5]
	v_mfma_f32_16x16x32_bf16 v[2:5], v[224:227], v[90:93], v[204:207]
	v_mfma_f32_16x16x32_bf16 v[18:21], v[228:231], v[94:97], v[2:5]
	v_mfma_f32_16x16x32_bf16 v[2:5], v[216:219], v[232:235], v[208:211]
	v_mfma_f32_16x16x32_bf16 v[6:9], v[220:223], v[236:239], v[2:5]
	v_mfma_f32_16x16x32_bf16 v[2:5], v[224:227], v[232:235], v[212:215]
	v_mfma_f32_16x16x32_bf16 v[2:5], v[228:231], v[236:239], v[2:5]
	s_setprio 0
	s_barrier
	s_add_u32 s76, s76, 0x80180
	s_addc_u32 s77, s77, 0
	s_add_u32 s57, s78, 0x200
	s_addc_u32 s78, s79, 0
	s_mov_b32 s79, 0
.LBB0_1208:
	ds_read_b128 v[74:77], v1
	ds_read_b128 v[82:85], v1 offset:1024
	ds_read_b128 v[90:93], v1 offset:2048
	ds_read_b128 v[94:97], v1 offset:3072
	ds_read_b128 v[138:141], v192
	ds_read_b128 v[150:153], v192 offset:1024
	ds_read_b128 v[154:157], v192 offset:2048
	ds_read_b128 v[158:161], v192 offset:3072
	s_add_u32 s0, s76, 0xfff80080
	s_addc_u32 s1, s77, -1
	s_cmp_eq_u32 s79, 28
	s_cselect_b32 s1, s69, s1
	s_cselect_b32 s0, s92, s0
	s_cselect_b32 s65, s67, s78
	s_cselect_b32 s64, s93, s57
	s_mov_b32 m0, s88
	v_lshl_add_u64 v[208:209], s[76:77], 0, v[174:175]
	ds_read_b128 v[162:165], v193
	ds_read_b128 v[166:169], v193 offset:1024
	ds_read_b128 v[180:183], v193 offset:2048
	ds_read_b128 v[184:187], v193 offset:3072
	ds_read_b128 v[188:191], v193 offset:4096
	ds_read_b128 v[196:199], v193 offset:5120
	ds_read_b128 v[200:203], v193 offset:6144
	ds_read_b128 v[204:207], v193 offset:7168
	global_load_lds_dwordx4 v[208:209], off
	v_lshl_add_u64 v[208:209], v[208:209], 0, s[28:29]
	s_mov_b32 m0, s89
	s_nop 0
	global_load_lds_dwordx4 v[208:209], off
	s_waitcnt vmcnt(8)
	s_waitcnt lgkmcnt(0)
	s_barrier
	s_waitcnt lgkmcnt(0)
	s_setprio 1
	v_mfma_f32_16x16x32_bf16 v[146:149], v[74:77], v[162:165], v[146:149]
	v_mfma_f32_16x16x32_bf16 v[142:145], v[90:93], v[162:165], v[142:145]
	v_mfma_f32_16x16x32_bf16 v[126:129], v[74:77], v[180:183], v[126:129]
	v_mfma_f32_16x16x32_bf16 v[122:125], v[90:93], v[180:183], v[122:125]
	v_mfma_f32_16x16x32_bf16 v[110:113], v[74:77], v[188:191], v[110:113]
	v_mfma_f32_16x16x32_bf16 v[106:109], v[90:93], v[188:191], v[106:109]
	v_mfma_f32_16x16x32_bf16 v[86:89], v[74:77], v[200:203], v[86:89]
	v_mfma_f32_16x16x32_bf16 v[78:81], v[90:93], v[200:203], v[78:81]
	v_mfma_f32_16x16x32_bf16 v[146:149], v[82:85], v[166:169], v[146:149]
	v_mfma_f32_16x16x32_bf16 v[142:145], v[94:97], v[166:169], v[142:145]
	v_mfma_f32_16x16x32_bf16 v[126:129], v[82:85], v[184:187], v[126:129]
	v_mfma_f32_16x16x32_bf16 v[122:125], v[94:97], v[184:187], v[122:125]
	v_mfma_f32_16x16x32_bf16 v[110:113], v[82:85], v[196:199], v[110:113]
	v_mfma_f32_16x16x32_bf16 v[106:109], v[94:97], v[196:199], v[106:109]
	v_mfma_f32_16x16x32_bf16 v[86:89], v[82:85], v[204:207], v[86:89]
	v_mfma_f32_16x16x32_bf16 v[78:81], v[94:97], v[204:207], v[78:81]
	v_mfma_f32_16x16x32_bf16 v[134:137], v[138:141], v[162:165], v[134:137]
	v_mfma_f32_16x16x32_bf16 v[130:133], v[154:157], v[162:165], v[130:133]
	v_mfma_f32_16x16x32_bf16 v[118:121], v[138:141], v[180:183], v[118:121]
	v_mfma_f32_16x16x32_bf16 v[114:117], v[154:157], v[180:183], v[114:117]
	v_mfma_f32_16x16x32_bf16 v[102:105], v[138:141], v[188:191], v[102:105]
	v_mfma_f32_16x16x32_bf16 v[98:101], v[154:157], v[188:191], v[98:101]
	v_mfma_f32_16x16x32_bf16 v[70:73], v[138:141], v[200:203], v[70:73]
	v_mfma_f32_16x16x32_bf16 v[66:69], v[154:157], v[200:203], v[66:69]
	v_mfma_f32_16x16x32_bf16 v[134:137], v[150:153], v[166:169], v[134:137]
	v_mfma_f32_16x16x32_bf16 v[130:133], v[158:161], v[166:169], v[130:133]
	v_mfma_f32_16x16x32_bf16 v[118:121], v[150:153], v[184:187], v[118:121]
	v_mfma_f32_16x16x32_bf16 v[114:117], v[158:161], v[184:187], v[114:117]
	v_mfma_f32_16x16x32_bf16 v[102:105], v[150:153], v[196:199], v[102:105]
	v_mfma_f32_16x16x32_bf16 v[98:101], v[158:161], v[196:199], v[98:101]
	v_mfma_f32_16x16x32_bf16 v[70:73], v[150:153], v[204:207], v[70:73]
	v_mfma_f32_16x16x32_bf16 v[66:69], v[158:161], v[204:207], v[66:69]
	s_setprio 0
	s_barrier
	s_mov_b32 m0, s94
	v_lshl_add_u64 v[208:209], s[64:65], 0, v[172:173]
	ds_read_b128 v[162:165], v193 offset:16384
	ds_read_b128 v[166:169], v193 offset:17408
	ds_read_b128 v[180:183], v193 offset:18432
	ds_read_b128 v[184:187], v193 offset:19456
	ds_read_b128 v[188:191], v193 offset:20480
	ds_read_b128 v[196:199], v193 offset:21504
	ds_read_b128 v[200:203], v193 offset:22528
	ds_read_b128 v[204:207], v193 offset:23552
	global_load_lds_dwordx4 v[208:209], off
	v_lshl_add_u64 v[210:211], v[208:209], 0, s[28:29]
	s_mov_b32 m0, s95
	s_nop 0
	global_load_lds_dwordx4 v[210:211], off
	v_lshl_add_u64 v[210:211], v[208:209], 0, s[30:31]
	s_mov_b32 m0, s40
	s_nop 0
	global_load_lds_dwordx4 v[210:211], off
	v_lshl_add_u64 v[210:211], v[208:209], 0, s[34:35]
	s_mov_b32 m0, s41
	s_nop 0
	global_load_lds_dwordx4 v[210:211], off
	v_lshl_add_u64 v[210:211], s[0:1], 0, v[170:171]
	s_mov_b32 m0, s47
	v_lshl_add_u64 v[212:213], v[210:211], 0, s[28:29]
	global_load_lds_dwordx4 v[210:211], off
	s_mov_b32 m0, s52
	s_nop 0
	global_load_lds_dwordx4 v[212:213], off
	s_waitcnt vmcnt(8)
	s_waitcnt lgkmcnt(0)
	s_barrier
	s_waitcnt lgkmcnt(0)
	s_setprio 1
	v_mfma_f32_16x16x32_bf16 v[62:65], v[74:77], v[162:165], v[62:65]
	v_mfma_f32_16x16x32_bf16 v[58:61], v[90:93], v[162:165], v[58:61]
	v_mfma_f32_16x16x32_bf16 v[46:49], v[74:77], v[180:183], v[46:49]
	v_mfma_f32_16x16x32_bf16 v[42:45], v[90:93], v[180:183], v[42:45]
	v_mfma_f32_16x16x32_bf16 v[30:33], v[74:77], v[188:191], v[30:33]
	v_mfma_f32_16x16x32_bf16 v[26:29], v[90:93], v[188:191], v[26:29]
	v_mfma_f32_16x16x32_bf16 v[14:17], v[74:77], v[200:203], v[14:17]
	v_mfma_f32_16x16x32_bf16 v[10:13], v[90:93], v[200:203], v[10:13]
	v_mfma_f32_16x16x32_bf16 v[62:65], v[82:85], v[166:169], v[62:65]
	v_mfma_f32_16x16x32_bf16 v[58:61], v[94:97], v[166:169], v[58:61]
	v_mfma_f32_16x16x32_bf16 v[46:49], v[82:85], v[184:187], v[46:49]
	v_mfma_f32_16x16x32_bf16 v[42:45], v[94:97], v[184:187], v[42:45]
	v_mfma_f32_16x16x32_bf16 v[30:33], v[82:85], v[196:199], v[30:33]
	v_mfma_f32_16x16x32_bf16 v[26:29], v[94:97], v[196:199], v[26:29]
	v_mfma_f32_16x16x32_bf16 v[14:17], v[82:85], v[204:207], v[14:17]
	v_mfma_f32_16x16x32_bf16 v[10:13], v[94:97], v[204:207], v[10:13]
	v_mfma_f32_16x16x32_bf16 v[54:57], v[138:141], v[162:165], v[54:57]
	v_mfma_f32_16x16x32_bf16 v[50:53], v[154:157], v[162:165], v[50:53]
	v_mfma_f32_16x16x32_bf16 v[38:41], v[138:141], v[180:183], v[38:41]
	v_mfma_f32_16x16x32_bf16 v[34:37], v[154:157], v[180:183], v[34:37]
	v_mfma_f32_16x16x32_bf16 v[22:25], v[138:141], v[188:191], v[22:25]
	v_mfma_f32_16x16x32_bf16 v[18:21], v[154:157], v[188:191], v[18:21]
	v_mfma_f32_16x16x32_bf16 v[6:9], v[138:141], v[200:203], v[6:9]
	v_mfma_f32_16x16x32_bf16 v[2:5], v[154:157], v[200:203], v[2:5]
	v_mfma_f32_16x16x32_bf16 v[54:57], v[150:153], v[166:169], v[54:57]
	v_mfma_f32_16x16x32_bf16 v[50:53], v[158:161], v[166:169], v[50:53]
	v_mfma_f32_16x16x32_bf16 v[38:41], v[150:153], v[184:187], v[38:41]
	v_mfma_f32_16x16x32_bf16 v[34:37], v[158:161], v[184:187], v[34:37]
	v_mfma_f32_16x16x32_bf16 v[22:25], v[150:153], v[196:199], v[22:25]
	v_mfma_f32_16x16x32_bf16 v[18:21], v[158:161], v[196:199], v[18:21]
	v_mfma_f32_16x16x32_bf16 v[6:9], v[150:153], v[204:207], v[6:9]
	v_mfma_f32_16x16x32_bf16 v[2:5], v[158:161], v[204:207], v[2:5]
	s_setprio 0
	s_barrier
; #define PG8_WAIT_V(n) asm volatile("s_waitcnt vmcnt(" #n ")" ::: "memory")
; #define PG8_BAR __builtin_amdgcn_s_barrier()
; template <class Epi, class Sched, bool ALIGN_EPI = true, bool SP2 = true, bool FULLLINE = false, bool NOSTAGE = false, bool FP8 = false>
; __device__ __forceinline__ void gemm_phase(PG8_LAS unsigned char* lds, const Gemm g, const Sched& S, const Epi& E) {
;     ...
;         static_assert(SP2, "only the SP2 loop is kept");
;         { const int t = 0; if constexpr (Epi::NST == 16) PG8_ITER(PG8_WAIT_V(24)); else if constexpr (Epi::NST == 8) PG8_ITER(PG8_WAIT_V(16)); else PG8_ITER(PG8_WAIT_V(8)); }
;         for (int t = 2; t < nt; t += 2) PG8_ITER(PG8_WAIT_V(8));
;     ...
;         if constexpr (ALIGN_EPI) { if (wr == 0) PG8_BAR; }
	ds_read_b128 v[74:77], v194
	ds_read_b128 v[82:85], v194 offset:1024
	ds_read_b128 v[90:93], v194 offset:2048
	ds_read_b128 v[94:97], v194 offset:3072
	ds_read_b128 v[138:141], v195
	ds_read_b128 v[150:153], v195 offset:1024
	ds_read_b128 v[154:157], v195 offset:2048
	ds_read_b128 v[158:161], v195 offset:3072
	s_mov_b32 m0, s53
	v_lshl_add_u64 v[212:213], v[210:211], 0, s[30:31]
	ds_read_b128 v[162:165], v193 offset:32768
	ds_read_b128 v[166:169], v193 offset:33792
	ds_read_b128 v[180:183], v193 offset:34816
	ds_read_b128 v[184:187], v193 offset:35840
	ds_read_b128 v[188:191], v193 offset:36864
	ds_read_b128 v[196:199], v193 offset:37888
	ds_read_b128 v[200:203], v193 offset:38912
	ds_read_b128 v[204:207], v193 offset:39936
	global_load_lds_dwordx4 v[212:213], off
	v_lshl_add_u64 v[212:213], v[210:211], 0, s[34:35]
	s_mov_b32 m0, s54
	s_nop 0
	global_load_lds_dwordx4 v[212:213], off
	s_waitcnt vmcnt(8)
	s_waitcnt lgkmcnt(0)
	s_barrier
	s_waitcnt lgkmcnt(0)
	s_setprio 1
	v_mfma_f32_16x16x32_bf16 v[146:149], v[74:77], v[162:165], v[146:149]
	v_mfma_f32_16x16x32_bf16 v[142:145], v[90:93], v[162:165], v[142:145]
	v_mfma_f32_16x16x32_bf16 v[126:129], v[74:77], v[180:183], v[126:129]
	v_mfma_f32_16x16x32_bf16 v[122:125], v[90:93], v[180:183], v[122:125]
	v_mfma_f32_16x16x32_bf16 v[110:113], v[74:77], v[188:191], v[110:113]
	v_mfma_f32_16x16x32_bf16 v[106:109], v[90:93], v[188:191], v[106:109]
	v_mfma_f32_16x16x32_bf16 v[86:89], v[74:77], v[200:203], v[86:89]
	v_mfma_f32_16x16x32_bf16 v[78:81], v[90:93], v[200:203], v[78:81]
	v_mfma_f32_16x16x32_bf16 v[146:149], v[82:85], v[166:169], v[146:149]
	v_mfma_f32_16x16x32_bf16 v[142:145], v[94:97], v[166:169], v[142:145]
	v_mfma_f32_16x16x32_bf16 v[126:129], v[82:85], v[184:187], v[126:129]
	v_mfma_f32_16x16x32_bf16 v[122:125], v[94:97], v[184:187], v[122:125]
	v_mfma_f32_16x16x32_bf16 v[110:113], v[82:85], v[196:199], v[110:113]
	v_mfma_f32_16x16x32_bf16 v[106:109], v[94:97], v[196:199], v[106:109]
	v_mfma_f32_16x16x32_bf16 v[86:89], v[82:85], v[204:207], v[86:89]
	v_mfma_f32_16x16x32_bf16 v[78:81], v[94:97], v[204:207], v[78:81]
	v_mfma_f32_16x16x32_bf16 v[134:137], v[138:141], v[162:165], v[134:137]
	v_mfma_f32_16x16x32_bf16 v[130:133], v[154:157], v[162:165], v[130:133]
	v_mfma_f32_16x16x32_bf16 v[118:121], v[138:141], v[180:183], v[118:121]
	v_mfma_f32_16x16x32_bf16 v[114:117], v[154:157], v[180:183], v[114:117]
	v_mfma_f32_16x16x32_bf16 v[102:105], v[138:141], v[188:191], v[102:105]
	v_mfma_f32_16x16x32_bf16 v[98:101], v[154:157], v[188:191], v[98:101]
	v_mfma_f32_16x16x32_bf16 v[70:73], v[138:141], v[200:203], v[70:73]
	v_mfma_f32_16x16x32_bf16 v[66:69], v[154:157], v[200:203], v[66:69]
	v_mfma_f32_16x16x32_bf16 v[134:137], v[150:153], v[166:169], v[134:137]
	v_mfma_f32_16x16x32_bf16 v[130:133], v[158:161], v[166:169], v[130:133]
	v_mfma_f32_16x16x32_bf16 v[118:121], v[150:153], v[184:187], v[118:121]
	v_mfma_f32_16x16x32_bf16 v[114:117], v[158:161], v[184:187], v[114:117]
	v_mfma_f32_16x16x32_bf16 v[102:105], v[150:153], v[196:199], v[102:105]
	v_mfma_f32_16x16x32_bf16 v[98:101], v[158:161], v[196:199], v[98:101]
	v_mfma_f32_16x16x32_bf16 v[70:73], v[150:153], v[204:207], v[70:73]
	v_mfma_f32_16x16x32_bf16 v[66:69], v[158:161], v[204:207], v[66:69]
	s_setprio 0
	s_barrier
	s_mov_b32 m0, s50
	v_lshl_add_u64 v[212:213], v[208:209], 0, s[36:37]
	ds_read_b128 v[162:165], v193 offset:49152
	ds_read_b128 v[166:169], v193 offset:50176
	ds_read_b128 v[180:183], v193 offset:51200
	ds_read_b128 v[184:187], v193 offset:52224
	ds_read_b128 v[188:191], v193 offset:53248
	ds_read_b128 v[196:199], v193 offset:54272
	ds_read_b128 v[200:203], v193 offset:55296
	ds_read_b128 v[204:207], v193 offset:56320
	global_load_lds_dwordx4 v[212:213], off
	v_lshl_add_u64 v[212:213], v[208:209], 0, s[38:39]
	s_mov_b32 m0, s51
	s_nop 0
	global_load_lds_dwordx4 v[212:213], off
	v_lshl_add_u64 v[212:213], v[208:209], 0, s[12:13]
	s_mov_b32 m0, s33
	v_lshl_add_u64 v[208:209], v[208:209], 0, s[14:15]
	global_load_lds_dwordx4 v[212:213], off
	s_mov_b32 m0, s56
	s_nop 0
	global_load_lds_dwordx4 v[208:209], off
	v_lshl_add_u64 v[208:209], v[210:211], 0, s[36:37]
	s_mov_b32 m0, s55
	s_nop 0
	global_load_lds_dwordx4 v[208:209], off
	v_lshl_add_u64 v[208:209], v[210:211], 0, s[38:39]
	s_mov_b32 m0, s62
	s_nop 0
	global_load_lds_dwordx4 v[208:209], off
	s_waitcnt vmcnt(8)
	s_waitcnt lgkmcnt(0)
	s_barrier
	s_waitcnt lgkmcnt(0)
	s_setprio 1
	v_mfma_f32_16x16x32_bf16 v[62:65], v[74:77], v[162:165], v[62:65]
	v_mfma_f32_16x16x32_bf16 v[58:61], v[90:93], v[162:165], v[58:61]
	v_mfma_f32_16x16x32_bf16 v[46:49], v[74:77], v[180:183], v[46:49]
	v_mfma_f32_16x16x32_bf16 v[42:45], v[90:93], v[180:183], v[42:45]
	v_mfma_f32_16x16x32_bf16 v[30:33], v[74:77], v[188:191], v[30:33]
	v_mfma_f32_16x16x32_bf16 v[26:29], v[90:93], v[188:191], v[26:29]
	v_mfma_f32_16x16x32_bf16 v[14:17], v[74:77], v[200:203], v[14:17]
	v_mfma_f32_16x16x32_bf16 v[10:13], v[90:93], v[200:203], v[10:13]
	v_mfma_f32_16x16x32_bf16 v[62:65], v[82:85], v[166:169], v[62:65]
	v_mfma_f32_16x16x32_bf16 v[58:61], v[94:97], v[166:169], v[58:61]
	v_mfma_f32_16x16x32_bf16 v[46:49], v[82:85], v[184:187], v[46:49]
	v_mfma_f32_16x16x32_bf16 v[42:45], v[94:97], v[184:187], v[42:45]
	v_mfma_f32_16x16x32_bf16 v[30:33], v[82:85], v[196:199], v[30:33]
	v_mfma_f32_16x16x32_bf16 v[26:29], v[94:97], v[196:199], v[26:29]
	v_mfma_f32_16x16x32_bf16 v[14:17], v[82:85], v[204:207], v[14:17]
	v_mfma_f32_16x16x32_bf16 v[10:13], v[94:97], v[204:207], v[10:13]
	v_mfma_f32_16x16x32_bf16 v[54:57], v[138:141], v[162:165], v[54:57]
	v_mfma_f32_16x16x32_bf16 v[50:53], v[154:157], v[162:165], v[50:53]
	v_mfma_f32_16x16x32_bf16 v[38:41], v[138:141], v[180:183], v[38:41]
	v_mfma_f32_16x16x32_bf16 v[34:37], v[154:157], v[180:183], v[34:37]
	v_mfma_f32_16x16x32_bf16 v[22:25], v[138:141], v[188:191], v[22:25]
	v_mfma_f32_16x16x32_bf16 v[18:21], v[154:157], v[188:191], v[18:21]
	v_mfma_f32_16x16x32_bf16 v[6:9], v[138:141], v[200:203], v[6:9]
	v_mfma_f32_16x16x32_bf16 v[2:5], v[154:157], v[200:203], v[2:5]
	v_mfma_f32_16x16x32_bf16 v[54:57], v[150:153], v[166:169], v[54:57]
	v_mfma_f32_16x16x32_bf16 v[50:53], v[158:161], v[166:169], v[50:53]
	v_mfma_f32_16x16x32_bf16 v[38:41], v[150:153], v[184:187], v[38:41]
	v_mfma_f32_16x16x32_bf16 v[34:37], v[158:161], v[184:187], v[34:37]
	v_mfma_f32_16x16x32_bf16 v[22:25], v[150:153], v[196:199], v[22:25]
	v_mfma_f32_16x16x32_bf16 v[18:21], v[158:161], v[196:199], v[18:21]
	v_mfma_f32_16x16x32_bf16 v[6:9], v[150:153], v[204:207], v[6:9]
	v_mfma_f32_16x16x32_bf16 v[2:5], v[158:161], v[204:207], v[2:5]
	s_setprio 0
	s_barrier
	s_add_i32 s79, s79, 2
	s_add_u32 s76, s76, 0x100
	s_addc_u32 s77, s77, 0
	s_add_u32 s57, s57, 0x100
	s_addc_u32 s78, s78, 0
	s_cmp_gt_u32 s79, 29
	s_cbranch_scc0 .LBB0_1208
	s_and_b64 vcc, exec, s[10:11]
	s_cbranch_vccz .LBB0_1211
	s_barrier

; #define PG8_STAGE(bufoff, gbase, voff) do { if constexpr (!NOSTAGE) _Pragma("unroll") for (int _i = 0; _i < 2; ++_i) \
;         __builtin_amdgcn_global_load_lds((const unsigned*)((const char*)(gbase) + (size_t)_i * pstep##voff + v##voff), (PG8_LAS unsigned*)(lds + (bufoff) + ldsw + _i * 8192), 16, 0, 0); } while (0)
; #define PG8_WAIT_V(n) asm volatile("s_waitcnt vmcnt(" #n ")" ::: "memory")
; #define PG8_BAR __builtin_amdgcn_s_barrier()
; template <class Epi, class Sched, bool ALIGN_EPI = true, bool SP2 = true, bool FULLLINE = false, bool NOSTAGE = false, bool FP8 = false>
; __device__ __forceinline__ void gemm_phase(PG8_LAS unsigned char* lds, const Gemm g, const Sched& S, const Epi& E) {
;     ...
;     const int aoff = lds_byte(wr * 64 + fr, fq * 8), boff = lds_byte(wc * 32 + fr, fq * 8);
;     ...
;     PG8_STAGE(PG8_SB(0, 0), cB, offB); PG8_STAGE(PG8_SB(0, 1), cB + hstepB, offB); PG8_STAGE(PG8_SA(0, 0), cA, offA); PG8_STAGE(PG8_SA(0, 1), cA + hstepA, offA);
;     PG8_STAGE(PG8_SB(1, 0), cB + kstep, offB); PG8_STAGE(PG8_SA(1, 0), cA + kstep, offA); PG8_STAGE(PG8_SB(1, 1), cB + hstepB + kstep, offB);
;     if (wr == 1) PG8_BAR;
;     PG8_WAIT_V(0); PG8_BAR;
;     PG8_BAR;
;     } else {
;     PG8_STAGE(PG8_SB(0, 0), cB, offB); PG8_STAGE(PG8_SA(0, 0), cA, offA); PG8_STAGE(PG8_SB(0, 1), cB + hstepB, offB); PG8_STAGE(PG8_SA(0, 1), cA + hstepA, offA);
;     if (wr == 1) PG8_BAR;
;     PG8_WAIT_V(4); PG8_BAR;
;     PG8_STAGE(PG8_SB(1, 0), cB + kstep, offB); PG8_STAGE(PG8_SA(1, 0), cA + kstep, offA); PG8_STAGE(PG8_SB(1, 1), cB + hstepB + kstep, offB);
;     PG8_WAIT_V(6); PG8_BAR;
;     }
;     if (wr == 1) __builtin_amdgcn_s_setprio(1);
;     for (;;) {
;         const bool has_next = S.next(ui + 1, nxt);
;         const char* nA = has_next ? PG8_ABASE(nxt) : cA; const char* nB = has_next ? PG8_BBASE(nxt) : cB;
.LBB0_1373:
	s_waitcnt vmcnt(0)
	v_cndmask_b32_e64 v4, 0, 1, s[10:11]
	v_cmp_ne_u32_e64 s[6:7], 1, v4
	s_andn2_b64 vcc, exec, s[10:11]
	s_barrier
	s_barrier
	s_cbranch_vccnz .LBB0_1375
.LBB0_1375:
	v_and_b32_e32 v4, 48, v0
	v_lshlrev_b32_e32 v5, 6, v0
	s_movk_i32 s1, 0x3c0
	v_and_or_b32 v4, v5, s1, v4
	v_lshlrev_b32_e32 v5, 2, v0
	s_lshl_b32 s0, s13, 13
	v_and_b32_e32 v5, 32, v5
	v_bitop3_b32 v6, v4, s0, v5 bitop3:0xde
	s_lshl_b32 s0, s12, 5
	s_and_b32 s62, s0, 0x60
	s_lshl_b32 s0, s62, 7
	s_lshl_b32 s55, s13, 6
	v_bitop3_b32 v4, s0, v4, v5 bitop3:0xf6
	v_lshlrev_b32_e32 v5, 9, v0
	s_cmpk_lt_u32 s9, 0x100
	v_and_b32_e32 v5, 0x30000, v5
	v_lshlrev_b32_e32 v3, 12, v3
	s_cselect_b64 s[10:11], -1, 0
	v_or3_b32 v1, v1, v5, v3
	s_add_i32 s83, 0, 0x10000
	s_add_i32 s80, 0, 0x14000
	s_add_i32 s84, 0, 0x18000
	s_add_i32 s85, 0, 0x1c000
	s_sext_i32_i16 s88, s8
	s_ashr_i32 s63, s86, 31
	v_add_u32_e32 v134, v1, v2
	v_mov_b32_e32 v135, 0
	s_mov_b32 s75, 0
	v_mov_b64_e32 v[136:137], 0xb00
	v_mov_b64_e32 v[138:139], 0xaff
	v_add_u32_e32 v1, s83, v4
	v_add_u32_e32 v142, s80, v4
	v_add_u32_e32 v143, 0, v6
	s_mov_b64 s[12:13], 0x80080
	s_add_i32 s81, s45, 0xc000
	s_mov_b64 s[14:15], 0xc0080
	s_add_i32 s82, s45, 0xe000
	s_mov_b64 s[16:17], 0x100
	s_add_i32 s83, s83, s43
	s_mov_b64 s[18:19], 0x40100
	s_mov_b64 s[20:21], 0x80100
	s_mov_b64 s[22:23], 0xc0100
	v_add_u32_e32 v144, s84, v4
	v_add_u32_e32 v145, s85, v4
	s_mov_b64 s[24:25], 0x180
	s_waitcnt lgkmcnt(0)
	s_mov_b64 s[26:27], 0x40180
	s_mov_b64 s[28:29], 0x40000
	s_mov_b64 s[30:31], 0x80000
	s_mov_b64 s[34:35], 0xc0000
	s_mov_b64 s[36:37], 0x80
	s_mov_b64 s[38:39], 0x40080
	s_movk_i32 s87, 0x2c00
	s_branch .LBB0_1378

; template <class Epi, class Sched, bool ALIGN_EPI = true, bool SP2 = true, bool FULLLINE = false, bool NOSTAGE = false, bool FP8 = false>
; __device__ __forceinline__ void gemm_phase(PG8_LAS unsigned char* lds, const Gemm g, const Sched& S, const Epi& E) {
;     ...
;         const bool has_next = S.next(ui + 1, nxt);
;         const char* nA = has_next ? PG8_ABASE(nxt) : cA; const char* nB = has_next ? PG8_BBASE(nxt) : cB;
.LBB0_1380:
	s_ashr_i32 s69, s68, 31
	s_lshl_b64 s[0:1], s[68:69], 20
	s_add_u32 s70, s58, s0
	ds_read_b128 v[2:5], v1
	ds_read_b128 v[6:9], v1 offset:1024
	ds_read_b128 v[10:13], v1 offset:2048
	ds_read_b128 v[14:17], v1 offset:3072
	ds_read_b128 v[18:21], v142
	ds_read_b128 v[22:25], v142 offset:1024
	ds_read_b128 v[26:29], v142 offset:2048
	ds_read_b128 v[30:33], v142 offset:3072
	s_addc_u32 s71, s59, s1
	s_ashr_i32 s67, s66, 31
	s_lshl_b64 s[0:1], s[66:67], 20
	s_add_u32 s72, s3, s0
	s_addc_u32 s73, s42, s1
	s_and_b64 s[0:1], s[8:9], exec
	s_cselect_b32 s67, s71, s79
	s_cselect_b32 s69, s70, s78
	s_cselect_b32 s89, s73, s77
	s_cselect_b32 s90, s72, s76
	v_lshl_add_u64 v[140:141], s[78:79], 0, v[132:133]
	s_mov_b32 m0, s81
	v_lshl_add_u64 v[66:67], v[140:141], 0, s[12:13]
	ds_read_b128 v[34:37], v143
	ds_read_b128 v[38:41], v143 offset:1024
	ds_read_b128 v[42:45], v143 offset:2048
	ds_read_b128 v[46:49], v143 offset:3072
	ds_read_b128 v[50:53], v143 offset:4096
	ds_read_b128 v[54:57], v143 offset:5120
	ds_read_b128 v[58:61], v143 offset:6144
	ds_read_b128 v[62:65], v143 offset:7168
	global_load_lds_dwordx4 v[66:67], off
	v_lshl_add_u64 v[66:67], v[140:141], 0, s[14:15]
	s_mov_b32 m0, s82
	s_nop 0
	global_load_lds_dwordx4 v[66:67], off
	s_waitcnt vmcnt(16)
	s_waitcnt lgkmcnt(0)
	s_barrier
	s_waitcnt lgkmcnt(0)
	s_setprio 1
	v_mfma_f32_16x16x32_bf16 v[86:89], v[10:13], v[50:53], 0
	v_mfma_f32_16x16x32_bf16 v[90:93], v[14:17], v[54:57], v[86:89]
	v_mfma_f32_16x16x32_bf16 v[86:89], v[2:5], v[58:61], 0
	v_mfma_f32_16x16x32_bf16 v[66:69], v[2:5], v[34:37], 0
	v_mfma_f32_16x16x32_bf16 v[70:73], v[10:13], v[34:37], 0
	v_mfma_f32_16x16x32_bf16 v[74:77], v[2:5], v[42:45], 0
	v_mfma_f32_16x16x32_bf16 v[78:81], v[10:13], v[42:45], 0
	v_mfma_f32_16x16x32_bf16 v[82:85], v[2:5], v[50:53], 0
	v_mfma_f32_16x16x32_bf16 v[94:97], v[6:9], v[62:65], v[86:89]
	v_mfma_f32_16x16x32_bf16 v[86:89], v[10:13], v[58:61], 0
	v_mfma_f32_16x16x32_bf16 v[66:69], v[6:9], v[38:41], v[66:69]
	v_mfma_f32_16x16x32_bf16 v[70:73], v[14:17], v[38:41], v[70:73]
	v_mfma_f32_16x16x32_bf16 v[74:77], v[6:9], v[46:49], v[74:77]
	v_mfma_f32_16x16x32_bf16 v[78:81], v[14:17], v[46:49], v[78:81]
	v_mfma_f32_16x16x32_bf16 v[82:85], v[6:9], v[54:57], v[82:85]
	v_mfma_f32_16x16x32_bf16 v[106:109], v[14:17], v[62:65], v[86:89]
	v_mfma_f32_16x16x32_bf16 v[86:89], v[18:21], v[34:37], 0
	v_mfma_f32_16x16x32_bf16 v[34:37], v[26:29], v[34:37], 0
	v_mfma_f32_16x16x32_bf16 v[110:113], v[22:25], v[38:41], v[86:89]
	v_mfma_f32_16x16x32_bf16 v[34:37], v[30:33], v[38:41], v[34:37]
	v_mfma_f32_16x16x32_bf16 v[38:41], v[18:21], v[42:45], 0
	v_mfma_f32_16x16x32_bf16 v[42:45], v[26:29], v[42:45], 0
	v_mfma_f32_16x16x32_bf16 v[38:41], v[22:25], v[46:49], v[38:41]
	v_mfma_f32_16x16x32_bf16 v[42:45], v[30:33], v[46:49], v[42:45]
	v_mfma_f32_16x16x32_bf16 v[46:49], v[18:21], v[50:53], 0
	v_mfma_f32_16x16x32_bf16 v[50:53], v[26:29], v[50:53], 0
	v_mfma_f32_16x16x32_bf16 v[46:49], v[22:25], v[54:57], v[46:49]
	v_mfma_f32_16x16x32_bf16 v[50:53], v[30:33], v[54:57], v[50:53]
	v_mfma_f32_16x16x32_bf16 v[54:57], v[18:21], v[58:61], 0
	v_mfma_f32_16x16x32_bf16 v[58:61], v[26:29], v[58:61], 0
	v_mfma_f32_16x16x32_bf16 v[54:57], v[22:25], v[62:65], v[54:57]
	v_mfma_f32_16x16x32_bf16 v[58:61], v[30:33], v[62:65], v[58:61]
	s_setprio 0
	s_barrier
	v_lshl_add_u64 v[238:239], s[76:77], 0, v[130:131]
	s_mov_b32 m0, s83
	v_lshl_add_u64 v[146:147], v[238:239], 0, s[16:17]
	s_add_i32 s91, s83, 0x2000
	ds_read_b128 v[62:65], v143 offset:16384
	ds_read_b128 v[86:89], v143 offset:17408
	ds_read_b128 v[98:101], v143 offset:18432
	ds_read_b128 v[102:105], v143 offset:19456
	ds_read_b128 v[114:117], v143 offset:20480
	ds_read_b128 v[118:121], v143 offset:21504
	ds_read_b128 v[122:125], v143 offset:22528
	ds_read_b128 v[126:129], v143 offset:23552
	global_load_lds_dwordx4 v[146:147], off
	v_lshl_add_u64 v[146:147], v[238:239], 0, s[18:19]
	s_mov_b32 m0, s91
	s_add_i32 s40, s80, s43
	global_load_lds_dwordx4 v[146:147], off
	v_lshl_add_u64 v[146:147], v[238:239], 0, s[20:21]
	s_mov_b32 m0, s40
	s_add_i32 s41, s40, 0x2000
	global_load_lds_dwordx4 v[146:147], off
	v_lshl_add_u64 v[146:147], v[238:239], 0, s[22:23]
	s_mov_b32 m0, s41
	s_nop 0
	global_load_lds_dwordx4 v[146:147], off
	v_lshl_add_u64 v[146:147], v[140:141], 0, s[16:17]
	s_mov_b32 m0, s45
	s_nop 0
	global_load_lds_dwordx4 v[146:147], off
	v_lshl_add_u64 v[146:147], v[140:141], 0, s[18:19]
	s_mov_b32 m0, s46
	s_nop 0
	global_load_lds_dwordx4 v[146:147], off
	s_waitcnt vmcnt(16)
	s_waitcnt lgkmcnt(0)
	s_barrier
	s_waitcnt lgkmcnt(0)
	s_setprio 1
	v_mfma_f32_16x16x32_bf16 v[146:149], v[2:5], v[62:65], 0
	v_mfma_f32_16x16x32_bf16 v[154:157], v[2:5], v[98:101], 0
	v_mfma_f32_16x16x32_bf16 v[162:165], v[2:5], v[114:117], 0
	v_mfma_f32_16x16x32_bf16 v[2:5], v[2:5], v[122:125], 0
	v_mfma_f32_16x16x32_bf16 v[146:149], v[6:9], v[86:89], v[146:149]
	v_mfma_f32_16x16x32_bf16 v[154:157], v[6:9], v[102:105], v[154:157]
	v_mfma_f32_16x16x32_bf16 v[162:165], v[6:9], v[118:121], v[162:165]
	v_mfma_f32_16x16x32_bf16 v[2:5], v[6:9], v[126:129], v[2:5]
	v_mfma_f32_16x16x32_bf16 v[6:9], v[10:13], v[122:125], 0
	v_mfma_f32_16x16x32_bf16 v[150:153], v[10:13], v[62:65], 0
	v_mfma_f32_16x16x32_bf16 v[158:161], v[10:13], v[98:101], 0
	v_mfma_f32_16x16x32_bf16 v[166:169], v[10:13], v[114:117], 0
	v_mfma_f32_16x16x32_bf16 v[10:13], v[14:17], v[126:129], v[6:9]
	v_mfma_f32_16x16x32_bf16 v[150:153], v[14:17], v[86:89], v[150:153]
	v_mfma_f32_16x16x32_bf16 v[158:161], v[14:17], v[102:105], v[158:161]
	v_mfma_f32_16x16x32_bf16 v[166:169], v[14:17], v[118:121], v[166:169]
	v_mfma_f32_16x16x32_bf16 v[6:9], v[18:21], v[62:65], 0
	v_mfma_f32_16x16x32_bf16 v[14:17], v[22:25], v[86:89], v[6:9]
	v_mfma_f32_16x16x32_bf16 v[6:9], v[26:29], v[62:65], 0
	v_mfma_f32_16x16x32_bf16 v[170:173], v[30:33], v[86:89], v[6:9]
	v_mfma_f32_16x16x32_bf16 v[6:9], v[18:21], v[98:101], 0
	v_mfma_f32_16x16x32_bf16 v[174:177], v[22:25], v[102:105], v[6:9]
	v_mfma_f32_16x16x32_bf16 v[6:9], v[26:29], v[98:101], 0
	v_mfma_f32_16x16x32_bf16 v[178:181], v[30:33], v[102:105], v[6:9]
	v_mfma_f32_16x16x32_bf16 v[6:9], v[18:21], v[114:117], 0
	v_mfma_f32_16x16x32_bf16 v[182:185], v[22:25], v[118:121], v[6:9]
	v_mfma_f32_16x16x32_bf16 v[6:9], v[26:29], v[114:117], 0
	v_mfma_f32_16x16x32_bf16 v[186:189], v[30:33], v[118:121], v[6:9]
	v_mfma_f32_16x16x32_bf16 v[6:9], v[18:21], v[122:125], 0
	v_mfma_f32_16x16x32_bf16 v[190:193], v[22:25], v[126:129], v[6:9]
	v_mfma_f32_16x16x32_bf16 v[6:9], v[26:29], v[122:125], 0
	v_mfma_f32_16x16x32_bf16 v[194:197], v[30:33], v[126:129], v[6:9]
	s_setprio 0
	s_barrier
; #define PG8_WAIT_V(n) asm volatile("s_waitcnt vmcnt(" #n ")" ::: "memory")
; template <class Epi, class Sched, bool ALIGN_EPI = true, bool SP2 = true, bool FULLLINE = false, bool NOSTAGE = false, bool FP8 = false>
; __device__ __forceinline__ void gemm_phase(PG8_LAS unsigned char* lds, const Gemm g, const Sched& S, const Epi& E) {
;     ...
;         static_assert(SP2, "only the SP2 loop is kept");
;         { const int t = 0; if constexpr (Epi::NST == 16) PG8_ITER(PG8_WAIT_V(24)); else if constexpr (Epi::NST == 8) PG8_ITER(PG8_WAIT_V(16)); else PG8_ITER(PG8_WAIT_V(8)); }
;         for (int t = 2; t < nt; t += 2) PG8_ITER(PG8_WAIT_V(8));
	s_nop 5
	ds_read_b128 v[6:9], v144
	ds_read_b128 v[26:29], v144 offset:1024
	ds_read_b128 v[30:33], v144 offset:2048
	ds_read_b128 v[62:65], v144 offset:3072
	ds_read_b128 v[198:201], v145
	ds_read_b128 v[202:205], v145 offset:1024
	ds_read_b128 v[206:209], v145 offset:2048
	ds_read_b128 v[210:213], v145 offset:3072
	s_mov_b32 m0, s47
	v_lshl_add_u64 v[86:87], v[140:141], 0, s[20:21]
	ds_read_b128 v[18:21], v143 offset:32768
	ds_read_b128 v[22:25], v143 offset:33792
	ds_read_b128 v[214:217], v143 offset:34816
	ds_read_b128 v[218:221], v143 offset:35840
	ds_read_b128 v[222:225], v143 offset:36864
	ds_read_b128 v[226:229], v143 offset:37888
	ds_read_b128 v[230:233], v143 offset:38912
	ds_read_b128 v[234:237], v143 offset:39936
	global_load_lds_dwordx4 v[86:87], off
	v_lshl_add_u64 v[86:87], v[140:141], 0, s[22:23]
	s_mov_b32 m0, s52
	s_nop 0
	global_load_lds_dwordx4 v[86:87], off
	s_waitcnt vmcnt(8)
	s_waitcnt lgkmcnt(0)
	s_barrier
	s_waitcnt lgkmcnt(0)
	s_setprio 1
	v_mfma_f32_16x16x32_bf16 v[66:69], v[6:9], v[18:21], v[66:69]
	v_mfma_f32_16x16x32_bf16 v[118:121], v[26:29], v[22:25], v[66:69]
	v_mfma_f32_16x16x32_bf16 v[66:69], v[30:33], v[18:21], v[70:73]
	v_mfma_f32_16x16x32_bf16 v[114:117], v[62:65], v[22:25], v[66:69]
	v_mfma_f32_16x16x32_bf16 v[66:69], v[6:9], v[214:217], v[74:77]
	v_mfma_f32_16x16x32_bf16 v[102:105], v[26:29], v[218:221], v[66:69]
	v_mfma_f32_16x16x32_bf16 v[66:69], v[30:33], v[214:217], v[78:81]
	v_mfma_f32_16x16x32_bf16 v[98:101], v[62:65], v[218:221], v[66:69]
	v_mfma_f32_16x16x32_bf16 v[66:69], v[6:9], v[222:225], v[82:85]
	v_mfma_f32_16x16x32_bf16 v[86:89], v[26:29], v[226:229], v[66:69]
	v_mfma_f32_16x16x32_bf16 v[66:69], v[30:33], v[222:225], v[90:93]
	v_mfma_f32_16x16x32_bf16 v[82:85], v[62:65], v[226:229], v[66:69]
	v_mfma_f32_16x16x32_bf16 v[66:69], v[6:9], v[230:233], v[94:97]
	v_mfma_f32_16x16x32_bf16 v[70:73], v[26:29], v[234:237], v[66:69]
	v_mfma_f32_16x16x32_bf16 v[66:69], v[30:33], v[230:233], v[106:109]
	v_mfma_f32_16x16x32_bf16 v[66:69], v[62:65], v[234:237], v[66:69]
	v_mfma_f32_16x16x32_bf16 v[74:77], v[198:201], v[18:21], v[110:113]
	v_mfma_f32_16x16x32_bf16 v[18:21], v[206:209], v[18:21], v[34:37]
	v_mfma_f32_16x16x32_bf16 v[122:125], v[210:213], v[22:25], v[18:21]
	v_mfma_f32_16x16x32_bf16 v[18:21], v[198:201], v[214:217], v[38:41]
	v_mfma_f32_16x16x32_bf16 v[110:113], v[202:205], v[218:221], v[18:21]
	v_mfma_f32_16x16x32_bf16 v[18:21], v[206:209], v[214:217], v[42:45]
	v_mfma_f32_16x16x32_bf16 v[106:109], v[210:213], v[218:221], v[18:21]
	v_mfma_f32_16x16x32_bf16 v[18:21], v[198:201], v[222:225], v[46:49]
	v_mfma_f32_16x16x32_bf16 v[94:97], v[202:205], v[226:229], v[18:21]
	v_mfma_f32_16x16x32_bf16 v[18:21], v[206:209], v[222:225], v[50:53]
	v_mfma_f32_16x16x32_bf16 v[90:93], v[210:213], v[226:229], v[18:21]
	v_mfma_f32_16x16x32_bf16 v[18:21], v[198:201], v[230:233], v[54:57]
	v_mfma_f32_16x16x32_bf16 v[78:81], v[202:205], v[234:237], v[18:21]
	v_mfma_f32_16x16x32_bf16 v[18:21], v[206:209], v[230:233], v[58:61]
	v_mfma_f32_16x16x32_bf16 v[126:129], v[202:205], v[22:25], v[74:77]
	v_mfma_f32_16x16x32_bf16 v[74:77], v[210:213], v[234:237], v[18:21]
	s_setprio 0
	s_barrier
	s_add_i32 s50, s84, s43
	s_nop 3
	v_lshl_add_u64 v[18:19], v[238:239], 0, s[24:25]
	s_mov_b32 m0, s50
	s_add_i32 s51, s50, 0x2000
	ds_read_b128 v[42:45], v143 offset:49152
	ds_read_b128 v[46:49], v143 offset:50176
	ds_read_b128 v[214:217], v143 offset:51200
	ds_read_b128 v[218:221], v143 offset:52224
	ds_read_b128 v[222:225], v143 offset:53248
	ds_read_b128 v[226:229], v143 offset:54272
	ds_read_b128 v[230:233], v143 offset:55296
	ds_read_b128 v[234:237], v143 offset:56320
	global_load_lds_dwordx4 v[18:19], off
	v_lshl_add_u64 v[18:19], v[238:239], 0, s[26:27]
	s_mov_b32 m0, s51
	s_mov_b64 s[0:1], 0x80180
	s_add_i32 s33, s85, s43
	global_load_lds_dwordx4 v[18:19], off
	v_lshl_add_u64 v[18:19], v[238:239], 0, s[0:1]
	s_mov_b32 m0, s33
	s_mov_b64 s[0:1], 0xc0180
	s_add_i32 s56, s33, 0x2000
	global_load_lds_dwordx4 v[18:19], off
	v_lshl_add_u64 v[18:19], v[238:239], 0, s[0:1]
	s_mov_b32 m0, s56
	s_nop 0
	global_load_lds_dwordx4 v[18:19], off
	v_lshl_add_u64 v[18:19], v[140:141], 0, s[24:25]
	s_mov_b32 m0, s53
	s_nop 0
	global_load_lds_dwordx4 v[18:19], off
	v_lshl_add_u64 v[18:19], v[140:141], 0, s[26:27]
	s_mov_b32 m0, s54
	s_nop 0
	global_load_lds_dwordx4 v[18:19], off
	s_waitcnt vmcnt(8)
	s_waitcnt lgkmcnt(0)
	s_barrier
	s_waitcnt lgkmcnt(0)
	s_setprio 1
	v_mfma_f32_16x16x32_bf16 v[18:21], v[6:9], v[42:45], v[146:149]
	v_mfma_f32_16x16x32_bf16 v[54:57], v[26:29], v[46:49], v[18:21]
	v_mfma_f32_16x16x32_bf16 v[18:21], v[30:33], v[42:45], v[150:153]
	v_mfma_f32_16x16x32_bf16 v[50:53], v[62:65], v[46:49], v[18:21]
	v_mfma_f32_16x16x32_bf16 v[18:21], v[6:9], v[214:217], v[154:157]
	v_mfma_f32_16x16x32_bf16 v[38:41], v[26:29], v[218:221], v[18:21]
	v_mfma_f32_16x16x32_bf16 v[18:21], v[30:33], v[214:217], v[158:161]
	v_mfma_f32_16x16x32_bf16 v[34:37], v[62:65], v[218:221], v[18:21]
	v_mfma_f32_16x16x32_bf16 v[18:21], v[6:9], v[222:225], v[162:165]
	v_mfma_f32_16x16x32_bf16 v[2:5], v[6:9], v[230:233], v[2:5]
	v_mfma_f32_16x16x32_bf16 v[22:25], v[26:29], v[226:229], v[18:21]
	v_mfma_f32_16x16x32_bf16 v[18:21], v[30:33], v[222:225], v[166:169]
	v_mfma_f32_16x16x32_bf16 v[6:9], v[26:29], v[234:237], v[2:5]
	v_mfma_f32_16x16x32_bf16 v[2:5], v[30:33], v[230:233], v[10:13]
	v_mfma_f32_16x16x32_bf16 v[18:21], v[62:65], v[226:229], v[18:21]
	v_mfma_f32_16x16x32_bf16 v[2:5], v[62:65], v[234:237], v[2:5]
	v_mfma_f32_16x16x32_bf16 v[10:13], v[198:201], v[42:45], v[14:17]
	v_mfma_f32_16x16x32_bf16 v[62:65], v[202:205], v[46:49], v[10:13]
	v_mfma_f32_16x16x32_bf16 v[10:13], v[206:209], v[42:45], v[170:173]
	v_mfma_f32_16x16x32_bf16 v[58:61], v[210:213], v[46:49], v[10:13]
	v_mfma_f32_16x16x32_bf16 v[10:13], v[198:201], v[214:217], v[174:177]
	v_mfma_f32_16x16x32_bf16 v[46:49], v[202:205], v[218:221], v[10:13]
	v_mfma_f32_16x16x32_bf16 v[10:13], v[206:209], v[214:217], v[178:181]
	v_mfma_f32_16x16x32_bf16 v[42:45], v[210:213], v[218:221], v[10:13]
	v_mfma_f32_16x16x32_bf16 v[10:13], v[198:201], v[222:225], v[182:185]
	v_mfma_f32_16x16x32_bf16 v[30:33], v[202:205], v[226:229], v[10:13]
	v_mfma_f32_16x16x32_bf16 v[10:13], v[206:209], v[222:225], v[186:189]
	v_mfma_f32_16x16x32_bf16 v[26:29], v[210:213], v[226:229], v[10:13]
	v_mfma_f32_16x16x32_bf16 v[10:13], v[198:201], v[230:233], v[190:193]
	v_mfma_f32_16x16x32_bf16 v[14:17], v[202:205], v[234:237], v[10:13]
	v_mfma_f32_16x16x32_bf16 v[10:13], v[206:209], v[230:233], v[194:197]
	v_mfma_f32_16x16x32_bf16 v[10:13], v[210:213], v[234:237], v[10:13]
	s_setprio 0
	s_barrier
	s_add_u32 s78, s78, 0x80180
	s_addc_u32 s79, s79, 0
	s_add_u32 s57, s76, 0x200
	s_addc_u32 s76, s77, 0
	s_mov_b32 s77, 0
.LBB0_1381:
	ds_read_b128 v[146:149], v1
	ds_read_b128 v[150:153], v1 offset:1024
	ds_read_b128 v[154:157], v1 offset:2048
	ds_read_b128 v[158:161], v1 offset:3072
	ds_read_b128 v[162:165], v142
	ds_read_b128 v[166:169], v142 offset:1024
	ds_read_b128 v[170:173], v142 offset:2048
	ds_read_b128 v[174:177], v142 offset:3072
	s_add_u32 s0, s78, 0xfff80080
	s_addc_u32 s1, s79, -1
	s_cmp_eq_u32 s77, 28
	s_cselect_b32 s1, s67, s1
	s_cselect_b32 s0, s69, s0
	s_cselect_b32 s65, s89, s76
	s_cselect_b32 s64, s90, s57
	s_mov_b32 m0, s81
	v_lshl_add_u64 v[140:141], s[78:79], 0, v[134:135]
	ds_read_b128 v[178:181], v143
	ds_read_b128 v[182:185], v143 offset:1024
	ds_read_b128 v[186:189], v143 offset:2048
	ds_read_b128 v[190:193], v143 offset:3072
	ds_read_b128 v[194:197], v143 offset:4096
	ds_read_b128 v[198:201], v143 offset:5120
	ds_read_b128 v[202:205], v143 offset:6144
	ds_read_b128 v[206:209], v143 offset:7168
	global_load_lds_dwordx4 v[140:141], off
	v_lshl_add_u64 v[140:141], v[140:141], 0, s[28:29]
	s_mov_b32 m0, s82
	s_nop 0
	global_load_lds_dwordx4 v[140:141], off
	s_waitcnt vmcnt(8)
	s_waitcnt lgkmcnt(0)
	s_barrier
	s_waitcnt lgkmcnt(0)
	s_setprio 1
	v_mfma_f32_16x16x32_bf16 v[118:121], v[146:149], v[178:181], v[118:121]
	v_mfma_f32_16x16x32_bf16 v[114:117], v[154:157], v[178:181], v[114:117]
	v_mfma_f32_16x16x32_bf16 v[102:105], v[146:149], v[186:189], v[102:105]
	v_mfma_f32_16x16x32_bf16 v[98:101], v[154:157], v[186:189], v[98:101]
	v_mfma_f32_16x16x32_bf16 v[86:89], v[146:149], v[194:197], v[86:89]
	v_mfma_f32_16x16x32_bf16 v[82:85], v[154:157], v[194:197], v[82:85]
	v_mfma_f32_16x16x32_bf16 v[70:73], v[146:149], v[202:205], v[70:73]
	v_mfma_f32_16x16x32_bf16 v[66:69], v[154:157], v[202:205], v[66:69]
	v_mfma_f32_16x16x32_bf16 v[118:121], v[150:153], v[182:185], v[118:121]
	v_mfma_f32_16x16x32_bf16 v[114:117], v[158:161], v[182:185], v[114:117]
	v_mfma_f32_16x16x32_bf16 v[102:105], v[150:153], v[190:193], v[102:105]
	v_mfma_f32_16x16x32_bf16 v[98:101], v[158:161], v[190:193], v[98:101]
	v_mfma_f32_16x16x32_bf16 v[86:89], v[150:153], v[198:201], v[86:89]
	v_mfma_f32_16x16x32_bf16 v[82:85], v[158:161], v[198:201], v[82:85]
	v_mfma_f32_16x16x32_bf16 v[70:73], v[150:153], v[206:209], v[70:73]
	v_mfma_f32_16x16x32_bf16 v[66:69], v[158:161], v[206:209], v[66:69]
	v_mfma_f32_16x16x32_bf16 v[126:129], v[162:165], v[178:181], v[126:129]
	v_mfma_f32_16x16x32_bf16 v[122:125], v[170:173], v[178:181], v[122:125]
	v_mfma_f32_16x16x32_bf16 v[110:113], v[162:165], v[186:189], v[110:113]
	v_mfma_f32_16x16x32_bf16 v[106:109], v[170:173], v[186:189], v[106:109]
	v_mfma_f32_16x16x32_bf16 v[94:97], v[162:165], v[194:197], v[94:97]
	v_mfma_f32_16x16x32_bf16 v[90:93], v[170:173], v[194:197], v[90:93]
	v_mfma_f32_16x16x32_bf16 v[78:81], v[162:165], v[202:205], v[78:81]
	v_mfma_f32_16x16x32_bf16 v[74:77], v[170:173], v[202:205], v[74:77]
	v_mfma_f32_16x16x32_bf16 v[126:129], v[166:169], v[182:185], v[126:129]
	v_mfma_f32_16x16x32_bf16 v[122:125], v[174:177], v[182:185], v[122:125]
	v_mfma_f32_16x16x32_bf16 v[110:113], v[166:169], v[190:193], v[110:113]
	v_mfma_f32_16x16x32_bf16 v[106:109], v[174:177], v[190:193], v[106:109]
	v_mfma_f32_16x16x32_bf16 v[94:97], v[166:169], v[198:201], v[94:97]
	v_mfma_f32_16x16x32_bf16 v[90:93], v[174:177], v[198:201], v[90:93]
	v_mfma_f32_16x16x32_bf16 v[78:81], v[166:169], v[206:209], v[78:81]
	v_mfma_f32_16x16x32_bf16 v[74:77], v[174:177], v[206:209], v[74:77]
	s_setprio 0
	s_barrier
	s_mov_b32 m0, s83
	v_lshl_add_u64 v[140:141], s[64:65], 0, v[130:131]
	ds_read_b128 v[178:181], v143 offset:16384
	ds_read_b128 v[182:185], v143 offset:17408
	ds_read_b128 v[186:189], v143 offset:18432
	ds_read_b128 v[190:193], v143 offset:19456
	ds_read_b128 v[194:197], v143 offset:20480
	ds_read_b128 v[198:201], v143 offset:21504
	ds_read_b128 v[202:205], v143 offset:22528
	ds_read_b128 v[206:209], v143 offset:23552
	global_load_lds_dwordx4 v[140:141], off
	v_lshl_add_u64 v[210:211], v[140:141], 0, s[28:29]
	s_mov_b32 m0, s91
	s_nop 0
	global_load_lds_dwordx4 v[210:211], off
	v_lshl_add_u64 v[210:211], v[140:141], 0, s[30:31]
	s_mov_b32 m0, s40
	s_nop 0
	global_load_lds_dwordx4 v[210:211], off
	v_lshl_add_u64 v[210:211], v[140:141], 0, s[34:35]
	s_mov_b32 m0, s41
	s_nop 0
	global_load_lds_dwordx4 v[210:211], off
	v_lshl_add_u64 v[210:211], s[0:1], 0, v[132:133]
	s_mov_b32 m0, s45
	v_lshl_add_u64 v[212:213], v[210:211], 0, s[28:29]
	global_load_lds_dwordx4 v[210:211], off
	s_mov_b32 m0, s46
	s_nop 0
	global_load_lds_dwordx4 v[212:213], off
	s_waitcnt vmcnt(8)
	s_waitcnt lgkmcnt(0)
	s_barrier
	s_waitcnt lgkmcnt(0)
	s_setprio 1
	v_mfma_f32_16x16x32_bf16 v[54:57], v[146:149], v[178:181], v[54:57]
	v_mfma_f32_16x16x32_bf16 v[50:53], v[154:157], v[178:181], v[50:53]
	v_mfma_f32_16x16x32_bf16 v[38:41], v[146:149], v[186:189], v[38:41]
	v_mfma_f32_16x16x32_bf16 v[34:37], v[154:157], v[186:189], v[34:37]
	v_mfma_f32_16x16x32_bf16 v[22:25], v[146:149], v[194:197], v[22:25]
	v_mfma_f32_16x16x32_bf16 v[18:21], v[154:157], v[194:197], v[18:21]
	v_mfma_f32_16x16x32_bf16 v[6:9], v[146:149], v[202:205], v[6:9]
	v_mfma_f32_16x16x32_bf16 v[2:5], v[154:157], v[202:205], v[2:5]
	v_mfma_f32_16x16x32_bf16 v[54:57], v[150:153], v[182:185], v[54:57]
	v_mfma_f32_16x16x32_bf16 v[50:53], v[158:161], v[182:185], v[50:53]
	v_mfma_f32_16x16x32_bf16 v[38:41], v[150:153], v[190:193], v[38:41]
	v_mfma_f32_16x16x32_bf16 v[34:37], v[158:161], v[190:193], v[34:37]
	v_mfma_f32_16x16x32_bf16 v[22:25], v[150:153], v[198:201], v[22:25]
	v_mfma_f32_16x16x32_bf16 v[18:21], v[158:161], v[198:201], v[18:21]
	v_mfma_f32_16x16x32_bf16 v[6:9], v[150:153], v[206:209], v[6:9]
	v_mfma_f32_16x16x32_bf16 v[2:5], v[158:161], v[206:209], v[2:5]
	v_mfma_f32_16x16x32_bf16 v[62:65], v[162:165], v[178:181], v[62:65]
	v_mfma_f32_16x16x32_bf16 v[58:61], v[170:173], v[178:181], v[58:61]
	v_mfma_f32_16x16x32_bf16 v[46:49], v[162:165], v[186:189], v[46:49]
	v_mfma_f32_16x16x32_bf16 v[42:45], v[170:173], v[186:189], v[42:45]
	v_mfma_f32_16x16x32_bf16 v[30:33], v[162:165], v[194:197], v[30:33]
	v_mfma_f32_16x16x32_bf16 v[26:29], v[170:173], v[194:197], v[26:29]
	v_mfma_f32_16x16x32_bf16 v[14:17], v[162:165], v[202:205], v[14:17]
	v_mfma_f32_16x16x32_bf16 v[10:13], v[170:173], v[202:205], v[10:13]
	v_mfma_f32_16x16x32_bf16 v[62:65], v[166:169], v[182:185], v[62:65]
	v_mfma_f32_16x16x32_bf16 v[58:61], v[174:177], v[182:185], v[58:61]
	v_mfma_f32_16x16x32_bf16 v[46:49], v[166:169], v[190:193], v[46:49]
	v_mfma_f32_16x16x32_bf16 v[42:45], v[174:177], v[190:193], v[42:45]
	v_mfma_f32_16x16x32_bf16 v[30:33], v[166:169], v[198:201], v[30:33]
	v_mfma_f32_16x16x32_bf16 v[26:29], v[174:177], v[198:201], v[26:29]
	v_mfma_f32_16x16x32_bf16 v[14:17], v[166:169], v[206:209], v[14:17]
	v_mfma_f32_16x16x32_bf16 v[10:13], v[174:177], v[206:209], v[10:13]
	s_setprio 0
	s_barrier
	ds_read_b128 v[146:149], v144
	ds_read_b128 v[150:153], v144 offset:1024
	ds_read_b128 v[154:157], v144 offset:2048
	ds_read_b128 v[158:161], v144 offset:3072
	ds_read_b128 v[162:165], v145
	ds_read_b128 v[166:169], v145 offset:1024
	ds_read_b128 v[170:173], v145 offset:2048
	ds_read_b128 v[174:177], v145 offset:3072
	s_mov_b32 m0, s47
	v_lshl_add_u64 v[212:213], v[210:211], 0, s[30:31]
	ds_read_b128 v[178:181], v143 offset:32768
	ds_read_b128 v[182:185], v143 offset:33792
	ds_read_b128 v[186:189], v143 offset:34816
	ds_read_b128 v[190:193], v143 offset:35840
	ds_read_b128 v[194:197], v143 offset:36864
	ds_read_b128 v[198:201], v143 offset:37888
	ds_read_b128 v[202:205], v143 offset:38912
	ds_read_b128 v[206:209], v143 offset:39936
	global_load_lds_dwordx4 v[212:213], off
	v_lshl_add_u64 v[212:213], v[210:211], 0, s[34:35]
	s_mov_b32 m0, s52
	s_nop 0
	global_load_lds_dwordx4 v[212:213], off
	s_waitcnt vmcnt(8)
	s_waitcnt lgkmcnt(0)
	s_barrier
	s_waitcnt lgkmcnt(0)
	s_setprio 1
	v_mfma_f32_16x16x32_bf16 v[118:121], v[146:149], v[178:181], v[118:121]
	v_mfma_f32_16x16x32_bf16 v[114:117], v[154:157], v[178:181], v[114:117]
	v_mfma_f32_16x16x32_bf16 v[102:105], v[146:149], v[186:189], v[102:105]
	v_mfma_f32_16x16x32_bf16 v[98:101], v[154:157], v[186:189], v[98:101]
	v_mfma_f32_16x16x32_bf16 v[86:89], v[146:149], v[194:197], v[86:89]
	v_mfma_f32_16x16x32_bf16 v[82:85], v[154:157], v[194:197], v[82:85]
	v_mfma_f32_16x16x32_bf16 v[70:73], v[146:149], v[202:205], v[70:73]
	v_mfma_f32_16x16x32_bf16 v[66:69], v[154:157], v[202:205], v[66:69]
	v_mfma_f32_16x16x32_bf16 v[118:121], v[150:153], v[182:185], v[118:121]
	v_mfma_f32_16x16x32_bf16 v[114:117], v[158:161], v[182:185], v[114:117]
	v_mfma_f32_16x16x32_bf16 v[102:105], v[150:153], v[190:193], v[102:105]
	v_mfma_f32_16x16x32_bf16 v[98:101], v[158:161], v[190:193], v[98:101]
	v_mfma_f32_16x16x32_bf16 v[86:89], v[150:153], v[198:201], v[86:89]
	v_mfma_f32_16x16x32_bf16 v[82:85], v[158:161], v[198:201], v[82:85]
	v_mfma_f32_16x16x32_bf16 v[70:73], v[150:153], v[206:209], v[70:73]
	v_mfma_f32_16x16x32_bf16 v[66:69], v[158:161], v[206:209], v[66:69]
	v_mfma_f32_16x16x32_bf16 v[126:129], v[162:165], v[178:181], v[126:129]
	v_mfma_f32_16x16x32_bf16 v[122:125], v[170:173], v[178:181], v[122:125]
	v_mfma_f32_16x16x32_bf16 v[110:113], v[162:165], v[186:189], v[110:113]
	v_mfma_f32_16x16x32_bf16 v[106:109], v[170:173], v[186:189], v[106:109]
	v_mfma_f32_16x16x32_bf16 v[94:97], v[162:165], v[194:197], v[94:97]
	v_mfma_f32_16x16x32_bf16 v[90:93], v[170:173], v[194:197], v[90:93]
	v_mfma_f32_16x16x32_bf16 v[78:81], v[162:165], v[202:205], v[78:81]
	v_mfma_f32_16x16x32_bf16 v[74:77], v[170:173], v[202:205], v[74:77]
	v_mfma_f32_16x16x32_bf16 v[126:129], v[166:169], v[182:185], v[126:129]
	v_mfma_f32_16x16x32_bf16 v[122:125], v[174:177], v[182:185], v[122:125]
	v_mfma_f32_16x16x32_bf16 v[110:113], v[166:169], v[190:193], v[110:113]
	v_mfma_f32_16x16x32_bf16 v[106:109], v[174:177], v[190:193], v[106:109]
	v_mfma_f32_16x16x32_bf16 v[94:97], v[166:169], v[198:201], v[94:97]
	v_mfma_f32_16x16x32_bf16 v[90:93], v[174:177], v[198:201], v[90:93]
	v_mfma_f32_16x16x32_bf16 v[78:81], v[166:169], v[206:209], v[78:81]
	v_mfma_f32_16x16x32_bf16 v[74:77], v[174:177], v[206:209], v[74:77]
	s_setprio 0
	s_barrier
; #define PG8_WAIT_V(n) asm volatile("s_waitcnt vmcnt(" #n ")" ::: "memory")
; #define PG8_BAR __builtin_amdgcn_s_barrier()
; template <class Epi, class Sched, bool ALIGN_EPI = true, bool SP2 = true, bool FULLLINE = false, bool NOSTAGE = false, bool FP8 = false>
; __device__ __forceinline__ void gemm_phase(PG8_LAS unsigned char* lds, const Gemm g, const Sched& S, const Epi& E) {
;     ...
;         static_assert(SP2, "only the SP2 loop is kept");
;         { const int t = 0; if constexpr (Epi::NST == 16) PG8_ITER(PG8_WAIT_V(24)); else if constexpr (Epi::NST == 8) PG8_ITER(PG8_WAIT_V(16)); else PG8_ITER(PG8_WAIT_V(8)); }
;         for (int t = 2; t < nt; t += 2) PG8_ITER(PG8_WAIT_V(8));
;     ...
;         if constexpr (ALIGN_EPI) { if (wr == 0) PG8_BAR; }
	s_mov_b32 m0, s50
	v_lshl_add_u64 v[212:213], v[140:141], 0, s[36:37]
	ds_read_b128 v[178:181], v143 offset:49152
	ds_read_b128 v[182:185], v143 offset:50176
	ds_read_b128 v[186:189], v143 offset:51200
	ds_read_b128 v[190:193], v143 offset:52224
	ds_read_b128 v[194:197], v143 offset:53248
	ds_read_b128 v[198:201], v143 offset:54272
	ds_read_b128 v[202:205], v143 offset:55296
	ds_read_b128 v[206:209], v143 offset:56320
	global_load_lds_dwordx4 v[212:213], off
	v_lshl_add_u64 v[212:213], v[140:141], 0, s[38:39]
	s_mov_b32 m0, s51
	s_nop 0
	global_load_lds_dwordx4 v[212:213], off
	v_lshl_add_u64 v[212:213], v[140:141], 0, s[12:13]
	s_mov_b32 m0, s33
	v_lshl_add_u64 v[140:141], v[140:141], 0, s[14:15]
	global_load_lds_dwordx4 v[212:213], off
	s_mov_b32 m0, s56
	s_nop 0
	global_load_lds_dwordx4 v[140:141], off
	v_lshl_add_u64 v[140:141], v[210:211], 0, s[36:37]
	s_mov_b32 m0, s53
	s_nop 0
	global_load_lds_dwordx4 v[140:141], off
	v_lshl_add_u64 v[140:141], v[210:211], 0, s[38:39]
	s_mov_b32 m0, s54
	s_nop 0
	global_load_lds_dwordx4 v[140:141], off
	s_waitcnt vmcnt(8)
	s_waitcnt lgkmcnt(0)
	s_barrier
	s_waitcnt lgkmcnt(0)
	s_setprio 1
	v_mfma_f32_16x16x32_bf16 v[54:57], v[146:149], v[178:181], v[54:57]
	v_mfma_f32_16x16x32_bf16 v[50:53], v[154:157], v[178:181], v[50:53]
	v_mfma_f32_16x16x32_bf16 v[38:41], v[146:149], v[186:189], v[38:41]
	v_mfma_f32_16x16x32_bf16 v[34:37], v[154:157], v[186:189], v[34:37]
	v_mfma_f32_16x16x32_bf16 v[22:25], v[146:149], v[194:197], v[22:25]
	v_mfma_f32_16x16x32_bf16 v[18:21], v[154:157], v[194:197], v[18:21]
	v_mfma_f32_16x16x32_bf16 v[6:9], v[146:149], v[202:205], v[6:9]
	v_mfma_f32_16x16x32_bf16 v[2:5], v[154:157], v[202:205], v[2:5]
	v_mfma_f32_16x16x32_bf16 v[54:57], v[150:153], v[182:185], v[54:57]
	v_mfma_f32_16x16x32_bf16 v[50:53], v[158:161], v[182:185], v[50:53]
	v_mfma_f32_16x16x32_bf16 v[38:41], v[150:153], v[190:193], v[38:41]
	v_mfma_f32_16x16x32_bf16 v[34:37], v[158:161], v[190:193], v[34:37]
	v_mfma_f32_16x16x32_bf16 v[22:25], v[150:153], v[198:201], v[22:25]
	v_mfma_f32_16x16x32_bf16 v[18:21], v[158:161], v[198:201], v[18:21]
	v_mfma_f32_16x16x32_bf16 v[6:9], v[150:153], v[206:209], v[6:9]
	v_mfma_f32_16x16x32_bf16 v[2:5], v[158:161], v[206:209], v[2:5]
	v_mfma_f32_16x16x32_bf16 v[62:65], v[162:165], v[178:181], v[62:65]
	v_mfma_f32_16x16x32_bf16 v[58:61], v[170:173], v[178:181], v[58:61]
	v_mfma_f32_16x16x32_bf16 v[46:49], v[162:165], v[186:189], v[46:49]
	v_mfma_f32_16x16x32_bf16 v[42:45], v[170:173], v[186:189], v[42:45]
	v_mfma_f32_16x16x32_bf16 v[30:33], v[162:165], v[194:197], v[30:33]
	v_mfma_f32_16x16x32_bf16 v[26:29], v[170:173], v[194:197], v[26:29]
	v_mfma_f32_16x16x32_bf16 v[14:17], v[162:165], v[202:205], v[14:17]
	v_mfma_f32_16x16x32_bf16 v[10:13], v[170:173], v[202:205], v[10:13]
	v_mfma_f32_16x16x32_bf16 v[62:65], v[166:169], v[182:185], v[62:65]
	v_mfma_f32_16x16x32_bf16 v[58:61], v[174:177], v[182:185], v[58:61]
	v_mfma_f32_16x16x32_bf16 v[46:49], v[166:169], v[190:193], v[46:49]
	v_mfma_f32_16x16x32_bf16 v[42:45], v[174:177], v[190:193], v[42:45]
	v_mfma_f32_16x16x32_bf16 v[30:33], v[166:169], v[198:201], v[30:33]
	v_mfma_f32_16x16x32_bf16 v[26:29], v[174:177], v[198:201], v[26:29]
	v_mfma_f32_16x16x32_bf16 v[14:17], v[166:169], v[206:209], v[14:17]
	v_mfma_f32_16x16x32_bf16 v[10:13], v[174:177], v[206:209], v[10:13]
	s_setprio 0
	s_barrier
	s_add_i32 s77, s77, 2
	s_add_u32 s78, s78, 0x100
	s_addc_u32 s79, s79, 0
	s_add_u32 s57, s57, 0x100
	s_addc_u32 s76, s76, 0
	s_cmp_gt_u32 s77, 29
	s_cbranch_scc0 .LBB0_1381
	s_and_b64 vcc, exec, s[10:11]
	s_cbranch_vccz .LBB0_1384
	s_barrier

; #define PG8_STAGE(bufoff, gbase, voff) do { if constexpr (!NOSTAGE) _Pragma("unroll") for (int _i = 0; _i < 2; ++_i) \
;         __builtin_amdgcn_global_load_lds((const unsigned*)((const char*)(gbase) + (size_t)_i * pstep##voff + v##voff), (PG8_LAS unsigned*)(lds + (bufoff) + ldsw + _i * 8192), 16, 0, 0); } while (0)
; #define PG8_WAIT_V(n) asm volatile("s_waitcnt vmcnt(" #n ")" ::: "memory")
; #define PG8_BAR __builtin_amdgcn_s_barrier()
; template <class Epi, class Sched, bool ALIGN_EPI = true, bool SP2 = true, bool FULLLINE = false, bool NOSTAGE = false, bool FP8 = false>
; __device__ __forceinline__ void gemm_phase(PG8_LAS unsigned char* lds, const Gemm g, const Sched& S, const Epi& E) {
;     ...
;     const int aoff = lds_byte(wr * 64 + fr, fq * 8), boff = lds_byte(wc * 32 + fr, fq * 8);
;     ...
;     PG8_STAGE(PG8_SB(0, 0), cB, offB); PG8_STAGE(PG8_SB(0, 1), cB + hstepB, offB); PG8_STAGE(PG8_SA(0, 0), cA, offA); PG8_STAGE(PG8_SA(0, 1), cA + hstepA, offA);
;     PG8_STAGE(PG8_SB(1, 0), cB + kstep, offB); PG8_STAGE(PG8_SA(1, 0), cA + kstep, offA); PG8_STAGE(PG8_SB(1, 1), cB + hstepB + kstep, offB);
;     if (wr == 1) PG8_BAR;
;     PG8_WAIT_V(0); PG8_BAR;
;     PG8_BAR;
;     } else {
;     PG8_STAGE(PG8_SB(0, 0), cB, offB); PG8_STAGE(PG8_SA(0, 0), cA, offA); PG8_STAGE(PG8_SB(0, 1), cB + hstepB, offB); PG8_STAGE(PG8_SA(0, 1), cA + hstepA, offA);
;     if (wr == 1) PG8_BAR;
;     PG8_WAIT_V(4); PG8_BAR;
;     PG8_STAGE(PG8_SB(1, 0), cB + kstep, offB); PG8_STAGE(PG8_SA(1, 0), cA + kstep, offA); PG8_STAGE(PG8_SB(1, 1), cB + hstepB + kstep, offB);
;     PG8_WAIT_V(6); PG8_BAR;
;     }
;     if (wr == 1) __builtin_amdgcn_s_setprio(1);
;     for (;;) {
;         const bool has_next = S.next(ui + 1, nxt);
;         const char* nA = has_next ? PG8_ABASE(nxt) : cA; const char* nB = has_next ? PG8_BBASE(nxt) : cB;
.LBB0_1468:
	s_waitcnt vmcnt(0)
	v_cndmask_b32_e64 v4, 0, 1, s[8:9]
	s_lshr_b32 s13, s6, 3
	v_cmp_ne_u32_e64 s[6:7], 1, v4
	s_andn2_b64 vcc, exec, s[8:9]
	s_barrier
	s_barrier
	s_cbranch_vccnz .LBB0_1470
.LBB0_1470:
	v_and_b32_e32 v4, 48, v0
	v_lshlrev_b32_e32 v5, 6, v0
	s_movk_i32 s1, 0x3c0
	s_add_u32 s55, s48, 0x16a000
	v_and_or_b32 v4, v5, s1, v4
	v_lshlrev_b32_e32 v5, 2, v0
	s_addc_u32 s62, s49, 0
	s_lshl_b32 s0, s12, 13
	v_and_b32_e32 v5, 32, v5
	v_bitop3_b32 v6, v4, s0, v5 bitop3:0xde
	s_lshl_b32 s0, s11, 5
	s_and_b32 s74, s0, 0x60
	s_lshl_b32 s63, s12, 6
	s_lshl_b32 s0, s74, 7
	s_cmpk_lt_u32 s10, 0x100
	v_add_u16_e32 v1, v1, v2
	s_sext_i32_i8 s84, s13
	v_bitop3_b32 v4, s0, v4, v5 bitop3:0xf6
	s_cselect_b64 s[12:13], -1, 0
	v_lshrrev_b16_e32 v1, 1, v1
	s_add_i32 s77, 0, 0x10000
	s_add_i32 s78, 0, 0x14000
	s_add_i32 s79, 0, 0x18000
	s_add_i32 s80, 0, 0x1c000
	s_ashr_i32 s75, s86, 31
	v_add_lshl_u32 v174, v3, v1, 1
	v_mov_b32_e32 v175, 0
	s_mov_b32 s76, 0
	v_mov_b64_e32 v[176:177], 0x200
	v_mov_b64_e32 v[178:179], 0x1ff
	v_add_u32_e32 v1, s77, v4
	v_add_u32_e32 v192, s78, v4
	v_add_u32_e32 v193, 0, v6
	s_mov_b64 s[14:15], 0x160080
	s_mov_b64 s[16:17], 0x210080
	s_mov_b64 s[18:19], 0x100
	s_mov_b64 s[20:21], 0xb0100
	s_mov_b64 s[22:23], 0x160100
	s_mov_b64 s[24:25], 0x210100
	v_add_u32_e32 v194, s79, v4
	v_add_u32_e32 v195, s80, v4
	s_waitcnt lgkmcnt(0)
	s_mov_b64 s[26:27], 0x180
	s_mov_b64 s[28:29], 0xb0180
	s_mov_b64 s[30:31], 0xb0000
	s_mov_b64 s[34:35], 0x160000
	s_mov_b64 s[36:37], 0x210000
	s_mov_b64 s[38:39], 0x80
	s_mov_b64 s[66:67], 0xb0080
	s_branch .LBB0_1473

; #define PG8_WAIT_V(n) asm volatile("s_waitcnt vmcnt(" #n ")" ::: "memory")
; template <class Epi, class Sched, bool ALIGN_EPI = true, bool SP2 = true, bool FULLLINE = false, bool NOSTAGE = false, bool FP8 = false>
; __device__ __forceinline__ void gemm_phase(PG8_LAS unsigned char* lds, const Gemm g, const Sched& S, const Epi& E) {
;     ...
;         static_assert(SP2, "only the SP2 loop is kept");
;         { const int t = 0; if constexpr (Epi::NST == 16) PG8_ITER(PG8_WAIT_V(24)); else if constexpr (Epi::NST == 8) PG8_ITER(PG8_WAIT_V(16)); else PG8_ITER(PG8_WAIT_V(8)); }
.LBB0_1483:
	ds_read_b128 v[2:5], v1
	ds_read_b128 v[6:9], v1 offset:1024
	ds_read_b128 v[10:13], v1 offset:2048
	ds_read_b128 v[14:17], v1 offset:3072
	ds_read_b128 v[18:21], v192
	ds_read_b128 v[22:25], v192 offset:1024
	ds_read_b128 v[26:29], v192 offset:2048
	ds_read_b128 v[30:33], v192 offset:3072
	v_lshl_add_u64 v[248:249], s[70:71], 0, v[170:171]
	s_add_i32 s85, s45, 0xc000
	v_lshl_add_u64 v[66:67], v[248:249], 0, s[14:15]
	s_mov_b32 m0, s85
	s_add_i32 s87, s45, 0xe000
	ds_read_b128 v[34:37], v193
	ds_read_b128 v[38:41], v193 offset:1024
	ds_read_b128 v[42:45], v193 offset:2048
	ds_read_b128 v[46:49], v193 offset:3072
	ds_read_b128 v[50:53], v193 offset:4096
	ds_read_b128 v[54:57], v193 offset:5120
	ds_read_b128 v[58:61], v193 offset:6144
	ds_read_b128 v[62:65], v193 offset:7168
	global_load_lds_dwordx4 v[66:67], off
	v_lshl_add_u64 v[66:67], v[248:249], 0, s[16:17]
	s_mov_b32 m0, s87
	s_nop 0
	global_load_lds_dwordx4 v[66:67], off
	s_waitcnt vmcnt(24)
	s_waitcnt lgkmcnt(0)
	s_barrier
	s_waitcnt lgkmcnt(0)
	s_setprio 1
	v_mfma_f32_16x16x32_bf16 v[66:69], v[2:5], v[34:37], 0
	v_mfma_f32_16x16x32_bf16 v[70:73], v[10:13], v[34:37], 0
	v_mfma_f32_16x16x32_bf16 v[78:81], v[10:13], v[42:45], 0
	v_mfma_f32_16x16x32_bf16 v[86:89], v[10:13], v[50:53], 0
	v_mfma_f32_16x16x32_bf16 v[66:69], v[6:9], v[38:41], v[66:69]
	v_mfma_f32_16x16x32_bf16 v[70:73], v[14:17], v[38:41], v[70:73]
	v_mfma_f32_16x16x32_bf16 v[74:77], v[2:5], v[42:45], 0
	v_mfma_f32_16x16x32_bf16 v[78:81], v[14:17], v[46:49], v[78:81]
	v_mfma_f32_16x16x32_bf16 v[82:85], v[2:5], v[50:53], 0
	v_mfma_f32_16x16x32_bf16 v[86:89], v[14:17], v[54:57], v[86:89]
	v_mfma_f32_16x16x32_bf16 v[90:93], v[2:5], v[58:61], 0
	v_mfma_f32_16x16x32_bf16 v[94:97], v[10:13], v[58:61], 0
	v_mfma_f32_16x16x32_bf16 v[74:77], v[6:9], v[46:49], v[74:77]
	v_mfma_f32_16x16x32_bf16 v[82:85], v[6:9], v[54:57], v[82:85]
	v_mfma_f32_16x16x32_bf16 v[90:93], v[6:9], v[62:65], v[90:93]
	v_mfma_f32_16x16x32_bf16 v[94:97], v[14:17], v[62:65], v[94:97]
	v_mfma_f32_16x16x32_bf16 v[98:101], v[18:21], v[34:37], 0
	v_mfma_f32_16x16x32_bf16 v[34:37], v[26:29], v[34:37], 0
	v_mfma_f32_16x16x32_bf16 v[98:101], v[22:25], v[38:41], v[98:101]
	v_mfma_f32_16x16x32_bf16 v[34:37], v[30:33], v[38:41], v[34:37]
	v_mfma_f32_16x16x32_bf16 v[38:41], v[18:21], v[42:45], 0
	v_mfma_f32_16x16x32_bf16 v[42:45], v[26:29], v[42:45], 0
	v_mfma_f32_16x16x32_bf16 v[38:41], v[22:25], v[46:49], v[38:41]
	v_mfma_f32_16x16x32_bf16 v[42:45], v[30:33], v[46:49], v[42:45]
	v_mfma_f32_16x16x32_bf16 v[46:49], v[18:21], v[50:53], 0
	v_mfma_f32_16x16x32_bf16 v[50:53], v[26:29], v[50:53], 0
	v_mfma_f32_16x16x32_bf16 v[46:49], v[22:25], v[54:57], v[46:49]
	v_mfma_f32_16x16x32_bf16 v[50:53], v[30:33], v[54:57], v[50:53]
	v_mfma_f32_16x16x32_bf16 v[54:57], v[18:21], v[58:61], 0
	v_mfma_f32_16x16x32_bf16 v[58:61], v[26:29], v[58:61], 0
	v_mfma_f32_16x16x32_bf16 v[54:57], v[22:25], v[62:65], v[54:57]
	v_mfma_f32_16x16x32_bf16 v[58:61], v[30:33], v[62:65], v[58:61]
	s_setprio 0
	s_barrier
	v_lshl_add_u64 v[250:251], s[72:73], 0, v[172:173]
	s_add_i32 s88, s77, s44
	v_lshl_add_u64 v[130:131], v[250:251], 0, s[18:19]
	s_mov_b32 m0, s88
	s_add_i32 s89, s88, 0x2000
	ds_read_b128 v[62:65], v193 offset:16384
	ds_read_b128 v[102:105], v193 offset:17408
	ds_read_b128 v[106:109], v193 offset:18432
	ds_read_b128 v[110:113], v193 offset:19456
	ds_read_b128 v[114:117], v193 offset:20480
	ds_read_b128 v[118:121], v193 offset:21504
	ds_read_b128 v[122:125], v193 offset:22528
	ds_read_b128 v[126:129], v193 offset:23552
	global_load_lds_dwordx4 v[130:131], off
	v_lshl_add_u64 v[130:131], v[250:251], 0, s[20:21]
	s_mov_b32 m0, s89
	s_add_i32 s40, s78, s44
	global_load_lds_dwordx4 v[130:131], off
	v_lshl_add_u64 v[130:131], v[250:251], 0, s[22:23]
	s_mov_b32 m0, s40
	s_add_i32 s41, s40, 0x2000
	global_load_lds_dwordx4 v[130:131], off
	v_lshl_add_u64 v[130:131], v[250:251], 0, s[24:25]
	s_mov_b32 m0, s41
	s_nop 0
	global_load_lds_dwordx4 v[130:131], off
	v_lshl_add_u64 v[130:131], v[248:249], 0, s[18:19]
	s_mov_b32 m0, s45
	s_nop 0
	global_load_lds_dwordx4 v[130:131], off
	v_lshl_add_u64 v[130:131], v[248:249], 0, s[20:21]
	s_mov_b32 m0, s46
	s_nop 0
	global_load_lds_dwordx4 v[130:131], off
	s_waitcnt vmcnt(24)
	s_waitcnt lgkmcnt(0)
	s_barrier
	s_waitcnt lgkmcnt(0)
	s_setprio 1
	v_mfma_f32_16x16x32_bf16 v[130:133], v[2:5], v[62:65], 0
	v_mfma_f32_16x16x32_bf16 v[138:141], v[6:9], v[102:105], v[130:133]
	v_mfma_f32_16x16x32_bf16 v[130:133], v[10:13], v[62:65], 0
	v_mfma_f32_16x16x32_bf16 v[150:153], v[14:17], v[102:105], v[130:133]
	v_mfma_f32_16x16x32_bf16 v[130:133], v[2:5], v[106:109], 0
	v_mfma_f32_16x16x32_bf16 v[154:157], v[6:9], v[110:113], v[130:133]
	v_mfma_f32_16x16x32_bf16 v[130:133], v[10:13], v[106:109], 0
	v_mfma_f32_16x16x32_bf16 v[158:161], v[14:17], v[110:113], v[130:133]
	v_mfma_f32_16x16x32_bf16 v[130:133], v[2:5], v[114:117], 0
	v_mfma_f32_16x16x32_bf16 v[2:5], v[2:5], v[122:125], 0
	v_mfma_f32_16x16x32_bf16 v[162:165], v[6:9], v[118:121], v[130:133]
	v_mfma_f32_16x16x32_bf16 v[2:5], v[6:9], v[126:129], v[2:5]
	v_mfma_f32_16x16x32_bf16 v[6:9], v[10:13], v[122:125], 0
	v_mfma_f32_16x16x32_bf16 v[130:133], v[10:13], v[114:117], 0
	v_mfma_f32_16x16x32_bf16 v[6:9], v[14:17], v[126:129], v[6:9]
	v_mfma_f32_16x16x32_bf16 v[166:169], v[14:17], v[118:121], v[130:133]
	v_mfma_f32_16x16x32_bf16 v[10:13], v[18:21], v[62:65], 0
	v_mfma_f32_16x16x32_bf16 v[180:183], v[22:25], v[102:105], v[10:13]
	v_mfma_f32_16x16x32_bf16 v[10:13], v[26:29], v[62:65], 0
	v_mfma_f32_16x16x32_bf16 v[184:187], v[30:33], v[102:105], v[10:13]
	v_mfma_f32_16x16x32_bf16 v[10:13], v[18:21], v[106:109], 0
	v_mfma_f32_16x16x32_bf16 v[188:191], v[22:25], v[110:113], v[10:13]
	v_mfma_f32_16x16x32_bf16 v[10:13], v[26:29], v[106:109], 0
	v_mfma_f32_16x16x32_bf16 v[196:199], v[30:33], v[110:113], v[10:13]
	v_mfma_f32_16x16x32_bf16 v[10:13], v[18:21], v[114:117], 0
	v_mfma_f32_16x16x32_bf16 v[200:203], v[22:25], v[118:121], v[10:13]
	v_mfma_f32_16x16x32_bf16 v[10:13], v[26:29], v[114:117], 0
	v_mfma_f32_16x16x32_bf16 v[204:207], v[30:33], v[118:121], v[10:13]
	v_mfma_f32_16x16x32_bf16 v[10:13], v[18:21], v[122:125], 0
	v_mfma_f32_16x16x32_bf16 v[208:211], v[22:25], v[126:129], v[10:13]
	v_mfma_f32_16x16x32_bf16 v[10:13], v[26:29], v[122:125], 0
	v_mfma_f32_16x16x32_bf16 v[212:215], v[30:33], v[126:129], v[10:13]
	s_setprio 0
	s_barrier
; #define PG8_WAIT_V(n) asm volatile("s_waitcnt vmcnt(" #n ")" ::: "memory")
; template <class Epi, class Sched, bool ALIGN_EPI = true, bool SP2 = true, bool FULLLINE = false, bool NOSTAGE = false, bool FP8 = false>
; __device__ __forceinline__ void gemm_phase(PG8_LAS unsigned char* lds, const Gemm g, const Sched& S, const Epi& E) {
;     ...
;         static_assert(SP2, "only the SP2 loop is kept");
;         { const int t = 0; if constexpr (Epi::NST == 16) PG8_ITER(PG8_WAIT_V(24)); else if constexpr (Epi::NST == 8) PG8_ITER(PG8_WAIT_V(16)); else PG8_ITER(PG8_WAIT_V(8)); }
	s_nop 5
	ds_read_b128 v[10:13], v194
	ds_read_b128 v[14:17], v194 offset:1024
	ds_read_b128 v[18:21], v194 offset:2048
	ds_read_b128 v[22:25], v194 offset:3072
	ds_read_b128 v[216:219], v195
	ds_read_b128 v[220:223], v195 offset:1024
	ds_read_b128 v[224:227], v195 offset:2048
	ds_read_b128 v[228:231], v195 offset:3072
	s_mov_b32 m0, s47
	v_lshl_add_u64 v[106:107], v[248:249], 0, s[22:23]
	ds_read_b128 v[26:29], v193 offset:32768
	ds_read_b128 v[30:33], v193 offset:33792
	ds_read_b128 v[62:65], v193 offset:34816
	ds_read_b128 v[102:105], v193 offset:35840
	ds_read_b128 v[232:235], v193 offset:36864
	ds_read_b128 v[236:239], v193 offset:37888
	ds_read_b128 v[240:243], v193 offset:38912
	ds_read_b128 v[244:247], v193 offset:39936
	global_load_lds_dwordx4 v[106:107], off
	v_lshl_add_u64 v[106:107], v[248:249], 0, s[24:25]
	s_mov_b32 m0, s52
	s_nop 0
	global_load_lds_dwordx4 v[106:107], off
	s_waitcnt vmcnt(8)
	s_waitcnt lgkmcnt(0)
	s_barrier
	s_waitcnt lgkmcnt(0)
	s_setprio 1
	v_mfma_f32_16x16x32_bf16 v[66:69], v[10:13], v[26:29], v[66:69]
	v_mfma_f32_16x16x32_bf16 v[146:149], v[14:17], v[30:33], v[66:69]
	v_mfma_f32_16x16x32_bf16 v[66:69], v[18:21], v[26:29], v[70:73]
	v_mfma_f32_16x16x32_bf16 v[142:145], v[22:25], v[30:33], v[66:69]
	v_mfma_f32_16x16x32_bf16 v[66:69], v[10:13], v[62:65], v[74:77]
	v_mfma_f32_16x16x32_bf16 v[126:129], v[14:17], v[102:105], v[66:69]
	v_mfma_f32_16x16x32_bf16 v[66:69], v[18:21], v[62:65], v[78:81]
	v_mfma_f32_16x16x32_bf16 v[122:125], v[22:25], v[102:105], v[66:69]
	v_mfma_f32_16x16x32_bf16 v[66:69], v[10:13], v[232:235], v[82:85]
	v_mfma_f32_16x16x32_bf16 v[110:113], v[14:17], v[236:239], v[66:69]
	v_mfma_f32_16x16x32_bf16 v[66:69], v[18:21], v[232:235], v[86:89]
	v_mfma_f32_16x16x32_bf16 v[106:109], v[22:25], v[236:239], v[66:69]
	v_mfma_f32_16x16x32_bf16 v[66:69], v[10:13], v[240:243], v[90:93]
	v_mfma_f32_16x16x32_bf16 v[86:89], v[14:17], v[244:247], v[66:69]
	v_mfma_f32_16x16x32_bf16 v[66:69], v[18:21], v[240:243], v[94:97]
	v_mfma_f32_16x16x32_bf16 v[78:81], v[22:25], v[244:247], v[66:69]
	v_mfma_f32_16x16x32_bf16 v[66:69], v[216:219], v[26:29], v[98:101]
	v_mfma_f32_16x16x32_bf16 v[26:29], v[224:227], v[26:29], v[34:37]
	v_mfma_f32_16x16x32_bf16 v[130:133], v[228:231], v[30:33], v[26:29]
	v_mfma_f32_16x16x32_bf16 v[26:29], v[216:219], v[62:65], v[38:41]
	v_mfma_f32_16x16x32_bf16 v[118:121], v[220:223], v[102:105], v[26:29]
	v_mfma_f32_16x16x32_bf16 v[26:29], v[224:227], v[62:65], v[42:45]
	v_mfma_f32_16x16x32_bf16 v[114:117], v[228:231], v[102:105], v[26:29]
	v_mfma_f32_16x16x32_bf16 v[26:29], v[216:219], v[232:235], v[46:49]
	v_mfma_f32_16x16x32_bf16 v[102:105], v[220:223], v[236:239], v[26:29]
	v_mfma_f32_16x16x32_bf16 v[26:29], v[224:227], v[232:235], v[50:53]
	v_mfma_f32_16x16x32_bf16 v[98:101], v[228:231], v[236:239], v[26:29]
	v_mfma_f32_16x16x32_bf16 v[26:29], v[216:219], v[240:243], v[54:57]
	v_mfma_f32_16x16x32_bf16 v[70:73], v[220:223], v[244:247], v[26:29]
	v_mfma_f32_16x16x32_bf16 v[26:29], v[224:227], v[240:243], v[58:61]
	v_mfma_f32_16x16x32_bf16 v[134:137], v[220:223], v[30:33], v[66:69]
	v_mfma_f32_16x16x32_bf16 v[66:69], v[228:231], v[244:247], v[26:29]
	s_setprio 0
	s_barrier
	s_add_i32 s50, s79, s44
	s_nop 3
	v_lshl_add_u64 v[26:27], v[250:251], 0, s[26:27]
	s_mov_b32 m0, s50
	s_add_i32 s51, s50, 0x2000
	ds_read_b128 v[34:37], v193 offset:49152
	ds_read_b128 v[38:41], v193 offset:50176
	ds_read_b128 v[74:77], v193 offset:51200
	ds_read_b128 v[82:85], v193 offset:52224
	ds_read_b128 v[90:93], v193 offset:53248
	ds_read_b128 v[94:97], v193 offset:54272
	ds_read_b128 v[232:235], v193 offset:55296
	ds_read_b128 v[236:239], v193 offset:56320
	global_load_lds_dwordx4 v[26:27], off
	v_lshl_add_u64 v[26:27], v[250:251], 0, s[28:29]
	s_mov_b32 m0, s51
	s_mov_b64 s[0:1], 0x160180
	s_add_i32 s33, s80, s44
	global_load_lds_dwordx4 v[26:27], off
	v_lshl_add_u64 v[26:27], v[250:251], 0, s[0:1]
	s_mov_b32 m0, s33
	s_mov_b64 s[0:1], 0x210180
	s_add_i32 s56, s33, 0x2000
	global_load_lds_dwordx4 v[26:27], off
	v_lshl_add_u64 v[26:27], v[250:251], 0, s[0:1]
	s_mov_b32 m0, s56
	s_nop 0
	global_load_lds_dwordx4 v[26:27], off
	v_lshl_add_u64 v[26:27], v[248:249], 0, s[26:27]
	s_mov_b32 m0, s53
	s_nop 0
	global_load_lds_dwordx4 v[26:27], off
	v_lshl_add_u64 v[26:27], v[248:249], 0, s[28:29]
	s_mov_b32 m0, s54
	s_nop 0
	global_load_lds_dwordx4 v[26:27], off
	s_waitcnt vmcnt(8)
	s_waitcnt lgkmcnt(0)
	s_barrier
	s_waitcnt lgkmcnt(0)
	s_setprio 1
	v_mfma_f32_16x16x32_bf16 v[26:29], v[10:13], v[34:37], v[138:141]
	v_mfma_f32_16x16x32_bf16 v[62:65], v[14:17], v[38:41], v[26:29]
	v_mfma_f32_16x16x32_bf16 v[26:29], v[18:21], v[34:37], v[150:153]
	v_mfma_f32_16x16x32_bf16 v[58:61], v[22:25], v[38:41], v[26:29]
	v_mfma_f32_16x16x32_bf16 v[26:29], v[10:13], v[74:77], v[154:157]
	v_mfma_f32_16x16x32_bf16 v[46:49], v[14:17], v[82:85], v[26:29]
	v_mfma_f32_16x16x32_bf16 v[26:29], v[18:21], v[74:77], v[158:161]
	v_mfma_f32_16x16x32_bf16 v[42:45], v[22:25], v[82:85], v[26:29]
	v_mfma_f32_16x16x32_bf16 v[26:29], v[10:13], v[90:93], v[162:165]
	v_mfma_f32_16x16x32_bf16 v[2:5], v[10:13], v[232:235], v[2:5]
	v_mfma_f32_16x16x32_bf16 v[30:33], v[14:17], v[94:97], v[26:29]
	v_mfma_f32_16x16x32_bf16 v[26:29], v[18:21], v[90:93], v[166:169]
	v_mfma_f32_16x16x32_bf16 v[14:17], v[14:17], v[236:239], v[2:5]
	v_mfma_f32_16x16x32_bf16 v[2:5], v[18:21], v[232:235], v[6:9]
	v_mfma_f32_16x16x32_bf16 v[26:29], v[22:25], v[94:97], v[26:29]
	v_mfma_f32_16x16x32_bf16 v[10:13], v[22:25], v[236:239], v[2:5]
	v_mfma_f32_16x16x32_bf16 v[2:5], v[216:219], v[34:37], v[180:183]
	v_mfma_f32_16x16x32_bf16 v[54:57], v[220:223], v[38:41], v[2:5]
	v_mfma_f32_16x16x32_bf16 v[2:5], v[224:227], v[34:37], v[184:187]
	v_mfma_f32_16x16x32_bf16 v[50:53], v[228:231], v[38:41], v[2:5]
	v_mfma_f32_16x16x32_bf16 v[2:5], v[216:219], v[74:77], v[188:191]
	v_mfma_f32_16x16x32_bf16 v[38:41], v[220:223], v[82:85], v[2:5]
	v_mfma_f32_16x16x32_bf16 v[2:5], v[224:227], v[74:77], v[196:199]
	v_mfma_f32_16x16x32_bf16 v[34:37], v[228:231], v[82:85], v[2:5]
	v_mfma_f32_16x16x32_bf16 v[2:5], v[216:219], v[90:93], v[200:203]
	v_mfma_f32_16x16x32_bf16 v[22:25], v[220:223], v[94:97], v[2:5]
	v_mfma_f32_16x16x32_bf16 v[2:5], v[224:227], v[90:93], v[204:207]
	v_mfma_f32_16x16x32_bf16 v[18:21], v[228:231], v[94:97], v[2:5]
	v_mfma_f32_16x16x32_bf16 v[2:5], v[216:219], v[232:235], v[208:211]
	v_mfma_f32_16x16x32_bf16 v[6:9], v[220:223], v[236:239], v[2:5]
	v_mfma_f32_16x16x32_bf16 v[2:5], v[224:227], v[232:235], v[212:215]
	v_mfma_f32_16x16x32_bf16 v[2:5], v[228:231], v[236:239], v[2:5]
	s_setprio 0
	s_barrier
	s_add_u32 s70, s70, 0x160180
	s_addc_u32 s71, s71, 0
	s_add_u32 s57, s72, 0x200
	s_addc_u32 s72, s73, 0
	s_mov_b32 s73, 0
; #define PG8_WAIT_V(n) asm volatile("s_waitcnt vmcnt(" #n ")" ::: "memory")
; template <class Epi, class Sched, bool ALIGN_EPI = true, bool SP2 = true, bool FULLLINE = false, bool NOSTAGE = false, bool FP8 = false>
; __device__ __forceinline__ void gemm_phase(PG8_LAS unsigned char* lds, const Gemm g, const Sched& S, const Epi& E) {
;     ...
;         for (int t = 2; t < nt; t += 2) PG8_ITER(PG8_WAIT_V(8));
.LBB0_1484:
	ds_read_b128 v[74:77], v1
	ds_read_b128 v[82:85], v1 offset:1024
	ds_read_b128 v[90:93], v1 offset:2048
	ds_read_b128 v[94:97], v1 offset:3072
	ds_read_b128 v[138:141], v192
	ds_read_b128 v[150:153], v192 offset:1024
	ds_read_b128 v[154:157], v192 offset:2048
	ds_read_b128 v[158:161], v192 offset:3072
	s_add_u32 s0, s70, 0xffea0080
	s_addc_u32 s1, s71, -1
	s_cmpk_eq_i32 s73, 0x54
	s_cselect_b32 s1, s11, s1
	s_cselect_b32 s0, s10, s0
	s_cselect_b32 s65, s69, s72
	s_cselect_b32 s64, s68, s57
	s_mov_b32 m0, s85
	v_lshl_add_u64 v[208:209], s[70:71], 0, v[174:175]
	ds_read_b128 v[162:165], v193
	ds_read_b128 v[166:169], v193 offset:1024
	ds_read_b128 v[180:183], v193 offset:2048
	ds_read_b128 v[184:187], v193 offset:3072
	ds_read_b128 v[188:191], v193 offset:4096
	ds_read_b128 v[196:199], v193 offset:5120
	ds_read_b128 v[200:203], v193 offset:6144
	ds_read_b128 v[204:207], v193 offset:7168
	global_load_lds_dwordx4 v[208:209], off
	v_lshl_add_u64 v[208:209], v[208:209], 0, s[30:31]
	s_mov_b32 m0, s87
	s_nop 0
	global_load_lds_dwordx4 v[208:209], off
	s_waitcnt vmcnt(8)
	s_waitcnt lgkmcnt(0)
	s_barrier
	s_waitcnt lgkmcnt(0)
	s_setprio 1
	v_mfma_f32_16x16x32_bf16 v[146:149], v[74:77], v[162:165], v[146:149]
	v_mfma_f32_16x16x32_bf16 v[142:145], v[90:93], v[162:165], v[142:145]
	v_mfma_f32_16x16x32_bf16 v[126:129], v[74:77], v[180:183], v[126:129]
	v_mfma_f32_16x16x32_bf16 v[122:125], v[90:93], v[180:183], v[122:125]
	v_mfma_f32_16x16x32_bf16 v[110:113], v[74:77], v[188:191], v[110:113]
	v_mfma_f32_16x16x32_bf16 v[106:109], v[90:93], v[188:191], v[106:109]
	v_mfma_f32_16x16x32_bf16 v[86:89], v[74:77], v[200:203], v[86:89]
	v_mfma_f32_16x16x32_bf16 v[78:81], v[90:93], v[200:203], v[78:81]
	v_mfma_f32_16x16x32_bf16 v[146:149], v[82:85], v[166:169], v[146:149]
	v_mfma_f32_16x16x32_bf16 v[142:145], v[94:97], v[166:169], v[142:145]
	v_mfma_f32_16x16x32_bf16 v[126:129], v[82:85], v[184:187], v[126:129]
	v_mfma_f32_16x16x32_bf16 v[122:125], v[94:97], v[184:187], v[122:125]
	v_mfma_f32_16x16x32_bf16 v[110:113], v[82:85], v[196:199], v[110:113]
	v_mfma_f32_16x16x32_bf16 v[106:109], v[94:97], v[196:199], v[106:109]
	v_mfma_f32_16x16x32_bf16 v[86:89], v[82:85], v[204:207], v[86:89]
	v_mfma_f32_16x16x32_bf16 v[78:81], v[94:97], v[204:207], v[78:81]
	v_mfma_f32_16x16x32_bf16 v[134:137], v[138:141], v[162:165], v[134:137]
	v_mfma_f32_16x16x32_bf16 v[130:133], v[154:157], v[162:165], v[130:133]
	v_mfma_f32_16x16x32_bf16 v[118:121], v[138:141], v[180:183], v[118:121]
	v_mfma_f32_16x16x32_bf16 v[114:117], v[154:157], v[180:183], v[114:117]
	v_mfma_f32_16x16x32_bf16 v[102:105], v[138:141], v[188:191], v[102:105]
	v_mfma_f32_16x16x32_bf16 v[98:101], v[154:157], v[188:191], v[98:101]
	v_mfma_f32_16x16x32_bf16 v[70:73], v[138:141], v[200:203], v[70:73]
	v_mfma_f32_16x16x32_bf16 v[66:69], v[154:157], v[200:203], v[66:69]
	v_mfma_f32_16x16x32_bf16 v[134:137], v[150:153], v[166:169], v[134:137]
	v_mfma_f32_16x16x32_bf16 v[130:133], v[158:161], v[166:169], v[130:133]
	v_mfma_f32_16x16x32_bf16 v[118:121], v[150:153], v[184:187], v[118:121]
	v_mfma_f32_16x16x32_bf16 v[114:117], v[158:161], v[184:187], v[114:117]
	v_mfma_f32_16x16x32_bf16 v[102:105], v[150:153], v[196:199], v[102:105]
	v_mfma_f32_16x16x32_bf16 v[98:101], v[158:161], v[196:199], v[98:101]
	v_mfma_f32_16x16x32_bf16 v[70:73], v[150:153], v[204:207], v[70:73]
	v_mfma_f32_16x16x32_bf16 v[66:69], v[158:161], v[204:207], v[66:69]
	s_setprio 0
	s_barrier
	s_mov_b32 m0, s88
	v_lshl_add_u64 v[208:209], s[64:65], 0, v[172:173]
	ds_read_b128 v[162:165], v193 offset:16384
	ds_read_b128 v[166:169], v193 offset:17408
	ds_read_b128 v[180:183], v193 offset:18432
	ds_read_b128 v[184:187], v193 offset:19456
	ds_read_b128 v[188:191], v193 offset:20480
	ds_read_b128 v[196:199], v193 offset:21504
	ds_read_b128 v[200:203], v193 offset:22528
	ds_read_b128 v[204:207], v193 offset:23552
	global_load_lds_dwordx4 v[208:209], off
	v_lshl_add_u64 v[210:211], v[208:209], 0, s[30:31]
	s_mov_b32 m0, s89
	s_nop 0
	global_load_lds_dwordx4 v[210:211], off
	v_lshl_add_u64 v[210:211], v[208:209], 0, s[34:35]
	s_mov_b32 m0, s40
	s_nop 0
	global_load_lds_dwordx4 v[210:211], off
	v_lshl_add_u64 v[210:211], v[208:209], 0, s[36:37]
	s_mov_b32 m0, s41
	s_nop 0
	global_load_lds_dwordx4 v[210:211], off
	v_lshl_add_u64 v[210:211], s[0:1], 0, v[170:171]
	s_mov_b32 m0, s45
	v_lshl_add_u64 v[212:213], v[210:211], 0, s[30:31]
	global_load_lds_dwordx4 v[210:211], off
	s_mov_b32 m0, s46
	s_nop 0
	global_load_lds_dwordx4 v[212:213], off
	s_waitcnt vmcnt(8)
	s_waitcnt lgkmcnt(0)
	s_barrier
; #define PG8_WAIT_V(n) asm volatile("s_waitcnt vmcnt(" #n ")" ::: "memory")
; template <class Epi, class Sched, bool ALIGN_EPI = true, bool SP2 = true, bool FULLLINE = false, bool NOSTAGE = false, bool FP8 = false>
; __device__ __forceinline__ void gemm_phase(PG8_LAS unsigned char* lds, const Gemm g, const Sched& S, const Epi& E) {
;     ...
;         for (int t = 2; t < nt; t += 2) PG8_ITER(PG8_WAIT_V(8));
	s_waitcnt lgkmcnt(0)
	s_setprio 1
	v_mfma_f32_16x16x32_bf16 v[62:65], v[74:77], v[162:165], v[62:65]
	v_mfma_f32_16x16x32_bf16 v[58:61], v[90:93], v[162:165], v[58:61]
	v_mfma_f32_16x16x32_bf16 v[46:49], v[74:77], v[180:183], v[46:49]
	v_mfma_f32_16x16x32_bf16 v[42:45], v[90:93], v[180:183], v[42:45]
	v_mfma_f32_16x16x32_bf16 v[30:33], v[74:77], v[188:191], v[30:33]
	v_mfma_f32_16x16x32_bf16 v[26:29], v[90:93], v[188:191], v[26:29]
	v_mfma_f32_16x16x32_bf16 v[14:17], v[74:77], v[200:203], v[14:17]
	v_mfma_f32_16x16x32_bf16 v[10:13], v[90:93], v[200:203], v[10:13]
	v_mfma_f32_16x16x32_bf16 v[62:65], v[82:85], v[166:169], v[62:65]
	v_mfma_f32_16x16x32_bf16 v[58:61], v[94:97], v[166:169], v[58:61]
	v_mfma_f32_16x16x32_bf16 v[46:49], v[82:85], v[184:187], v[46:49]
	v_mfma_f32_16x16x32_bf16 v[42:45], v[94:97], v[184:187], v[42:45]
	v_mfma_f32_16x16x32_bf16 v[30:33], v[82:85], v[196:199], v[30:33]
	v_mfma_f32_16x16x32_bf16 v[26:29], v[94:97], v[196:199], v[26:29]
	v_mfma_f32_16x16x32_bf16 v[14:17], v[82:85], v[204:207], v[14:17]
	v_mfma_f32_16x16x32_bf16 v[10:13], v[94:97], v[204:207], v[10:13]
	v_mfma_f32_16x16x32_bf16 v[54:57], v[138:141], v[162:165], v[54:57]
	v_mfma_f32_16x16x32_bf16 v[50:53], v[154:157], v[162:165], v[50:53]
	v_mfma_f32_16x16x32_bf16 v[38:41], v[138:141], v[180:183], v[38:41]
	v_mfma_f32_16x16x32_bf16 v[34:37], v[154:157], v[180:183], v[34:37]
	v_mfma_f32_16x16x32_bf16 v[22:25], v[138:141], v[188:191], v[22:25]
	v_mfma_f32_16x16x32_bf16 v[18:21], v[154:157], v[188:191], v[18:21]
	v_mfma_f32_16x16x32_bf16 v[6:9], v[138:141], v[200:203], v[6:9]
	v_mfma_f32_16x16x32_bf16 v[2:5], v[154:157], v[200:203], v[2:5]
	v_mfma_f32_16x16x32_bf16 v[54:57], v[150:153], v[166:169], v[54:57]
	v_mfma_f32_16x16x32_bf16 v[50:53], v[158:161], v[166:169], v[50:53]
	v_mfma_f32_16x16x32_bf16 v[38:41], v[150:153], v[184:187], v[38:41]
	v_mfma_f32_16x16x32_bf16 v[34:37], v[158:161], v[184:187], v[34:37]
	v_mfma_f32_16x16x32_bf16 v[22:25], v[150:153], v[196:199], v[22:25]
	v_mfma_f32_16x16x32_bf16 v[18:21], v[158:161], v[196:199], v[18:21]
	v_mfma_f32_16x16x32_bf16 v[6:9], v[150:153], v[204:207], v[6:9]
	v_mfma_f32_16x16x32_bf16 v[2:5], v[158:161], v[204:207], v[2:5]
	s_setprio 0
	s_barrier
	ds_read_b128 v[74:77], v194
	ds_read_b128 v[82:85], v194 offset:1024
	ds_read_b128 v[90:93], v194 offset:2048
	ds_read_b128 v[94:97], v194 offset:3072
	ds_read_b128 v[138:141], v195
	ds_read_b128 v[150:153], v195 offset:1024
	ds_read_b128 v[154:157], v195 offset:2048
	ds_read_b128 v[158:161], v195 offset:3072
	s_mov_b32 m0, s47
	v_lshl_add_u64 v[212:213], v[210:211], 0, s[34:35]
	ds_read_b128 v[162:165], v193 offset:32768
	ds_read_b128 v[166:169], v193 offset:33792
	ds_read_b128 v[180:183], v193 offset:34816
	ds_read_b128 v[184:187], v193 offset:35840
	ds_read_b128 v[188:191], v193 offset:36864
	ds_read_b128 v[196:199], v193 offset:37888
	ds_read_b128 v[200:203], v193 offset:38912
	ds_read_b128 v[204:207], v193 offset:39936
	global_load_lds_dwordx4 v[212:213], off
	v_lshl_add_u64 v[212:213], v[210:211], 0, s[36:37]
	s_mov_b32 m0, s52
	s_nop 0
	global_load_lds_dwordx4 v[212:213], off
	s_waitcnt vmcnt(8)
	s_waitcnt lgkmcnt(0)
	s_barrier
	s_waitcnt lgkmcnt(0)
	s_setprio 1
	v_mfma_f32_16x16x32_bf16 v[146:149], v[74:77], v[162:165], v[146:149]
	v_mfma_f32_16x16x32_bf16 v[142:145], v[90:93], v[162:165], v[142:145]
	v_mfma_f32_16x16x32_bf16 v[126:129], v[74:77], v[180:183], v[126:129]
	v_mfma_f32_16x16x32_bf16 v[122:125], v[90:93], v[180:183], v[122:125]
	v_mfma_f32_16x16x32_bf16 v[110:113], v[74:77], v[188:191], v[110:113]
	v_mfma_f32_16x16x32_bf16 v[106:109], v[90:93], v[188:191], v[106:109]
	v_mfma_f32_16x16x32_bf16 v[86:89], v[74:77], v[200:203], v[86:89]
	v_mfma_f32_16x16x32_bf16 v[78:81], v[90:93], v[200:203], v[78:81]
	v_mfma_f32_16x16x32_bf16 v[146:149], v[82:85], v[166:169], v[146:149]
	v_mfma_f32_16x16x32_bf16 v[142:145], v[94:97], v[166:169], v[142:145]
	v_mfma_f32_16x16x32_bf16 v[126:129], v[82:85], v[184:187], v[126:129]
	v_mfma_f32_16x16x32_bf16 v[122:125], v[94:97], v[184:187], v[122:125]
	v_mfma_f32_16x16x32_bf16 v[110:113], v[82:85], v[196:199], v[110:113]
	v_mfma_f32_16x16x32_bf16 v[106:109], v[94:97], v[196:199], v[106:109]
	v_mfma_f32_16x16x32_bf16 v[86:89], v[82:85], v[204:207], v[86:89]
	v_mfma_f32_16x16x32_bf16 v[78:81], v[94:97], v[204:207], v[78:81]
	v_mfma_f32_16x16x32_bf16 v[134:137], v[138:141], v[162:165], v[134:137]
	v_mfma_f32_16x16x32_bf16 v[130:133], v[154:157], v[162:165], v[130:133]
	v_mfma_f32_16x16x32_bf16 v[118:121], v[138:141], v[180:183], v[118:121]
	v_mfma_f32_16x16x32_bf16 v[114:117], v[154:157], v[180:183], v[114:117]
	v_mfma_f32_16x16x32_bf16 v[102:105], v[138:141], v[188:191], v[102:105]
	v_mfma_f32_16x16x32_bf16 v[98:101], v[154:157], v[188:191], v[98:101]
	v_mfma_f32_16x16x32_bf16 v[70:73], v[138:141], v[200:203], v[70:73]
	v_mfma_f32_16x16x32_bf16 v[66:69], v[154:157], v[200:203], v[66:69]
	v_mfma_f32_16x16x32_bf16 v[134:137], v[150:153], v[166:169], v[134:137]
	v_mfma_f32_16x16x32_bf16 v[130:133], v[158:161], v[166:169], v[130:133]
	v_mfma_f32_16x16x32_bf16 v[118:121], v[150:153], v[184:187], v[118:121]
	v_mfma_f32_16x16x32_bf16 v[114:117], v[158:161], v[184:187], v[114:117]
	v_mfma_f32_16x16x32_bf16 v[102:105], v[150:153], v[196:199], v[102:105]
	v_mfma_f32_16x16x32_bf16 v[98:101], v[158:161], v[196:199], v[98:101]
	v_mfma_f32_16x16x32_bf16 v[70:73], v[150:153], v[204:207], v[70:73]
	v_mfma_f32_16x16x32_bf16 v[66:69], v[158:161], v[204:207], v[66:69]
	s_setprio 0
	s_barrier
; #define PG8_WAIT_V(n) asm volatile("s_waitcnt vmcnt(" #n ")" ::: "memory")
; #define PG8_BAR __builtin_amdgcn_s_barrier()
; template <class Epi, class Sched, bool ALIGN_EPI = true, bool SP2 = true, bool FULLLINE = false, bool NOSTAGE = false, bool FP8 = false>
; __device__ __forceinline__ void gemm_phase(PG8_LAS unsigned char* lds, const Gemm g, const Sched& S, const Epi& E) {
;     ...
;         for (int t = 2; t < nt; t += 2) PG8_ITER(PG8_WAIT_V(8));
;     ...
;         if constexpr (ALIGN_EPI) { if (wr == 0) PG8_BAR; }
	s_mov_b32 m0, s50
	v_lshl_add_u64 v[212:213], v[208:209], 0, s[38:39]
	ds_read_b128 v[162:165], v193 offset:49152
	ds_read_b128 v[166:169], v193 offset:50176
	ds_read_b128 v[180:183], v193 offset:51200
	ds_read_b128 v[184:187], v193 offset:52224
	ds_read_b128 v[188:191], v193 offset:53248
	ds_read_b128 v[196:199], v193 offset:54272
	ds_read_b128 v[200:203], v193 offset:55296
	ds_read_b128 v[204:207], v193 offset:56320
	global_load_lds_dwordx4 v[212:213], off
	v_lshl_add_u64 v[212:213], v[208:209], 0, s[66:67]
	s_mov_b32 m0, s51
	s_nop 0
	global_load_lds_dwordx4 v[212:213], off
	v_lshl_add_u64 v[212:213], v[208:209], 0, s[14:15]
	s_mov_b32 m0, s33
	v_lshl_add_u64 v[208:209], v[208:209], 0, s[16:17]
	global_load_lds_dwordx4 v[212:213], off
	s_mov_b32 m0, s56
	s_nop 0
	global_load_lds_dwordx4 v[208:209], off
	v_lshl_add_u64 v[208:209], v[210:211], 0, s[38:39]
	s_mov_b32 m0, s53
	s_nop 0
	global_load_lds_dwordx4 v[208:209], off
	v_lshl_add_u64 v[208:209], v[210:211], 0, s[66:67]
	s_mov_b32 m0, s54
	s_nop 0
	global_load_lds_dwordx4 v[208:209], off
	s_waitcnt vmcnt(8)
	s_waitcnt lgkmcnt(0)
	s_barrier
	s_waitcnt lgkmcnt(0)
	s_setprio 1
	v_mfma_f32_16x16x32_bf16 v[62:65], v[74:77], v[162:165], v[62:65]
	v_mfma_f32_16x16x32_bf16 v[58:61], v[90:93], v[162:165], v[58:61]
	v_mfma_f32_16x16x32_bf16 v[46:49], v[74:77], v[180:183], v[46:49]
	v_mfma_f32_16x16x32_bf16 v[42:45], v[90:93], v[180:183], v[42:45]
	v_mfma_f32_16x16x32_bf16 v[30:33], v[74:77], v[188:191], v[30:33]
	v_mfma_f32_16x16x32_bf16 v[26:29], v[90:93], v[188:191], v[26:29]
	v_mfma_f32_16x16x32_bf16 v[14:17], v[74:77], v[200:203], v[14:17]
	v_mfma_f32_16x16x32_bf16 v[10:13], v[90:93], v[200:203], v[10:13]
	v_mfma_f32_16x16x32_bf16 v[62:65], v[82:85], v[166:169], v[62:65]
	v_mfma_f32_16x16x32_bf16 v[58:61], v[94:97], v[166:169], v[58:61]
	v_mfma_f32_16x16x32_bf16 v[46:49], v[82:85], v[184:187], v[46:49]
	v_mfma_f32_16x16x32_bf16 v[42:45], v[94:97], v[184:187], v[42:45]
	v_mfma_f32_16x16x32_bf16 v[30:33], v[82:85], v[196:199], v[30:33]
	v_mfma_f32_16x16x32_bf16 v[26:29], v[94:97], v[196:199], v[26:29]
	v_mfma_f32_16x16x32_bf16 v[14:17], v[82:85], v[204:207], v[14:17]
	v_mfma_f32_16x16x32_bf16 v[10:13], v[94:97], v[204:207], v[10:13]
	v_mfma_f32_16x16x32_bf16 v[54:57], v[138:141], v[162:165], v[54:57]
	v_mfma_f32_16x16x32_bf16 v[50:53], v[154:157], v[162:165], v[50:53]
	v_mfma_f32_16x16x32_bf16 v[38:41], v[138:141], v[180:183], v[38:41]
	v_mfma_f32_16x16x32_bf16 v[34:37], v[154:157], v[180:183], v[34:37]
	v_mfma_f32_16x16x32_bf16 v[22:25], v[138:141], v[188:191], v[22:25]
	v_mfma_f32_16x16x32_bf16 v[18:21], v[154:157], v[188:191], v[18:21]
	v_mfma_f32_16x16x32_bf16 v[6:9], v[138:141], v[200:203], v[6:9]
	v_mfma_f32_16x16x32_bf16 v[2:5], v[154:157], v[200:203], v[2:5]
	v_mfma_f32_16x16x32_bf16 v[54:57], v[150:153], v[166:169], v[54:57]
	v_mfma_f32_16x16x32_bf16 v[50:53], v[158:161], v[166:169], v[50:53]
	v_mfma_f32_16x16x32_bf16 v[38:41], v[150:153], v[184:187], v[38:41]
	v_mfma_f32_16x16x32_bf16 v[34:37], v[158:161], v[184:187], v[34:37]
	v_mfma_f32_16x16x32_bf16 v[22:25], v[150:153], v[196:199], v[22:25]
	v_mfma_f32_16x16x32_bf16 v[18:21], v[158:161], v[196:199], v[18:21]
	v_mfma_f32_16x16x32_bf16 v[6:9], v[150:153], v[204:207], v[6:9]
	v_mfma_f32_16x16x32_bf16 v[2:5], v[158:161], v[204:207], v[2:5]
	s_setprio 0
	s_barrier
	s_add_i32 s73, s73, 2
	s_add_u32 s70, s70, 0x100
	s_addc_u32 s71, s71, 0
	s_add_u32 s57, s57, 0x100
	s_addc_u32 s72, s72, 0
	s_cmpk_gt_u32 s73, 0x55
	s_cbranch_scc0 .LBB0_1484
	s_and_b64 vcc, exec, s[12:13]
	s_cbranch_vccz .LBB0_1487
	s_barrier

; #define PG8_STAGE(bufoff, gbase, voff) do { if constexpr (!NOSTAGE) _Pragma("unroll") for (int _i = 0; _i < 2; ++_i) \
;         __builtin_amdgcn_global_load_lds((const unsigned*)((const char*)(gbase) + (size_t)_i * pstep##voff + v##voff), (PG8_LAS unsigned*)(lds + (bufoff) + ldsw + _i * 8192), 16, 0, 0); } while (0)
; #define PG8_WAIT_V(n) asm volatile("s_waitcnt vmcnt(" #n ")" ::: "memory")
; #define PG8_BAR __builtin_amdgcn_s_barrier()
; template <class Epi, class Sched, bool ALIGN_EPI = true, bool SP2 = true, bool FULLLINE = false, bool NOSTAGE = false, bool FP8 = false>
; __device__ __forceinline__ void gemm_phase(PG8_LAS unsigned char* lds, const Gemm g, const Sched& S, const Epi& E) {
;     const int tid = threadIdx.x, wid = __builtin_amdgcn_readfirstlane(tid >> 6), lane = tid & 63, wr = wid >> 2, wc = wid & 3, fr = lane & 15, fq = lane >> 4;
;     const int K = g.K, nt = K / BK;
;     unsigned voffA_, voffB_;
;     { int R, C; stage_rc(tid * 16, R, C); const int Rb = Epi::PERM ? ((R & ~31) + perm32(R & 31)) : R;
;       voffA_ = (unsigned)(R * g.lda + C) * 2u; voffB_ = (unsigned)(Rb * g.ldb + C) * 2u; }
;     const unsigned voffA = voffA_, voffB = voffB_;
;     const size_t pstepoffA = (size_t)64 * g.lda * 2, pstepoffB = (size_t)64 * g.ldb * 2;
;     const size_t kstep = (size_t)(BK * 2);
;     const size_t hstepA = (size_t)HALF * g.lda * 2, hstepB = (size_t)HALF * g.ldb * 2;
;     const size_t tstepA = 2 * hstepA, tstepB = 2 * hstepB;
;     const unsigned ldsw = (unsigned)wid * 1024u;
;     const int aoff = lds_byte(wr * 64 + fr, fq * 8), boff = lds_byte(wc * 32 + fr, fq * 8);
;     ...
;     if (wr == 1) PG8_BAR;
;     PG8_WAIT_V(0); PG8_BAR;
;     PG8_BAR;
;     } else {
;     PG8_STAGE(PG8_SB(0, 0), cB, offB); PG8_STAGE(PG8_SA(0, 0), cA, offA); PG8_STAGE(PG8_SB(0, 1), cB + hstepB, offB); PG8_STAGE(PG8_SA(0, 1), cA + hstepA, offA);
;     if (wr == 1) PG8_BAR;
;     PG8_WAIT_V(4); PG8_BAR;
;     PG8_STAGE(PG8_SB(1, 0), cB + kstep, offB); PG8_STAGE(PG8_SA(1, 0), cA + kstep, offA); PG8_STAGE(PG8_SB(1, 1), cB + hstepB + kstep, offB);
;     PG8_WAIT_V(6); PG8_BAR;
;     }
;     if (wr == 1) __builtin_amdgcn_s_setprio(1);
.LBB0_1638:
	s_waitcnt vmcnt(0)
	v_cndmask_b32_e64 v4, 0, 1, s[8:9]
	v_cmp_ne_u32_e64 s[6:7], 1, v4
	s_andn2_b64 vcc, exec, s[8:9]
	s_barrier
	s_barrier
	s_cbranch_vccnz .LBB0_1640
.LBB0_1640:
	s_add_u32 s63, s48, 0x21f00000
	s_addc_u32 s88, s49, 0
	v_and_b32_e32 v4, 48, v0
	v_lshlrev_b32_e32 v5, 6, v0
	s_movk_i32 s1, 0x3c0
	s_add_u32 s89, s48, 0x29f00000
	v_and_or_b32 v4, v5, s1, v4
	v_lshlrev_b32_e32 v5, 2, v0
	s_addc_u32 s90, s49, 0
	s_lshl_b32 s0, s13, 13
	v_and_b32_e32 v5, 32, v5
	v_bitop3_b32 v6, v4, s0, v5 bitop3:0xde
	s_lshl_b32 s0, s12, 5
	s_and_b32 s92, s0, 0x60
	s_lshl_b32 s0, s92, 7
	s_lshl_b32 s91, s13, 6
	v_bitop3_b32 v4, s0, v4, v5 bitop3:0xf6
	v_lshlrev_b32_e32 v5, 9, v0
	s_cmpk_lt_u32 s3, 0x100
	v_and_b32_e32 v5, 0x30000, v5
	v_lshlrev_b32_e32 v1, 12, v1
	s_cselect_b64 s[12:13], -1, 0
	v_or3_b32 v1, v2, v5, v1
	s_add_i32 s95, 0, 0x10000
	s_add_i32 s96, 0, 0x14000
	s_add_i32 s3, 0, 0x18000
	s_add_i32 s42, 0, 0x1c000
	s_ashr_i32 s93, s86, 31
	s_ashr_i32 s94, s2, 31
	v_add_u32_e32 v134, v1, v3
	v_mov_b32_e32 v135, 0
	s_mov_b32 s15, 0
	v_mov_b64_e32 v[136:137], 0x600
	v_mov_b64_e32 v[138:139], 0x5ff
	v_add_u32_e32 v144, s95, v4
	v_add_u32_e32 v145, s96, v4
	v_add_u32_e32 v146, 0, v6
	s_mov_b64 s[16:17], 0x80080
	s_add_i32 s97, s87, 0xc000
	s_mov_b64 s[18:19], 0xc0080
	s_add_i32 s47, s87, 0xe000
	s_mov_b64 s[20:21], 0x100
	s_mov_b64 s[22:23], 0x40100
	s_mov_b64 s[24:25], 0x80100
	s_mov_b64 s[26:27], 0xc0100
	v_add_u32_e32 v147, s3, v4
	v_add_u32_e32 v148, s42, v4
	s_mov_b64 s[28:29], 0x180
	s_mov_b64 s[30:31], 0x40180
	s_mov_b64 s[34:35], 0x40000
	s_mov_b64 s[36:37], 0x80000
	s_mov_b64 s[38:39], 0xc0000
	s_mov_b64 s[40:41], 0x80
	s_mov_b64 s[66:67], 0x40080
	s_mov_b32 s43, 0
	s_branch .LBB0_1643

; #define PG8_WAIT_V(n) asm volatile("s_waitcnt vmcnt(" #n ")" ::: "memory")
; template <class Epi, class Sched, bool ALIGN_EPI = true, bool SP2 = true, bool FULLLINE = false, bool NOSTAGE = false, bool FP8 = false>
; __device__ __forceinline__ void gemm_phase(PG8_LAS unsigned char* lds, const Gemm g, const Sched& S, const Epi& E) {
;     ...
;         const char* nA = has_next ? PG8_ABASE(nxt) : cA; const char* nB = has_next ? PG8_BBASE(nxt) : cB;
;     ...
;         static_assert(SP2, "only the SP2 loop is kept");
;         { const int t = 0; if constexpr (Epi::NST == 16) PG8_ITER(PG8_WAIT_V(24)); else if constexpr (Epi::NST == 8) PG8_ITER(PG8_WAIT_V(16)); else PG8_ITER(PG8_WAIT_V(8)); }
.LBB0_1645:
	s_ashr_i32 s71, s70, 31
	s_lshl_b64 s[0:1], s[70:71], 20
	s_add_u32 s72, s58, s0
	ds_read_b128 v[2:5], v144
	ds_read_b128 v[6:9], v144 offset:1024
	ds_read_b128 v[10:13], v144 offset:2048
	ds_read_b128 v[14:17], v144 offset:3072
	ds_read_b128 v[18:21], v145
	ds_read_b128 v[22:25], v145 offset:1024
	ds_read_b128 v[26:29], v145 offset:2048
	ds_read_b128 v[30:33], v145 offset:3072
	s_addc_u32 s73, s59, s1
	s_ashr_i32 s69, s68, 31
	s_lshl_b64 s[0:1], s[68:69], 20
	s_add_u32 s74, s44, s0
	s_addc_u32 s75, s45, s1
	s_and_b64 s[0:1], s[8:9], exec
	s_cselect_b32 s11, s73, s79
	s_cselect_b32 s14, s72, s78
	s_cselect_b32 s69, s75, s77
	s_cselect_b32 s71, s74, s76
	v_lshl_add_u64 v[242:243], s[78:79], 0, v[130:131]
	s_mov_b32 m0, s97
	v_lshl_add_u64 v[66:67], v[242:243], 0, s[16:17]
	ds_read_b128 v[34:37], v146
	ds_read_b128 v[38:41], v146 offset:1024
	ds_read_b128 v[42:45], v146 offset:2048
	ds_read_b128 v[46:49], v146 offset:3072
	ds_read_b128 v[50:53], v146 offset:4096
	ds_read_b128 v[54:57], v146 offset:5120
	ds_read_b128 v[58:61], v146 offset:6144
	ds_read_b128 v[62:65], v146 offset:7168
	global_load_lds_dwordx4 v[66:67], off
	v_lshl_add_u64 v[66:67], v[242:243], 0, s[18:19]
	s_mov_b32 m0, s47
	s_nop 0
	global_load_lds_dwordx4 v[66:67], off
	s_waitcnt vmcnt(24)
	s_waitcnt lgkmcnt(0)
	s_barrier
	s_waitcnt lgkmcnt(0)
	s_setprio 1
	v_mfma_f32_16x16x32_bf16 v[90:93], v[2:5], v[58:61], 0
	v_mfma_f32_16x16x32_bf16 v[66:69], v[2:5], v[34:37], 0
	v_mfma_f32_16x16x32_bf16 v[70:73], v[10:13], v[34:37], 0
	v_mfma_f32_16x16x32_bf16 v[74:77], v[2:5], v[42:45], 0
	v_mfma_f32_16x16x32_bf16 v[78:81], v[10:13], v[42:45], 0
	v_mfma_f32_16x16x32_bf16 v[82:85], v[2:5], v[50:53], 0
	v_mfma_f32_16x16x32_bf16 v[86:89], v[10:13], v[50:53], 0
	v_mfma_f32_16x16x32_bf16 v[98:101], v[6:9], v[62:65], v[90:93]
	v_mfma_f32_16x16x32_bf16 v[90:93], v[10:13], v[58:61], 0
	v_mfma_f32_16x16x32_bf16 v[66:69], v[6:9], v[38:41], v[66:69]
	v_mfma_f32_16x16x32_bf16 v[70:73], v[14:17], v[38:41], v[70:73]
	v_mfma_f32_16x16x32_bf16 v[74:77], v[6:9], v[46:49], v[74:77]
	v_mfma_f32_16x16x32_bf16 v[78:81], v[14:17], v[46:49], v[78:81]
	v_mfma_f32_16x16x32_bf16 v[82:85], v[6:9], v[54:57], v[82:85]
	v_mfma_f32_16x16x32_bf16 v[86:89], v[14:17], v[54:57], v[86:89]
	v_mfma_f32_16x16x32_bf16 v[102:105], v[14:17], v[62:65], v[90:93]
	v_mfma_f32_16x16x32_bf16 v[90:93], v[18:21], v[34:37], 0
	v_mfma_f32_16x16x32_bf16 v[34:37], v[26:29], v[34:37], 0
	v_mfma_f32_16x16x32_bf16 v[114:117], v[22:25], v[38:41], v[90:93]
	v_mfma_f32_16x16x32_bf16 v[34:37], v[30:33], v[38:41], v[34:37]
	v_mfma_f32_16x16x32_bf16 v[38:41], v[18:21], v[42:45], 0
	v_mfma_f32_16x16x32_bf16 v[42:45], v[26:29], v[42:45], 0
	v_mfma_f32_16x16x32_bf16 v[38:41], v[22:25], v[46:49], v[38:41]
	v_mfma_f32_16x16x32_bf16 v[42:45], v[30:33], v[46:49], v[42:45]
	v_mfma_f32_16x16x32_bf16 v[46:49], v[18:21], v[50:53], 0
	v_mfma_f32_16x16x32_bf16 v[50:53], v[26:29], v[50:53], 0
	v_mfma_f32_16x16x32_bf16 v[46:49], v[22:25], v[54:57], v[46:49]
	v_mfma_f32_16x16x32_bf16 v[50:53], v[30:33], v[54:57], v[50:53]
	v_mfma_f32_16x16x32_bf16 v[54:57], v[18:21], v[58:61], 0
	v_mfma_f32_16x16x32_bf16 v[58:61], v[26:29], v[58:61], 0
	v_mfma_f32_16x16x32_bf16 v[54:57], v[22:25], v[62:65], v[54:57]
	v_mfma_f32_16x16x32_bf16 v[58:61], v[30:33], v[62:65], v[58:61]
	s_setprio 0
	s_barrier
	v_lshl_add_u64 v[244:245], s[76:77], 0, v[132:133]
	s_add_i32 s81, s95, s46
	v_lshl_add_u64 v[140:141], v[244:245], 0, s[20:21]
	s_mov_b32 m0, s81
	s_add_i32 s82, s81, 0x2000
	ds_read_b128 v[62:65], v146 offset:16384
	ds_read_b128 v[90:93], v146 offset:17408
	ds_read_b128 v[94:97], v146 offset:18432
	ds_read_b128 v[106:109], v146 offset:19456
	ds_read_b128 v[110:113], v146 offset:20480
	ds_read_b128 v[118:121], v146 offset:21504
	ds_read_b128 v[122:125], v146 offset:22528
	ds_read_b128 v[126:129], v146 offset:23552
	global_load_lds_dwordx4 v[140:141], off
	v_lshl_add_u64 v[140:141], v[244:245], 0, s[22:23]
	s_mov_b32 m0, s82
	s_add_i32 s83, s96, s46
	global_load_lds_dwordx4 v[140:141], off
	v_lshl_add_u64 v[140:141], v[244:245], 0, s[24:25]
	s_mov_b32 m0, s83
	s_add_i32 s84, s83, 0x2000
	global_load_lds_dwordx4 v[140:141], off
	v_lshl_add_u64 v[140:141], v[244:245], 0, s[26:27]
	s_mov_b32 m0, s84
	s_nop 0
	global_load_lds_dwordx4 v[140:141], off
	v_lshl_add_u64 v[140:141], v[242:243], 0, s[20:21]
	s_mov_b32 m0, s87
	s_nop 0
	global_load_lds_dwordx4 v[140:141], off
	v_lshl_add_u64 v[140:141], v[242:243], 0, s[22:23]
	s_mov_b32 m0, s52
	s_nop 0
	global_load_lds_dwordx4 v[140:141], off
	s_waitcnt vmcnt(24)
	s_waitcnt lgkmcnt(0)
	s_barrier
	s_waitcnt lgkmcnt(0)
	s_setprio 1
	v_mfma_f32_16x16x32_bf16 v[140:143], v[2:5], v[62:65], 0
	v_mfma_f32_16x16x32_bf16 v[154:157], v[2:5], v[94:97], 0
	v_mfma_f32_16x16x32_bf16 v[162:165], v[2:5], v[110:113], 0
	v_mfma_f32_16x16x32_bf16 v[2:5], v[2:5], v[122:125], 0
	v_mfma_f32_16x16x32_bf16 v[140:143], v[6:9], v[90:93], v[140:143]
	v_mfma_f32_16x16x32_bf16 v[154:157], v[6:9], v[106:109], v[154:157]
	v_mfma_f32_16x16x32_bf16 v[162:165], v[6:9], v[118:121], v[162:165]
	v_mfma_f32_16x16x32_bf16 v[2:5], v[6:9], v[126:129], v[2:5]
	v_mfma_f32_16x16x32_bf16 v[6:9], v[10:13], v[122:125], 0
	v_mfma_f32_16x16x32_bf16 v[150:153], v[10:13], v[62:65], 0
	v_mfma_f32_16x16x32_bf16 v[158:161], v[10:13], v[94:97], 0
	v_mfma_f32_16x16x32_bf16 v[166:169], v[10:13], v[110:113], 0
	v_mfma_f32_16x16x32_bf16 v[6:9], v[14:17], v[126:129], v[6:9]
	v_mfma_f32_16x16x32_bf16 v[150:153], v[14:17], v[90:93], v[150:153]
	v_mfma_f32_16x16x32_bf16 v[158:161], v[14:17], v[106:109], v[158:161]
	v_mfma_f32_16x16x32_bf16 v[166:169], v[14:17], v[118:121], v[166:169]
	v_mfma_f32_16x16x32_bf16 v[10:13], v[18:21], v[62:65], 0
	v_mfma_f32_16x16x32_bf16 v[170:173], v[22:25], v[90:93], v[10:13]
	v_mfma_f32_16x16x32_bf16 v[10:13], v[26:29], v[62:65], 0
	v_mfma_f32_16x16x32_bf16 v[174:177], v[30:33], v[90:93], v[10:13]
	v_mfma_f32_16x16x32_bf16 v[10:13], v[18:21], v[94:97], 0
	v_mfma_f32_16x16x32_bf16 v[178:181], v[22:25], v[106:109], v[10:13]
	v_mfma_f32_16x16x32_bf16 v[10:13], v[26:29], v[94:97], 0
	v_mfma_f32_16x16x32_bf16 v[182:185], v[30:33], v[106:109], v[10:13]
	v_mfma_f32_16x16x32_bf16 v[10:13], v[18:21], v[110:113], 0
	v_mfma_f32_16x16x32_bf16 v[186:189], v[22:25], v[118:121], v[10:13]
	v_mfma_f32_16x16x32_bf16 v[10:13], v[26:29], v[110:113], 0
	v_mfma_f32_16x16x32_bf16 v[190:193], v[30:33], v[118:121], v[10:13]
	v_mfma_f32_16x16x32_bf16 v[10:13], v[18:21], v[122:125], 0
	v_mfma_f32_16x16x32_bf16 v[194:197], v[22:25], v[126:129], v[10:13]
	v_mfma_f32_16x16x32_bf16 v[10:13], v[26:29], v[122:125], 0
	v_mfma_f32_16x16x32_bf16 v[198:201], v[30:33], v[126:129], v[10:13]
	s_setprio 0
	s_barrier
; #define PG8_WAIT_V(n) asm volatile("s_waitcnt vmcnt(" #n ")" ::: "memory")
; template <class Epi, class Sched, bool ALIGN_EPI = true, bool SP2 = true, bool FULLLINE = false, bool NOSTAGE = false, bool FP8 = false>
; __device__ __forceinline__ void gemm_phase(PG8_LAS unsigned char* lds, const Gemm g, const Sched& S, const Epi& E) {
;     ...
;         static_assert(SP2, "only the SP2 loop is kept");
;         { const int t = 0; if constexpr (Epi::NST == 16) PG8_ITER(PG8_WAIT_V(24)); else if constexpr (Epi::NST == 8) PG8_ITER(PG8_WAIT_V(16)); else PG8_ITER(PG8_WAIT_V(8)); }
	s_nop 5
	ds_read_b128 v[10:13], v147
	ds_read_b128 v[14:17], v147 offset:1024
	ds_read_b128 v[18:21], v147 offset:2048
	ds_read_b128 v[22:25], v147 offset:3072
	ds_read_b128 v[202:205], v148
	ds_read_b128 v[206:209], v148 offset:1024
	ds_read_b128 v[210:213], v148 offset:2048
	ds_read_b128 v[214:217], v148 offset:3072
	s_mov_b32 m0, s53
	v_lshl_add_u64 v[90:91], v[242:243], 0, s[24:25]
	ds_read_b128 v[26:29], v146 offset:32768
	ds_read_b128 v[30:33], v146 offset:33792
	ds_read_b128 v[62:65], v146 offset:34816
	ds_read_b128 v[218:221], v146 offset:35840
	ds_read_b128 v[222:225], v146 offset:36864
	ds_read_b128 v[226:229], v146 offset:37888
	ds_read_b128 v[230:233], v146 offset:38912
	ds_read_b128 v[234:237], v146 offset:39936
	global_load_lds_dwordx4 v[90:91], off
	v_lshl_add_u64 v[90:91], v[242:243], 0, s[26:27]
	s_mov_b32 m0, s54
	s_nop 0
	global_load_lds_dwordx4 v[90:91], off
	s_waitcnt vmcnt(8)
	s_waitcnt lgkmcnt(0)
	s_barrier
	s_waitcnt lgkmcnt(0)
	s_setprio 1
	v_mfma_f32_16x16x32_bf16 v[66:69], v[10:13], v[26:29], v[66:69]
	v_mfma_f32_16x16x32_bf16 v[126:129], v[14:17], v[30:33], v[66:69]
	v_mfma_f32_16x16x32_bf16 v[66:69], v[18:21], v[26:29], v[70:73]
	v_mfma_f32_16x16x32_bf16 v[122:125], v[22:25], v[30:33], v[66:69]
	v_mfma_f32_16x16x32_bf16 v[66:69], v[10:13], v[62:65], v[74:77]
	v_mfma_f32_16x16x32_bf16 v[110:113], v[14:17], v[218:221], v[66:69]
	v_mfma_f32_16x16x32_bf16 v[66:69], v[18:21], v[62:65], v[78:81]
	v_mfma_f32_16x16x32_bf16 v[106:109], v[22:25], v[218:221], v[66:69]
	v_mfma_f32_16x16x32_bf16 v[66:69], v[10:13], v[222:225], v[82:85]
	v_mfma_f32_16x16x32_bf16 v[94:97], v[14:17], v[226:229], v[66:69]
	v_mfma_f32_16x16x32_bf16 v[66:69], v[18:21], v[222:225], v[86:89]
	v_mfma_f32_16x16x32_bf16 v[90:93], v[22:25], v[226:229], v[66:69]
	v_mfma_f32_16x16x32_bf16 v[66:69], v[10:13], v[230:233], v[98:101]
	v_mfma_f32_16x16x32_bf16 v[78:81], v[14:17], v[234:237], v[66:69]
	v_mfma_f32_16x16x32_bf16 v[66:69], v[18:21], v[230:233], v[102:105]
	v_mfma_f32_16x16x32_bf16 v[74:77], v[22:25], v[234:237], v[66:69]
	v_mfma_f32_16x16x32_bf16 v[66:69], v[202:205], v[26:29], v[114:117]
	v_mfma_f32_16x16x32_bf16 v[26:29], v[210:213], v[26:29], v[34:37]
	v_mfma_f32_16x16x32_bf16 v[114:117], v[214:217], v[30:33], v[26:29]
	v_mfma_f32_16x16x32_bf16 v[26:29], v[202:205], v[62:65], v[38:41]
	v_mfma_f32_16x16x32_bf16 v[102:105], v[206:209], v[218:221], v[26:29]
	v_mfma_f32_16x16x32_bf16 v[26:29], v[210:213], v[62:65], v[42:45]
	v_mfma_f32_16x16x32_bf16 v[98:101], v[214:217], v[218:221], v[26:29]
	v_mfma_f32_16x16x32_bf16 v[26:29], v[202:205], v[222:225], v[46:49]
	v_mfma_f32_16x16x32_bf16 v[86:89], v[206:209], v[226:229], v[26:29]
	v_mfma_f32_16x16x32_bf16 v[26:29], v[210:213], v[222:225], v[50:53]
	v_mfma_f32_16x16x32_bf16 v[82:85], v[214:217], v[226:229], v[26:29]
	v_mfma_f32_16x16x32_bf16 v[26:29], v[202:205], v[230:233], v[54:57]
	v_mfma_f32_16x16x32_bf16 v[70:73], v[206:209], v[234:237], v[26:29]
	v_mfma_f32_16x16x32_bf16 v[26:29], v[210:213], v[230:233], v[58:61]
	v_mfma_f32_16x16x32_bf16 v[118:121], v[206:209], v[30:33], v[66:69]
	v_mfma_f32_16x16x32_bf16 v[66:69], v[214:217], v[234:237], v[26:29]
	s_setprio 0
	s_barrier
	s_add_i32 s50, s3, s46
	s_nop 3
	v_lshl_add_u64 v[26:27], v[244:245], 0, s[28:29]
	s_mov_b32 m0, s50
	s_add_i32 s51, s50, 0x2000
	ds_read_b128 v[34:37], v146 offset:49152
	ds_read_b128 v[38:41], v146 offset:50176
	ds_read_b128 v[218:221], v146 offset:51200
	ds_read_b128 v[222:225], v146 offset:52224
	ds_read_b128 v[226:229], v146 offset:53248
	ds_read_b128 v[230:233], v146 offset:54272
	ds_read_b128 v[234:237], v146 offset:55296
	ds_read_b128 v[238:241], v146 offset:56320
	global_load_lds_dwordx4 v[26:27], off
	v_lshl_add_u64 v[26:27], v[244:245], 0, s[30:31]
	s_mov_b32 m0, s51
	s_mov_b64 s[0:1], 0x80180
	s_add_i32 s33, s42, s46
	global_load_lds_dwordx4 v[26:27], off
	v_lshl_add_u64 v[26:27], v[244:245], 0, s[0:1]
	s_mov_b32 m0, s33
	s_mov_b64 s[0:1], 0xc0180
	s_add_i32 s56, s33, 0x2000
	global_load_lds_dwordx4 v[26:27], off
	v_lshl_add_u64 v[26:27], v[244:245], 0, s[0:1]
	s_mov_b32 m0, s56
	s_nop 0
	global_load_lds_dwordx4 v[26:27], off
	v_lshl_add_u64 v[26:27], v[242:243], 0, s[28:29]
	s_mov_b32 m0, s55
	s_nop 0
	global_load_lds_dwordx4 v[26:27], off
	v_lshl_add_u64 v[26:27], v[242:243], 0, s[30:31]
	s_mov_b32 m0, s62
	s_nop 0
	global_load_lds_dwordx4 v[26:27], off
	s_waitcnt vmcnt(8)
	s_waitcnt lgkmcnt(0)
	s_barrier
	s_waitcnt lgkmcnt(0)
	s_setprio 1
	v_mfma_f32_16x16x32_bf16 v[26:29], v[10:13], v[34:37], v[140:143]
	v_mfma_f32_16x16x32_bf16 v[62:65], v[14:17], v[38:41], v[26:29]
	v_mfma_f32_16x16x32_bf16 v[26:29], v[18:21], v[34:37], v[150:153]
	v_mfma_f32_16x16x32_bf16 v[58:61], v[22:25], v[38:41], v[26:29]
	v_mfma_f32_16x16x32_bf16 v[26:29], v[10:13], v[218:221], v[154:157]
	v_mfma_f32_16x16x32_bf16 v[46:49], v[14:17], v[222:225], v[26:29]
	v_mfma_f32_16x16x32_bf16 v[26:29], v[18:21], v[218:221], v[158:161]
	v_mfma_f32_16x16x32_bf16 v[42:45], v[22:25], v[222:225], v[26:29]
	v_mfma_f32_16x16x32_bf16 v[26:29], v[10:13], v[226:229], v[162:165]
	v_mfma_f32_16x16x32_bf16 v[2:5], v[10:13], v[234:237], v[2:5]
	v_mfma_f32_16x16x32_bf16 v[30:33], v[14:17], v[230:233], v[26:29]
	v_mfma_f32_16x16x32_bf16 v[26:29], v[18:21], v[226:229], v[166:169]
	v_mfma_f32_16x16x32_bf16 v[14:17], v[14:17], v[238:241], v[2:5]
	v_mfma_f32_16x16x32_bf16 v[2:5], v[18:21], v[234:237], v[6:9]
	v_mfma_f32_16x16x32_bf16 v[26:29], v[22:25], v[230:233], v[26:29]
	v_mfma_f32_16x16x32_bf16 v[10:13], v[22:25], v[238:241], v[2:5]
	v_mfma_f32_16x16x32_bf16 v[2:5], v[202:205], v[34:37], v[170:173]
	v_mfma_f32_16x16x32_bf16 v[54:57], v[206:209], v[38:41], v[2:5]
	v_mfma_f32_16x16x32_bf16 v[2:5], v[210:213], v[34:37], v[174:177]
	v_mfma_f32_16x16x32_bf16 v[50:53], v[214:217], v[38:41], v[2:5]
	v_mfma_f32_16x16x32_bf16 v[2:5], v[202:205], v[218:221], v[178:181]
	v_mfma_f32_16x16x32_bf16 v[38:41], v[206:209], v[222:225], v[2:5]
	v_mfma_f32_16x16x32_bf16 v[2:5], v[210:213], v[218:221], v[182:185]
	v_mfma_f32_16x16x32_bf16 v[34:37], v[214:217], v[222:225], v[2:5]
	v_mfma_f32_16x16x32_bf16 v[2:5], v[202:205], v[226:229], v[186:189]
	v_mfma_f32_16x16x32_bf16 v[22:25], v[206:209], v[230:233], v[2:5]
	v_mfma_f32_16x16x32_bf16 v[2:5], v[210:213], v[226:229], v[190:193]
	v_mfma_f32_16x16x32_bf16 v[18:21], v[214:217], v[230:233], v[2:5]
	v_mfma_f32_16x16x32_bf16 v[2:5], v[202:205], v[234:237], v[194:197]
	v_mfma_f32_16x16x32_bf16 v[6:9], v[206:209], v[238:241], v[2:5]
	v_mfma_f32_16x16x32_bf16 v[2:5], v[210:213], v[234:237], v[198:201]
	v_mfma_f32_16x16x32_bf16 v[2:5], v[214:217], v[238:241], v[2:5]
	s_setprio 0
	s_barrier
	s_add_u32 s78, s78, 0x80180
	s_addc_u32 s79, s79, 0
	s_add_u32 s57, s76, 0x200
	s_addc_u32 s76, s77, 0
	s_mov_b32 s77, 0
; #define PG8_WAIT_V(n) asm volatile("s_waitcnt vmcnt(" #n ")" ::: "memory")
; template <class Epi, class Sched, bool ALIGN_EPI = true, bool SP2 = true, bool FULLLINE = false, bool NOSTAGE = false, bool FP8 = false>
; __device__ __forceinline__ void gemm_phase(PG8_LAS unsigned char* lds, const Gemm g, const Sched& S, const Epi& E) {
;     ...
;         for (int t = 2; t < nt; t += 2) PG8_ITER(PG8_WAIT_V(8));
.LBB0_1646:
	ds_read_b128 v[140:143], v144
	ds_read_b128 v[150:153], v144 offset:1024
	ds_read_b128 v[154:157], v144 offset:2048
	ds_read_b128 v[158:161], v144 offset:3072
	ds_read_b128 v[162:165], v145
	ds_read_b128 v[166:169], v145 offset:1024
	ds_read_b128 v[170:173], v145 offset:2048
	ds_read_b128 v[174:177], v145 offset:3072
	s_add_u32 s0, s78, 0xfff80080
	s_addc_u32 s1, s79, -1
	s_cmp_eq_u32 s77, 28
	s_cselect_b32 s1, s11, s1
	s_cselect_b32 s0, s14, s0
	s_cselect_b32 s65, s69, s76
	s_cselect_b32 s64, s71, s57
	s_mov_b32 m0, s97
	v_lshl_add_u64 v[210:211], s[78:79], 0, v[134:135]
	ds_read_b128 v[178:181], v146
	ds_read_b128 v[182:185], v146 offset:1024
	ds_read_b128 v[186:189], v146 offset:2048
	ds_read_b128 v[190:193], v146 offset:3072
	ds_read_b128 v[194:197], v146 offset:4096
	ds_read_b128 v[198:201], v146 offset:5120
	ds_read_b128 v[202:205], v146 offset:6144
	ds_read_b128 v[206:209], v146 offset:7168
	global_load_lds_dwordx4 v[210:211], off
	v_lshl_add_u64 v[210:211], v[210:211], 0, s[34:35]
	s_mov_b32 m0, s47
	s_nop 0
	global_load_lds_dwordx4 v[210:211], off
	s_waitcnt vmcnt(8)
	s_waitcnt lgkmcnt(0)
	s_barrier
	s_waitcnt lgkmcnt(0)
	s_setprio 1
	v_mfma_f32_16x16x32_bf16 v[126:129], v[140:143], v[178:181], v[126:129]
	v_mfma_f32_16x16x32_bf16 v[122:125], v[154:157], v[178:181], v[122:125]
	v_mfma_f32_16x16x32_bf16 v[110:113], v[140:143], v[186:189], v[110:113]
	v_mfma_f32_16x16x32_bf16 v[106:109], v[154:157], v[186:189], v[106:109]
	v_mfma_f32_16x16x32_bf16 v[94:97], v[140:143], v[194:197], v[94:97]
	v_mfma_f32_16x16x32_bf16 v[90:93], v[154:157], v[194:197], v[90:93]
	v_mfma_f32_16x16x32_bf16 v[78:81], v[140:143], v[202:205], v[78:81]
	v_mfma_f32_16x16x32_bf16 v[74:77], v[154:157], v[202:205], v[74:77]
	v_mfma_f32_16x16x32_bf16 v[126:129], v[150:153], v[182:185], v[126:129]
	v_mfma_f32_16x16x32_bf16 v[122:125], v[158:161], v[182:185], v[122:125]
	v_mfma_f32_16x16x32_bf16 v[110:113], v[150:153], v[190:193], v[110:113]
	v_mfma_f32_16x16x32_bf16 v[106:109], v[158:161], v[190:193], v[106:109]
	v_mfma_f32_16x16x32_bf16 v[94:97], v[150:153], v[198:201], v[94:97]
	v_mfma_f32_16x16x32_bf16 v[90:93], v[158:161], v[198:201], v[90:93]
	v_mfma_f32_16x16x32_bf16 v[78:81], v[150:153], v[206:209], v[78:81]
	v_mfma_f32_16x16x32_bf16 v[74:77], v[158:161], v[206:209], v[74:77]
	v_mfma_f32_16x16x32_bf16 v[118:121], v[162:165], v[178:181], v[118:121]
	v_mfma_f32_16x16x32_bf16 v[114:117], v[170:173], v[178:181], v[114:117]
	v_mfma_f32_16x16x32_bf16 v[102:105], v[162:165], v[186:189], v[102:105]
	v_mfma_f32_16x16x32_bf16 v[98:101], v[170:173], v[186:189], v[98:101]
	v_mfma_f32_16x16x32_bf16 v[86:89], v[162:165], v[194:197], v[86:89]
	v_mfma_f32_16x16x32_bf16 v[82:85], v[170:173], v[194:197], v[82:85]
	v_mfma_f32_16x16x32_bf16 v[70:73], v[162:165], v[202:205], v[70:73]
	v_mfma_f32_16x16x32_bf16 v[66:69], v[170:173], v[202:205], v[66:69]
	v_mfma_f32_16x16x32_bf16 v[118:121], v[166:169], v[182:185], v[118:121]
	v_mfma_f32_16x16x32_bf16 v[114:117], v[174:177], v[182:185], v[114:117]
	v_mfma_f32_16x16x32_bf16 v[102:105], v[166:169], v[190:193], v[102:105]
	v_mfma_f32_16x16x32_bf16 v[98:101], v[174:177], v[190:193], v[98:101]
	v_mfma_f32_16x16x32_bf16 v[86:89], v[166:169], v[198:201], v[86:89]
	v_mfma_f32_16x16x32_bf16 v[82:85], v[174:177], v[198:201], v[82:85]
	v_mfma_f32_16x16x32_bf16 v[70:73], v[166:169], v[206:209], v[70:73]
	v_mfma_f32_16x16x32_bf16 v[66:69], v[174:177], v[206:209], v[66:69]
	s_setprio 0
	s_barrier
	s_mov_b32 m0, s81
	v_lshl_add_u64 v[210:211], s[64:65], 0, v[132:133]
	ds_read_b128 v[178:181], v146 offset:16384
	ds_read_b128 v[182:185], v146 offset:17408
	ds_read_b128 v[186:189], v146 offset:18432
	ds_read_b128 v[190:193], v146 offset:19456
	ds_read_b128 v[194:197], v146 offset:20480
	ds_read_b128 v[198:201], v146 offset:21504
	ds_read_b128 v[202:205], v146 offset:22528
	ds_read_b128 v[206:209], v146 offset:23552
	global_load_lds_dwordx4 v[210:211], off
	v_lshl_add_u64 v[212:213], v[210:211], 0, s[34:35]
	s_mov_b32 m0, s82
	s_nop 0
	global_load_lds_dwordx4 v[212:213], off
	v_lshl_add_u64 v[212:213], v[210:211], 0, s[36:37]
	s_mov_b32 m0, s83
	s_nop 0
	global_load_lds_dwordx4 v[212:213], off
	v_lshl_add_u64 v[212:213], v[210:211], 0, s[38:39]
	s_mov_b32 m0, s84
	s_nop 0
	global_load_lds_dwordx4 v[212:213], off
	v_lshl_add_u64 v[212:213], s[0:1], 0, v[130:131]
	s_mov_b32 m0, s87
	v_lshl_add_u64 v[214:215], v[212:213], 0, s[34:35]
	global_load_lds_dwordx4 v[212:213], off
	s_mov_b32 m0, s52
	s_nop 0
	global_load_lds_dwordx4 v[214:215], off
	s_waitcnt vmcnt(8)
	s_waitcnt lgkmcnt(0)
	s_barrier
; #define PG8_WAIT_V(n) asm volatile("s_waitcnt vmcnt(" #n ")" ::: "memory")
; template <class Epi, class Sched, bool ALIGN_EPI = true, bool SP2 = true, bool FULLLINE = false, bool NOSTAGE = false, bool FP8 = false>
; __device__ __forceinline__ void gemm_phase(PG8_LAS unsigned char* lds, const Gemm g, const Sched& S, const Epi& E) {
;     ...
;         for (int t = 2; t < nt; t += 2) PG8_ITER(PG8_WAIT_V(8));
	s_waitcnt lgkmcnt(0)
	s_setprio 1
	v_mfma_f32_16x16x32_bf16 v[62:65], v[140:143], v[178:181], v[62:65]
	v_mfma_f32_16x16x32_bf16 v[58:61], v[154:157], v[178:181], v[58:61]
	v_mfma_f32_16x16x32_bf16 v[46:49], v[140:143], v[186:189], v[46:49]
	v_mfma_f32_16x16x32_bf16 v[42:45], v[154:157], v[186:189], v[42:45]
	v_mfma_f32_16x16x32_bf16 v[30:33], v[140:143], v[194:197], v[30:33]
	v_mfma_f32_16x16x32_bf16 v[26:29], v[154:157], v[194:197], v[26:29]
	v_mfma_f32_16x16x32_bf16 v[14:17], v[140:143], v[202:205], v[14:17]
	v_mfma_f32_16x16x32_bf16 v[10:13], v[154:157], v[202:205], v[10:13]
	v_mfma_f32_16x16x32_bf16 v[62:65], v[150:153], v[182:185], v[62:65]
	v_mfma_f32_16x16x32_bf16 v[58:61], v[158:161], v[182:185], v[58:61]
	v_mfma_f32_16x16x32_bf16 v[46:49], v[150:153], v[190:193], v[46:49]
	v_mfma_f32_16x16x32_bf16 v[42:45], v[158:161], v[190:193], v[42:45]
	v_mfma_f32_16x16x32_bf16 v[30:33], v[150:153], v[198:201], v[30:33]
	v_mfma_f32_16x16x32_bf16 v[26:29], v[158:161], v[198:201], v[26:29]
	v_mfma_f32_16x16x32_bf16 v[14:17], v[150:153], v[206:209], v[14:17]
	v_mfma_f32_16x16x32_bf16 v[10:13], v[158:161], v[206:209], v[10:13]
	v_mfma_f32_16x16x32_bf16 v[54:57], v[162:165], v[178:181], v[54:57]
	v_mfma_f32_16x16x32_bf16 v[50:53], v[170:173], v[178:181], v[50:53]
	v_mfma_f32_16x16x32_bf16 v[38:41], v[162:165], v[186:189], v[38:41]
	v_mfma_f32_16x16x32_bf16 v[34:37], v[170:173], v[186:189], v[34:37]
	v_mfma_f32_16x16x32_bf16 v[22:25], v[162:165], v[194:197], v[22:25]
	v_mfma_f32_16x16x32_bf16 v[18:21], v[170:173], v[194:197], v[18:21]
	v_mfma_f32_16x16x32_bf16 v[6:9], v[162:165], v[202:205], v[6:9]
	v_mfma_f32_16x16x32_bf16 v[2:5], v[170:173], v[202:205], v[2:5]
	v_mfma_f32_16x16x32_bf16 v[54:57], v[166:169], v[182:185], v[54:57]
	v_mfma_f32_16x16x32_bf16 v[50:53], v[174:177], v[182:185], v[50:53]
	v_mfma_f32_16x16x32_bf16 v[38:41], v[166:169], v[190:193], v[38:41]
	v_mfma_f32_16x16x32_bf16 v[34:37], v[174:177], v[190:193], v[34:37]
	v_mfma_f32_16x16x32_bf16 v[22:25], v[166:169], v[198:201], v[22:25]
	v_mfma_f32_16x16x32_bf16 v[18:21], v[174:177], v[198:201], v[18:21]
	v_mfma_f32_16x16x32_bf16 v[6:9], v[166:169], v[206:209], v[6:9]
	v_mfma_f32_16x16x32_bf16 v[2:5], v[174:177], v[206:209], v[2:5]
	s_setprio 0
	s_barrier
	ds_read_b128 v[140:143], v147
	ds_read_b128 v[150:153], v147 offset:1024
	ds_read_b128 v[154:157], v147 offset:2048
	ds_read_b128 v[158:161], v147 offset:3072
	ds_read_b128 v[162:165], v148
	ds_read_b128 v[166:169], v148 offset:1024
	ds_read_b128 v[170:173], v148 offset:2048
	ds_read_b128 v[174:177], v148 offset:3072
	s_mov_b32 m0, s53
	v_lshl_add_u64 v[214:215], v[212:213], 0, s[36:37]
	ds_read_b128 v[178:181], v146 offset:32768
	ds_read_b128 v[182:185], v146 offset:33792
	ds_read_b128 v[186:189], v146 offset:34816
	ds_read_b128 v[190:193], v146 offset:35840
	ds_read_b128 v[194:197], v146 offset:36864
	ds_read_b128 v[198:201], v146 offset:37888
	ds_read_b128 v[202:205], v146 offset:38912
	ds_read_b128 v[206:209], v146 offset:39936
	global_load_lds_dwordx4 v[214:215], off
	v_lshl_add_u64 v[214:215], v[212:213], 0, s[38:39]
	s_mov_b32 m0, s54
	s_nop 0
	global_load_lds_dwordx4 v[214:215], off
	s_waitcnt vmcnt(8)
	s_waitcnt lgkmcnt(0)
	s_barrier
	s_waitcnt lgkmcnt(0)
	s_setprio 1
	v_mfma_f32_16x16x32_bf16 v[126:129], v[140:143], v[178:181], v[126:129]
	v_mfma_f32_16x16x32_bf16 v[122:125], v[154:157], v[178:181], v[122:125]
	v_mfma_f32_16x16x32_bf16 v[110:113], v[140:143], v[186:189], v[110:113]
	v_mfma_f32_16x16x32_bf16 v[106:109], v[154:157], v[186:189], v[106:109]
	v_mfma_f32_16x16x32_bf16 v[94:97], v[140:143], v[194:197], v[94:97]
	v_mfma_f32_16x16x32_bf16 v[90:93], v[154:157], v[194:197], v[90:93]
	v_mfma_f32_16x16x32_bf16 v[78:81], v[140:143], v[202:205], v[78:81]
	v_mfma_f32_16x16x32_bf16 v[74:77], v[154:157], v[202:205], v[74:77]
	v_mfma_f32_16x16x32_bf16 v[126:129], v[150:153], v[182:185], v[126:129]
	v_mfma_f32_16x16x32_bf16 v[122:125], v[158:161], v[182:185], v[122:125]
	v_mfma_f32_16x16x32_bf16 v[110:113], v[150:153], v[190:193], v[110:113]
	v_mfma_f32_16x16x32_bf16 v[106:109], v[158:161], v[190:193], v[106:109]
	v_mfma_f32_16x16x32_bf16 v[94:97], v[150:153], v[198:201], v[94:97]
	v_mfma_f32_16x16x32_bf16 v[90:93], v[158:161], v[198:201], v[90:93]
	v_mfma_f32_16x16x32_bf16 v[78:81], v[150:153], v[206:209], v[78:81]
	v_mfma_f32_16x16x32_bf16 v[74:77], v[158:161], v[206:209], v[74:77]
	v_mfma_f32_16x16x32_bf16 v[118:121], v[162:165], v[178:181], v[118:121]
	v_mfma_f32_16x16x32_bf16 v[114:117], v[170:173], v[178:181], v[114:117]
	v_mfma_f32_16x16x32_bf16 v[102:105], v[162:165], v[186:189], v[102:105]
	v_mfma_f32_16x16x32_bf16 v[98:101], v[170:173], v[186:189], v[98:101]
	v_mfma_f32_16x16x32_bf16 v[86:89], v[162:165], v[194:197], v[86:89]
	v_mfma_f32_16x16x32_bf16 v[82:85], v[170:173], v[194:197], v[82:85]
	v_mfma_f32_16x16x32_bf16 v[70:73], v[162:165], v[202:205], v[70:73]
	v_mfma_f32_16x16x32_bf16 v[66:69], v[170:173], v[202:205], v[66:69]
	v_mfma_f32_16x16x32_bf16 v[118:121], v[166:169], v[182:185], v[118:121]
	v_mfma_f32_16x16x32_bf16 v[114:117], v[174:177], v[182:185], v[114:117]
	v_mfma_f32_16x16x32_bf16 v[102:105], v[166:169], v[190:193], v[102:105]
	v_mfma_f32_16x16x32_bf16 v[98:101], v[174:177], v[190:193], v[98:101]
	v_mfma_f32_16x16x32_bf16 v[86:89], v[166:169], v[198:201], v[86:89]
	v_mfma_f32_16x16x32_bf16 v[82:85], v[174:177], v[198:201], v[82:85]
	v_mfma_f32_16x16x32_bf16 v[70:73], v[166:169], v[206:209], v[70:73]
	v_mfma_f32_16x16x32_bf16 v[66:69], v[174:177], v[206:209], v[66:69]
	s_setprio 0
	s_barrier
; #define PG8_WAIT_V(n) asm volatile("s_waitcnt vmcnt(" #n ")" ::: "memory")
; #define PG8_BAR __builtin_amdgcn_s_barrier()
; template <class Epi, class Sched, bool ALIGN_EPI = true, bool SP2 = true, bool FULLLINE = false, bool NOSTAGE = false, bool FP8 = false>
; __device__ __forceinline__ void gemm_phase(PG8_LAS unsigned char* lds, const Gemm g, const Sched& S, const Epi& E) {
;     ...
;         for (int t = 2; t < nt; t += 2) PG8_ITER(PG8_WAIT_V(8));
;     ...
;         if constexpr (ALIGN_EPI) { if (wr == 0) PG8_BAR; }
	s_mov_b32 m0, s50
	v_lshl_add_u64 v[214:215], v[210:211], 0, s[40:41]
	ds_read_b128 v[178:181], v146 offset:49152
	ds_read_b128 v[182:185], v146 offset:50176
	ds_read_b128 v[186:189], v146 offset:51200
	ds_read_b128 v[190:193], v146 offset:52224
	ds_read_b128 v[194:197], v146 offset:53248
	ds_read_b128 v[198:201], v146 offset:54272
	ds_read_b128 v[202:205], v146 offset:55296
	ds_read_b128 v[206:209], v146 offset:56320
	global_load_lds_dwordx4 v[214:215], off
	v_lshl_add_u64 v[214:215], v[210:211], 0, s[66:67]
	s_mov_b32 m0, s51
	s_nop 0
	global_load_lds_dwordx4 v[214:215], off
	v_lshl_add_u64 v[214:215], v[210:211], 0, s[16:17]
	s_mov_b32 m0, s33
	v_lshl_add_u64 v[210:211], v[210:211], 0, s[18:19]
	global_load_lds_dwordx4 v[214:215], off
	s_mov_b32 m0, s56
	s_nop 0
	global_load_lds_dwordx4 v[210:211], off
	v_lshl_add_u64 v[210:211], v[212:213], 0, s[40:41]
	s_mov_b32 m0, s55
	s_nop 0
	global_load_lds_dwordx4 v[210:211], off
	v_lshl_add_u64 v[210:211], v[212:213], 0, s[66:67]
	s_mov_b32 m0, s62
	s_nop 0
	global_load_lds_dwordx4 v[210:211], off
	s_waitcnt vmcnt(8)
	s_waitcnt lgkmcnt(0)
	s_barrier
	s_waitcnt lgkmcnt(0)
	s_setprio 1
	v_mfma_f32_16x16x32_bf16 v[62:65], v[140:143], v[178:181], v[62:65]
	v_mfma_f32_16x16x32_bf16 v[58:61], v[154:157], v[178:181], v[58:61]
	v_mfma_f32_16x16x32_bf16 v[46:49], v[140:143], v[186:189], v[46:49]
	v_mfma_f32_16x16x32_bf16 v[42:45], v[154:157], v[186:189], v[42:45]
	v_mfma_f32_16x16x32_bf16 v[30:33], v[140:143], v[194:197], v[30:33]
	v_mfma_f32_16x16x32_bf16 v[26:29], v[154:157], v[194:197], v[26:29]
	v_mfma_f32_16x16x32_bf16 v[14:17], v[140:143], v[202:205], v[14:17]
	v_mfma_f32_16x16x32_bf16 v[10:13], v[154:157], v[202:205], v[10:13]
	v_mfma_f32_16x16x32_bf16 v[62:65], v[150:153], v[182:185], v[62:65]
	v_mfma_f32_16x16x32_bf16 v[58:61], v[158:161], v[182:185], v[58:61]
	v_mfma_f32_16x16x32_bf16 v[46:49], v[150:153], v[190:193], v[46:49]
	v_mfma_f32_16x16x32_bf16 v[42:45], v[158:161], v[190:193], v[42:45]
	v_mfma_f32_16x16x32_bf16 v[30:33], v[150:153], v[198:201], v[30:33]
	v_mfma_f32_16x16x32_bf16 v[26:29], v[158:161], v[198:201], v[26:29]
	v_mfma_f32_16x16x32_bf16 v[14:17], v[150:153], v[206:209], v[14:17]
	v_mfma_f32_16x16x32_bf16 v[10:13], v[158:161], v[206:209], v[10:13]
	v_mfma_f32_16x16x32_bf16 v[54:57], v[162:165], v[178:181], v[54:57]
	v_mfma_f32_16x16x32_bf16 v[50:53], v[170:173], v[178:181], v[50:53]
	v_mfma_f32_16x16x32_bf16 v[38:41], v[162:165], v[186:189], v[38:41]
	v_mfma_f32_16x16x32_bf16 v[34:37], v[170:173], v[186:189], v[34:37]
	v_mfma_f32_16x16x32_bf16 v[22:25], v[162:165], v[194:197], v[22:25]
	v_mfma_f32_16x16x32_bf16 v[18:21], v[170:173], v[194:197], v[18:21]
	v_mfma_f32_16x16x32_bf16 v[6:9], v[162:165], v[202:205], v[6:9]
	v_mfma_f32_16x16x32_bf16 v[2:5], v[170:173], v[202:205], v[2:5]
	v_mfma_f32_16x16x32_bf16 v[54:57], v[166:169], v[182:185], v[54:57]
	v_mfma_f32_16x16x32_bf16 v[50:53], v[174:177], v[182:185], v[50:53]
	v_mfma_f32_16x16x32_bf16 v[38:41], v[166:169], v[190:193], v[38:41]
	v_mfma_f32_16x16x32_bf16 v[34:37], v[174:177], v[190:193], v[34:37]
	v_mfma_f32_16x16x32_bf16 v[22:25], v[166:169], v[198:201], v[22:25]
	v_mfma_f32_16x16x32_bf16 v[18:21], v[174:177], v[198:201], v[18:21]
	v_mfma_f32_16x16x32_bf16 v[6:9], v[166:169], v[206:209], v[6:9]
	v_mfma_f32_16x16x32_bf16 v[2:5], v[174:177], v[206:209], v[2:5]
	s_setprio 0
	s_barrier
	s_add_i32 s77, s77, 2
	s_add_u32 s78, s78, 0x100
	s_addc_u32 s79, s79, 0
	s_add_u32 s57, s57, 0x100
	s_addc_u32 s76, s76, 0
	s_cmp_gt_u32 s77, 29
	s_cbranch_scc0 .LBB0_1646
	s_and_b64 vcc, exec, s[12:13]
	s_cbranch_vccz .LBB0_1649
	s_barrier

; #define PG8_STAGE(bufoff, gbase, voff) do { if constexpr (!NOSTAGE) _Pragma("unroll") for (int _i = 0; _i < 2; ++_i) \
;         __builtin_amdgcn_global_load_lds((const unsigned*)((const char*)(gbase) + (size_t)_i * pstep##voff + v##voff), (PG8_LAS unsigned*)(lds + (bufoff) + ldsw + _i * 8192), 16, 0, 0); } while (0)
; #define PG8_WAIT_V(n) asm volatile("s_waitcnt vmcnt(" #n ")" ::: "memory")
; #define PG8_BAR __builtin_amdgcn_s_barrier()
; template <class Epi, class Sched, bool ALIGN_EPI = true, bool SP2 = true, bool FULLLINE = false, bool NOSTAGE = false, bool FP8 = false>
; __device__ __forceinline__ void gemm_phase(PG8_LAS unsigned char* lds, const Gemm g, const Sched& S, const Epi& E) {
;     const int tid = threadIdx.x, wid = __builtin_amdgcn_readfirstlane(tid >> 6), lane = tid & 63, wr = wid >> 2, wc = wid & 3, fr = lane & 15, fq = lane >> 4;
;     const int K = g.K, nt = K / BK;
;     unsigned voffA_, voffB_;
;     { int R, C; stage_rc(tid * 16, R, C); const int Rb = Epi::PERM ? ((R & ~31) + perm32(R & 31)) : R;
;       voffA_ = (unsigned)(R * g.lda + C) * 2u; voffB_ = (unsigned)(Rb * g.ldb + C) * 2u; }
;     const unsigned voffA = voffA_, voffB = voffB_;
;     const size_t pstepoffA = (size_t)64 * g.lda * 2, pstepoffB = (size_t)64 * g.ldb * 2;
;     const size_t kstep = (size_t)(BK * 2);
;     const size_t hstepA = (size_t)HALF * g.lda * 2, hstepB = (size_t)HALF * g.ldb * 2;
;     const size_t tstepA = 2 * hstepA, tstepB = 2 * hstepB;
;     const unsigned ldsw = (unsigned)wid * 1024u;
;     const int aoff = lds_byte(wr * 64 + fr, fq * 8), boff = lds_byte(wc * 32 + fr, fq * 8);
;     ...
;     if (wr == 1) PG8_BAR;
;     PG8_WAIT_V(0); PG8_BAR;
;     PG8_BAR;
;     } else {
;     PG8_STAGE(PG8_SB(0, 0), cB, offB); PG8_STAGE(PG8_SA(0, 0), cA, offA); PG8_STAGE(PG8_SB(0, 1), cB + hstepB, offB); PG8_STAGE(PG8_SA(0, 1), cA + hstepA, offA);
;     if (wr == 1) PG8_BAR;
;     PG8_WAIT_V(4); PG8_BAR;
;     PG8_STAGE(PG8_SB(1, 0), cB + kstep, offB); PG8_STAGE(PG8_SA(1, 0), cA + kstep, offA); PG8_STAGE(PG8_SB(1, 1), cB + hstepB + kstep, offB);
;     PG8_WAIT_V(6); PG8_BAR;
;     }
;     if (wr == 1) __builtin_amdgcn_s_setprio(1);
.LBB0_2085:
	s_waitcnt vmcnt(0)
	v_cndmask_b32_e64 v4, 0, 1, s[10:11]
	v_cmp_ne_u32_e64 s[6:7], 1, v4
	s_andn2_b64 vcc, exec, s[10:11]
	s_barrier
	s_barrier
	s_cbranch_vccnz .LBB0_2087
.LBB0_2087:
	v_and_b32_e32 v4, 48, v0
	v_lshlrev_b32_e32 v5, 6, v0
	s_movk_i32 s1, 0x3c0
	s_add_u32 s63, s48, 0x1c4000
	v_and_or_b32 v4, v5, s1, v4
	v_lshlrev_b32_e32 v5, 2, v0
	s_addc_u32 s78, s49, 0
	s_lshl_b32 s0, s13, 13
	v_and_b32_e32 v5, 32, v5
	v_bitop3_b32 v6, v4, s0, v5 bitop3:0xde
	s_lshl_b32 s0, s12, 5
	s_and_b32 s80, s0, 0x60
	s_lshl_b32 s0, s80, 7
	s_lshl_b32 s79, s13, 6
	v_bitop3_b32 v4, s0, v4, v5 bitop3:0xf6
	v_lshlrev_b32_e32 v5, 9, v0
	s_cmpk_lt_u32 s9, 0x100
	v_and_b32_e32 v5, 0x30000, v5
	v_lshlrev_b32_e32 v1, 12, v1
	s_cselect_b64 s[10:11], -1, 0
	v_or3_b32 v1, v2, v5, v1
	s_add_i32 s83, 0, 0x10000
	s_add_i32 s84, 0, 0x14000
	s_add_i32 s88, 0, 0x18000
	s_add_i32 s89, 0, 0x1c000
	s_sext_i32_i8 s73, s8
	s_ashr_i32 s81, s86, 31
	v_add_u32_e32 v174, v1, v3
	v_mov_b32_e32 v175, 0
	s_mov_b32 s82, 0
	v_mov_b64_e32 v[176:177], 0x200
	v_mov_b64_e32 v[178:179], 0x1ff
	v_add_u32_e32 v1, s83, v4
	v_add_u32_e32 v192, s84, v4
	v_add_u32_e32 v193, 0, v6
	s_mov_b64 s[12:13], 0x80080
	s_add_i32 s85, s47, 0xc000
	s_mov_b64 s[14:15], 0xc0080
	s_add_i32 s87, s47, 0xe000
	s_mov_b64 s[16:17], 0x100
	s_mov_b64 s[18:19], 0x40100
	s_mov_b64 s[20:21], 0x80100
	s_mov_b64 s[22:23], 0xc0100
	v_add_u32_e32 v194, s88, v4
	v_add_u32_e32 v195, s89, v4
	s_mov_b64 s[24:25], 0x180
	s_mov_b64 s[26:27], 0x40180
	s_mov_b64 s[28:29], 0x40000
	s_mov_b64 s[30:31], 0x80000
	s_mov_b64 s[34:35], 0xc0000
	s_mov_b64 s[36:37], 0x80
	s_mov_b64 s[38:39], 0x40080
	s_branch .LBB0_2090

; #define PG8_WAIT_V(n) asm volatile("s_waitcnt vmcnt(" #n ")" ::: "memory")
; template <class Epi, class Sched, bool ALIGN_EPI = true, bool SP2 = true, bool FULLLINE = false, bool NOSTAGE = false, bool FP8 = false>
; __device__ __forceinline__ void gemm_phase(PG8_LAS unsigned char* lds, const Gemm g, const Sched& S, const Epi& E) {
;     ...
;         const char* nA = has_next ? PG8_ABASE(nxt) : cA; const char* nB = has_next ? PG8_BBASE(nxt) : cB;
;     ...
;         static_assert(SP2, "only the SP2 loop is kept");
;         { const int t = 0; if constexpr (Epi::NST == 16) PG8_ITER(PG8_WAIT_V(24)); else if constexpr (Epi::NST == 8) PG8_ITER(PG8_WAIT_V(16)); else PG8_ITER(PG8_WAIT_V(8)); }
.LBB0_2096:
	s_ashr_i32 s67, s66, 31
	ds_read_b128 v[2:5], v1
	ds_read_b128 v[6:9], v1 offset:1024
	ds_read_b128 v[10:13], v1 offset:2048
	ds_read_b128 v[14:17], v1 offset:3072
	ds_read_b128 v[18:21], v192
	ds_read_b128 v[22:25], v192 offset:1024
	ds_read_b128 v[26:29], v192 offset:2048
	ds_read_b128 v[30:33], v192 offset:3072
	s_lshl_b64 s[0:1], s[66:67], 20
	s_add_u32 s68, s42, s0
	s_addc_u32 s69, s43, s1
	s_and_b64 s[0:1], s[8:9], exec
	s_cselect_b32 s67, s69, s75
	s_cselect_b32 s90, s68, s74
	s_ashr_i32 s41, s40, 31
	s_lshl_b64 s[0:1], s[40:41], 20
	s_add_u32 s70, s44, s0
	s_addc_u32 s71, s45, s1
	s_and_b64 s[0:1], s[8:9], exec
	s_cselect_b32 s41, s71, s77
	s_cselect_b32 s91, s70, s76
	v_lshl_add_u64 v[248:249], s[74:75], 0, v[170:171]
	s_mov_b32 m0, s85
	v_lshl_add_u64 v[66:67], v[248:249], 0, s[12:13]
	ds_read_b128 v[34:37], v193
	ds_read_b128 v[38:41], v193 offset:1024
	ds_read_b128 v[42:45], v193 offset:2048
	ds_read_b128 v[46:49], v193 offset:3072
	ds_read_b128 v[50:53], v193 offset:4096
	ds_read_b128 v[54:57], v193 offset:5120
	ds_read_b128 v[58:61], v193 offset:6144
	ds_read_b128 v[62:65], v193 offset:7168
	global_load_lds_dwordx4 v[66:67], off
	v_lshl_add_u64 v[66:67], v[248:249], 0, s[14:15]
	s_mov_b32 m0, s87
	s_nop 0
	global_load_lds_dwordx4 v[66:67], off
	s_waitcnt vmcnt(24)
	s_waitcnt lgkmcnt(0)
	s_barrier
	s_waitcnt lgkmcnt(0)
	s_setprio 1
	v_mfma_f32_16x16x32_bf16 v[66:69], v[2:5], v[34:37], 0
	v_mfma_f32_16x16x32_bf16 v[70:73], v[10:13], v[34:37], 0
	v_mfma_f32_16x16x32_bf16 v[78:81], v[10:13], v[42:45], 0
	v_mfma_f32_16x16x32_bf16 v[86:89], v[10:13], v[50:53], 0
	v_mfma_f32_16x16x32_bf16 v[66:69], v[6:9], v[38:41], v[66:69]
	v_mfma_f32_16x16x32_bf16 v[70:73], v[14:17], v[38:41], v[70:73]
	v_mfma_f32_16x16x32_bf16 v[74:77], v[2:5], v[42:45], 0
	v_mfma_f32_16x16x32_bf16 v[78:81], v[14:17], v[46:49], v[78:81]
	v_mfma_f32_16x16x32_bf16 v[82:85], v[2:5], v[50:53], 0
	v_mfma_f32_16x16x32_bf16 v[86:89], v[14:17], v[54:57], v[86:89]
	v_mfma_f32_16x16x32_bf16 v[90:93], v[2:5], v[58:61], 0
	v_mfma_f32_16x16x32_bf16 v[94:97], v[10:13], v[58:61], 0
	v_mfma_f32_16x16x32_bf16 v[74:77], v[6:9], v[46:49], v[74:77]
	v_mfma_f32_16x16x32_bf16 v[82:85], v[6:9], v[54:57], v[82:85]
	v_mfma_f32_16x16x32_bf16 v[90:93], v[6:9], v[62:65], v[90:93]
	v_mfma_f32_16x16x32_bf16 v[94:97], v[14:17], v[62:65], v[94:97]
	v_mfma_f32_16x16x32_bf16 v[98:101], v[18:21], v[34:37], 0
	v_mfma_f32_16x16x32_bf16 v[34:37], v[26:29], v[34:37], 0
	v_mfma_f32_16x16x32_bf16 v[98:101], v[22:25], v[38:41], v[98:101]
	v_mfma_f32_16x16x32_bf16 v[34:37], v[30:33], v[38:41], v[34:37]
	v_mfma_f32_16x16x32_bf16 v[38:41], v[18:21], v[42:45], 0
	v_mfma_f32_16x16x32_bf16 v[42:45], v[26:29], v[42:45], 0
	v_mfma_f32_16x16x32_bf16 v[38:41], v[22:25], v[46:49], v[38:41]
	v_mfma_f32_16x16x32_bf16 v[42:45], v[30:33], v[46:49], v[42:45]
	v_mfma_f32_16x16x32_bf16 v[46:49], v[18:21], v[50:53], 0
	v_mfma_f32_16x16x32_bf16 v[50:53], v[26:29], v[50:53], 0
	v_mfma_f32_16x16x32_bf16 v[46:49], v[22:25], v[54:57], v[46:49]
	v_mfma_f32_16x16x32_bf16 v[50:53], v[30:33], v[54:57], v[50:53]
	v_mfma_f32_16x16x32_bf16 v[54:57], v[18:21], v[58:61], 0
	v_mfma_f32_16x16x32_bf16 v[58:61], v[26:29], v[58:61], 0
	v_mfma_f32_16x16x32_bf16 v[54:57], v[22:25], v[62:65], v[54:57]
	v_mfma_f32_16x16x32_bf16 v[58:61], v[30:33], v[62:65], v[58:61]
	s_setprio 0
	s_barrier
	v_lshl_add_u64 v[250:251], s[76:77], 0, v[172:173]
	s_add_i32 s92, s83, s46
	v_lshl_add_u64 v[130:131], v[250:251], 0, s[16:17]
	s_mov_b32 m0, s92
	s_add_i32 s93, s92, 0x2000
	ds_read_b128 v[62:65], v193 offset:16384
	ds_read_b128 v[102:105], v193 offset:17408
	ds_read_b128 v[106:109], v193 offset:18432
	ds_read_b128 v[110:113], v193 offset:19456
	ds_read_b128 v[114:117], v193 offset:20480
	ds_read_b128 v[118:121], v193 offset:21504
	ds_read_b128 v[122:125], v193 offset:22528
	ds_read_b128 v[126:129], v193 offset:23552
	global_load_lds_dwordx4 v[130:131], off
	v_lshl_add_u64 v[130:131], v[250:251], 0, s[18:19]
	s_mov_b32 m0, s93
	s_add_i32 s94, s84, s46
	global_load_lds_dwordx4 v[130:131], off
	v_lshl_add_u64 v[130:131], v[250:251], 0, s[20:21]
	s_mov_b32 m0, s94
	s_add_i32 s95, s94, 0x2000
	global_load_lds_dwordx4 v[130:131], off
	v_lshl_add_u64 v[130:131], v[250:251], 0, s[22:23]
	s_mov_b32 m0, s95
	s_nop 0
	global_load_lds_dwordx4 v[130:131], off
	v_lshl_add_u64 v[130:131], v[248:249], 0, s[16:17]
	s_mov_b32 m0, s47
	s_nop 0
	global_load_lds_dwordx4 v[130:131], off
	v_lshl_add_u64 v[130:131], v[248:249], 0, s[18:19]
	s_mov_b32 m0, s52
	s_nop 0
	global_load_lds_dwordx4 v[130:131], off
	s_waitcnt vmcnt(24)
	s_waitcnt lgkmcnt(0)
	s_barrier
; #define PG8_WAIT_V(n) asm volatile("s_waitcnt vmcnt(" #n ")" ::: "memory")
; template <class Epi, class Sched, bool ALIGN_EPI = true, bool SP2 = true, bool FULLLINE = false, bool NOSTAGE = false, bool FP8 = false>
; __device__ __forceinline__ void gemm_phase(PG8_LAS unsigned char* lds, const Gemm g, const Sched& S, const Epi& E) {
;     ...
;         static_assert(SP2, "only the SP2 loop is kept");
;         { const int t = 0; if constexpr (Epi::NST == 16) PG8_ITER(PG8_WAIT_V(24)); else if constexpr (Epi::NST == 8) PG8_ITER(PG8_WAIT_V(16)); else PG8_ITER(PG8_WAIT_V(8)); }
	s_waitcnt lgkmcnt(0)
	s_setprio 1
	v_mfma_f32_16x16x32_bf16 v[130:133], v[2:5], v[62:65], 0
	v_mfma_f32_16x16x32_bf16 v[138:141], v[6:9], v[102:105], v[130:133]
	v_mfma_f32_16x16x32_bf16 v[130:133], v[10:13], v[62:65], 0
	v_mfma_f32_16x16x32_bf16 v[150:153], v[14:17], v[102:105], v[130:133]
	v_mfma_f32_16x16x32_bf16 v[130:133], v[2:5], v[106:109], 0
	v_mfma_f32_16x16x32_bf16 v[154:157], v[6:9], v[110:113], v[130:133]
	v_mfma_f32_16x16x32_bf16 v[130:133], v[10:13], v[106:109], 0
	v_mfma_f32_16x16x32_bf16 v[158:161], v[14:17], v[110:113], v[130:133]
	v_mfma_f32_16x16x32_bf16 v[130:133], v[2:5], v[114:117], 0
	v_mfma_f32_16x16x32_bf16 v[2:5], v[2:5], v[122:125], 0
	v_mfma_f32_16x16x32_bf16 v[162:165], v[6:9], v[118:121], v[130:133]
	v_mfma_f32_16x16x32_bf16 v[2:5], v[6:9], v[126:129], v[2:5]
	v_mfma_f32_16x16x32_bf16 v[6:9], v[10:13], v[122:125], 0
	v_mfma_f32_16x16x32_bf16 v[130:133], v[10:13], v[114:117], 0
	v_mfma_f32_16x16x32_bf16 v[6:9], v[14:17], v[126:129], v[6:9]
	v_mfma_f32_16x16x32_bf16 v[166:169], v[14:17], v[118:121], v[130:133]
	v_mfma_f32_16x16x32_bf16 v[10:13], v[18:21], v[62:65], 0
	v_mfma_f32_16x16x32_bf16 v[180:183], v[22:25], v[102:105], v[10:13]
	v_mfma_f32_16x16x32_bf16 v[10:13], v[26:29], v[62:65], 0
	v_mfma_f32_16x16x32_bf16 v[184:187], v[30:33], v[102:105], v[10:13]
	v_mfma_f32_16x16x32_bf16 v[10:13], v[18:21], v[106:109], 0
	v_mfma_f32_16x16x32_bf16 v[188:191], v[22:25], v[110:113], v[10:13]
	v_mfma_f32_16x16x32_bf16 v[10:13], v[26:29], v[106:109], 0
	v_mfma_f32_16x16x32_bf16 v[196:199], v[30:33], v[110:113], v[10:13]
	v_mfma_f32_16x16x32_bf16 v[10:13], v[18:21], v[114:117], 0
	v_mfma_f32_16x16x32_bf16 v[200:203], v[22:25], v[118:121], v[10:13]
	v_mfma_f32_16x16x32_bf16 v[10:13], v[26:29], v[114:117], 0
	v_mfma_f32_16x16x32_bf16 v[204:207], v[30:33], v[118:121], v[10:13]
	v_mfma_f32_16x16x32_bf16 v[10:13], v[18:21], v[122:125], 0
	v_mfma_f32_16x16x32_bf16 v[208:211], v[22:25], v[126:129], v[10:13]
	v_mfma_f32_16x16x32_bf16 v[10:13], v[26:29], v[122:125], 0
	v_mfma_f32_16x16x32_bf16 v[212:215], v[30:33], v[126:129], v[10:13]
	s_setprio 0
	s_barrier
	s_nop 5
	ds_read_b128 v[10:13], v194
	ds_read_b128 v[14:17], v194 offset:1024
	ds_read_b128 v[18:21], v194 offset:2048
	ds_read_b128 v[22:25], v194 offset:3072
	ds_read_b128 v[216:219], v195
	ds_read_b128 v[220:223], v195 offset:1024
	ds_read_b128 v[224:227], v195 offset:2048
	ds_read_b128 v[228:231], v195 offset:3072
	s_mov_b32 m0, s53
	v_lshl_add_u64 v[106:107], v[248:249], 0, s[20:21]
	ds_read_b128 v[26:29], v193 offset:32768
	ds_read_b128 v[30:33], v193 offset:33792
	ds_read_b128 v[62:65], v193 offset:34816
	ds_read_b128 v[102:105], v193 offset:35840
	ds_read_b128 v[232:235], v193 offset:36864
	ds_read_b128 v[236:239], v193 offset:37888
	ds_read_b128 v[240:243], v193 offset:38912
	ds_read_b128 v[244:247], v193 offset:39936
	global_load_lds_dwordx4 v[106:107], off
	v_lshl_add_u64 v[106:107], v[248:249], 0, s[22:23]
	s_mov_b32 m0, s54
	s_nop 0
	global_load_lds_dwordx4 v[106:107], off
	s_waitcnt vmcnt(8)
	s_waitcnt lgkmcnt(0)
	s_barrier
	s_waitcnt lgkmcnt(0)
	s_setprio 1
	v_mfma_f32_16x16x32_bf16 v[66:69], v[10:13], v[26:29], v[66:69]
	v_mfma_f32_16x16x32_bf16 v[146:149], v[14:17], v[30:33], v[66:69]
	v_mfma_f32_16x16x32_bf16 v[66:69], v[18:21], v[26:29], v[70:73]
	v_mfma_f32_16x16x32_bf16 v[142:145], v[22:25], v[30:33], v[66:69]
	v_mfma_f32_16x16x32_bf16 v[66:69], v[10:13], v[62:65], v[74:77]
	v_mfma_f32_16x16x32_bf16 v[126:129], v[14:17], v[102:105], v[66:69]
	v_mfma_f32_16x16x32_bf16 v[66:69], v[18:21], v[62:65], v[78:81]
	v_mfma_f32_16x16x32_bf16 v[122:125], v[22:25], v[102:105], v[66:69]
	v_mfma_f32_16x16x32_bf16 v[66:69], v[10:13], v[232:235], v[82:85]
	v_mfma_f32_16x16x32_bf16 v[110:113], v[14:17], v[236:239], v[66:69]
	v_mfma_f32_16x16x32_bf16 v[66:69], v[18:21], v[232:235], v[86:89]
	v_mfma_f32_16x16x32_bf16 v[106:109], v[22:25], v[236:239], v[66:69]
	v_mfma_f32_16x16x32_bf16 v[66:69], v[10:13], v[240:243], v[90:93]
	v_mfma_f32_16x16x32_bf16 v[86:89], v[14:17], v[244:247], v[66:69]
	v_mfma_f32_16x16x32_bf16 v[66:69], v[18:21], v[240:243], v[94:97]
	v_mfma_f32_16x16x32_bf16 v[78:81], v[22:25], v[244:247], v[66:69]
	v_mfma_f32_16x16x32_bf16 v[66:69], v[216:219], v[26:29], v[98:101]
	v_mfma_f32_16x16x32_bf16 v[26:29], v[224:227], v[26:29], v[34:37]
	v_mfma_f32_16x16x32_bf16 v[130:133], v[228:231], v[30:33], v[26:29]
	v_mfma_f32_16x16x32_bf16 v[26:29], v[216:219], v[62:65], v[38:41]
	v_mfma_f32_16x16x32_bf16 v[118:121], v[220:223], v[102:105], v[26:29]
	v_mfma_f32_16x16x32_bf16 v[26:29], v[224:227], v[62:65], v[42:45]
	v_mfma_f32_16x16x32_bf16 v[114:117], v[228:231], v[102:105], v[26:29]
	v_mfma_f32_16x16x32_bf16 v[26:29], v[216:219], v[232:235], v[46:49]
	v_mfma_f32_16x16x32_bf16 v[102:105], v[220:223], v[236:239], v[26:29]
	v_mfma_f32_16x16x32_bf16 v[26:29], v[224:227], v[232:235], v[50:53]
	v_mfma_f32_16x16x32_bf16 v[98:101], v[228:231], v[236:239], v[26:29]
	v_mfma_f32_16x16x32_bf16 v[26:29], v[216:219], v[240:243], v[54:57]
	v_mfma_f32_16x16x32_bf16 v[70:73], v[220:223], v[244:247], v[26:29]
	v_mfma_f32_16x16x32_bf16 v[26:29], v[224:227], v[240:243], v[58:61]
	v_mfma_f32_16x16x32_bf16 v[134:137], v[220:223], v[30:33], v[66:69]
	v_mfma_f32_16x16x32_bf16 v[66:69], v[228:231], v[244:247], v[26:29]
	s_setprio 0
	s_barrier
; #define PG8_WAIT_V(n) asm volatile("s_waitcnt vmcnt(" #n ")" ::: "memory")
; template <class Epi, class Sched, bool ALIGN_EPI = true, bool SP2 = true, bool FULLLINE = false, bool NOSTAGE = false, bool FP8 = false>
; __device__ __forceinline__ void gemm_phase(PG8_LAS unsigned char* lds, const Gemm g, const Sched& S, const Epi& E) {
;     ...
;         static_assert(SP2, "only the SP2 loop is kept");
;         { const int t = 0; if constexpr (Epi::NST == 16) PG8_ITER(PG8_WAIT_V(24)); else if constexpr (Epi::NST == 8) PG8_ITER(PG8_WAIT_V(16)); else PG8_ITER(PG8_WAIT_V(8)); }
;         for (int t = 2; t < nt; t += 2) PG8_ITER(PG8_WAIT_V(8));
	s_add_i32 s50, s88, s46
	s_nop 3
	v_lshl_add_u64 v[26:27], v[250:251], 0, s[24:25]
	s_mov_b32 m0, s50
	s_add_i32 s51, s50, 0x2000
	ds_read_b128 v[34:37], v193 offset:49152
	ds_read_b128 v[38:41], v193 offset:50176
	ds_read_b128 v[74:77], v193 offset:51200
	ds_read_b128 v[82:85], v193 offset:52224
	ds_read_b128 v[90:93], v193 offset:53248
	ds_read_b128 v[94:97], v193 offset:54272
	ds_read_b128 v[232:235], v193 offset:55296
	ds_read_b128 v[236:239], v193 offset:56320
	global_load_lds_dwordx4 v[26:27], off
	v_lshl_add_u64 v[26:27], v[250:251], 0, s[26:27]
	s_mov_b32 m0, s51
	s_mov_b64 s[0:1], 0x80180
	s_add_i32 s33, s89, s46
	global_load_lds_dwordx4 v[26:27], off
	v_lshl_add_u64 v[26:27], v[250:251], 0, s[0:1]
	s_mov_b32 m0, s33
	s_mov_b64 s[0:1], 0xc0180
	s_add_i32 s56, s33, 0x2000
	global_load_lds_dwordx4 v[26:27], off
	v_lshl_add_u64 v[26:27], v[250:251], 0, s[0:1]
	s_mov_b32 m0, s56
	s_nop 0
	global_load_lds_dwordx4 v[26:27], off
	v_lshl_add_u64 v[26:27], v[248:249], 0, s[24:25]
	s_mov_b32 m0, s55
	s_nop 0
	global_load_lds_dwordx4 v[26:27], off
	v_lshl_add_u64 v[26:27], v[248:249], 0, s[26:27]
	s_mov_b32 m0, s62
	s_nop 0
	global_load_lds_dwordx4 v[26:27], off
	s_waitcnt vmcnt(8)
	s_waitcnt lgkmcnt(0)
	s_barrier
	s_waitcnt lgkmcnt(0)
	s_setprio 1
	v_mfma_f32_16x16x32_bf16 v[26:29], v[10:13], v[34:37], v[138:141]
	v_mfma_f32_16x16x32_bf16 v[62:65], v[14:17], v[38:41], v[26:29]
	v_mfma_f32_16x16x32_bf16 v[26:29], v[18:21], v[34:37], v[150:153]
	v_mfma_f32_16x16x32_bf16 v[58:61], v[22:25], v[38:41], v[26:29]
	v_mfma_f32_16x16x32_bf16 v[26:29], v[10:13], v[74:77], v[154:157]
	v_mfma_f32_16x16x32_bf16 v[46:49], v[14:17], v[82:85], v[26:29]
	v_mfma_f32_16x16x32_bf16 v[26:29], v[18:21], v[74:77], v[158:161]
	v_mfma_f32_16x16x32_bf16 v[42:45], v[22:25], v[82:85], v[26:29]
	v_mfma_f32_16x16x32_bf16 v[26:29], v[10:13], v[90:93], v[162:165]
	v_mfma_f32_16x16x32_bf16 v[2:5], v[10:13], v[232:235], v[2:5]
	v_mfma_f32_16x16x32_bf16 v[30:33], v[14:17], v[94:97], v[26:29]
	v_mfma_f32_16x16x32_bf16 v[26:29], v[18:21], v[90:93], v[166:169]
	v_mfma_f32_16x16x32_bf16 v[14:17], v[14:17], v[236:239], v[2:5]
	v_mfma_f32_16x16x32_bf16 v[2:5], v[18:21], v[232:235], v[6:9]
	v_mfma_f32_16x16x32_bf16 v[26:29], v[22:25], v[94:97], v[26:29]
	v_mfma_f32_16x16x32_bf16 v[10:13], v[22:25], v[236:239], v[2:5]
	v_mfma_f32_16x16x32_bf16 v[2:5], v[216:219], v[34:37], v[180:183]
	v_mfma_f32_16x16x32_bf16 v[54:57], v[220:223], v[38:41], v[2:5]
	v_mfma_f32_16x16x32_bf16 v[2:5], v[224:227], v[34:37], v[184:187]
	v_mfma_f32_16x16x32_bf16 v[50:53], v[228:231], v[38:41], v[2:5]
	v_mfma_f32_16x16x32_bf16 v[2:5], v[216:219], v[74:77], v[188:191]
	v_mfma_f32_16x16x32_bf16 v[38:41], v[220:223], v[82:85], v[2:5]
	v_mfma_f32_16x16x32_bf16 v[2:5], v[224:227], v[74:77], v[196:199]
	v_mfma_f32_16x16x32_bf16 v[34:37], v[228:231], v[82:85], v[2:5]
	v_mfma_f32_16x16x32_bf16 v[2:5], v[216:219], v[90:93], v[200:203]
	v_mfma_f32_16x16x32_bf16 v[22:25], v[220:223], v[94:97], v[2:5]
	v_mfma_f32_16x16x32_bf16 v[2:5], v[224:227], v[90:93], v[204:207]
	v_mfma_f32_16x16x32_bf16 v[18:21], v[228:231], v[94:97], v[2:5]
	v_mfma_f32_16x16x32_bf16 v[2:5], v[216:219], v[232:235], v[208:211]
	v_mfma_f32_16x16x32_bf16 v[6:9], v[220:223], v[236:239], v[2:5]
	v_mfma_f32_16x16x32_bf16 v[2:5], v[224:227], v[232:235], v[212:215]
	v_mfma_f32_16x16x32_bf16 v[2:5], v[228:231], v[236:239], v[2:5]
	s_setprio 0
	s_barrier
	s_add_u32 s74, s74, 0x80180
	s_addc_u32 s75, s75, 0
	s_add_u32 s57, s76, 0x200
	s_addc_u32 s76, s77, 0
	s_mov_b32 s77, 0
.LBB0_2097:
	ds_read_b128 v[74:77], v1
	ds_read_b128 v[82:85], v1 offset:1024
	ds_read_b128 v[90:93], v1 offset:2048
	ds_read_b128 v[94:97], v1 offset:3072
	ds_read_b128 v[138:141], v192
	ds_read_b128 v[150:153], v192 offset:1024
	ds_read_b128 v[154:157], v192 offset:2048
	ds_read_b128 v[158:161], v192 offset:3072
	s_add_u32 s0, s74, 0xfff80080
	s_addc_u32 s1, s75, -1
	s_cmp_eq_u32 s77, 28
	s_cselect_b32 s1, s67, s1
	s_cselect_b32 s0, s90, s0
	s_cselect_b32 s65, s41, s76
	s_cselect_b32 s64, s91, s57
	s_mov_b32 m0, s85
	v_lshl_add_u64 v[208:209], s[74:75], 0, v[174:175]
	ds_read_b128 v[162:165], v193
	ds_read_b128 v[166:169], v193 offset:1024
	ds_read_b128 v[180:183], v193 offset:2048
	ds_read_b128 v[184:187], v193 offset:3072
	ds_read_b128 v[188:191], v193 offset:4096
	ds_read_b128 v[196:199], v193 offset:5120
	ds_read_b128 v[200:203], v193 offset:6144
	ds_read_b128 v[204:207], v193 offset:7168
	global_load_lds_dwordx4 v[208:209], off
	v_lshl_add_u64 v[208:209], v[208:209], 0, s[28:29]
	s_mov_b32 m0, s87
	s_nop 0
	global_load_lds_dwordx4 v[208:209], off
	s_waitcnt vmcnt(8)
	s_waitcnt lgkmcnt(0)
	s_barrier
; #define PG8_WAIT_V(n) asm volatile("s_waitcnt vmcnt(" #n ")" ::: "memory")
; template <class Epi, class Sched, bool ALIGN_EPI = true, bool SP2 = true, bool FULLLINE = false, bool NOSTAGE = false, bool FP8 = false>
; __device__ __forceinline__ void gemm_phase(PG8_LAS unsigned char* lds, const Gemm g, const Sched& S, const Epi& E) {
;     ...
;         for (int t = 2; t < nt; t += 2) PG8_ITER(PG8_WAIT_V(8));
	s_waitcnt lgkmcnt(0)
	s_setprio 1
	v_mfma_f32_16x16x32_bf16 v[146:149], v[74:77], v[162:165], v[146:149]
	v_mfma_f32_16x16x32_bf16 v[142:145], v[90:93], v[162:165], v[142:145]
	v_mfma_f32_16x16x32_bf16 v[126:129], v[74:77], v[180:183], v[126:129]
	v_mfma_f32_16x16x32_bf16 v[122:125], v[90:93], v[180:183], v[122:125]
	v_mfma_f32_16x16x32_bf16 v[110:113], v[74:77], v[188:191], v[110:113]
	v_mfma_f32_16x16x32_bf16 v[106:109], v[90:93], v[188:191], v[106:109]
	v_mfma_f32_16x16x32_bf16 v[86:89], v[74:77], v[200:203], v[86:89]
	v_mfma_f32_16x16x32_bf16 v[78:81], v[90:93], v[200:203], v[78:81]
	v_mfma_f32_16x16x32_bf16 v[146:149], v[82:85], v[166:169], v[146:149]
	v_mfma_f32_16x16x32_bf16 v[142:145], v[94:97], v[166:169], v[142:145]
	v_mfma_f32_16x16x32_bf16 v[126:129], v[82:85], v[184:187], v[126:129]
	v_mfma_f32_16x16x32_bf16 v[122:125], v[94:97], v[184:187], v[122:125]
	v_mfma_f32_16x16x32_bf16 v[110:113], v[82:85], v[196:199], v[110:113]
	v_mfma_f32_16x16x32_bf16 v[106:109], v[94:97], v[196:199], v[106:109]
	v_mfma_f32_16x16x32_bf16 v[86:89], v[82:85], v[204:207], v[86:89]
	v_mfma_f32_16x16x32_bf16 v[78:81], v[94:97], v[204:207], v[78:81]
	v_mfma_f32_16x16x32_bf16 v[134:137], v[138:141], v[162:165], v[134:137]
	v_mfma_f32_16x16x32_bf16 v[130:133], v[154:157], v[162:165], v[130:133]
	v_mfma_f32_16x16x32_bf16 v[118:121], v[138:141], v[180:183], v[118:121]
	v_mfma_f32_16x16x32_bf16 v[114:117], v[154:157], v[180:183], v[114:117]
	v_mfma_f32_16x16x32_bf16 v[102:105], v[138:141], v[188:191], v[102:105]
	v_mfma_f32_16x16x32_bf16 v[98:101], v[154:157], v[188:191], v[98:101]
	v_mfma_f32_16x16x32_bf16 v[70:73], v[138:141], v[200:203], v[70:73]
	v_mfma_f32_16x16x32_bf16 v[66:69], v[154:157], v[200:203], v[66:69]
	v_mfma_f32_16x16x32_bf16 v[134:137], v[150:153], v[166:169], v[134:137]
	v_mfma_f32_16x16x32_bf16 v[130:133], v[158:161], v[166:169], v[130:133]
	v_mfma_f32_16x16x32_bf16 v[118:121], v[150:153], v[184:187], v[118:121]
	v_mfma_f32_16x16x32_bf16 v[114:117], v[158:161], v[184:187], v[114:117]
	v_mfma_f32_16x16x32_bf16 v[102:105], v[150:153], v[196:199], v[102:105]
	v_mfma_f32_16x16x32_bf16 v[98:101], v[158:161], v[196:199], v[98:101]
	v_mfma_f32_16x16x32_bf16 v[70:73], v[150:153], v[204:207], v[70:73]
	v_mfma_f32_16x16x32_bf16 v[66:69], v[158:161], v[204:207], v[66:69]
	s_setprio 0
	s_barrier
	s_mov_b32 m0, s92
	v_lshl_add_u64 v[208:209], s[64:65], 0, v[172:173]
	ds_read_b128 v[162:165], v193 offset:16384
	ds_read_b128 v[166:169], v193 offset:17408
	ds_read_b128 v[180:183], v193 offset:18432
	ds_read_b128 v[184:187], v193 offset:19456
	ds_read_b128 v[188:191], v193 offset:20480
	ds_read_b128 v[196:199], v193 offset:21504
	ds_read_b128 v[200:203], v193 offset:22528
	ds_read_b128 v[204:207], v193 offset:23552
	global_load_lds_dwordx4 v[208:209], off
	v_lshl_add_u64 v[210:211], v[208:209], 0, s[28:29]
	s_mov_b32 m0, s93
	s_nop 0
	global_load_lds_dwordx4 v[210:211], off
	v_lshl_add_u64 v[210:211], v[208:209], 0, s[30:31]
	s_mov_b32 m0, s94
	s_nop 0
	global_load_lds_dwordx4 v[210:211], off
	v_lshl_add_u64 v[210:211], v[208:209], 0, s[34:35]
	s_mov_b32 m0, s95
	s_nop 0
	global_load_lds_dwordx4 v[210:211], off
	v_lshl_add_u64 v[210:211], s[0:1], 0, v[170:171]
	s_mov_b32 m0, s47
	v_lshl_add_u64 v[212:213], v[210:211], 0, s[28:29]
	global_load_lds_dwordx4 v[210:211], off
	s_mov_b32 m0, s52
	s_nop 0
	global_load_lds_dwordx4 v[212:213], off
	s_waitcnt vmcnt(8)
	s_waitcnt lgkmcnt(0)
	s_barrier
	s_waitcnt lgkmcnt(0)
	s_setprio 1
	v_mfma_f32_16x16x32_bf16 v[62:65], v[74:77], v[162:165], v[62:65]
	v_mfma_f32_16x16x32_bf16 v[58:61], v[90:93], v[162:165], v[58:61]
	v_mfma_f32_16x16x32_bf16 v[46:49], v[74:77], v[180:183], v[46:49]
	v_mfma_f32_16x16x32_bf16 v[42:45], v[90:93], v[180:183], v[42:45]
	v_mfma_f32_16x16x32_bf16 v[30:33], v[74:77], v[188:191], v[30:33]
	v_mfma_f32_16x16x32_bf16 v[26:29], v[90:93], v[188:191], v[26:29]
	v_mfma_f32_16x16x32_bf16 v[14:17], v[74:77], v[200:203], v[14:17]
	v_mfma_f32_16x16x32_bf16 v[10:13], v[90:93], v[200:203], v[10:13]
	v_mfma_f32_16x16x32_bf16 v[62:65], v[82:85], v[166:169], v[62:65]
	v_mfma_f32_16x16x32_bf16 v[58:61], v[94:97], v[166:169], v[58:61]
	v_mfma_f32_16x16x32_bf16 v[46:49], v[82:85], v[184:187], v[46:49]
	v_mfma_f32_16x16x32_bf16 v[42:45], v[94:97], v[184:187], v[42:45]
	v_mfma_f32_16x16x32_bf16 v[30:33], v[82:85], v[196:199], v[30:33]
	v_mfma_f32_16x16x32_bf16 v[26:29], v[94:97], v[196:199], v[26:29]
	v_mfma_f32_16x16x32_bf16 v[14:17], v[82:85], v[204:207], v[14:17]
	v_mfma_f32_16x16x32_bf16 v[10:13], v[94:97], v[204:207], v[10:13]
	v_mfma_f32_16x16x32_bf16 v[54:57], v[138:141], v[162:165], v[54:57]
	v_mfma_f32_16x16x32_bf16 v[50:53], v[154:157], v[162:165], v[50:53]
	v_mfma_f32_16x16x32_bf16 v[38:41], v[138:141], v[180:183], v[38:41]
	v_mfma_f32_16x16x32_bf16 v[34:37], v[154:157], v[180:183], v[34:37]
	v_mfma_f32_16x16x32_bf16 v[22:25], v[138:141], v[188:191], v[22:25]
	v_mfma_f32_16x16x32_bf16 v[18:21], v[154:157], v[188:191], v[18:21]
	v_mfma_f32_16x16x32_bf16 v[6:9], v[138:141], v[200:203], v[6:9]
	v_mfma_f32_16x16x32_bf16 v[2:5], v[154:157], v[200:203], v[2:5]
	v_mfma_f32_16x16x32_bf16 v[54:57], v[150:153], v[166:169], v[54:57]
	v_mfma_f32_16x16x32_bf16 v[50:53], v[158:161], v[166:169], v[50:53]
	v_mfma_f32_16x16x32_bf16 v[38:41], v[150:153], v[184:187], v[38:41]
	v_mfma_f32_16x16x32_bf16 v[34:37], v[158:161], v[184:187], v[34:37]
	v_mfma_f32_16x16x32_bf16 v[22:25], v[150:153], v[196:199], v[22:25]
	v_mfma_f32_16x16x32_bf16 v[18:21], v[158:161], v[196:199], v[18:21]
	v_mfma_f32_16x16x32_bf16 v[6:9], v[150:153], v[204:207], v[6:9]
	v_mfma_f32_16x16x32_bf16 v[2:5], v[158:161], v[204:207], v[2:5]
	s_setprio 0
	s_barrier
; #define PG8_WAIT_V(n) asm volatile("s_waitcnt vmcnt(" #n ")" ::: "memory")
; #define PG8_BAR __builtin_amdgcn_s_barrier()
; template <class Epi, class Sched, bool ALIGN_EPI = true, bool SP2 = true, bool FULLLINE = false, bool NOSTAGE = false, bool FP8 = false>
; __device__ __forceinline__ void gemm_phase(PG8_LAS unsigned char* lds, const Gemm g, const Sched& S, const Epi& E) {
;     ...
;         for (int t = 2; t < nt; t += 2) PG8_ITER(PG8_WAIT_V(8));
;     ...
;         if constexpr (ALIGN_EPI) { if (wr == 0) PG8_BAR; }
	ds_read_b128 v[74:77], v194
	ds_read_b128 v[82:85], v194 offset:1024
	ds_read_b128 v[90:93], v194 offset:2048
	ds_read_b128 v[94:97], v194 offset:3072
	ds_read_b128 v[138:141], v195
	ds_read_b128 v[150:153], v195 offset:1024
	ds_read_b128 v[154:157], v195 offset:2048
	ds_read_b128 v[158:161], v195 offset:3072
	s_mov_b32 m0, s53
	v_lshl_add_u64 v[212:213], v[210:211], 0, s[30:31]
	ds_read_b128 v[162:165], v193 offset:32768
	ds_read_b128 v[166:169], v193 offset:33792
	ds_read_b128 v[180:183], v193 offset:34816
	ds_read_b128 v[184:187], v193 offset:35840
	ds_read_b128 v[188:191], v193 offset:36864
	ds_read_b128 v[196:199], v193 offset:37888
	ds_read_b128 v[200:203], v193 offset:38912
	ds_read_b128 v[204:207], v193 offset:39936
	global_load_lds_dwordx4 v[212:213], off
	v_lshl_add_u64 v[212:213], v[210:211], 0, s[34:35]
	s_mov_b32 m0, s54
	s_nop 0
	global_load_lds_dwordx4 v[212:213], off
	s_waitcnt vmcnt(8)
	s_waitcnt lgkmcnt(0)
	s_barrier
	s_waitcnt lgkmcnt(0)
	s_setprio 1
	v_mfma_f32_16x16x32_bf16 v[146:149], v[74:77], v[162:165], v[146:149]
	v_mfma_f32_16x16x32_bf16 v[142:145], v[90:93], v[162:165], v[142:145]
	v_mfma_f32_16x16x32_bf16 v[126:129], v[74:77], v[180:183], v[126:129]
	v_mfma_f32_16x16x32_bf16 v[122:125], v[90:93], v[180:183], v[122:125]
	v_mfma_f32_16x16x32_bf16 v[110:113], v[74:77], v[188:191], v[110:113]
	v_mfma_f32_16x16x32_bf16 v[106:109], v[90:93], v[188:191], v[106:109]
	v_mfma_f32_16x16x32_bf16 v[86:89], v[74:77], v[200:203], v[86:89]
	v_mfma_f32_16x16x32_bf16 v[78:81], v[90:93], v[200:203], v[78:81]
	v_mfma_f32_16x16x32_bf16 v[146:149], v[82:85], v[166:169], v[146:149]
	v_mfma_f32_16x16x32_bf16 v[142:145], v[94:97], v[166:169], v[142:145]
	v_mfma_f32_16x16x32_bf16 v[126:129], v[82:85], v[184:187], v[126:129]
	v_mfma_f32_16x16x32_bf16 v[122:125], v[94:97], v[184:187], v[122:125]
	v_mfma_f32_16x16x32_bf16 v[110:113], v[82:85], v[196:199], v[110:113]
	v_mfma_f32_16x16x32_bf16 v[106:109], v[94:97], v[196:199], v[106:109]
	v_mfma_f32_16x16x32_bf16 v[86:89], v[82:85], v[204:207], v[86:89]
	v_mfma_f32_16x16x32_bf16 v[78:81], v[94:97], v[204:207], v[78:81]
	v_mfma_f32_16x16x32_bf16 v[134:137], v[138:141], v[162:165], v[134:137]
	v_mfma_f32_16x16x32_bf16 v[130:133], v[154:157], v[162:165], v[130:133]
	v_mfma_f32_16x16x32_bf16 v[118:121], v[138:141], v[180:183], v[118:121]
	v_mfma_f32_16x16x32_bf16 v[114:117], v[154:157], v[180:183], v[114:117]
	v_mfma_f32_16x16x32_bf16 v[102:105], v[138:141], v[188:191], v[102:105]
	v_mfma_f32_16x16x32_bf16 v[98:101], v[154:157], v[188:191], v[98:101]
	v_mfma_f32_16x16x32_bf16 v[70:73], v[138:141], v[200:203], v[70:73]
	v_mfma_f32_16x16x32_bf16 v[66:69], v[154:157], v[200:203], v[66:69]
	v_mfma_f32_16x16x32_bf16 v[134:137], v[150:153], v[166:169], v[134:137]
	v_mfma_f32_16x16x32_bf16 v[130:133], v[158:161], v[166:169], v[130:133]
	v_mfma_f32_16x16x32_bf16 v[118:121], v[150:153], v[184:187], v[118:121]
	v_mfma_f32_16x16x32_bf16 v[114:117], v[158:161], v[184:187], v[114:117]
	v_mfma_f32_16x16x32_bf16 v[102:105], v[150:153], v[196:199], v[102:105]
	v_mfma_f32_16x16x32_bf16 v[98:101], v[158:161], v[196:199], v[98:101]
	v_mfma_f32_16x16x32_bf16 v[70:73], v[150:153], v[204:207], v[70:73]
	v_mfma_f32_16x16x32_bf16 v[66:69], v[158:161], v[204:207], v[66:69]
	s_setprio 0
	s_barrier
	s_mov_b32 m0, s50
	v_lshl_add_u64 v[212:213], v[208:209], 0, s[36:37]
	ds_read_b128 v[162:165], v193 offset:49152
	ds_read_b128 v[166:169], v193 offset:50176
	ds_read_b128 v[180:183], v193 offset:51200
	ds_read_b128 v[184:187], v193 offset:52224
	ds_read_b128 v[188:191], v193 offset:53248
	ds_read_b128 v[196:199], v193 offset:54272
	ds_read_b128 v[200:203], v193 offset:55296
	ds_read_b128 v[204:207], v193 offset:56320
	global_load_lds_dwordx4 v[212:213], off
	v_lshl_add_u64 v[212:213], v[208:209], 0, s[38:39]
	s_mov_b32 m0, s51
	s_nop 0
	global_load_lds_dwordx4 v[212:213], off
	v_lshl_add_u64 v[212:213], v[208:209], 0, s[12:13]
	s_mov_b32 m0, s33
	v_lshl_add_u64 v[208:209], v[208:209], 0, s[14:15]
	global_load_lds_dwordx4 v[212:213], off
	s_mov_b32 m0, s56
	s_nop 0
	global_load_lds_dwordx4 v[208:209], off
	v_lshl_add_u64 v[208:209], v[210:211], 0, s[36:37]
	s_mov_b32 m0, s55
	s_nop 0
	global_load_lds_dwordx4 v[208:209], off
	v_lshl_add_u64 v[208:209], v[210:211], 0, s[38:39]
	s_mov_b32 m0, s62
	s_nop 0
	global_load_lds_dwordx4 v[208:209], off
	s_waitcnt vmcnt(8)
	s_waitcnt lgkmcnt(0)
	s_barrier
	s_waitcnt lgkmcnt(0)
	s_setprio 1
	v_mfma_f32_16x16x32_bf16 v[62:65], v[74:77], v[162:165], v[62:65]
	v_mfma_f32_16x16x32_bf16 v[58:61], v[90:93], v[162:165], v[58:61]
	v_mfma_f32_16x16x32_bf16 v[46:49], v[74:77], v[180:183], v[46:49]
	v_mfma_f32_16x16x32_bf16 v[42:45], v[90:93], v[180:183], v[42:45]
	v_mfma_f32_16x16x32_bf16 v[30:33], v[74:77], v[188:191], v[30:33]
	v_mfma_f32_16x16x32_bf16 v[26:29], v[90:93], v[188:191], v[26:29]
	v_mfma_f32_16x16x32_bf16 v[14:17], v[74:77], v[200:203], v[14:17]
	v_mfma_f32_16x16x32_bf16 v[10:13], v[90:93], v[200:203], v[10:13]
	v_mfma_f32_16x16x32_bf16 v[62:65], v[82:85], v[166:169], v[62:65]
	v_mfma_f32_16x16x32_bf16 v[58:61], v[94:97], v[166:169], v[58:61]
	v_mfma_f32_16x16x32_bf16 v[46:49], v[82:85], v[184:187], v[46:49]
	v_mfma_f32_16x16x32_bf16 v[42:45], v[94:97], v[184:187], v[42:45]
	v_mfma_f32_16x16x32_bf16 v[30:33], v[82:85], v[196:199], v[30:33]
	v_mfma_f32_16x16x32_bf16 v[26:29], v[94:97], v[196:199], v[26:29]
	v_mfma_f32_16x16x32_bf16 v[14:17], v[82:85], v[204:207], v[14:17]
	v_mfma_f32_16x16x32_bf16 v[10:13], v[94:97], v[204:207], v[10:13]
	v_mfma_f32_16x16x32_bf16 v[54:57], v[138:141], v[162:165], v[54:57]
	v_mfma_f32_16x16x32_bf16 v[50:53], v[154:157], v[162:165], v[50:53]
	v_mfma_f32_16x16x32_bf16 v[38:41], v[138:141], v[180:183], v[38:41]
	v_mfma_f32_16x16x32_bf16 v[34:37], v[154:157], v[180:183], v[34:37]
	v_mfma_f32_16x16x32_bf16 v[22:25], v[138:141], v[188:191], v[22:25]
	v_mfma_f32_16x16x32_bf16 v[18:21], v[154:157], v[188:191], v[18:21]
	v_mfma_f32_16x16x32_bf16 v[6:9], v[138:141], v[200:203], v[6:9]
	v_mfma_f32_16x16x32_bf16 v[2:5], v[154:157], v[200:203], v[2:5]
	v_mfma_f32_16x16x32_bf16 v[54:57], v[150:153], v[166:169], v[54:57]
	v_mfma_f32_16x16x32_bf16 v[50:53], v[158:161], v[166:169], v[50:53]
	v_mfma_f32_16x16x32_bf16 v[38:41], v[150:153], v[184:187], v[38:41]
	v_mfma_f32_16x16x32_bf16 v[34:37], v[158:161], v[184:187], v[34:37]
	v_mfma_f32_16x16x32_bf16 v[22:25], v[150:153], v[196:199], v[22:25]
	v_mfma_f32_16x16x32_bf16 v[18:21], v[158:161], v[196:199], v[18:21]
	v_mfma_f32_16x16x32_bf16 v[6:9], v[150:153], v[204:207], v[6:9]
	v_mfma_f32_16x16x32_bf16 v[2:5], v[158:161], v[204:207], v[2:5]
	s_setprio 0
	s_barrier
	s_add_i32 s77, s77, 2
	s_add_u32 s74, s74, 0x100
	s_addc_u32 s75, s75, 0
	s_add_u32 s57, s57, 0x100
	s_addc_u32 s76, s76, 0
	s_cmp_gt_u32 s77, 29
	s_cbranch_scc0 .LBB0_2097
	s_and_b64 vcc, exec, s[10:11]
	s_cbranch_vccz .LBB0_2100
	s_barrier

; #define PG8_STAGE(bufoff, gbase, voff) do { if constexpr (!NOSTAGE) _Pragma("unroll") for (int _i = 0; _i < 2; ++_i) \
;         __builtin_amdgcn_global_load_lds((const unsigned*)((const char*)(gbase) + (size_t)_i * pstep##voff + v##voff), (PG8_LAS unsigned*)(lds + (bufoff) + ldsw + _i * 8192), 16, 0, 0); } while (0)
; #define PG8_WAIT_V(n) asm volatile("s_waitcnt vmcnt(" #n ")" ::: "memory")
; #define PG8_BAR __builtin_amdgcn_s_barrier()
; template <class Epi, class Sched, bool ALIGN_EPI = true, bool SP2 = true, bool FULLLINE = false, bool NOSTAGE = false, bool FP8 = false>
; __device__ __forceinline__ void gemm_phase(PG8_LAS unsigned char* lds, const Gemm g, const Sched& S, const Epi& E) {
;     const int tid = threadIdx.x, wid = __builtin_amdgcn_readfirstlane(tid >> 6), lane = tid & 63, wr = wid >> 2, wc = wid & 3, fr = lane & 15, fq = lane >> 4;
;     const int K = g.K, nt = K / BK;
;     unsigned voffA_, voffB_;
;     { int R, C; stage_rc(tid * 16, R, C); const int Rb = Epi::PERM ? ((R & ~31) + perm32(R & 31)) : R;
;       voffA_ = (unsigned)(R * g.lda + C) * 2u; voffB_ = (unsigned)(Rb * g.ldb + C) * 2u; }
;     const unsigned voffA = voffA_, voffB = voffB_;
;     const size_t pstepoffA = (size_t)64 * g.lda * 2, pstepoffB = (size_t)64 * g.ldb * 2;
;     const size_t kstep = (size_t)(BK * 2);
;     const size_t hstepA = (size_t)HALF * g.lda * 2, hstepB = (size_t)HALF * g.ldb * 2;
;     const size_t tstepA = 2 * hstepA, tstepB = 2 * hstepB;
;     const unsigned ldsw = (unsigned)wid * 1024u;
;     const int aoff = lds_byte(wr * 64 + fr, fq * 8), boff = lds_byte(wc * 32 + fr, fq * 8);
;     ...
;     if (wr == 1) PG8_BAR;
;     PG8_WAIT_V(0); PG8_BAR;
;     PG8_BAR;
;     } else {
;     PG8_STAGE(PG8_SB(0, 0), cB, offB); PG8_STAGE(PG8_SA(0, 0), cA, offA); PG8_STAGE(PG8_SB(0, 1), cB + hstepB, offB); PG8_STAGE(PG8_SA(0, 1), cA + hstepA, offA);
;     if (wr == 1) PG8_BAR;
;     PG8_WAIT_V(4); PG8_BAR;
;     PG8_STAGE(PG8_SB(1, 0), cB + kstep, offB); PG8_STAGE(PG8_SA(1, 0), cA + kstep, offA); PG8_STAGE(PG8_SB(1, 1), cB + hstepB + kstep, offB);
;     PG8_WAIT_V(6); PG8_BAR;
;     }
;     if (wr == 1) __builtin_amdgcn_s_setprio(1);
.LBB0_2279:
	s_waitcnt vmcnt(0)
	v_cndmask_b32_e64 v4, 0, 1, s[10:11]
	v_cmp_ne_u32_e64 s[6:7], 1, v4
	s_andn2_b64 vcc, exec, s[10:11]
	s_barrier
	s_barrier
	s_cbranch_vccnz .LBB0_2281
.LBB0_2281:
	v_and_b32_e32 v4, 48, v0
	v_lshlrev_b32_e32 v5, 6, v0
	s_movk_i32 s1, 0x3c0
	v_and_or_b32 v4, v5, s1, v4
	v_lshlrev_b32_e32 v5, 2, v0
	s_lshl_b32 s0, s13, 13
	v_and_b32_e32 v5, 32, v5
	v_bitop3_b32 v6, v4, s0, v5 bitop3:0xde
	s_lshl_b32 s0, s12, 5
	s_and_b32 s71, s0, 0x60
	s_lshl_b32 s0, s71, 7
	s_lshl_b32 s55, s13, 6
	v_bitop3_b32 v4, s0, v4, v5 bitop3:0xf6
	v_lshlrev_b32_e32 v5, 9, v0
	s_cmpk_lt_u32 s9, 0x100
	v_and_b32_e32 v5, 0x30000, v5
	v_lshlrev_b32_e32 v3, 12, v3
	s_cselect_b64 s[10:11], -1, 0
	v_or3_b32 v1, v1, v5, v3
	s_add_i32 s81, 0, 0x10000
	s_add_i32 s78, 0, 0x14000
	s_add_i32 s82, 0, 0x18000
	s_add_i32 s83, 0, 0x1c000
	s_sext_i32_i16 s85, s8
	s_ashr_i32 s76, s86, 31
	v_add_u32_e32 v134, v1, v2
	v_mov_b32_e32 v135, 0
	s_mov_b32 s77, 0
	v_mov_b64_e32 v[136:137], 0xb00
	v_mov_b64_e32 v[138:139], 0xaff
	v_add_u32_e32 v1, s81, v4
	v_add_u32_e32 v142, s78, v4
	v_add_u32_e32 v143, 0, v6
	s_mov_b64 s[12:13], 0x80080
	s_add_i32 s79, s45, 0xc000
	s_mov_b64 s[14:15], 0xc0080
	s_add_i32 s80, s45, 0xe000
	s_mov_b64 s[16:17], 0x100
	s_add_i32 s81, s81, s43
	s_mov_b64 s[18:19], 0x40100
	s_mov_b64 s[20:21], 0x80100
	s_mov_b64 s[22:23], 0xc0100
	v_add_u32_e32 v144, s82, v4
	v_add_u32_e32 v145, s83, v4
	s_mov_b64 s[24:25], 0x180
	s_mov_b64 s[26:27], 0x40180
	s_mov_b64 s[28:29], 0x40000
	s_mov_b64 s[30:31], 0x80000
	s_mov_b64 s[34:35], 0xc0000
	s_mov_b64 s[36:37], 0x80
	s_mov_b64 s[38:39], 0x40080
	s_movk_i32 s84, 0x2c00
	s_branch .LBB0_2284

; #define PG8_WAIT_V(n) asm volatile("s_waitcnt vmcnt(" #n ")" ::: "memory")
; template <class Epi, class Sched, bool ALIGN_EPI = true, bool SP2 = true, bool FULLLINE = false, bool NOSTAGE = false, bool FP8 = false>
; __device__ __forceinline__ void gemm_phase(PG8_LAS unsigned char* lds, const Gemm g, const Sched& S, const Epi& E) {
;     ...
;         const char* nA = has_next ? PG8_ABASE(nxt) : cA; const char* nB = has_next ? PG8_BBASE(nxt) : cB;
;     ...
;         static_assert(SP2, "only the SP2 loop is kept");
;         { const int t = 0; if constexpr (Epi::NST == 16) PG8_ITER(PG8_WAIT_V(24)); else if constexpr (Epi::NST == 8) PG8_ITER(PG8_WAIT_V(16)); else PG8_ITER(PG8_WAIT_V(8)); }
.LBB0_2286:
	s_ashr_i32 s63, s62, 31
	s_lshl_b64 s[0:1], s[62:63], 20
	s_add_u32 s66, s58, s0
	ds_read_b128 v[2:5], v1
	ds_read_b128 v[6:9], v1 offset:1024
	ds_read_b128 v[10:13], v1 offset:2048
	ds_read_b128 v[14:17], v1 offset:3072
	ds_read_b128 v[18:21], v142
	ds_read_b128 v[22:25], v142 offset:1024
	ds_read_b128 v[26:29], v142 offset:2048
	ds_read_b128 v[30:33], v142 offset:3072
	s_addc_u32 s67, s59, s1
	s_ashr_i32 s41, s40, 31
	s_lshl_b64 s[0:1], s[40:41], 20
	s_add_u32 s68, s3, s0
	s_addc_u32 s69, s42, s1
	s_and_b64 s[0:1], s[8:9], exec
	s_cselect_b32 s41, s67, s75
	s_cselect_b32 s63, s66, s74
	s_cselect_b32 s87, s69, s73
	s_cselect_b32 s88, s68, s72
	v_lshl_add_u64 v[140:141], s[74:75], 0, v[132:133]
	s_mov_b32 m0, s79
	v_lshl_add_u64 v[66:67], v[140:141], 0, s[12:13]
	ds_read_b128 v[34:37], v143
	ds_read_b128 v[38:41], v143 offset:1024
	ds_read_b128 v[42:45], v143 offset:2048
	ds_read_b128 v[46:49], v143 offset:3072
	ds_read_b128 v[50:53], v143 offset:4096
	ds_read_b128 v[54:57], v143 offset:5120
	ds_read_b128 v[58:61], v143 offset:6144
	ds_read_b128 v[62:65], v143 offset:7168
	global_load_lds_dwordx4 v[66:67], off
	v_lshl_add_u64 v[66:67], v[140:141], 0, s[14:15]
	s_mov_b32 m0, s80
	s_nop 0
	global_load_lds_dwordx4 v[66:67], off
	s_waitcnt vmcnt(16)
	s_waitcnt lgkmcnt(0)
	s_barrier
	s_waitcnt lgkmcnt(0)
	s_setprio 1
	v_mfma_f32_16x16x32_bf16 v[86:89], v[10:13], v[50:53], 0
	v_mfma_f32_16x16x32_bf16 v[90:93], v[14:17], v[54:57], v[86:89]
	v_mfma_f32_16x16x32_bf16 v[86:89], v[2:5], v[58:61], 0
	v_mfma_f32_16x16x32_bf16 v[66:69], v[2:5], v[34:37], 0
	v_mfma_f32_16x16x32_bf16 v[70:73], v[10:13], v[34:37], 0
	v_mfma_f32_16x16x32_bf16 v[74:77], v[2:5], v[42:45], 0
	v_mfma_f32_16x16x32_bf16 v[78:81], v[10:13], v[42:45], 0
	v_mfma_f32_16x16x32_bf16 v[82:85], v[2:5], v[50:53], 0
	v_mfma_f32_16x16x32_bf16 v[94:97], v[6:9], v[62:65], v[86:89]
	v_mfma_f32_16x16x32_bf16 v[86:89], v[10:13], v[58:61], 0
	v_mfma_f32_16x16x32_bf16 v[66:69], v[6:9], v[38:41], v[66:69]
	v_mfma_f32_16x16x32_bf16 v[70:73], v[14:17], v[38:41], v[70:73]
	v_mfma_f32_16x16x32_bf16 v[74:77], v[6:9], v[46:49], v[74:77]
	v_mfma_f32_16x16x32_bf16 v[78:81], v[14:17], v[46:49], v[78:81]
	v_mfma_f32_16x16x32_bf16 v[82:85], v[6:9], v[54:57], v[82:85]
	v_mfma_f32_16x16x32_bf16 v[106:109], v[14:17], v[62:65], v[86:89]
	v_mfma_f32_16x16x32_bf16 v[86:89], v[18:21], v[34:37], 0
	v_mfma_f32_16x16x32_bf16 v[34:37], v[26:29], v[34:37], 0
	v_mfma_f32_16x16x32_bf16 v[110:113], v[22:25], v[38:41], v[86:89]
	v_mfma_f32_16x16x32_bf16 v[34:37], v[30:33], v[38:41], v[34:37]
	v_mfma_f32_16x16x32_bf16 v[38:41], v[18:21], v[42:45], 0
	v_mfma_f32_16x16x32_bf16 v[42:45], v[26:29], v[42:45], 0
	v_mfma_f32_16x16x32_bf16 v[38:41], v[22:25], v[46:49], v[38:41]
	v_mfma_f32_16x16x32_bf16 v[42:45], v[30:33], v[46:49], v[42:45]
	v_mfma_f32_16x16x32_bf16 v[46:49], v[18:21], v[50:53], 0
	v_mfma_f32_16x16x32_bf16 v[50:53], v[26:29], v[50:53], 0
	v_mfma_f32_16x16x32_bf16 v[46:49], v[22:25], v[54:57], v[46:49]
	v_mfma_f32_16x16x32_bf16 v[50:53], v[30:33], v[54:57], v[50:53]
	v_mfma_f32_16x16x32_bf16 v[54:57], v[18:21], v[58:61], 0
	v_mfma_f32_16x16x32_bf16 v[58:61], v[26:29], v[58:61], 0
	v_mfma_f32_16x16x32_bf16 v[54:57], v[22:25], v[62:65], v[54:57]
	v_mfma_f32_16x16x32_bf16 v[58:61], v[30:33], v[62:65], v[58:61]
	s_setprio 0
	s_barrier
	v_lshl_add_u64 v[238:239], s[72:73], 0, v[130:131]
	s_mov_b32 m0, s81
	v_lshl_add_u64 v[146:147], v[238:239], 0, s[16:17]
	s_add_i32 s89, s81, 0x2000
	ds_read_b128 v[62:65], v143 offset:16384
	ds_read_b128 v[86:89], v143 offset:17408
	ds_read_b128 v[98:101], v143 offset:18432
	ds_read_b128 v[102:105], v143 offset:19456
	ds_read_b128 v[114:117], v143 offset:20480
	ds_read_b128 v[118:121], v143 offset:21504
	ds_read_b128 v[122:125], v143 offset:22528
	ds_read_b128 v[126:129], v143 offset:23552
	global_load_lds_dwordx4 v[146:147], off
	v_lshl_add_u64 v[146:147], v[238:239], 0, s[18:19]
	s_mov_b32 m0, s89
	s_add_i32 s90, s78, s43
	global_load_lds_dwordx4 v[146:147], off
	v_lshl_add_u64 v[146:147], v[238:239], 0, s[20:21]
	s_mov_b32 m0, s90
	s_add_i32 s91, s90, 0x2000
	global_load_lds_dwordx4 v[146:147], off
	v_lshl_add_u64 v[146:147], v[238:239], 0, s[22:23]
	s_mov_b32 m0, s91
	s_nop 0
	global_load_lds_dwordx4 v[146:147], off
	v_lshl_add_u64 v[146:147], v[140:141], 0, s[16:17]
	s_mov_b32 m0, s45
	s_nop 0
	global_load_lds_dwordx4 v[146:147], off
	v_lshl_add_u64 v[146:147], v[140:141], 0, s[18:19]
	s_mov_b32 m0, s46
	s_nop 0
	global_load_lds_dwordx4 v[146:147], off
	s_waitcnt vmcnt(16)
	s_waitcnt lgkmcnt(0)
	s_barrier
	s_waitcnt lgkmcnt(0)
	s_setprio 1
	v_mfma_f32_16x16x32_bf16 v[146:149], v[2:5], v[62:65], 0
	v_mfma_f32_16x16x32_bf16 v[154:157], v[2:5], v[98:101], 0
	v_mfma_f32_16x16x32_bf16 v[162:165], v[2:5], v[114:117], 0
	v_mfma_f32_16x16x32_bf16 v[2:5], v[2:5], v[122:125], 0
	v_mfma_f32_16x16x32_bf16 v[146:149], v[6:9], v[86:89], v[146:149]
	v_mfma_f32_16x16x32_bf16 v[154:157], v[6:9], v[102:105], v[154:157]
	v_mfma_f32_16x16x32_bf16 v[162:165], v[6:9], v[118:121], v[162:165]
	v_mfma_f32_16x16x32_bf16 v[2:5], v[6:9], v[126:129], v[2:5]
	v_mfma_f32_16x16x32_bf16 v[6:9], v[10:13], v[122:125], 0
	v_mfma_f32_16x16x32_bf16 v[150:153], v[10:13], v[62:65], 0
	v_mfma_f32_16x16x32_bf16 v[158:161], v[10:13], v[98:101], 0
	v_mfma_f32_16x16x32_bf16 v[166:169], v[10:13], v[114:117], 0
	v_mfma_f32_16x16x32_bf16 v[10:13], v[14:17], v[126:129], v[6:9]
	v_mfma_f32_16x16x32_bf16 v[150:153], v[14:17], v[86:89], v[150:153]
	v_mfma_f32_16x16x32_bf16 v[158:161], v[14:17], v[102:105], v[158:161]
	v_mfma_f32_16x16x32_bf16 v[166:169], v[14:17], v[118:121], v[166:169]
	v_mfma_f32_16x16x32_bf16 v[6:9], v[18:21], v[62:65], 0
	v_mfma_f32_16x16x32_bf16 v[14:17], v[22:25], v[86:89], v[6:9]
	v_mfma_f32_16x16x32_bf16 v[6:9], v[26:29], v[62:65], 0
	v_mfma_f32_16x16x32_bf16 v[170:173], v[30:33], v[86:89], v[6:9]
	v_mfma_f32_16x16x32_bf16 v[6:9], v[18:21], v[98:101], 0
	v_mfma_f32_16x16x32_bf16 v[174:177], v[22:25], v[102:105], v[6:9]
	v_mfma_f32_16x16x32_bf16 v[6:9], v[26:29], v[98:101], 0
	v_mfma_f32_16x16x32_bf16 v[178:181], v[30:33], v[102:105], v[6:9]
	v_mfma_f32_16x16x32_bf16 v[6:9], v[18:21], v[114:117], 0
	v_mfma_f32_16x16x32_bf16 v[182:185], v[22:25], v[118:121], v[6:9]
	v_mfma_f32_16x16x32_bf16 v[6:9], v[26:29], v[114:117], 0
	v_mfma_f32_16x16x32_bf16 v[186:189], v[30:33], v[118:121], v[6:9]
	v_mfma_f32_16x16x32_bf16 v[6:9], v[18:21], v[122:125], 0
	v_mfma_f32_16x16x32_bf16 v[190:193], v[22:25], v[126:129], v[6:9]
	v_mfma_f32_16x16x32_bf16 v[6:9], v[26:29], v[122:125], 0
	v_mfma_f32_16x16x32_bf16 v[194:197], v[30:33], v[126:129], v[6:9]
	s_setprio 0
	s_barrier
; #define PG8_WAIT_V(n) asm volatile("s_waitcnt vmcnt(" #n ")" ::: "memory")
; template <class Epi, class Sched, bool ALIGN_EPI = true, bool SP2 = true, bool FULLLINE = false, bool NOSTAGE = false, bool FP8 = false>
; __device__ __forceinline__ void gemm_phase(PG8_LAS unsigned char* lds, const Gemm g, const Sched& S, const Epi& E) {
;     ...
;         static_assert(SP2, "only the SP2 loop is kept");
;         { const int t = 0; if constexpr (Epi::NST == 16) PG8_ITER(PG8_WAIT_V(24)); else if constexpr (Epi::NST == 8) PG8_ITER(PG8_WAIT_V(16)); else PG8_ITER(PG8_WAIT_V(8)); }
	s_nop 5
	ds_read_b128 v[6:9], v144
	ds_read_b128 v[26:29], v144 offset:1024
	ds_read_b128 v[30:33], v144 offset:2048
	ds_read_b128 v[62:65], v144 offset:3072
	ds_read_b128 v[198:201], v145
	ds_read_b128 v[202:205], v145 offset:1024
	ds_read_b128 v[206:209], v145 offset:2048
	ds_read_b128 v[210:213], v145 offset:3072
	s_mov_b32 m0, s47
	v_lshl_add_u64 v[86:87], v[140:141], 0, s[20:21]
	ds_read_b128 v[18:21], v143 offset:32768
	ds_read_b128 v[22:25], v143 offset:33792
	ds_read_b128 v[214:217], v143 offset:34816
	ds_read_b128 v[218:221], v143 offset:35840
	ds_read_b128 v[222:225], v143 offset:36864
	ds_read_b128 v[226:229], v143 offset:37888
	ds_read_b128 v[230:233], v143 offset:38912
	ds_read_b128 v[234:237], v143 offset:39936
	global_load_lds_dwordx4 v[86:87], off
	v_lshl_add_u64 v[86:87], v[140:141], 0, s[22:23]
	s_mov_b32 m0, s52
	s_nop 0
	global_load_lds_dwordx4 v[86:87], off
	s_waitcnt vmcnt(8)
	s_waitcnt lgkmcnt(0)
	s_barrier
	s_waitcnt lgkmcnt(0)
	s_setprio 1
	v_mfma_f32_16x16x32_bf16 v[66:69], v[6:9], v[18:21], v[66:69]
	v_mfma_f32_16x16x32_bf16 v[118:121], v[26:29], v[22:25], v[66:69]
	v_mfma_f32_16x16x32_bf16 v[66:69], v[30:33], v[18:21], v[70:73]
	v_mfma_f32_16x16x32_bf16 v[114:117], v[62:65], v[22:25], v[66:69]
	v_mfma_f32_16x16x32_bf16 v[66:69], v[6:9], v[214:217], v[74:77]
	v_mfma_f32_16x16x32_bf16 v[102:105], v[26:29], v[218:221], v[66:69]
	v_mfma_f32_16x16x32_bf16 v[66:69], v[30:33], v[214:217], v[78:81]
	v_mfma_f32_16x16x32_bf16 v[98:101], v[62:65], v[218:221], v[66:69]
	v_mfma_f32_16x16x32_bf16 v[66:69], v[6:9], v[222:225], v[82:85]
	v_mfma_f32_16x16x32_bf16 v[86:89], v[26:29], v[226:229], v[66:69]
	v_mfma_f32_16x16x32_bf16 v[66:69], v[30:33], v[222:225], v[90:93]
	v_mfma_f32_16x16x32_bf16 v[82:85], v[62:65], v[226:229], v[66:69]
	v_mfma_f32_16x16x32_bf16 v[66:69], v[6:9], v[230:233], v[94:97]
	v_mfma_f32_16x16x32_bf16 v[70:73], v[26:29], v[234:237], v[66:69]
	v_mfma_f32_16x16x32_bf16 v[66:69], v[30:33], v[230:233], v[106:109]
	v_mfma_f32_16x16x32_bf16 v[66:69], v[62:65], v[234:237], v[66:69]
	v_mfma_f32_16x16x32_bf16 v[74:77], v[198:201], v[18:21], v[110:113]
	v_mfma_f32_16x16x32_bf16 v[18:21], v[206:209], v[18:21], v[34:37]
	v_mfma_f32_16x16x32_bf16 v[122:125], v[210:213], v[22:25], v[18:21]
	v_mfma_f32_16x16x32_bf16 v[18:21], v[198:201], v[214:217], v[38:41]
	v_mfma_f32_16x16x32_bf16 v[110:113], v[202:205], v[218:221], v[18:21]
	v_mfma_f32_16x16x32_bf16 v[18:21], v[206:209], v[214:217], v[42:45]
	v_mfma_f32_16x16x32_bf16 v[106:109], v[210:213], v[218:221], v[18:21]
	v_mfma_f32_16x16x32_bf16 v[18:21], v[198:201], v[222:225], v[46:49]
	v_mfma_f32_16x16x32_bf16 v[94:97], v[202:205], v[226:229], v[18:21]
	v_mfma_f32_16x16x32_bf16 v[18:21], v[206:209], v[222:225], v[50:53]
	v_mfma_f32_16x16x32_bf16 v[90:93], v[210:213], v[226:229], v[18:21]
	v_mfma_f32_16x16x32_bf16 v[18:21], v[198:201], v[230:233], v[54:57]
	v_mfma_f32_16x16x32_bf16 v[78:81], v[202:205], v[234:237], v[18:21]
	v_mfma_f32_16x16x32_bf16 v[18:21], v[206:209], v[230:233], v[58:61]
	v_mfma_f32_16x16x32_bf16 v[126:129], v[202:205], v[22:25], v[74:77]
	v_mfma_f32_16x16x32_bf16 v[74:77], v[210:213], v[234:237], v[18:21]
	s_setprio 0
	s_barrier
	s_add_i32 s50, s82, s43
	s_nop 3
	v_lshl_add_u64 v[18:19], v[238:239], 0, s[24:25]
	s_mov_b32 m0, s50
	s_add_i32 s51, s50, 0x2000
	ds_read_b128 v[42:45], v143 offset:49152
	ds_read_b128 v[46:49], v143 offset:50176
	ds_read_b128 v[214:217], v143 offset:51200
	ds_read_b128 v[218:221], v143 offset:52224
	ds_read_b128 v[222:225], v143 offset:53248
	ds_read_b128 v[226:229], v143 offset:54272
	ds_read_b128 v[230:233], v143 offset:55296
	ds_read_b128 v[234:237], v143 offset:56320
	global_load_lds_dwordx4 v[18:19], off
	v_lshl_add_u64 v[18:19], v[238:239], 0, s[26:27]
	s_mov_b32 m0, s51
	s_mov_b64 s[0:1], 0x80180
	s_add_i32 s33, s83, s43
	global_load_lds_dwordx4 v[18:19], off
	v_lshl_add_u64 v[18:19], v[238:239], 0, s[0:1]
	s_mov_b32 m0, s33
	s_mov_b64 s[0:1], 0xc0180
	s_add_i32 s56, s33, 0x2000
	global_load_lds_dwordx4 v[18:19], off
	v_lshl_add_u64 v[18:19], v[238:239], 0, s[0:1]
	s_mov_b32 m0, s56
	s_nop 0
	global_load_lds_dwordx4 v[18:19], off
	v_lshl_add_u64 v[18:19], v[140:141], 0, s[24:25]
	s_mov_b32 m0, s53
	s_nop 0
	global_load_lds_dwordx4 v[18:19], off
	v_lshl_add_u64 v[18:19], v[140:141], 0, s[26:27]
	s_mov_b32 m0, s54
	s_nop 0
	global_load_lds_dwordx4 v[18:19], off
	s_waitcnt vmcnt(8)
	s_waitcnt lgkmcnt(0)
	s_barrier
	s_waitcnt lgkmcnt(0)
	s_setprio 1
	v_mfma_f32_16x16x32_bf16 v[18:21], v[6:9], v[42:45], v[146:149]
	v_mfma_f32_16x16x32_bf16 v[54:57], v[26:29], v[46:49], v[18:21]
	v_mfma_f32_16x16x32_bf16 v[18:21], v[30:33], v[42:45], v[150:153]
	v_mfma_f32_16x16x32_bf16 v[50:53], v[62:65], v[46:49], v[18:21]
	v_mfma_f32_16x16x32_bf16 v[18:21], v[6:9], v[214:217], v[154:157]
	v_mfma_f32_16x16x32_bf16 v[38:41], v[26:29], v[218:221], v[18:21]
	v_mfma_f32_16x16x32_bf16 v[18:21], v[30:33], v[214:217], v[158:161]
	v_mfma_f32_16x16x32_bf16 v[34:37], v[62:65], v[218:221], v[18:21]
	v_mfma_f32_16x16x32_bf16 v[18:21], v[6:9], v[222:225], v[162:165]
	v_mfma_f32_16x16x32_bf16 v[2:5], v[6:9], v[230:233], v[2:5]
	v_mfma_f32_16x16x32_bf16 v[22:25], v[26:29], v[226:229], v[18:21]
	v_mfma_f32_16x16x32_bf16 v[18:21], v[30:33], v[222:225], v[166:169]
	v_mfma_f32_16x16x32_bf16 v[6:9], v[26:29], v[234:237], v[2:5]
	v_mfma_f32_16x16x32_bf16 v[2:5], v[30:33], v[230:233], v[10:13]
	v_mfma_f32_16x16x32_bf16 v[18:21], v[62:65], v[226:229], v[18:21]
	v_mfma_f32_16x16x32_bf16 v[2:5], v[62:65], v[234:237], v[2:5]
	v_mfma_f32_16x16x32_bf16 v[10:13], v[198:201], v[42:45], v[14:17]
	v_mfma_f32_16x16x32_bf16 v[62:65], v[202:205], v[46:49], v[10:13]
	v_mfma_f32_16x16x32_bf16 v[10:13], v[206:209], v[42:45], v[170:173]
	v_mfma_f32_16x16x32_bf16 v[58:61], v[210:213], v[46:49], v[10:13]
	v_mfma_f32_16x16x32_bf16 v[10:13], v[198:201], v[214:217], v[174:177]
	v_mfma_f32_16x16x32_bf16 v[46:49], v[202:205], v[218:221], v[10:13]
	v_mfma_f32_16x16x32_bf16 v[10:13], v[206:209], v[214:217], v[178:181]
	v_mfma_f32_16x16x32_bf16 v[42:45], v[210:213], v[218:221], v[10:13]
	v_mfma_f32_16x16x32_bf16 v[10:13], v[198:201], v[222:225], v[182:185]
	v_mfma_f32_16x16x32_bf16 v[30:33], v[202:205], v[226:229], v[10:13]
	v_mfma_f32_16x16x32_bf16 v[10:13], v[206:209], v[222:225], v[186:189]
	v_mfma_f32_16x16x32_bf16 v[26:29], v[210:213], v[226:229], v[10:13]
	v_mfma_f32_16x16x32_bf16 v[10:13], v[198:201], v[230:233], v[190:193]
	v_mfma_f32_16x16x32_bf16 v[14:17], v[202:205], v[234:237], v[10:13]
	v_mfma_f32_16x16x32_bf16 v[10:13], v[206:209], v[230:233], v[194:197]
	v_mfma_f32_16x16x32_bf16 v[10:13], v[210:213], v[234:237], v[10:13]
	s_setprio 0
	s_barrier
	s_add_u32 s74, s74, 0x80180
	s_addc_u32 s75, s75, 0
	s_add_u32 s57, s72, 0x200
	s_addc_u32 s72, s73, 0
	s_mov_b32 s73, 0
; #define PG8_WAIT_V(n) asm volatile("s_waitcnt vmcnt(" #n ")" ::: "memory")
; template <class Epi, class Sched, bool ALIGN_EPI = true, bool SP2 = true, bool FULLLINE = false, bool NOSTAGE = false, bool FP8 = false>
; __device__ __forceinline__ void gemm_phase(PG8_LAS unsigned char* lds, const Gemm g, const Sched& S, const Epi& E) {
;     ...
;         for (int t = 2; t < nt; t += 2) PG8_ITER(PG8_WAIT_V(8));
.LBB0_2287:
	ds_read_b128 v[146:149], v1
	ds_read_b128 v[150:153], v1 offset:1024
	ds_read_b128 v[154:157], v1 offset:2048
	ds_read_b128 v[158:161], v1 offset:3072
	ds_read_b128 v[162:165], v142
	ds_read_b128 v[166:169], v142 offset:1024
	ds_read_b128 v[170:173], v142 offset:2048
	ds_read_b128 v[174:177], v142 offset:3072
	s_add_u32 s0, s74, 0xfff80080
	s_addc_u32 s1, s75, -1
	s_cmp_eq_u32 s73, 28
	s_cselect_b32 s1, s41, s1
	s_cselect_b32 s0, s63, s0
	s_cselect_b32 s65, s87, s72
	s_cselect_b32 s64, s88, s57
	s_mov_b32 m0, s79
	v_lshl_add_u64 v[140:141], s[74:75], 0, v[134:135]
	ds_read_b128 v[178:181], v143
	ds_read_b128 v[182:185], v143 offset:1024
	ds_read_b128 v[186:189], v143 offset:2048
	ds_read_b128 v[190:193], v143 offset:3072
	ds_read_b128 v[194:197], v143 offset:4096
	ds_read_b128 v[198:201], v143 offset:5120
	ds_read_b128 v[202:205], v143 offset:6144
	ds_read_b128 v[206:209], v143 offset:7168
	global_load_lds_dwordx4 v[140:141], off
	v_lshl_add_u64 v[140:141], v[140:141], 0, s[28:29]
	s_mov_b32 m0, s80
	s_nop 0
	global_load_lds_dwordx4 v[140:141], off
	s_waitcnt vmcnt(8)
	s_waitcnt lgkmcnt(0)
	s_barrier
	s_waitcnt lgkmcnt(0)
	s_setprio 1
	v_mfma_f32_16x16x32_bf16 v[118:121], v[146:149], v[178:181], v[118:121]
	v_mfma_f32_16x16x32_bf16 v[114:117], v[154:157], v[178:181], v[114:117]
	v_mfma_f32_16x16x32_bf16 v[102:105], v[146:149], v[186:189], v[102:105]
	v_mfma_f32_16x16x32_bf16 v[98:101], v[154:157], v[186:189], v[98:101]
	v_mfma_f32_16x16x32_bf16 v[86:89], v[146:149], v[194:197], v[86:89]
	v_mfma_f32_16x16x32_bf16 v[82:85], v[154:157], v[194:197], v[82:85]
	v_mfma_f32_16x16x32_bf16 v[70:73], v[146:149], v[202:205], v[70:73]
	v_mfma_f32_16x16x32_bf16 v[66:69], v[154:157], v[202:205], v[66:69]
	v_mfma_f32_16x16x32_bf16 v[118:121], v[150:153], v[182:185], v[118:121]
	v_mfma_f32_16x16x32_bf16 v[114:117], v[158:161], v[182:185], v[114:117]
	v_mfma_f32_16x16x32_bf16 v[102:105], v[150:153], v[190:193], v[102:105]
	v_mfma_f32_16x16x32_bf16 v[98:101], v[158:161], v[190:193], v[98:101]
	v_mfma_f32_16x16x32_bf16 v[86:89], v[150:153], v[198:201], v[86:89]
	v_mfma_f32_16x16x32_bf16 v[82:85], v[158:161], v[198:201], v[82:85]
	v_mfma_f32_16x16x32_bf16 v[70:73], v[150:153], v[206:209], v[70:73]
	v_mfma_f32_16x16x32_bf16 v[66:69], v[158:161], v[206:209], v[66:69]
	v_mfma_f32_16x16x32_bf16 v[126:129], v[162:165], v[178:181], v[126:129]
	v_mfma_f32_16x16x32_bf16 v[122:125], v[170:173], v[178:181], v[122:125]
	v_mfma_f32_16x16x32_bf16 v[110:113], v[162:165], v[186:189], v[110:113]
	v_mfma_f32_16x16x32_bf16 v[106:109], v[170:173], v[186:189], v[106:109]
	v_mfma_f32_16x16x32_bf16 v[94:97], v[162:165], v[194:197], v[94:97]
	v_mfma_f32_16x16x32_bf16 v[90:93], v[170:173], v[194:197], v[90:93]
	v_mfma_f32_16x16x32_bf16 v[78:81], v[162:165], v[202:205], v[78:81]
	v_mfma_f32_16x16x32_bf16 v[74:77], v[170:173], v[202:205], v[74:77]
	v_mfma_f32_16x16x32_bf16 v[126:129], v[166:169], v[182:185], v[126:129]
	v_mfma_f32_16x16x32_bf16 v[122:125], v[174:177], v[182:185], v[122:125]
	v_mfma_f32_16x16x32_bf16 v[110:113], v[166:169], v[190:193], v[110:113]
	v_mfma_f32_16x16x32_bf16 v[106:109], v[174:177], v[190:193], v[106:109]
	v_mfma_f32_16x16x32_bf16 v[94:97], v[166:169], v[198:201], v[94:97]
	v_mfma_f32_16x16x32_bf16 v[90:93], v[174:177], v[198:201], v[90:93]
	v_mfma_f32_16x16x32_bf16 v[78:81], v[166:169], v[206:209], v[78:81]
	v_mfma_f32_16x16x32_bf16 v[74:77], v[174:177], v[206:209], v[74:77]
	s_setprio 0
	s_barrier
	s_mov_b32 m0, s81
	v_lshl_add_u64 v[140:141], s[64:65], 0, v[130:131]
	ds_read_b128 v[178:181], v143 offset:16384
	ds_read_b128 v[182:185], v143 offset:17408
	ds_read_b128 v[186:189], v143 offset:18432
	ds_read_b128 v[190:193], v143 offset:19456
	ds_read_b128 v[194:197], v143 offset:20480
	ds_read_b128 v[198:201], v143 offset:21504
	ds_read_b128 v[202:205], v143 offset:22528
	ds_read_b128 v[206:209], v143 offset:23552
	global_load_lds_dwordx4 v[140:141], off
	v_lshl_add_u64 v[210:211], v[140:141], 0, s[28:29]
	s_mov_b32 m0, s89
	s_nop 0
	global_load_lds_dwordx4 v[210:211], off
	v_lshl_add_u64 v[210:211], v[140:141], 0, s[30:31]
	s_mov_b32 m0, s90
	s_nop 0
	global_load_lds_dwordx4 v[210:211], off
	v_lshl_add_u64 v[210:211], v[140:141], 0, s[34:35]
	s_mov_b32 m0, s91
	s_nop 0
	global_load_lds_dwordx4 v[210:211], off
	v_lshl_add_u64 v[210:211], s[0:1], 0, v[132:133]
	s_mov_b32 m0, s45
	v_lshl_add_u64 v[212:213], v[210:211], 0, s[28:29]
	global_load_lds_dwordx4 v[210:211], off
	s_mov_b32 m0, s46
	s_nop 0
	global_load_lds_dwordx4 v[212:213], off
	s_waitcnt vmcnt(8)
	s_waitcnt lgkmcnt(0)
	s_barrier
; #define PG8_WAIT_V(n) asm volatile("s_waitcnt vmcnt(" #n ")" ::: "memory")
; template <class Epi, class Sched, bool ALIGN_EPI = true, bool SP2 = true, bool FULLLINE = false, bool NOSTAGE = false, bool FP8 = false>
; __device__ __forceinline__ void gemm_phase(PG8_LAS unsigned char* lds, const Gemm g, const Sched& S, const Epi& E) {
;     ...
;         for (int t = 2; t < nt; t += 2) PG8_ITER(PG8_WAIT_V(8));
	s_waitcnt lgkmcnt(0)
	s_setprio 1
	v_mfma_f32_16x16x32_bf16 v[54:57], v[146:149], v[178:181], v[54:57]
	v_mfma_f32_16x16x32_bf16 v[50:53], v[154:157], v[178:181], v[50:53]
	v_mfma_f32_16x16x32_bf16 v[38:41], v[146:149], v[186:189], v[38:41]
	v_mfma_f32_16x16x32_bf16 v[34:37], v[154:157], v[186:189], v[34:37]
	v_mfma_f32_16x16x32_bf16 v[22:25], v[146:149], v[194:197], v[22:25]
	v_mfma_f32_16x16x32_bf16 v[18:21], v[154:157], v[194:197], v[18:21]
	v_mfma_f32_16x16x32_bf16 v[6:9], v[146:149], v[202:205], v[6:9]
	v_mfma_f32_16x16x32_bf16 v[2:5], v[154:157], v[202:205], v[2:5]
	v_mfma_f32_16x16x32_bf16 v[54:57], v[150:153], v[182:185], v[54:57]
	v_mfma_f32_16x16x32_bf16 v[50:53], v[158:161], v[182:185], v[50:53]
	v_mfma_f32_16x16x32_bf16 v[38:41], v[150:153], v[190:193], v[38:41]
	v_mfma_f32_16x16x32_bf16 v[34:37], v[158:161], v[190:193], v[34:37]
	v_mfma_f32_16x16x32_bf16 v[22:25], v[150:153], v[198:201], v[22:25]
	v_mfma_f32_16x16x32_bf16 v[18:21], v[158:161], v[198:201], v[18:21]
	v_mfma_f32_16x16x32_bf16 v[6:9], v[150:153], v[206:209], v[6:9]
	v_mfma_f32_16x16x32_bf16 v[2:5], v[158:161], v[206:209], v[2:5]
	v_mfma_f32_16x16x32_bf16 v[62:65], v[162:165], v[178:181], v[62:65]
	v_mfma_f32_16x16x32_bf16 v[58:61], v[170:173], v[178:181], v[58:61]
	v_mfma_f32_16x16x32_bf16 v[46:49], v[162:165], v[186:189], v[46:49]
	v_mfma_f32_16x16x32_bf16 v[42:45], v[170:173], v[186:189], v[42:45]
	v_mfma_f32_16x16x32_bf16 v[30:33], v[162:165], v[194:197], v[30:33]
	v_mfma_f32_16x16x32_bf16 v[26:29], v[170:173], v[194:197], v[26:29]
	v_mfma_f32_16x16x32_bf16 v[14:17], v[162:165], v[202:205], v[14:17]
	v_mfma_f32_16x16x32_bf16 v[10:13], v[170:173], v[202:205], v[10:13]
	v_mfma_f32_16x16x32_bf16 v[62:65], v[166:169], v[182:185], v[62:65]
	v_mfma_f32_16x16x32_bf16 v[58:61], v[174:177], v[182:185], v[58:61]
	v_mfma_f32_16x16x32_bf16 v[46:49], v[166:169], v[190:193], v[46:49]
	v_mfma_f32_16x16x32_bf16 v[42:45], v[174:177], v[190:193], v[42:45]
	v_mfma_f32_16x16x32_bf16 v[30:33], v[166:169], v[198:201], v[30:33]
	v_mfma_f32_16x16x32_bf16 v[26:29], v[174:177], v[198:201], v[26:29]
	v_mfma_f32_16x16x32_bf16 v[14:17], v[166:169], v[206:209], v[14:17]
	v_mfma_f32_16x16x32_bf16 v[10:13], v[174:177], v[206:209], v[10:13]
	s_setprio 0
	s_barrier
	ds_read_b128 v[146:149], v144
	ds_read_b128 v[150:153], v144 offset:1024
	ds_read_b128 v[154:157], v144 offset:2048
	ds_read_b128 v[158:161], v144 offset:3072
	ds_read_b128 v[162:165], v145
	ds_read_b128 v[166:169], v145 offset:1024
	ds_read_b128 v[170:173], v145 offset:2048
	ds_read_b128 v[174:177], v145 offset:3072
	s_mov_b32 m0, s47
	v_lshl_add_u64 v[212:213], v[210:211], 0, s[30:31]
	ds_read_b128 v[178:181], v143 offset:32768
	ds_read_b128 v[182:185], v143 offset:33792
	ds_read_b128 v[186:189], v143 offset:34816
	ds_read_b128 v[190:193], v143 offset:35840
	ds_read_b128 v[194:197], v143 offset:36864
	ds_read_b128 v[198:201], v143 offset:37888
	ds_read_b128 v[202:205], v143 offset:38912
	ds_read_b128 v[206:209], v143 offset:39936
	global_load_lds_dwordx4 v[212:213], off
	v_lshl_add_u64 v[212:213], v[210:211], 0, s[34:35]
	s_mov_b32 m0, s52
	s_nop 0
	global_load_lds_dwordx4 v[212:213], off
	s_waitcnt vmcnt(8)
	s_waitcnt lgkmcnt(0)
	s_barrier
	s_waitcnt lgkmcnt(0)
	s_setprio 1
	v_mfma_f32_16x16x32_bf16 v[118:121], v[146:149], v[178:181], v[118:121]
	v_mfma_f32_16x16x32_bf16 v[114:117], v[154:157], v[178:181], v[114:117]
	v_mfma_f32_16x16x32_bf16 v[102:105], v[146:149], v[186:189], v[102:105]
	v_mfma_f32_16x16x32_bf16 v[98:101], v[154:157], v[186:189], v[98:101]
	v_mfma_f32_16x16x32_bf16 v[86:89], v[146:149], v[194:197], v[86:89]
	v_mfma_f32_16x16x32_bf16 v[82:85], v[154:157], v[194:197], v[82:85]
	v_mfma_f32_16x16x32_bf16 v[70:73], v[146:149], v[202:205], v[70:73]
	v_mfma_f32_16x16x32_bf16 v[66:69], v[154:157], v[202:205], v[66:69]
	v_mfma_f32_16x16x32_bf16 v[118:121], v[150:153], v[182:185], v[118:121]
	v_mfma_f32_16x16x32_bf16 v[114:117], v[158:161], v[182:185], v[114:117]
	v_mfma_f32_16x16x32_bf16 v[102:105], v[150:153], v[190:193], v[102:105]
	v_mfma_f32_16x16x32_bf16 v[98:101], v[158:161], v[190:193], v[98:101]
	v_mfma_f32_16x16x32_bf16 v[86:89], v[150:153], v[198:201], v[86:89]
	v_mfma_f32_16x16x32_bf16 v[82:85], v[158:161], v[198:201], v[82:85]
	v_mfma_f32_16x16x32_bf16 v[70:73], v[150:153], v[206:209], v[70:73]
	v_mfma_f32_16x16x32_bf16 v[66:69], v[158:161], v[206:209], v[66:69]
	v_mfma_f32_16x16x32_bf16 v[126:129], v[162:165], v[178:181], v[126:129]
	v_mfma_f32_16x16x32_bf16 v[122:125], v[170:173], v[178:181], v[122:125]
	v_mfma_f32_16x16x32_bf16 v[110:113], v[162:165], v[186:189], v[110:113]
	v_mfma_f32_16x16x32_bf16 v[106:109], v[170:173], v[186:189], v[106:109]
	v_mfma_f32_16x16x32_bf16 v[94:97], v[162:165], v[194:197], v[94:97]
	v_mfma_f32_16x16x32_bf16 v[90:93], v[170:173], v[194:197], v[90:93]
	v_mfma_f32_16x16x32_bf16 v[78:81], v[162:165], v[202:205], v[78:81]
	v_mfma_f32_16x16x32_bf16 v[74:77], v[170:173], v[202:205], v[74:77]
	v_mfma_f32_16x16x32_bf16 v[126:129], v[166:169], v[182:185], v[126:129]
	v_mfma_f32_16x16x32_bf16 v[122:125], v[174:177], v[182:185], v[122:125]
	v_mfma_f32_16x16x32_bf16 v[110:113], v[166:169], v[190:193], v[110:113]
	v_mfma_f32_16x16x32_bf16 v[106:109], v[174:177], v[190:193], v[106:109]
	v_mfma_f32_16x16x32_bf16 v[94:97], v[166:169], v[198:201], v[94:97]
	v_mfma_f32_16x16x32_bf16 v[90:93], v[174:177], v[198:201], v[90:93]
	v_mfma_f32_16x16x32_bf16 v[78:81], v[166:169], v[206:209], v[78:81]
	v_mfma_f32_16x16x32_bf16 v[74:77], v[174:177], v[206:209], v[74:77]
	s_setprio 0
	s_barrier
; #define PG8_WAIT_V(n) asm volatile("s_waitcnt vmcnt(" #n ")" ::: "memory")
; #define PG8_BAR __builtin_amdgcn_s_barrier()
; template <class Epi, class Sched, bool ALIGN_EPI = true, bool SP2 = true, bool FULLLINE = false, bool NOSTAGE = false, bool FP8 = false>
; __device__ __forceinline__ void gemm_phase(PG8_LAS unsigned char* lds, const Gemm g, const Sched& S, const Epi& E) {
;     ...
;         for (int t = 2; t < nt; t += 2) PG8_ITER(PG8_WAIT_V(8));
;     ...
;         if constexpr (ALIGN_EPI) { if (wr == 0) PG8_BAR; }
	s_mov_b32 m0, s50
	v_lshl_add_u64 v[212:213], v[140:141], 0, s[36:37]
	ds_read_b128 v[178:181], v143 offset:49152
	ds_read_b128 v[182:185], v143 offset:50176
	ds_read_b128 v[186:189], v143 offset:51200
	ds_read_b128 v[190:193], v143 offset:52224
	ds_read_b128 v[194:197], v143 offset:53248
	ds_read_b128 v[198:201], v143 offset:54272
	ds_read_b128 v[202:205], v143 offset:55296
	ds_read_b128 v[206:209], v143 offset:56320
	global_load_lds_dwordx4 v[212:213], off
	v_lshl_add_u64 v[212:213], v[140:141], 0, s[38:39]
	s_mov_b32 m0, s51
	s_nop 0
	global_load_lds_dwordx4 v[212:213], off
	v_lshl_add_u64 v[212:213], v[140:141], 0, s[12:13]
	s_mov_b32 m0, s33
	v_lshl_add_u64 v[140:141], v[140:141], 0, s[14:15]
	global_load_lds_dwordx4 v[212:213], off
	s_mov_b32 m0, s56
	s_nop 0
	global_load_lds_dwordx4 v[140:141], off
	v_lshl_add_u64 v[140:141], v[210:211], 0, s[36:37]
	s_mov_b32 m0, s53
	s_nop 0
	global_load_lds_dwordx4 v[140:141], off
	v_lshl_add_u64 v[140:141], v[210:211], 0, s[38:39]
	s_mov_b32 m0, s54
	s_nop 0
	global_load_lds_dwordx4 v[140:141], off
	s_waitcnt vmcnt(8)
	s_waitcnt lgkmcnt(0)
	s_barrier
	s_waitcnt lgkmcnt(0)
	s_setprio 1
	v_mfma_f32_16x16x32_bf16 v[54:57], v[146:149], v[178:181], v[54:57]
	v_mfma_f32_16x16x32_bf16 v[50:53], v[154:157], v[178:181], v[50:53]
	v_mfma_f32_16x16x32_bf16 v[38:41], v[146:149], v[186:189], v[38:41]
	v_mfma_f32_16x16x32_bf16 v[34:37], v[154:157], v[186:189], v[34:37]
	v_mfma_f32_16x16x32_bf16 v[22:25], v[146:149], v[194:197], v[22:25]
	v_mfma_f32_16x16x32_bf16 v[18:21], v[154:157], v[194:197], v[18:21]
	v_mfma_f32_16x16x32_bf16 v[6:9], v[146:149], v[202:205], v[6:9]
	v_mfma_f32_16x16x32_bf16 v[2:5], v[154:157], v[202:205], v[2:5]
	v_mfma_f32_16x16x32_bf16 v[54:57], v[150:153], v[182:185], v[54:57]
	v_mfma_f32_16x16x32_bf16 v[50:53], v[158:161], v[182:185], v[50:53]
	v_mfma_f32_16x16x32_bf16 v[38:41], v[150:153], v[190:193], v[38:41]
	v_mfma_f32_16x16x32_bf16 v[34:37], v[158:161], v[190:193], v[34:37]
	v_mfma_f32_16x16x32_bf16 v[22:25], v[150:153], v[198:201], v[22:25]
	v_mfma_f32_16x16x32_bf16 v[18:21], v[158:161], v[198:201], v[18:21]
	v_mfma_f32_16x16x32_bf16 v[6:9], v[150:153], v[206:209], v[6:9]
	v_mfma_f32_16x16x32_bf16 v[2:5], v[158:161], v[206:209], v[2:5]
	v_mfma_f32_16x16x32_bf16 v[62:65], v[162:165], v[178:181], v[62:65]
	v_mfma_f32_16x16x32_bf16 v[58:61], v[170:173], v[178:181], v[58:61]
	v_mfma_f32_16x16x32_bf16 v[46:49], v[162:165], v[186:189], v[46:49]
	v_mfma_f32_16x16x32_bf16 v[42:45], v[170:173], v[186:189], v[42:45]
	v_mfma_f32_16x16x32_bf16 v[30:33], v[162:165], v[194:197], v[30:33]
	v_mfma_f32_16x16x32_bf16 v[26:29], v[170:173], v[194:197], v[26:29]
	v_mfma_f32_16x16x32_bf16 v[14:17], v[162:165], v[202:205], v[14:17]
	v_mfma_f32_16x16x32_bf16 v[10:13], v[170:173], v[202:205], v[10:13]
	v_mfma_f32_16x16x32_bf16 v[62:65], v[166:169], v[182:185], v[62:65]
	v_mfma_f32_16x16x32_bf16 v[58:61], v[174:177], v[182:185], v[58:61]
	v_mfma_f32_16x16x32_bf16 v[46:49], v[166:169], v[190:193], v[46:49]
	v_mfma_f32_16x16x32_bf16 v[42:45], v[174:177], v[190:193], v[42:45]
	v_mfma_f32_16x16x32_bf16 v[30:33], v[166:169], v[198:201], v[30:33]
	v_mfma_f32_16x16x32_bf16 v[26:29], v[174:177], v[198:201], v[26:29]
	v_mfma_f32_16x16x32_bf16 v[14:17], v[166:169], v[206:209], v[14:17]
	v_mfma_f32_16x16x32_bf16 v[10:13], v[174:177], v[206:209], v[10:13]
	s_setprio 0
	s_barrier
	s_add_i32 s73, s73, 2
	s_add_u32 s74, s74, 0x100
	s_addc_u32 s75, s75, 0
	s_add_u32 s57, s57, 0x100
	s_addc_u32 s72, s72, 0
	s_cmp_gt_u32 s73, 29
	s_cbranch_scc0 .LBB0_2287
	s_and_b64 vcc, exec, s[10:11]
	s_cbranch_vccz .LBB0_2290
	s_barrier

; #define PG8_STAGE(bufoff, gbase, voff) do { if constexpr (!NOSTAGE) _Pragma("unroll") for (int _i = 0; _i < 2; ++_i) \
;         __builtin_amdgcn_global_load_lds((const unsigned*)((const char*)(gbase) + (size_t)_i * pstep##voff + v##voff), (PG8_LAS unsigned*)(lds + (bufoff) + ldsw + _i * 8192), 16, 0, 0); } while (0)
; #define PG8_WAIT_V(n) asm volatile("s_waitcnt vmcnt(" #n ")" ::: "memory")
; #define PG8_BAR __builtin_amdgcn_s_barrier()
; template <class Epi, class Sched, bool ALIGN_EPI = true, bool SP2 = true, bool FULLLINE = false, bool NOSTAGE = false, bool FP8 = false>
; __device__ __forceinline__ void gemm_phase(PG8_LAS unsigned char* lds, const Gemm g, const Sched& S, const Epi& E) {
;     const int tid = threadIdx.x, wid = __builtin_amdgcn_readfirstlane(tid >> 6), lane = tid & 63, wr = wid >> 2, wc = wid & 3, fr = lane & 15, fq = lane >> 4;
;     const int K = g.K, nt = K / BK;
;     unsigned voffA_, voffB_;
;     { int R, C; stage_rc(tid * 16, R, C); const int Rb = Epi::PERM ? ((R & ~31) + perm32(R & 31)) : R;
;       voffA_ = (unsigned)(R * g.lda + C) * 2u; voffB_ = (unsigned)(Rb * g.ldb + C) * 2u; }
;     const unsigned voffA = voffA_, voffB = voffB_;
;     const size_t pstepoffA = (size_t)64 * g.lda * 2, pstepoffB = (size_t)64 * g.ldb * 2;
;     const size_t kstep = (size_t)(BK * 2);
;     const size_t hstepA = (size_t)HALF * g.lda * 2, hstepB = (size_t)HALF * g.ldb * 2;
;     const size_t tstepA = 2 * hstepA, tstepB = 2 * hstepB;
;     const unsigned ldsw = (unsigned)wid * 1024u;
;     const int aoff = lds_byte(wr * 64 + fr, fq * 8), boff = lds_byte(wc * 32 + fr, fq * 8);
;     ...
;     if (wr == 1) PG8_BAR;
;     PG8_WAIT_V(0); PG8_BAR;
;     PG8_BAR;
;     } else {
;     PG8_STAGE(PG8_SB(0, 0), cB, offB); PG8_STAGE(PG8_SA(0, 0), cA, offA); PG8_STAGE(PG8_SB(0, 1), cB + hstepB, offB); PG8_STAGE(PG8_SA(0, 1), cA + hstepA, offA);
;     if (wr == 1) PG8_BAR;
;     PG8_WAIT_V(4); PG8_BAR;
;     PG8_STAGE(PG8_SB(1, 0), cB + kstep, offB); PG8_STAGE(PG8_SA(1, 0), cA + kstep, offA); PG8_STAGE(PG8_SB(1, 1), cB + hstepB + kstep, offB);
;     PG8_WAIT_V(6); PG8_BAR;
;     }
;     if (wr == 1) __builtin_amdgcn_s_setprio(1);
.LBB0_2374:
	s_waitcnt vmcnt(0)
	v_cndmask_b32_e64 v4, 0, 1, s[8:9]
	s_lshr_b32 s13, s6, 3
	v_cmp_ne_u32_e64 s[6:7], 1, v4
	s_andn2_b64 vcc, exec, s[8:9]
	s_barrier
	s_barrier
	s_cbranch_vccnz .LBB0_2376
.LBB0_2376:
	v_and_b32_e32 v4, 48, v0
	v_lshlrev_b32_e32 v5, 6, v0
	s_movk_i32 s1, 0x3c0
	s_add_u32 s55, s48, 0x1ca000
	v_and_or_b32 v4, v5, s1, v4
	v_lshlrev_b32_e32 v5, 2, v0
	s_addc_u32 s70, s49, 0
	s_lshl_b32 s0, s12, 13
	v_and_b32_e32 v5, 32, v5
	v_bitop3_b32 v6, v4, s0, v5 bitop3:0xde
	s_lshl_b32 s0, s11, 5
	s_and_b32 s72, s0, 0x60
	s_lshl_b32 s71, s12, 6
	s_lshl_b32 s0, s72, 7
	s_cmpk_lt_u32 s10, 0x100
	v_add_u16_e32 v1, v1, v2
	s_sext_i32_i8 s82, s13
	v_bitop3_b32 v4, s0, v4, v5 bitop3:0xf6
	s_cselect_b64 s[12:13], -1, 0
	v_lshrrev_b16_e32 v1, 1, v1
	s_add_i32 s75, 0, 0x10000
	s_add_i32 s76, 0, 0x14000
	s_add_i32 s77, 0, 0x18000
	s_add_i32 s78, 0, 0x1c000
	s_ashr_i32 s73, s86, 31
	v_add_lshl_u32 v174, v3, v1, 1
	v_mov_b32_e32 v175, 0
	s_mov_b32 s74, 0
	v_mov_b64_e32 v[176:177], 0x200
	v_mov_b64_e32 v[178:179], 0x1ff
	v_add_u32_e32 v1, s75, v4
	v_add_u32_e32 v192, s76, v4
	v_add_u32_e32 v193, 0, v6
	s_mov_b64 s[14:15], 0x160080
	s_mov_b64 s[16:17], 0x210080
	s_mov_b64 s[18:19], 0x100
	s_mov_b64 s[20:21], 0xb0100
	s_mov_b64 s[22:23], 0x160100
	s_mov_b64 s[24:25], 0x210100
	v_add_u32_e32 v194, s77, v4
	v_add_u32_e32 v195, s78, v4
	s_mov_b64 s[26:27], 0x180
	s_mov_b64 s[28:29], 0xb0180
	s_mov_b64 s[30:31], 0xb0000
	s_mov_b64 s[34:35], 0x160000
	s_mov_b64 s[36:37], 0x210000
	s_mov_b64 s[38:39], 0x80
	s_mov_b64 s[40:41], 0xb0080
	s_branch .LBB0_2379

; #define PG8_WAIT_V(n) asm volatile("s_waitcnt vmcnt(" #n ")" ::: "memory")
; template <class Epi, class Sched, bool ALIGN_EPI = true, bool SP2 = true, bool FULLLINE = false, bool NOSTAGE = false, bool FP8 = false>
; __device__ __forceinline__ void gemm_phase(PG8_LAS unsigned char* lds, const Gemm g, const Sched& S, const Epi& E) {
;     ...
;         static_assert(SP2, "only the SP2 loop is kept");
;         { const int t = 0; if constexpr (Epi::NST == 16) PG8_ITER(PG8_WAIT_V(24)); else if constexpr (Epi::NST == 8) PG8_ITER(PG8_WAIT_V(16)); else PG8_ITER(PG8_WAIT_V(8)); }
.LBB0_2389:
	ds_read_b128 v[2:5], v1
	ds_read_b128 v[6:9], v1 offset:1024
	ds_read_b128 v[10:13], v1 offset:2048
	ds_read_b128 v[14:17], v1 offset:3072
	ds_read_b128 v[18:21], v192
	ds_read_b128 v[22:25], v192 offset:1024
	ds_read_b128 v[26:29], v192 offset:2048
	ds_read_b128 v[30:33], v192 offset:3072
	v_lshl_add_u64 v[244:245], s[66:67], 0, v[170:171]
	s_add_i32 s83, s45, 0xc000
	v_lshl_add_u64 v[66:67], v[244:245], 0, s[14:15]
	s_mov_b32 m0, s83
	s_add_i32 s84, s45, 0xe000
	ds_read_b128 v[34:37], v193
	ds_read_b128 v[38:41], v193 offset:1024
	ds_read_b128 v[42:45], v193 offset:2048
	ds_read_b128 v[46:49], v193 offset:3072
	ds_read_b128 v[50:53], v193 offset:4096
	ds_read_b128 v[54:57], v193 offset:5120
	ds_read_b128 v[58:61], v193 offset:6144
	ds_read_b128 v[62:65], v193 offset:7168
	global_load_lds_dwordx4 v[66:67], off
	v_lshl_add_u64 v[66:67], v[244:245], 0, s[16:17]
	s_mov_b32 m0, s84
	s_nop 0
	global_load_lds_dwordx4 v[66:67], off
	s_waitcnt vmcnt(24)
	s_waitcnt lgkmcnt(0)
	s_barrier
	s_waitcnt lgkmcnt(0)
	s_setprio 1
	v_mfma_f32_16x16x32_bf16 v[66:69], v[2:5], v[34:37], 0
	v_mfma_f32_16x16x32_bf16 v[70:73], v[10:13], v[34:37], 0
	v_mfma_f32_16x16x32_bf16 v[74:77], v[2:5], v[42:45], 0
	v_mfma_f32_16x16x32_bf16 v[78:81], v[10:13], v[42:45], 0
	v_mfma_f32_16x16x32_bf16 v[90:93], v[2:5], v[58:61], 0
	v_mfma_f32_16x16x32_bf16 v[94:97], v[10:13], v[58:61], 0
	v_mfma_f32_16x16x32_bf16 v[66:69], v[6:9], v[38:41], v[66:69]
	v_mfma_f32_16x16x32_bf16 v[70:73], v[14:17], v[38:41], v[70:73]
	v_mfma_f32_16x16x32_bf16 v[74:77], v[6:9], v[46:49], v[74:77]
	v_mfma_f32_16x16x32_bf16 v[78:81], v[14:17], v[46:49], v[78:81]
	v_mfma_f32_16x16x32_bf16 v[82:85], v[2:5], v[50:53], 0
	v_mfma_f32_16x16x32_bf16 v[86:89], v[10:13], v[50:53], 0
	v_mfma_f32_16x16x32_bf16 v[90:93], v[6:9], v[62:65], v[90:93]
	v_mfma_f32_16x16x32_bf16 v[94:97], v[14:17], v[62:65], v[94:97]
	v_mfma_f32_16x16x32_bf16 v[82:85], v[6:9], v[54:57], v[82:85]
	v_mfma_f32_16x16x32_bf16 v[86:89], v[14:17], v[54:57], v[86:89]
	v_mfma_f32_16x16x32_bf16 v[98:101], v[18:21], v[34:37], 0
	v_mfma_f32_16x16x32_bf16 v[34:37], v[26:29], v[34:37], 0
	v_mfma_f32_16x16x32_bf16 v[98:101], v[22:25], v[38:41], v[98:101]
	v_mfma_f32_16x16x32_bf16 v[34:37], v[30:33], v[38:41], v[34:37]
	v_mfma_f32_16x16x32_bf16 v[38:41], v[18:21], v[42:45], 0
	v_mfma_f32_16x16x32_bf16 v[42:45], v[26:29], v[42:45], 0
	v_mfma_f32_16x16x32_bf16 v[38:41], v[22:25], v[46:49], v[38:41]
	v_mfma_f32_16x16x32_bf16 v[42:45], v[30:33], v[46:49], v[42:45]
	v_mfma_f32_16x16x32_bf16 v[46:49], v[18:21], v[50:53], 0
	v_mfma_f32_16x16x32_bf16 v[50:53], v[26:29], v[50:53], 0
	v_mfma_f32_16x16x32_bf16 v[46:49], v[22:25], v[54:57], v[46:49]
	v_mfma_f32_16x16x32_bf16 v[50:53], v[30:33], v[54:57], v[50:53]
	v_mfma_f32_16x16x32_bf16 v[54:57], v[18:21], v[58:61], 0
	v_mfma_f32_16x16x32_bf16 v[58:61], v[26:29], v[58:61], 0
	v_mfma_f32_16x16x32_bf16 v[54:57], v[22:25], v[62:65], v[54:57]
	v_mfma_f32_16x16x32_bf16 v[58:61], v[30:33], v[62:65], v[58:61]
	s_setprio 0
	s_barrier
	v_lshl_add_u64 v[246:247], s[68:69], 0, v[172:173]
	s_add_i32 s85, s75, s44
	v_lshl_add_u64 v[130:131], v[246:247], 0, s[18:19]
	s_mov_b32 m0, s85
	s_add_i32 s87, s85, 0x2000
	ds_read_b128 v[62:65], v193 offset:16384
	ds_read_b128 v[102:105], v193 offset:17408
	ds_read_b128 v[106:109], v193 offset:18432
	ds_read_b128 v[110:113], v193 offset:19456
	ds_read_b128 v[114:117], v193 offset:20480
	ds_read_b128 v[118:121], v193 offset:21504
	ds_read_b128 v[122:125], v193 offset:22528
	ds_read_b128 v[126:129], v193 offset:23552
	global_load_lds_dwordx4 v[130:131], off
	v_lshl_add_u64 v[130:131], v[246:247], 0, s[20:21]
	s_mov_b32 m0, s87
	s_add_i32 s88, s76, s44
	global_load_lds_dwordx4 v[130:131], off
	v_lshl_add_u64 v[130:131], v[246:247], 0, s[22:23]
	s_mov_b32 m0, s88
	s_add_i32 s89, s88, 0x2000
	global_load_lds_dwordx4 v[130:131], off
	v_lshl_add_u64 v[130:131], v[246:247], 0, s[24:25]
	s_mov_b32 m0, s89
	s_nop 0
	global_load_lds_dwordx4 v[130:131], off
	v_lshl_add_u64 v[130:131], v[244:245], 0, s[18:19]
	s_mov_b32 m0, s45
	s_nop 0
	global_load_lds_dwordx4 v[130:131], off
	v_lshl_add_u64 v[130:131], v[244:245], 0, s[20:21]
	s_mov_b32 m0, s46
	s_nop 0
	global_load_lds_dwordx4 v[130:131], off
	s_waitcnt vmcnt(24)
	s_waitcnt lgkmcnt(0)
	s_barrier
	s_waitcnt lgkmcnt(0)
	s_setprio 1
	v_mfma_f32_16x16x32_bf16 v[130:133], v[2:5], v[62:65], 0
	v_mfma_f32_16x16x32_bf16 v[146:149], v[6:9], v[102:105], v[130:133]
	v_mfma_f32_16x16x32_bf16 v[130:133], v[10:13], v[62:65], 0
	v_mfma_f32_16x16x32_bf16 v[150:153], v[14:17], v[102:105], v[130:133]
	v_mfma_f32_16x16x32_bf16 v[130:133], v[2:5], v[106:109], 0
	v_mfma_f32_16x16x32_bf16 v[154:157], v[6:9], v[110:113], v[130:133]
	v_mfma_f32_16x16x32_bf16 v[130:133], v[10:13], v[106:109], 0
	v_mfma_f32_16x16x32_bf16 v[158:161], v[14:17], v[110:113], v[130:133]
	v_mfma_f32_16x16x32_bf16 v[130:133], v[2:5], v[114:117], 0
	v_mfma_f32_16x16x32_bf16 v[2:5], v[2:5], v[122:125], 0
	v_mfma_f32_16x16x32_bf16 v[162:165], v[6:9], v[118:121], v[130:133]
	v_mfma_f32_16x16x32_bf16 v[2:5], v[6:9], v[126:129], v[2:5]
	v_mfma_f32_16x16x32_bf16 v[6:9], v[10:13], v[122:125], 0
	v_mfma_f32_16x16x32_bf16 v[130:133], v[10:13], v[114:117], 0
	v_mfma_f32_16x16x32_bf16 v[6:9], v[14:17], v[126:129], v[6:9]
	v_mfma_f32_16x16x32_bf16 v[166:169], v[14:17], v[118:121], v[130:133]
	v_mfma_f32_16x16x32_bf16 v[10:13], v[18:21], v[62:65], 0
	v_mfma_f32_16x16x32_bf16 v[180:183], v[22:25], v[102:105], v[10:13]
	v_mfma_f32_16x16x32_bf16 v[10:13], v[26:29], v[62:65], 0
	v_mfma_f32_16x16x32_bf16 v[102:105], v[30:33], v[102:105], v[10:13]
	v_mfma_f32_16x16x32_bf16 v[10:13], v[18:21], v[106:109], 0
	v_mfma_f32_16x16x32_bf16 v[184:187], v[22:25], v[110:113], v[10:13]
	v_mfma_f32_16x16x32_bf16 v[10:13], v[26:29], v[106:109], 0
	v_mfma_f32_16x16x32_bf16 v[188:191], v[30:33], v[110:113], v[10:13]
	v_mfma_f32_16x16x32_bf16 v[10:13], v[18:21], v[114:117], 0
	v_mfma_f32_16x16x32_bf16 v[196:199], v[22:25], v[118:121], v[10:13]
	v_mfma_f32_16x16x32_bf16 v[10:13], v[26:29], v[114:117], 0
	v_mfma_f32_16x16x32_bf16 v[200:203], v[30:33], v[118:121], v[10:13]
	v_mfma_f32_16x16x32_bf16 v[10:13], v[18:21], v[122:125], 0
	v_mfma_f32_16x16x32_bf16 v[204:207], v[22:25], v[126:129], v[10:13]
	v_mfma_f32_16x16x32_bf16 v[10:13], v[26:29], v[122:125], 0
	v_mfma_f32_16x16x32_bf16 v[208:211], v[30:33], v[126:129], v[10:13]
	s_setprio 0
	s_barrier
; #define PG8_WAIT_V(n) asm volatile("s_waitcnt vmcnt(" #n ")" ::: "memory")
; template <class Epi, class Sched, bool ALIGN_EPI = true, bool SP2 = true, bool FULLLINE = false, bool NOSTAGE = false, bool FP8 = false>
; __device__ __forceinline__ void gemm_phase(PG8_LAS unsigned char* lds, const Gemm g, const Sched& S, const Epi& E) {
;     ...
;         static_assert(SP2, "only the SP2 loop is kept");
;         { const int t = 0; if constexpr (Epi::NST == 16) PG8_ITER(PG8_WAIT_V(24)); else if constexpr (Epi::NST == 8) PG8_ITER(PG8_WAIT_V(16)); else PG8_ITER(PG8_WAIT_V(8)); }
;         for (int t = 2; t < nt; t += 2) PG8_ITER(PG8_WAIT_V(8));
	s_nop 5
	ds_read_b128 v[10:13], v194
	ds_read_b128 v[14:17], v194 offset:1024
	ds_read_b128 v[18:21], v194 offset:2048
	ds_read_b128 v[22:25], v194 offset:3072
	ds_read_b128 v[212:215], v195
	ds_read_b128 v[216:219], v195 offset:1024
	ds_read_b128 v[220:223], v195 offset:2048
	ds_read_b128 v[224:227], v195 offset:3072
	s_mov_b32 m0, s47
	v_lshl_add_u64 v[106:107], v[244:245], 0, s[22:23]
	ds_read_b128 v[26:29], v193 offset:32768
	ds_read_b128 v[30:33], v193 offset:33792
	ds_read_b128 v[62:65], v193 offset:34816
	ds_read_b128 v[114:117], v193 offset:35840
	ds_read_b128 v[228:231], v193 offset:36864
	ds_read_b128 v[232:235], v193 offset:37888
	ds_read_b128 v[236:239], v193 offset:38912
	ds_read_b128 v[240:243], v193 offset:39936
	global_load_lds_dwordx4 v[106:107], off
	v_lshl_add_u64 v[106:107], v[244:245], 0, s[24:25]
	s_mov_b32 m0, s52
	s_nop 0
	global_load_lds_dwordx4 v[106:107], off
	s_waitcnt vmcnt(8)
	s_waitcnt lgkmcnt(0)
	s_barrier
	s_waitcnt lgkmcnt(0)
	s_setprio 1
	v_mfma_f32_16x16x32_bf16 v[66:69], v[10:13], v[26:29], v[66:69]
	v_mfma_f32_16x16x32_bf16 v[142:145], v[14:17], v[30:33], v[66:69]
	v_mfma_f32_16x16x32_bf16 v[66:69], v[18:21], v[26:29], v[70:73]
	v_mfma_f32_16x16x32_bf16 v[138:141], v[22:25], v[30:33], v[66:69]
	v_mfma_f32_16x16x32_bf16 v[66:69], v[10:13], v[62:65], v[74:77]
	v_mfma_f32_16x16x32_bf16 v[126:129], v[14:17], v[114:117], v[66:69]
	v_mfma_f32_16x16x32_bf16 v[66:69], v[18:21], v[62:65], v[78:81]
	v_mfma_f32_16x16x32_bf16 v[122:125], v[22:25], v[114:117], v[66:69]
	v_mfma_f32_16x16x32_bf16 v[66:69], v[10:13], v[228:231], v[82:85]
	v_mfma_f32_16x16x32_bf16 v[110:113], v[14:17], v[232:235], v[66:69]
	v_mfma_f32_16x16x32_bf16 v[66:69], v[18:21], v[228:231], v[86:89]
	v_mfma_f32_16x16x32_bf16 v[106:109], v[22:25], v[232:235], v[66:69]
	v_mfma_f32_16x16x32_bf16 v[66:69], v[10:13], v[236:239], v[90:93]
	v_mfma_f32_16x16x32_bf16 v[78:81], v[14:17], v[240:243], v[66:69]
	v_mfma_f32_16x16x32_bf16 v[66:69], v[18:21], v[236:239], v[94:97]
	v_mfma_f32_16x16x32_bf16 v[74:77], v[22:25], v[240:243], v[66:69]
	v_mfma_f32_16x16x32_bf16 v[66:69], v[212:215], v[26:29], v[98:101]
	v_mfma_f32_16x16x32_bf16 v[26:29], v[220:223], v[26:29], v[34:37]
	v_mfma_f32_16x16x32_bf16 v[130:133], v[224:227], v[30:33], v[26:29]
	v_mfma_f32_16x16x32_bf16 v[26:29], v[212:215], v[62:65], v[38:41]
	v_mfma_f32_16x16x32_bf16 v[118:121], v[216:219], v[114:117], v[26:29]
	v_mfma_f32_16x16x32_bf16 v[26:29], v[220:223], v[62:65], v[42:45]
	v_mfma_f32_16x16x32_bf16 v[114:117], v[224:227], v[114:117], v[26:29]
	v_mfma_f32_16x16x32_bf16 v[26:29], v[212:215], v[228:231], v[46:49]
	v_mfma_f32_16x16x32_bf16 v[94:97], v[216:219], v[232:235], v[26:29]
	v_mfma_f32_16x16x32_bf16 v[26:29], v[220:223], v[228:231], v[50:53]
	v_mfma_f32_16x16x32_bf16 v[90:93], v[224:227], v[232:235], v[26:29]
	v_mfma_f32_16x16x32_bf16 v[26:29], v[212:215], v[236:239], v[54:57]
	v_mfma_f32_16x16x32_bf16 v[70:73], v[216:219], v[240:243], v[26:29]
	v_mfma_f32_16x16x32_bf16 v[26:29], v[220:223], v[236:239], v[58:61]
	v_mfma_f32_16x16x32_bf16 v[134:137], v[216:219], v[30:33], v[66:69]
	v_mfma_f32_16x16x32_bf16 v[66:69], v[224:227], v[240:243], v[26:29]
	s_setprio 0
	s_barrier
	s_add_i32 s50, s77, s44
	s_nop 3
	v_lshl_add_u64 v[26:27], v[246:247], 0, s[26:27]
	s_mov_b32 m0, s50
	s_add_i32 s51, s50, 0x2000
	ds_read_b128 v[34:37], v193 offset:49152
	ds_read_b128 v[38:41], v193 offset:50176
	ds_read_b128 v[82:85], v193 offset:51200
	ds_read_b128 v[86:89], v193 offset:52224
	ds_read_b128 v[98:101], v193 offset:53248
	ds_read_b128 v[228:231], v193 offset:54272
	ds_read_b128 v[232:235], v193 offset:55296
	ds_read_b128 v[236:239], v193 offset:56320
	global_load_lds_dwordx4 v[26:27], off
	v_lshl_add_u64 v[26:27], v[246:247], 0, s[28:29]
	s_mov_b32 m0, s51
	s_mov_b64 s[0:1], 0x160180
	s_add_i32 s33, s78, s44
	global_load_lds_dwordx4 v[26:27], off
	v_lshl_add_u64 v[26:27], v[246:247], 0, s[0:1]
	s_mov_b32 m0, s33
	s_mov_b64 s[0:1], 0x210180
	s_add_i32 s56, s33, 0x2000
	global_load_lds_dwordx4 v[26:27], off
	v_lshl_add_u64 v[26:27], v[246:247], 0, s[0:1]
	s_mov_b32 m0, s56
	s_nop 0
	global_load_lds_dwordx4 v[26:27], off
	v_lshl_add_u64 v[26:27], v[244:245], 0, s[26:27]
	s_mov_b32 m0, s53
	s_nop 0
	global_load_lds_dwordx4 v[26:27], off
	v_lshl_add_u64 v[26:27], v[244:245], 0, s[28:29]
	s_mov_b32 m0, s54
	s_nop 0
	global_load_lds_dwordx4 v[26:27], off
	s_waitcnt vmcnt(8)
	s_waitcnt lgkmcnt(0)
	s_barrier
	s_waitcnt lgkmcnt(0)
	s_setprio 1
	v_mfma_f32_16x16x32_bf16 v[26:29], v[10:13], v[34:37], v[146:149]
	v_mfma_f32_16x16x32_bf16 v[62:65], v[14:17], v[38:41], v[26:29]
	v_mfma_f32_16x16x32_bf16 v[26:29], v[18:21], v[34:37], v[150:153]
	v_mfma_f32_16x16x32_bf16 v[58:61], v[22:25], v[38:41], v[26:29]
	v_mfma_f32_16x16x32_bf16 v[26:29], v[10:13], v[82:85], v[154:157]
	v_mfma_f32_16x16x32_bf16 v[46:49], v[14:17], v[86:89], v[26:29]
	v_mfma_f32_16x16x32_bf16 v[26:29], v[18:21], v[82:85], v[158:161]
	v_mfma_f32_16x16x32_bf16 v[42:45], v[22:25], v[86:89], v[26:29]
	v_mfma_f32_16x16x32_bf16 v[26:29], v[10:13], v[98:101], v[162:165]
	v_mfma_f32_16x16x32_bf16 v[2:5], v[10:13], v[232:235], v[2:5]
	v_mfma_f32_16x16x32_bf16 v[30:33], v[14:17], v[228:231], v[26:29]
	v_mfma_f32_16x16x32_bf16 v[26:29], v[18:21], v[98:101], v[166:169]
	v_mfma_f32_16x16x32_bf16 v[14:17], v[14:17], v[236:239], v[2:5]
	v_mfma_f32_16x16x32_bf16 v[2:5], v[18:21], v[232:235], v[6:9]
	v_mfma_f32_16x16x32_bf16 v[26:29], v[22:25], v[228:231], v[26:29]
	v_mfma_f32_16x16x32_bf16 v[10:13], v[22:25], v[236:239], v[2:5]
	v_mfma_f32_16x16x32_bf16 v[2:5], v[212:215], v[34:37], v[180:183]
	v_mfma_f32_16x16x32_bf16 v[54:57], v[216:219], v[38:41], v[2:5]
	v_mfma_f32_16x16x32_bf16 v[2:5], v[220:223], v[34:37], v[102:105]
	v_mfma_f32_16x16x32_bf16 v[50:53], v[224:227], v[38:41], v[2:5]
	v_mfma_f32_16x16x32_bf16 v[2:5], v[212:215], v[82:85], v[184:187]
	v_mfma_f32_16x16x32_bf16 v[38:41], v[216:219], v[86:89], v[2:5]
	v_mfma_f32_16x16x32_bf16 v[2:5], v[220:223], v[82:85], v[188:191]
	v_mfma_f32_16x16x32_bf16 v[34:37], v[224:227], v[86:89], v[2:5]
	v_mfma_f32_16x16x32_bf16 v[2:5], v[212:215], v[98:101], v[196:199]
	v_mfma_f32_16x16x32_bf16 v[22:25], v[216:219], v[228:231], v[2:5]
	v_mfma_f32_16x16x32_bf16 v[2:5], v[220:223], v[98:101], v[200:203]
	v_mfma_f32_16x16x32_bf16 v[18:21], v[224:227], v[228:231], v[2:5]
	v_mfma_f32_16x16x32_bf16 v[2:5], v[212:215], v[232:235], v[204:207]
	v_mfma_f32_16x16x32_bf16 v[6:9], v[216:219], v[236:239], v[2:5]
	v_mfma_f32_16x16x32_bf16 v[2:5], v[220:223], v[232:235], v[208:211]
	v_mfma_f32_16x16x32_bf16 v[2:5], v[224:227], v[236:239], v[2:5]
	s_setprio 0
	s_barrier
	s_add_u32 s66, s66, 0x160180
	s_addc_u32 s67, s67, 0
	s_add_u32 s57, s68, 0x200
	s_addc_u32 s68, s69, 0
	s_mov_b32 s69, 0
.LBB0_2390:
	ds_read_b128 v[82:85], v1
	ds_read_b128 v[86:89], v1 offset:1024
	ds_read_b128 v[98:101], v1 offset:2048
	ds_read_b128 v[102:105], v1 offset:3072
	ds_read_b128 v[146:149], v192
	ds_read_b128 v[150:153], v192 offset:1024
	ds_read_b128 v[154:157], v192 offset:2048
	ds_read_b128 v[158:161], v192 offset:3072
	s_add_u32 s0, s66, 0xffea0080
	s_addc_u32 s1, s67, -1
	s_cmpk_eq_i32 s69, 0x54
	s_cselect_b32 s1, s11, s1
	s_cselect_b32 s0, s10, s0
	s_cselect_b32 s65, s63, s68
	s_cselect_b32 s64, s62, s57
	s_mov_b32 m0, s83
	v_lshl_add_u64 v[208:209], s[66:67], 0, v[174:175]
	ds_read_b128 v[162:165], v193
	ds_read_b128 v[166:169], v193 offset:1024
	ds_read_b128 v[180:183], v193 offset:2048
	ds_read_b128 v[184:187], v193 offset:3072
	ds_read_b128 v[188:191], v193 offset:4096
	ds_read_b128 v[196:199], v193 offset:5120
	ds_read_b128 v[200:203], v193 offset:6144
	ds_read_b128 v[204:207], v193 offset:7168
	global_load_lds_dwordx4 v[208:209], off
	v_lshl_add_u64 v[208:209], v[208:209], 0, s[30:31]
	s_mov_b32 m0, s84
	s_nop 0
	global_load_lds_dwordx4 v[208:209], off
	s_waitcnt vmcnt(8)
	s_waitcnt lgkmcnt(0)
	s_barrier
	s_waitcnt lgkmcnt(0)
	s_setprio 1
	v_mfma_f32_16x16x32_bf16 v[142:145], v[82:85], v[162:165], v[142:145]
	v_mfma_f32_16x16x32_bf16 v[138:141], v[98:101], v[162:165], v[138:141]
	v_mfma_f32_16x16x32_bf16 v[126:129], v[82:85], v[180:183], v[126:129]
	v_mfma_f32_16x16x32_bf16 v[122:125], v[98:101], v[180:183], v[122:125]
	v_mfma_f32_16x16x32_bf16 v[110:113], v[82:85], v[188:191], v[110:113]
	v_mfma_f32_16x16x32_bf16 v[106:109], v[98:101], v[188:191], v[106:109]
	v_mfma_f32_16x16x32_bf16 v[78:81], v[82:85], v[200:203], v[78:81]
	v_mfma_f32_16x16x32_bf16 v[74:77], v[98:101], v[200:203], v[74:77]
	v_mfma_f32_16x16x32_bf16 v[142:145], v[86:89], v[166:169], v[142:145]
	v_mfma_f32_16x16x32_bf16 v[138:141], v[102:105], v[166:169], v[138:141]
	v_mfma_f32_16x16x32_bf16 v[126:129], v[86:89], v[184:187], v[126:129]
	v_mfma_f32_16x16x32_bf16 v[122:125], v[102:105], v[184:187], v[122:125]
	v_mfma_f32_16x16x32_bf16 v[110:113], v[86:89], v[196:199], v[110:113]
	v_mfma_f32_16x16x32_bf16 v[106:109], v[102:105], v[196:199], v[106:109]
	v_mfma_f32_16x16x32_bf16 v[78:81], v[86:89], v[204:207], v[78:81]
	v_mfma_f32_16x16x32_bf16 v[74:77], v[102:105], v[204:207], v[74:77]
	v_mfma_f32_16x16x32_bf16 v[134:137], v[146:149], v[162:165], v[134:137]
	v_mfma_f32_16x16x32_bf16 v[130:133], v[154:157], v[162:165], v[130:133]
	v_mfma_f32_16x16x32_bf16 v[118:121], v[146:149], v[180:183], v[118:121]
	v_mfma_f32_16x16x32_bf16 v[114:117], v[154:157], v[180:183], v[114:117]
	v_mfma_f32_16x16x32_bf16 v[94:97], v[146:149], v[188:191], v[94:97]
	v_mfma_f32_16x16x32_bf16 v[90:93], v[154:157], v[188:191], v[90:93]
	v_mfma_f32_16x16x32_bf16 v[70:73], v[146:149], v[200:203], v[70:73]
	v_mfma_f32_16x16x32_bf16 v[66:69], v[154:157], v[200:203], v[66:69]
	v_mfma_f32_16x16x32_bf16 v[134:137], v[150:153], v[166:169], v[134:137]
	v_mfma_f32_16x16x32_bf16 v[130:133], v[158:161], v[166:169], v[130:133]
	v_mfma_f32_16x16x32_bf16 v[118:121], v[150:153], v[184:187], v[118:121]
	v_mfma_f32_16x16x32_bf16 v[114:117], v[158:161], v[184:187], v[114:117]
	v_mfma_f32_16x16x32_bf16 v[94:97], v[150:153], v[196:199], v[94:97]
	v_mfma_f32_16x16x32_bf16 v[90:93], v[158:161], v[196:199], v[90:93]
	v_mfma_f32_16x16x32_bf16 v[70:73], v[150:153], v[204:207], v[70:73]
	v_mfma_f32_16x16x32_bf16 v[66:69], v[158:161], v[204:207], v[66:69]
	s_setprio 0
	s_barrier
	s_mov_b32 m0, s85
	v_lshl_add_u64 v[208:209], s[64:65], 0, v[172:173]
	ds_read_b128 v[162:165], v193 offset:16384
	ds_read_b128 v[166:169], v193 offset:17408
	ds_read_b128 v[180:183], v193 offset:18432
	ds_read_b128 v[184:187], v193 offset:19456
	ds_read_b128 v[188:191], v193 offset:20480
	ds_read_b128 v[196:199], v193 offset:21504
	ds_read_b128 v[200:203], v193 offset:22528
	ds_read_b128 v[204:207], v193 offset:23552
	global_load_lds_dwordx4 v[208:209], off
	v_lshl_add_u64 v[210:211], v[208:209], 0, s[30:31]
	s_mov_b32 m0, s87
	s_nop 0
	global_load_lds_dwordx4 v[210:211], off
	v_lshl_add_u64 v[210:211], v[208:209], 0, s[34:35]
	s_mov_b32 m0, s88
	s_nop 0
	global_load_lds_dwordx4 v[210:211], off
	v_lshl_add_u64 v[210:211], v[208:209], 0, s[36:37]
	s_mov_b32 m0, s89
	s_nop 0
	global_load_lds_dwordx4 v[210:211], off
	v_lshl_add_u64 v[210:211], s[0:1], 0, v[170:171]
	s_mov_b32 m0, s45
	v_lshl_add_u64 v[212:213], v[210:211], 0, s[30:31]
	global_load_lds_dwordx4 v[210:211], off
	s_mov_b32 m0, s46
	s_nop 0
	global_load_lds_dwordx4 v[212:213], off
	s_waitcnt vmcnt(8)
	s_waitcnt lgkmcnt(0)
	s_barrier
	s_waitcnt lgkmcnt(0)
	s_setprio 1
	v_mfma_f32_16x16x32_bf16 v[62:65], v[82:85], v[162:165], v[62:65]
	v_mfma_f32_16x16x32_bf16 v[58:61], v[98:101], v[162:165], v[58:61]
	v_mfma_f32_16x16x32_bf16 v[46:49], v[82:85], v[180:183], v[46:49]
	v_mfma_f32_16x16x32_bf16 v[42:45], v[98:101], v[180:183], v[42:45]
	v_mfma_f32_16x16x32_bf16 v[30:33], v[82:85], v[188:191], v[30:33]
	v_mfma_f32_16x16x32_bf16 v[26:29], v[98:101], v[188:191], v[26:29]
	v_mfma_f32_16x16x32_bf16 v[14:17], v[82:85], v[200:203], v[14:17]
	v_mfma_f32_16x16x32_bf16 v[10:13], v[98:101], v[200:203], v[10:13]
	v_mfma_f32_16x16x32_bf16 v[62:65], v[86:89], v[166:169], v[62:65]
	v_mfma_f32_16x16x32_bf16 v[58:61], v[102:105], v[166:169], v[58:61]
	v_mfma_f32_16x16x32_bf16 v[46:49], v[86:89], v[184:187], v[46:49]
	v_mfma_f32_16x16x32_bf16 v[42:45], v[102:105], v[184:187], v[42:45]
	v_mfma_f32_16x16x32_bf16 v[30:33], v[86:89], v[196:199], v[30:33]
	v_mfma_f32_16x16x32_bf16 v[26:29], v[102:105], v[196:199], v[26:29]
	v_mfma_f32_16x16x32_bf16 v[14:17], v[86:89], v[204:207], v[14:17]
	v_mfma_f32_16x16x32_bf16 v[10:13], v[102:105], v[204:207], v[10:13]
	v_mfma_f32_16x16x32_bf16 v[54:57], v[146:149], v[162:165], v[54:57]
	v_mfma_f32_16x16x32_bf16 v[50:53], v[154:157], v[162:165], v[50:53]
	v_mfma_f32_16x16x32_bf16 v[38:41], v[146:149], v[180:183], v[38:41]
	v_mfma_f32_16x16x32_bf16 v[34:37], v[154:157], v[180:183], v[34:37]
	v_mfma_f32_16x16x32_bf16 v[22:25], v[146:149], v[188:191], v[22:25]
	v_mfma_f32_16x16x32_bf16 v[18:21], v[154:157], v[188:191], v[18:21]
	v_mfma_f32_16x16x32_bf16 v[6:9], v[146:149], v[200:203], v[6:9]
	v_mfma_f32_16x16x32_bf16 v[2:5], v[154:157], v[200:203], v[2:5]
	v_mfma_f32_16x16x32_bf16 v[54:57], v[150:153], v[166:169], v[54:57]
	v_mfma_f32_16x16x32_bf16 v[50:53], v[158:161], v[166:169], v[50:53]
	v_mfma_f32_16x16x32_bf16 v[38:41], v[150:153], v[184:187], v[38:41]
	v_mfma_f32_16x16x32_bf16 v[34:37], v[158:161], v[184:187], v[34:37]
	v_mfma_f32_16x16x32_bf16 v[22:25], v[150:153], v[196:199], v[22:25]
	v_mfma_f32_16x16x32_bf16 v[18:21], v[158:161], v[196:199], v[18:21]
	v_mfma_f32_16x16x32_bf16 v[6:9], v[150:153], v[204:207], v[6:9]
	v_mfma_f32_16x16x32_bf16 v[2:5], v[158:161], v[204:207], v[2:5]
	s_setprio 0
	s_barrier
	ds_read_b128 v[82:85], v194
	ds_read_b128 v[86:89], v194 offset:1024
	ds_read_b128 v[98:101], v194 offset:2048
	ds_read_b128 v[102:105], v194 offset:3072
	ds_read_b128 v[146:149], v195
	ds_read_b128 v[150:153], v195 offset:1024
	ds_read_b128 v[154:157], v195 offset:2048
	ds_read_b128 v[158:161], v195 offset:3072
	s_mov_b32 m0, s47
	v_lshl_add_u64 v[212:213], v[210:211], 0, s[34:35]
	ds_read_b128 v[162:165], v193 offset:32768
	ds_read_b128 v[166:169], v193 offset:33792
	ds_read_b128 v[180:183], v193 offset:34816
	ds_read_b128 v[184:187], v193 offset:35840
	ds_read_b128 v[188:191], v193 offset:36864
	ds_read_b128 v[196:199], v193 offset:37888
	ds_read_b128 v[200:203], v193 offset:38912
	ds_read_b128 v[204:207], v193 offset:39936
	global_load_lds_dwordx4 v[212:213], off
	v_lshl_add_u64 v[212:213], v[210:211], 0, s[36:37]
	s_mov_b32 m0, s52
	s_nop 0
	global_load_lds_dwordx4 v[212:213], off
	s_waitcnt vmcnt(8)
	s_waitcnt lgkmcnt(0)
	s_barrier
	s_waitcnt lgkmcnt(0)
	s_setprio 1
	v_mfma_f32_16x16x32_bf16 v[142:145], v[82:85], v[162:165], v[142:145]
	v_mfma_f32_16x16x32_bf16 v[138:141], v[98:101], v[162:165], v[138:141]
	v_mfma_f32_16x16x32_bf16 v[126:129], v[82:85], v[180:183], v[126:129]
	v_mfma_f32_16x16x32_bf16 v[122:125], v[98:101], v[180:183], v[122:125]
	v_mfma_f32_16x16x32_bf16 v[110:113], v[82:85], v[188:191], v[110:113]
	v_mfma_f32_16x16x32_bf16 v[106:109], v[98:101], v[188:191], v[106:109]
	v_mfma_f32_16x16x32_bf16 v[78:81], v[82:85], v[200:203], v[78:81]
	v_mfma_f32_16x16x32_bf16 v[74:77], v[98:101], v[200:203], v[74:77]
	v_mfma_f32_16x16x32_bf16 v[142:145], v[86:89], v[166:169], v[142:145]
	v_mfma_f32_16x16x32_bf16 v[138:141], v[102:105], v[166:169], v[138:141]
	v_mfma_f32_16x16x32_bf16 v[126:129], v[86:89], v[184:187], v[126:129]
	v_mfma_f32_16x16x32_bf16 v[122:125], v[102:105], v[184:187], v[122:125]
	v_mfma_f32_16x16x32_bf16 v[110:113], v[86:89], v[196:199], v[110:113]
	v_mfma_f32_16x16x32_bf16 v[106:109], v[102:105], v[196:199], v[106:109]
	v_mfma_f32_16x16x32_bf16 v[78:81], v[86:89], v[204:207], v[78:81]
	v_mfma_f32_16x16x32_bf16 v[74:77], v[102:105], v[204:207], v[74:77]
	v_mfma_f32_16x16x32_bf16 v[134:137], v[146:149], v[162:165], v[134:137]
	v_mfma_f32_16x16x32_bf16 v[130:133], v[154:157], v[162:165], v[130:133]
	v_mfma_f32_16x16x32_bf16 v[118:121], v[146:149], v[180:183], v[118:121]
	v_mfma_f32_16x16x32_bf16 v[114:117], v[154:157], v[180:183], v[114:117]
	v_mfma_f32_16x16x32_bf16 v[94:97], v[146:149], v[188:191], v[94:97]
	v_mfma_f32_16x16x32_bf16 v[90:93], v[154:157], v[188:191], v[90:93]
	v_mfma_f32_16x16x32_bf16 v[70:73], v[146:149], v[200:203], v[70:73]
	v_mfma_f32_16x16x32_bf16 v[66:69], v[154:157], v[200:203], v[66:69]
	v_mfma_f32_16x16x32_bf16 v[134:137], v[150:153], v[166:169], v[134:137]
	v_mfma_f32_16x16x32_bf16 v[130:133], v[158:161], v[166:169], v[130:133]
	v_mfma_f32_16x16x32_bf16 v[118:121], v[150:153], v[184:187], v[118:121]
	v_mfma_f32_16x16x32_bf16 v[114:117], v[158:161], v[184:187], v[114:117]
	v_mfma_f32_16x16x32_bf16 v[94:97], v[150:153], v[196:199], v[94:97]
	v_mfma_f32_16x16x32_bf16 v[90:93], v[158:161], v[196:199], v[90:93]
	v_mfma_f32_16x16x32_bf16 v[70:73], v[150:153], v[204:207], v[70:73]
	v_mfma_f32_16x16x32_bf16 v[66:69], v[158:161], v[204:207], v[66:69]
	s_setprio 0
	s_barrier
; #define PG8_WAIT_V(n) asm volatile("s_waitcnt vmcnt(" #n ")" ::: "memory")
; #define PG8_BAR __builtin_amdgcn_s_barrier()
; template <class Epi, class Sched, bool ALIGN_EPI = true, bool SP2 = true, bool FULLLINE = false, bool NOSTAGE = false, bool FP8 = false>
; __device__ __forceinline__ void gemm_phase(PG8_LAS unsigned char* lds, const Gemm g, const Sched& S, const Epi& E) {
;     ...
;         static_assert(SP2, "only the SP2 loop is kept");
;         { const int t = 0; if constexpr (Epi::NST == 16) PG8_ITER(PG8_WAIT_V(24)); else if constexpr (Epi::NST == 8) PG8_ITER(PG8_WAIT_V(16)); else PG8_ITER(PG8_WAIT_V(8)); }
;         for (int t = 2; t < nt; t += 2) PG8_ITER(PG8_WAIT_V(8));
;     ...
;         if constexpr (ALIGN_EPI) { if (wr == 0) PG8_BAR; }
	s_mov_b32 m0, s50
	v_lshl_add_u64 v[212:213], v[208:209], 0, s[38:39]
	ds_read_b128 v[162:165], v193 offset:49152
	ds_read_b128 v[166:169], v193 offset:50176
	ds_read_b128 v[180:183], v193 offset:51200
	ds_read_b128 v[184:187], v193 offset:52224
	ds_read_b128 v[188:191], v193 offset:53248
	ds_read_b128 v[196:199], v193 offset:54272
	ds_read_b128 v[200:203], v193 offset:55296
	ds_read_b128 v[204:207], v193 offset:56320
	global_load_lds_dwordx4 v[212:213], off
	v_lshl_add_u64 v[212:213], v[208:209], 0, s[40:41]
	s_mov_b32 m0, s51
	s_nop 0
	global_load_lds_dwordx4 v[212:213], off
	v_lshl_add_u64 v[212:213], v[208:209], 0, s[14:15]
	s_mov_b32 m0, s33
	v_lshl_add_u64 v[208:209], v[208:209], 0, s[16:17]
	global_load_lds_dwordx4 v[212:213], off
	s_mov_b32 m0, s56
	s_nop 0
	global_load_lds_dwordx4 v[208:209], off
	v_lshl_add_u64 v[208:209], v[210:211], 0, s[38:39]
	s_mov_b32 m0, s53
	s_nop 0
	global_load_lds_dwordx4 v[208:209], off
	v_lshl_add_u64 v[208:209], v[210:211], 0, s[40:41]
	s_mov_b32 m0, s54
	s_nop 0
	global_load_lds_dwordx4 v[208:209], off
	s_waitcnt vmcnt(8)
	s_waitcnt lgkmcnt(0)
	s_barrier
	s_waitcnt lgkmcnt(0)
	s_setprio 1
	v_mfma_f32_16x16x32_bf16 v[62:65], v[82:85], v[162:165], v[62:65]
	v_mfma_f32_16x16x32_bf16 v[58:61], v[98:101], v[162:165], v[58:61]
	v_mfma_f32_16x16x32_bf16 v[46:49], v[82:85], v[180:183], v[46:49]
	v_mfma_f32_16x16x32_bf16 v[42:45], v[98:101], v[180:183], v[42:45]
	v_mfma_f32_16x16x32_bf16 v[30:33], v[82:85], v[188:191], v[30:33]
	v_mfma_f32_16x16x32_bf16 v[26:29], v[98:101], v[188:191], v[26:29]
	v_mfma_f32_16x16x32_bf16 v[14:17], v[82:85], v[200:203], v[14:17]
	v_mfma_f32_16x16x32_bf16 v[10:13], v[98:101], v[200:203], v[10:13]
	v_mfma_f32_16x16x32_bf16 v[62:65], v[86:89], v[166:169], v[62:65]
	v_mfma_f32_16x16x32_bf16 v[58:61], v[102:105], v[166:169], v[58:61]
	v_mfma_f32_16x16x32_bf16 v[46:49], v[86:89], v[184:187], v[46:49]
	v_mfma_f32_16x16x32_bf16 v[42:45], v[102:105], v[184:187], v[42:45]
	v_mfma_f32_16x16x32_bf16 v[30:33], v[86:89], v[196:199], v[30:33]
	v_mfma_f32_16x16x32_bf16 v[26:29], v[102:105], v[196:199], v[26:29]
	v_mfma_f32_16x16x32_bf16 v[14:17], v[86:89], v[204:207], v[14:17]
	v_mfma_f32_16x16x32_bf16 v[10:13], v[102:105], v[204:207], v[10:13]
	v_mfma_f32_16x16x32_bf16 v[54:57], v[146:149], v[162:165], v[54:57]
	v_mfma_f32_16x16x32_bf16 v[50:53], v[154:157], v[162:165], v[50:53]
	v_mfma_f32_16x16x32_bf16 v[38:41], v[146:149], v[180:183], v[38:41]
	v_mfma_f32_16x16x32_bf16 v[34:37], v[154:157], v[180:183], v[34:37]
	v_mfma_f32_16x16x32_bf16 v[22:25], v[146:149], v[188:191], v[22:25]
	v_mfma_f32_16x16x32_bf16 v[18:21], v[154:157], v[188:191], v[18:21]
	v_mfma_f32_16x16x32_bf16 v[6:9], v[146:149], v[200:203], v[6:9]
	v_mfma_f32_16x16x32_bf16 v[2:5], v[154:157], v[200:203], v[2:5]
	v_mfma_f32_16x16x32_bf16 v[54:57], v[150:153], v[166:169], v[54:57]
	v_mfma_f32_16x16x32_bf16 v[50:53], v[158:161], v[166:169], v[50:53]
	v_mfma_f32_16x16x32_bf16 v[38:41], v[150:153], v[184:187], v[38:41]
	v_mfma_f32_16x16x32_bf16 v[34:37], v[158:161], v[184:187], v[34:37]
	v_mfma_f32_16x16x32_bf16 v[22:25], v[150:153], v[196:199], v[22:25]
	v_mfma_f32_16x16x32_bf16 v[18:21], v[158:161], v[196:199], v[18:21]
	v_mfma_f32_16x16x32_bf16 v[6:9], v[150:153], v[204:207], v[6:9]
	v_mfma_f32_16x16x32_bf16 v[2:5], v[158:161], v[204:207], v[2:5]
	s_setprio 0
	s_barrier
	s_add_i32 s69, s69, 2
	s_add_u32 s66, s66, 0x100
	s_addc_u32 s67, s67, 0
	s_add_u32 s57, s57, 0x100
	s_addc_u32 s68, s68, 0
	s_cmpk_gt_u32 s69, 0x55
	s_cbranch_scc0 .LBB0_2390
	s_and_b64 vcc, exec, s[12:13]
	s_cbranch_vccz .LBB0_2393
	s_barrier

; #define PG8_STAGE(bufoff, gbase, voff) do { if constexpr (!NOSTAGE) _Pragma("unroll") for (int _i = 0; _i < 2; ++_i) \
;         __builtin_amdgcn_global_load_lds((const unsigned*)((const char*)(gbase) + (size_t)_i * pstep##voff + v##voff), (PG8_LAS unsigned*)(lds + (bufoff) + ldsw + _i * 8192), 16, 0, 0); } while (0)
; #define PG8_WAIT_V(n) asm volatile("s_waitcnt vmcnt(" #n ")" ::: "memory")
; #define PG8_BAR __builtin_amdgcn_s_barrier()
; template <class Epi, class Sched, bool ALIGN_EPI = true, bool SP2 = true, bool FULLLINE = false, bool NOSTAGE = false, bool FP8 = false>
; __device__ __forceinline__ void gemm_phase(PG8_LAS unsigned char* lds, const Gemm g, const Sched& S, const Epi& E) {
;     const int tid = threadIdx.x, wid = __builtin_amdgcn_readfirstlane(tid >> 6), lane = tid & 63, wr = wid >> 2, wc = wid & 3, fr = lane & 15, fq = lane >> 4;
;     const int K = g.K, nt = K / BK;
;     unsigned voffA_, voffB_;
;     { int R, C; stage_rc(tid * 16, R, C); const int Rb = Epi::PERM ? ((R & ~31) + perm32(R & 31)) : R;
;       voffA_ = (unsigned)(R * g.lda + C) * 2u; voffB_ = (unsigned)(Rb * g.ldb + C) * 2u; }
;     const unsigned voffA = voffA_, voffB = voffB_;
;     const size_t pstepoffA = (size_t)64 * g.lda * 2, pstepoffB = (size_t)64 * g.ldb * 2;
;     const size_t kstep = (size_t)(BK * 2);
;     const size_t hstepA = (size_t)HALF * g.lda * 2, hstepB = (size_t)HALF * g.ldb * 2;
;     const size_t tstepA = 2 * hstepA, tstepB = 2 * hstepB;
;     const unsigned ldsw = (unsigned)wid * 1024u;
;     const int aoff = lds_byte(wr * 64 + fr, fq * 8), boff = lds_byte(wc * 32 + fr, fq * 8);
;     ...
;     if (wr == 1) PG8_BAR;
;     PG8_WAIT_V(0); PG8_BAR;
;     PG8_BAR;
;     } else {
;     PG8_STAGE(PG8_SB(0, 0), cB, offB); PG8_STAGE(PG8_SA(0, 0), cA, offA); PG8_STAGE(PG8_SB(0, 1), cB + hstepB, offB); PG8_STAGE(PG8_SA(0, 1), cA + hstepA, offA);
;     if (wr == 1) PG8_BAR;
;     PG8_WAIT_V(4); PG8_BAR;
;     PG8_STAGE(PG8_SB(1, 0), cB + kstep, offB); PG8_STAGE(PG8_SA(1, 0), cA + kstep, offA); PG8_STAGE(PG8_SB(1, 1), cB + hstepB + kstep, offB);
;     PG8_WAIT_V(6); PG8_BAR;
;     }
;     if (wr == 1) __builtin_amdgcn_s_setprio(1);
.LBB0_2668:
	s_waitcnt vmcnt(0)
	v_cndmask_b32_e64 v4, 0, 1, s[8:9]
	v_cmp_ne_u32_e64 s[6:7], 1, v4
	s_andn2_b64 vcc, exec, s[8:9]
	s_barrier
	s_barrier
	s_cbranch_vccnz .LBB0_2670
.LBB0_2670:
	v_and_b32_e32 v4, 48, v0
	v_lshlrev_b32_e32 v5, 6, v0
	s_movk_i32 s1, 0x3c0
	s_add_u32 s68, s48, 0x224000
	v_and_or_b32 v4, v5, s1, v4
	v_lshlrev_b32_e32 v5, 2, v0
	s_addc_u32 s69, s49, 0
	s_lshl_b32 s0, s14, 13
	v_and_b32_e32 v5, 32, v5
	v_bitop3_b32 v6, v4, s0, v5 bitop3:0xde
	s_lshl_b32 s0, s11, 5
	s_and_b32 s71, s0, 0x60
	s_lshl_b32 s70, s14, 6
	s_lshl_b32 s0, s71, 7
	s_cmpk_lt_u32 s10, 0x100
	v_bitop3_b32 v4, s0, v4, v5 bitop3:0xf6
	s_cselect_b64 s[14:15], -1, 0
	s_ashr_i32 s72, s86, 31
	s_ashr_i32 s73, s2, 31
	v_lshlrev_b32_e32 v5, 9, v0
	s_cmp_lg_u64 s[12:13], 0
	v_and_b32_e32 v5, 0x30000, v5
	v_lshlrev_b32_e32 v1, 12, v1
	s_cselect_b64 s[16:17], -1, 0
	v_or3_b32 v1, v2, v5, v1
	s_add_i32 s75, 0, 0x10000
	s_add_i32 s76, 0, 0x14000
	s_add_i32 s77, 0, 0x18000
	s_add_i32 s78, 0, 0x1c000
	v_add_u32_e32 v182, v1, v3
	v_mov_b32_e32 v183, 0
	s_mov_b32 s74, 0
	v_mov_b64_e32 v[184:185], 0x200
	v_mov_b64_e32 v[186:187], 0x1ff
	v_add_u32_e32 v1, s75, v4
	v_add_u32_e32 v200, s76, v4
	v_add_u32_e32 v201, 0, v6
	s_mov_b64 s[18:19], 0x100
	v_add_u32_e32 v202, s77, v4
	v_add_u32_e32 v203, s78, v4
	s_mov_b64 s[20:21], 0x180
	s_mov_b64 s[22:23], 0x40000
	s_mov_b64 s[24:25], 0x80000
	s_mov_b64 s[26:27], 0x80
	s_mov_b64 s[28:29], 0xb0000
	s_branch .LBB0_2673

.LBB0_2681:
	ds_read_b128 v[2:5], v1
	ds_read_b128 v[6:9], v1 offset:1024
	ds_read_b128 v[10:13], v1 offset:2048
	ds_read_b128 v[14:17], v1 offset:3072
	ds_read_b128 v[18:21], v200
	ds_read_b128 v[22:25], v200 offset:1024
	ds_read_b128 v[26:29], v200 offset:2048
	ds_read_b128 v[30:33], v200 offset:3072
	s_ashr_i32 s31, s30, 31
	s_lshl_b64 s[0:1], s[30:31], 18
	s_add_u32 s38, s43, s0
	s_addc_u32 s39, s46, s1
	s_and_b64 s[0:1], s[10:11], exec
	s_cselect_b32 s31, s39, s63
	s_cselect_b32 s35, s38, s62
	v_lshl_add_u64 v[244:245], s[66:67], 0, v[178:179]
	s_mov_b64 s[0:1], 0x80080
	s_add_i32 s79, s41, 0xc000
	v_lshl_add_u64 v[66:67], v[244:245], 0, s[0:1]
	s_mov_b32 m0, s79
	s_mov_b64 s[0:1], 0xc0080
	s_add_i32 s80, s41, 0xe000
	ds_read_b128 v[34:37], v201
	ds_read_b128 v[38:41], v201 offset:1024
	ds_read_b128 v[42:45], v201 offset:2048
	ds_read_b128 v[46:49], v201 offset:3072
	ds_read_b128 v[50:53], v201 offset:4096
	ds_read_b128 v[54:57], v201 offset:5120
	ds_read_b128 v[58:61], v201 offset:6144
	ds_read_b128 v[62:65], v201 offset:7168
	global_load_lds_dwordx4 v[66:67], off
	v_lshl_add_u64 v[66:67], v[244:245], 0, s[0:1]
	s_mov_b32 m0, s80
	s_nop 0
	global_load_lds_dwordx4 v[66:67], off
	s_waitcnt vmcnt(24)
	s_waitcnt lgkmcnt(0)
	s_barrier
	s_waitcnt lgkmcnt(0)
	s_setprio 1
	v_mfma_f32_16x16x32_bf16 v[66:69], v[2:5], v[34:37], 0
	v_mfma_f32_16x16x32_bf16 v[70:73], v[10:13], v[34:37], 0
	v_mfma_f32_16x16x32_bf16 v[74:77], v[2:5], v[42:45], 0
	v_mfma_f32_16x16x32_bf16 v[78:81], v[10:13], v[42:45], 0
	v_mfma_f32_16x16x32_bf16 v[82:85], v[2:5], v[50:53], 0
	v_mfma_f32_16x16x32_bf16 v[90:93], v[2:5], v[58:61], 0
	v_mfma_f32_16x16x32_bf16 v[66:69], v[6:9], v[38:41], v[66:69]
	v_mfma_f32_16x16x32_bf16 v[70:73], v[14:17], v[38:41], v[70:73]
	v_mfma_f32_16x16x32_bf16 v[74:77], v[6:9], v[46:49], v[74:77]
	v_mfma_f32_16x16x32_bf16 v[78:81], v[14:17], v[46:49], v[78:81]
	v_mfma_f32_16x16x32_bf16 v[82:85], v[6:9], v[54:57], v[82:85]
	v_mfma_f32_16x16x32_bf16 v[86:89], v[10:13], v[50:53], 0
	v_mfma_f32_16x16x32_bf16 v[90:93], v[6:9], v[62:65], v[90:93]
	v_mfma_f32_16x16x32_bf16 v[94:97], v[10:13], v[58:61], 0
	v_mfma_f32_16x16x32_bf16 v[86:89], v[14:17], v[54:57], v[86:89]
	v_mfma_f32_16x16x32_bf16 v[94:97], v[14:17], v[62:65], v[94:97]
	v_mfma_f32_16x16x32_bf16 v[98:101], v[18:21], v[34:37], 0
	v_mfma_f32_16x16x32_bf16 v[34:37], v[26:29], v[34:37], 0
	v_mfma_f32_16x16x32_bf16 v[102:105], v[22:25], v[38:41], v[98:101]
	v_mfma_f32_16x16x32_bf16 v[34:37], v[30:33], v[38:41], v[34:37]
	v_mfma_f32_16x16x32_bf16 v[38:41], v[18:21], v[42:45], 0
	v_mfma_f32_16x16x32_bf16 v[42:45], v[26:29], v[42:45], 0
	v_mfma_f32_16x16x32_bf16 v[38:41], v[22:25], v[46:49], v[38:41]
	v_mfma_f32_16x16x32_bf16 v[42:45], v[30:33], v[46:49], v[42:45]
	v_mfma_f32_16x16x32_bf16 v[46:49], v[18:21], v[50:53], 0
	v_mfma_f32_16x16x32_bf16 v[50:53], v[26:29], v[50:53], 0
	v_mfma_f32_16x16x32_bf16 v[46:49], v[22:25], v[54:57], v[46:49]
	v_mfma_f32_16x16x32_bf16 v[50:53], v[30:33], v[54:57], v[50:53]
	v_mfma_f32_16x16x32_bf16 v[54:57], v[18:21], v[58:61], 0
	v_mfma_f32_16x16x32_bf16 v[58:61], v[26:29], v[58:61], 0
	v_mfma_f32_16x16x32_bf16 v[54:57], v[22:25], v[62:65], v[54:57]
	v_mfma_f32_16x16x32_bf16 v[58:61], v[30:33], v[62:65], v[58:61]
	s_setprio 0
	s_barrier
	v_lshl_add_u64 v[246:247], s[62:63], 0, v[180:181]
	s_add_i32 s81, s75, s47
	v_lshl_add_u64 v[130:131], v[246:247], 0, s[18:19]
	s_mov_b32 m0, s81
	s_mov_b64 s[0:1], 0x10100
	s_add_i32 s82, s81, 0x2000
	ds_read_b128 v[62:65], v201 offset:16384
	ds_read_b128 v[98:101], v201 offset:17408
	ds_read_b128 v[106:109], v201 offset:18432
	ds_read_b128 v[110:113], v201 offset:19456
	ds_read_b128 v[114:117], v201 offset:20480
	ds_read_b128 v[118:121], v201 offset:21504
	ds_read_b128 v[122:125], v201 offset:22528
	ds_read_b128 v[126:129], v201 offset:23552
	global_load_lds_dwordx4 v[130:131], off
	v_lshl_add_u64 v[130:131], v[246:247], 0, s[0:1]
	s_mov_b32 m0, s82
	s_mov_b64 s[0:1], 0x20100
	s_add_i32 s83, s76, s47
	global_load_lds_dwordx4 v[130:131], off
	v_lshl_add_u64 v[130:131], v[246:247], 0, s[0:1]
	s_mov_b32 m0, s83
	s_mov_b64 s[0:1], 0x30100
	s_add_i32 s84, s83, 0x2000
	global_load_lds_dwordx4 v[130:131], off
	v_lshl_add_u64 v[130:131], v[246:247], 0, s[0:1]
	s_mov_b32 m0, s84
	s_mov_b64 s[0:1], 0x40100
	global_load_lds_dwordx4 v[130:131], off
	v_lshl_add_u64 v[130:131], v[244:245], 0, s[18:19]
	s_mov_b32 m0, s41
	s_nop 0
	global_load_lds_dwordx4 v[130:131], off
	v_lshl_add_u64 v[130:131], v[244:245], 0, s[0:1]
	s_mov_b32 m0, s45
	s_nop 0
	global_load_lds_dwordx4 v[130:131], off
	s_waitcnt vmcnt(24)
	s_waitcnt lgkmcnt(0)
	s_barrier
	s_waitcnt lgkmcnt(0)
	s_setprio 1
	v_mfma_f32_16x16x32_bf16 v[130:133], v[2:5], v[62:65], 0
	v_mfma_f32_16x16x32_bf16 v[146:149], v[6:9], v[98:101], v[130:133]
	v_mfma_f32_16x16x32_bf16 v[130:133], v[10:13], v[62:65], 0
	v_mfma_f32_16x16x32_bf16 v[150:153], v[14:17], v[98:101], v[130:133]
	v_mfma_f32_16x16x32_bf16 v[130:133], v[2:5], v[106:109], 0
	v_mfma_f32_16x16x32_bf16 v[154:157], v[6:9], v[110:113], v[130:133]
	v_mfma_f32_16x16x32_bf16 v[130:133], v[10:13], v[106:109], 0
	v_mfma_f32_16x16x32_bf16 v[158:161], v[14:17], v[110:113], v[130:133]
	v_mfma_f32_16x16x32_bf16 v[130:133], v[2:5], v[114:117], 0
	v_mfma_f32_16x16x32_bf16 v[2:5], v[2:5], v[122:125], 0
	v_mfma_f32_16x16x32_bf16 v[162:165], v[6:9], v[118:121], v[130:133]
	v_mfma_f32_16x16x32_bf16 v[2:5], v[6:9], v[126:129], v[2:5]
	v_mfma_f32_16x16x32_bf16 v[6:9], v[10:13], v[122:125], 0
	v_mfma_f32_16x16x32_bf16 v[130:133], v[10:13], v[114:117], 0
	v_mfma_f32_16x16x32_bf16 v[6:9], v[14:17], v[126:129], v[6:9]
	v_mfma_f32_16x16x32_bf16 v[166:169], v[14:17], v[118:121], v[130:133]
	v_mfma_f32_16x16x32_bf16 v[10:13], v[18:21], v[62:65], 0
	v_mfma_f32_16x16x32_bf16 v[170:173], v[22:25], v[98:101], v[10:13]
	v_mfma_f32_16x16x32_bf16 v[10:13], v[26:29], v[62:65], 0
	v_mfma_f32_16x16x32_bf16 v[174:177], v[30:33], v[98:101], v[10:13]
	v_mfma_f32_16x16x32_bf16 v[10:13], v[18:21], v[106:109], 0
	v_mfma_f32_16x16x32_bf16 v[188:191], v[22:25], v[110:113], v[10:13]
	v_mfma_f32_16x16x32_bf16 v[10:13], v[26:29], v[106:109], 0
	v_mfma_f32_16x16x32_bf16 v[106:109], v[30:33], v[110:113], v[10:13]
	v_mfma_f32_16x16x32_bf16 v[10:13], v[18:21], v[114:117], 0
	v_mfma_f32_16x16x32_bf16 v[192:195], v[22:25], v[118:121], v[10:13]
	v_mfma_f32_16x16x32_bf16 v[10:13], v[26:29], v[114:117], 0
	v_mfma_f32_16x16x32_bf16 v[196:199], v[30:33], v[118:121], v[10:13]
	v_mfma_f32_16x16x32_bf16 v[10:13], v[18:21], v[122:125], 0
	v_mfma_f32_16x16x32_bf16 v[204:207], v[22:25], v[126:129], v[10:13]
	v_mfma_f32_16x16x32_bf16 v[10:13], v[26:29], v[122:125], 0
	v_mfma_f32_16x16x32_bf16 v[208:211], v[30:33], v[126:129], v[10:13]
	s_setprio 0
	s_barrier
	s_nop 5
	ds_read_b128 v[10:13], v202
	ds_read_b128 v[14:17], v202 offset:1024
	ds_read_b128 v[18:21], v202 offset:2048
	ds_read_b128 v[22:25], v202 offset:3072
	ds_read_b128 v[212:215], v203
	ds_read_b128 v[216:219], v203 offset:1024
	ds_read_b128 v[220:223], v203 offset:2048
	ds_read_b128 v[224:227], v203 offset:3072
	s_mov_b64 s[0:1], 0x80100
	s_mov_b32 m0, s52
	v_lshl_add_u64 v[98:99], v[244:245], 0, s[0:1]
	s_mov_b64 s[0:1], 0xc0100
	ds_read_b128 v[26:29], v201 offset:32768
	ds_read_b128 v[30:33], v201 offset:33792
	ds_read_b128 v[62:65], v201 offset:34816
	ds_read_b128 v[114:117], v201 offset:35840
	ds_read_b128 v[228:231], v201 offset:36864
	ds_read_b128 v[232:235], v201 offset:37888
	ds_read_b128 v[236:239], v201 offset:38912
	ds_read_b128 v[240:243], v201 offset:39936
	global_load_lds_dwordx4 v[98:99], off
	v_lshl_add_u64 v[98:99], v[244:245], 0, s[0:1]
	s_mov_b32 m0, s53
	s_nop 0
	global_load_lds_dwordx4 v[98:99], off
	s_waitcnt vmcnt(8)
	s_waitcnt lgkmcnt(0)
	s_barrier
	s_waitcnt lgkmcnt(0)
	s_setprio 1
	v_mfma_f32_16x16x32_bf16 v[66:69], v[10:13], v[26:29], v[66:69]
	v_mfma_f32_16x16x32_bf16 v[134:137], v[14:17], v[30:33], v[66:69]
	v_mfma_f32_16x16x32_bf16 v[66:69], v[18:21], v[26:29], v[70:73]
	v_mfma_f32_16x16x32_bf16 v[130:133], v[22:25], v[30:33], v[66:69]
	v_mfma_f32_16x16x32_bf16 v[66:69], v[10:13], v[62:65], v[74:77]
	v_mfma_f32_16x16x32_bf16 v[126:129], v[14:17], v[114:117], v[66:69]
	v_mfma_f32_16x16x32_bf16 v[66:69], v[18:21], v[62:65], v[78:81]
	v_mfma_f32_16x16x32_bf16 v[122:125], v[22:25], v[114:117], v[66:69]
	v_mfma_f32_16x16x32_bf16 v[66:69], v[10:13], v[228:231], v[82:85]
	v_mfma_f32_16x16x32_bf16 v[110:113], v[14:17], v[232:235], v[66:69]
	v_mfma_f32_16x16x32_bf16 v[66:69], v[18:21], v[228:231], v[86:89]
	v_mfma_f32_16x16x32_bf16 v[98:101], v[22:25], v[232:235], v[66:69]
	v_mfma_f32_16x16x32_bf16 v[66:69], v[10:13], v[236:239], v[90:93]
	v_mfma_f32_16x16x32_bf16 v[78:81], v[14:17], v[240:243], v[66:69]
	v_mfma_f32_16x16x32_bf16 v[66:69], v[18:21], v[236:239], v[94:97]
	v_mfma_f32_16x16x32_bf16 v[74:77], v[22:25], v[240:243], v[66:69]
	v_mfma_f32_16x16x32_bf16 v[66:69], v[212:215], v[26:29], v[102:105]
	v_mfma_f32_16x16x32_bf16 v[26:29], v[220:223], v[26:29], v[34:37]
	v_mfma_f32_16x16x32_bf16 v[138:141], v[224:227], v[30:33], v[26:29]
	v_mfma_f32_16x16x32_bf16 v[26:29], v[212:215], v[62:65], v[38:41]
	v_mfma_f32_16x16x32_bf16 v[118:121], v[216:219], v[114:117], v[26:29]
	v_mfma_f32_16x16x32_bf16 v[26:29], v[220:223], v[62:65], v[42:45]
	v_mfma_f32_16x16x32_bf16 v[114:117], v[224:227], v[114:117], v[26:29]
	v_mfma_f32_16x16x32_bf16 v[26:29], v[212:215], v[228:231], v[46:49]
	v_mfma_f32_16x16x32_bf16 v[90:93], v[216:219], v[232:235], v[26:29]
	v_mfma_f32_16x16x32_bf16 v[26:29], v[220:223], v[228:231], v[50:53]
	v_mfma_f32_16x16x32_bf16 v[82:85], v[224:227], v[232:235], v[26:29]
	v_mfma_f32_16x16x32_bf16 v[26:29], v[212:215], v[236:239], v[54:57]
	v_mfma_f32_16x16x32_bf16 v[70:73], v[216:219], v[240:243], v[26:29]
	v_mfma_f32_16x16x32_bf16 v[26:29], v[220:223], v[236:239], v[58:61]
	v_mfma_f32_16x16x32_bf16 v[142:145], v[216:219], v[30:33], v[66:69]
	v_mfma_f32_16x16x32_bf16 v[66:69], v[224:227], v[240:243], v[26:29]
	s_setprio 0
	s_barrier
; #define PG8_WAIT_V(n) asm volatile("s_waitcnt vmcnt(" #n ")" ::: "memory")
; template <class Epi, class Sched, bool ALIGN_EPI = true, bool SP2 = true, bool FULLLINE = false, bool NOSTAGE = false, bool FP8 = false>
; __device__ __forceinline__ void gemm_phase(PG8_LAS unsigned char* lds, const Gemm g, const Sched& S, const Epi& E) {
;     ...
;         static_assert(SP2, "only the SP2 loop is kept");
;         { const int t = 0; if constexpr (Epi::NST == 16) PG8_ITER(PG8_WAIT_V(24)); else if constexpr (Epi::NST == 8) PG8_ITER(PG8_WAIT_V(16)); else PG8_ITER(PG8_WAIT_V(8)); }
;         for (int t = 2; t < nt; t += 2) PG8_ITER(PG8_WAIT_V(8));
	s_add_i32 s85, s77, s47
	s_nop 3
	v_lshl_add_u64 v[26:27], v[246:247], 0, s[20:21]
	s_mov_b32 m0, s85
	s_mov_b64 s[0:1], 0x10180
	s_add_i32 s87, s85, 0x2000
	ds_read_b128 v[34:37], v201 offset:49152
	ds_read_b128 v[38:41], v201 offset:50176
	ds_read_b128 v[86:89], v201 offset:51200
	ds_read_b128 v[94:97], v201 offset:52224
	ds_read_b128 v[102:105], v201 offset:53248
	ds_read_b128 v[228:231], v201 offset:54272
	ds_read_b128 v[232:235], v201 offset:55296
	ds_read_b128 v[236:239], v201 offset:56320
	global_load_lds_dwordx4 v[26:27], off
	v_lshl_add_u64 v[26:27], v[246:247], 0, s[0:1]
	s_mov_b32 m0, s87
	s_mov_b64 s[0:1], 0x20180
	s_add_i32 s50, s78, s47
	global_load_lds_dwordx4 v[26:27], off
	v_lshl_add_u64 v[26:27], v[246:247], 0, s[0:1]
	s_mov_b32 m0, s50
	s_mov_b64 s[0:1], 0x30180
	s_add_i32 s51, s50, 0x2000
	global_load_lds_dwordx4 v[26:27], off
	v_lshl_add_u64 v[26:27], v[246:247], 0, s[0:1]
	s_mov_b32 m0, s51
	s_mov_b64 s[0:1], 0x40180
	global_load_lds_dwordx4 v[26:27], off
	v_lshl_add_u64 v[26:27], v[244:245], 0, s[20:21]
	s_mov_b32 m0, s54
	s_nop 0
	global_load_lds_dwordx4 v[26:27], off
	v_lshl_add_u64 v[26:27], v[244:245], 0, s[0:1]
	s_mov_b32 m0, s55
	s_nop 0
	global_load_lds_dwordx4 v[26:27], off
	s_waitcnt vmcnt(8)
	s_waitcnt lgkmcnt(0)
	s_barrier
	s_waitcnt lgkmcnt(0)
	s_setprio 1
	v_mfma_f32_16x16x32_bf16 v[26:29], v[10:13], v[34:37], v[146:149]
	v_mfma_f32_16x16x32_bf16 v[62:65], v[14:17], v[38:41], v[26:29]
	v_mfma_f32_16x16x32_bf16 v[26:29], v[18:21], v[34:37], v[150:153]
	v_mfma_f32_16x16x32_bf16 v[58:61], v[22:25], v[38:41], v[26:29]
	v_mfma_f32_16x16x32_bf16 v[26:29], v[10:13], v[86:89], v[154:157]
	v_mfma_f32_16x16x32_bf16 v[46:49], v[14:17], v[94:97], v[26:29]
	v_mfma_f32_16x16x32_bf16 v[26:29], v[18:21], v[86:89], v[158:161]
	v_mfma_f32_16x16x32_bf16 v[42:45], v[22:25], v[94:97], v[26:29]
	v_mfma_f32_16x16x32_bf16 v[26:29], v[10:13], v[102:105], v[162:165]
	v_mfma_f32_16x16x32_bf16 v[2:5], v[10:13], v[232:235], v[2:5]
	v_mfma_f32_16x16x32_bf16 v[30:33], v[14:17], v[228:231], v[26:29]
	v_mfma_f32_16x16x32_bf16 v[26:29], v[18:21], v[102:105], v[166:169]
	v_mfma_f32_16x16x32_bf16 v[14:17], v[14:17], v[236:239], v[2:5]
	v_mfma_f32_16x16x32_bf16 v[2:5], v[18:21], v[232:235], v[6:9]
	v_mfma_f32_16x16x32_bf16 v[26:29], v[22:25], v[228:231], v[26:29]
	v_mfma_f32_16x16x32_bf16 v[10:13], v[22:25], v[236:239], v[2:5]
	v_mfma_f32_16x16x32_bf16 v[2:5], v[212:215], v[34:37], v[170:173]
	v_mfma_f32_16x16x32_bf16 v[54:57], v[216:219], v[38:41], v[2:5]
	v_mfma_f32_16x16x32_bf16 v[2:5], v[220:223], v[34:37], v[174:177]
	v_mfma_f32_16x16x32_bf16 v[50:53], v[224:227], v[38:41], v[2:5]
	v_mfma_f32_16x16x32_bf16 v[2:5], v[212:215], v[86:89], v[188:191]
	v_mfma_f32_16x16x32_bf16 v[38:41], v[216:219], v[94:97], v[2:5]
	v_mfma_f32_16x16x32_bf16 v[2:5], v[220:223], v[86:89], v[106:109]
	v_mfma_f32_16x16x32_bf16 v[34:37], v[224:227], v[94:97], v[2:5]
	v_mfma_f32_16x16x32_bf16 v[2:5], v[212:215], v[102:105], v[192:195]
	v_mfma_f32_16x16x32_bf16 v[22:25], v[216:219], v[228:231], v[2:5]
	v_mfma_f32_16x16x32_bf16 v[2:5], v[220:223], v[102:105], v[196:199]
	v_mfma_f32_16x16x32_bf16 v[18:21], v[224:227], v[228:231], v[2:5]
	v_mfma_f32_16x16x32_bf16 v[2:5], v[212:215], v[232:235], v[204:207]
	v_mfma_f32_16x16x32_bf16 v[6:9], v[216:219], v[236:239], v[2:5]
	v_mfma_f32_16x16x32_bf16 v[2:5], v[220:223], v[232:235], v[208:211]
	v_mfma_f32_16x16x32_bf16 v[2:5], v[224:227], v[236:239], v[2:5]
	s_setprio 0
	s_barrier
	s_add_u32 s10, s66, 0x80180
	s_addc_u32 s11, s67, 0
	s_add_u32 s33, s62, 0x200
	s_addc_u32 s56, s63, 0
	s_mov_b32 s57, 0
.LBB0_2682:
	ds_read_b128 v[86:89], v1
	ds_read_b128 v[94:97], v1 offset:1024
	ds_read_b128 v[102:105], v1 offset:2048
	ds_read_b128 v[106:109], v1 offset:3072
	ds_read_b128 v[146:149], v200
	ds_read_b128 v[150:153], v200 offset:1024
	ds_read_b128 v[154:157], v200 offset:2048
	ds_read_b128 v[158:161], v200 offset:3072
	s_add_u32 s0, s10, 0xfff80080
	s_addc_u32 s1, s11, -1
	s_cmp_eq_u32 s57, 4
	s_cselect_b32 s1, s37, s1
	s_cselect_b32 s0, s36, s0
	s_cselect_b32 s63, s31, s56
	s_cselect_b32 s62, s35, s33
	s_mov_b32 m0, s79
	v_lshl_add_u64 v[208:209], s[10:11], 0, v[182:183]
	ds_read_b128 v[162:165], v201
	ds_read_b128 v[166:169], v201 offset:1024
	ds_read_b128 v[170:173], v201 offset:2048
	ds_read_b128 v[174:177], v201 offset:3072
	ds_read_b128 v[188:191], v201 offset:4096
	ds_read_b128 v[192:195], v201 offset:5120
	ds_read_b128 v[196:199], v201 offset:6144
	ds_read_b128 v[204:207], v201 offset:7168
	global_load_lds_dwordx4 v[208:209], off
	v_lshl_add_u64 v[208:209], v[208:209], 0, s[22:23]
	s_mov_b32 m0, s80
	s_nop 0
	global_load_lds_dwordx4 v[208:209], off
	s_waitcnt vmcnt(8)
	s_waitcnt lgkmcnt(0)
	s_barrier
	s_waitcnt lgkmcnt(0)
	s_setprio 1
	v_mfma_f32_16x16x32_bf16 v[134:137], v[86:89], v[162:165], v[134:137]
	v_mfma_f32_16x16x32_bf16 v[130:133], v[102:105], v[162:165], v[130:133]
	v_mfma_f32_16x16x32_bf16 v[126:129], v[86:89], v[170:173], v[126:129]
	v_mfma_f32_16x16x32_bf16 v[122:125], v[102:105], v[170:173], v[122:125]
	v_mfma_f32_16x16x32_bf16 v[110:113], v[86:89], v[188:191], v[110:113]
	v_mfma_f32_16x16x32_bf16 v[98:101], v[102:105], v[188:191], v[98:101]
	v_mfma_f32_16x16x32_bf16 v[78:81], v[86:89], v[196:199], v[78:81]
	v_mfma_f32_16x16x32_bf16 v[74:77], v[102:105], v[196:199], v[74:77]
	v_mfma_f32_16x16x32_bf16 v[134:137], v[94:97], v[166:169], v[134:137]
	v_mfma_f32_16x16x32_bf16 v[130:133], v[106:109], v[166:169], v[130:133]
	v_mfma_f32_16x16x32_bf16 v[126:129], v[94:97], v[174:177], v[126:129]
	v_mfma_f32_16x16x32_bf16 v[122:125], v[106:109], v[174:177], v[122:125]
	v_mfma_f32_16x16x32_bf16 v[110:113], v[94:97], v[192:195], v[110:113]
	v_mfma_f32_16x16x32_bf16 v[98:101], v[106:109], v[192:195], v[98:101]
	v_mfma_f32_16x16x32_bf16 v[78:81], v[94:97], v[204:207], v[78:81]
	v_mfma_f32_16x16x32_bf16 v[74:77], v[106:109], v[204:207], v[74:77]
	v_mfma_f32_16x16x32_bf16 v[142:145], v[146:149], v[162:165], v[142:145]
	v_mfma_f32_16x16x32_bf16 v[138:141], v[154:157], v[162:165], v[138:141]
	v_mfma_f32_16x16x32_bf16 v[118:121], v[146:149], v[170:173], v[118:121]
	v_mfma_f32_16x16x32_bf16 v[114:117], v[154:157], v[170:173], v[114:117]
	v_mfma_f32_16x16x32_bf16 v[90:93], v[146:149], v[188:191], v[90:93]
	v_mfma_f32_16x16x32_bf16 v[82:85], v[154:157], v[188:191], v[82:85]
	v_mfma_f32_16x16x32_bf16 v[70:73], v[146:149], v[196:199], v[70:73]
	v_mfma_f32_16x16x32_bf16 v[66:69], v[154:157], v[196:199], v[66:69]
	v_mfma_f32_16x16x32_bf16 v[142:145], v[150:153], v[166:169], v[142:145]
	v_mfma_f32_16x16x32_bf16 v[138:141], v[158:161], v[166:169], v[138:141]
	v_mfma_f32_16x16x32_bf16 v[118:121], v[150:153], v[174:177], v[118:121]
	v_mfma_f32_16x16x32_bf16 v[114:117], v[158:161], v[174:177], v[114:117]
	v_mfma_f32_16x16x32_bf16 v[90:93], v[150:153], v[192:195], v[90:93]
	v_mfma_f32_16x16x32_bf16 v[82:85], v[158:161], v[192:195], v[82:85]
	v_mfma_f32_16x16x32_bf16 v[70:73], v[150:153], v[204:207], v[70:73]
	v_mfma_f32_16x16x32_bf16 v[66:69], v[158:161], v[204:207], v[66:69]
	s_setprio 0
	s_barrier
	s_mov_b32 m0, s81
	v_lshl_add_u64 v[208:209], s[62:63], 0, v[180:181]
	s_mov_b64 s[62:63], 0x10000
	ds_read_b128 v[162:165], v201 offset:16384
	ds_read_b128 v[166:169], v201 offset:17408
	ds_read_b128 v[170:173], v201 offset:18432
	ds_read_b128 v[174:177], v201 offset:19456
	ds_read_b128 v[188:191], v201 offset:20480
	ds_read_b128 v[192:195], v201 offset:21504
	ds_read_b128 v[196:199], v201 offset:22528
	ds_read_b128 v[204:207], v201 offset:23552
	global_load_lds_dwordx4 v[208:209], off
	v_lshl_add_u64 v[210:211], v[208:209], 0, s[62:63]
	s_mov_b32 m0, s82
	s_mov_b64 s[62:63], 0x20000
	global_load_lds_dwordx4 v[210:211], off
	v_lshl_add_u64 v[210:211], v[208:209], 0, s[62:63]
	s_mov_b32 m0, s83
	s_mov_b64 s[62:63], 0x30000
	global_load_lds_dwordx4 v[210:211], off
	v_lshl_add_u64 v[210:211], v[208:209], 0, s[62:63]
	s_mov_b32 m0, s84
	s_nop 0
	global_load_lds_dwordx4 v[210:211], off
	v_lshl_add_u64 v[210:211], s[0:1], 0, v[178:179]
	s_mov_b32 m0, s41
	v_lshl_add_u64 v[212:213], v[210:211], 0, s[22:23]
	global_load_lds_dwordx4 v[210:211], off
	s_mov_b32 m0, s45
	s_nop 0
	global_load_lds_dwordx4 v[212:213], off
	s_waitcnt vmcnt(8)
	s_waitcnt lgkmcnt(0)
	s_barrier
	s_waitcnt lgkmcnt(0)
	s_setprio 1
	v_mfma_f32_16x16x32_bf16 v[62:65], v[86:89], v[162:165], v[62:65]
	v_mfma_f32_16x16x32_bf16 v[58:61], v[102:105], v[162:165], v[58:61]
	v_mfma_f32_16x16x32_bf16 v[46:49], v[86:89], v[170:173], v[46:49]
	v_mfma_f32_16x16x32_bf16 v[42:45], v[102:105], v[170:173], v[42:45]
	v_mfma_f32_16x16x32_bf16 v[30:33], v[86:89], v[188:191], v[30:33]
	v_mfma_f32_16x16x32_bf16 v[26:29], v[102:105], v[188:191], v[26:29]
	v_mfma_f32_16x16x32_bf16 v[14:17], v[86:89], v[196:199], v[14:17]
	v_mfma_f32_16x16x32_bf16 v[10:13], v[102:105], v[196:199], v[10:13]
	v_mfma_f32_16x16x32_bf16 v[62:65], v[94:97], v[166:169], v[62:65]
	v_mfma_f32_16x16x32_bf16 v[58:61], v[106:109], v[166:169], v[58:61]
	v_mfma_f32_16x16x32_bf16 v[46:49], v[94:97], v[174:177], v[46:49]
	v_mfma_f32_16x16x32_bf16 v[42:45], v[106:109], v[174:177], v[42:45]
	v_mfma_f32_16x16x32_bf16 v[30:33], v[94:97], v[192:195], v[30:33]
	v_mfma_f32_16x16x32_bf16 v[26:29], v[106:109], v[192:195], v[26:29]
	v_mfma_f32_16x16x32_bf16 v[14:17], v[94:97], v[204:207], v[14:17]
	v_mfma_f32_16x16x32_bf16 v[10:13], v[106:109], v[204:207], v[10:13]
	v_mfma_f32_16x16x32_bf16 v[54:57], v[146:149], v[162:165], v[54:57]
	v_mfma_f32_16x16x32_bf16 v[50:53], v[154:157], v[162:165], v[50:53]
	v_mfma_f32_16x16x32_bf16 v[38:41], v[146:149], v[170:173], v[38:41]
	v_mfma_f32_16x16x32_bf16 v[34:37], v[154:157], v[170:173], v[34:37]
	v_mfma_f32_16x16x32_bf16 v[22:25], v[146:149], v[188:191], v[22:25]
	v_mfma_f32_16x16x32_bf16 v[18:21], v[154:157], v[188:191], v[18:21]
	v_mfma_f32_16x16x32_bf16 v[6:9], v[146:149], v[196:199], v[6:9]
	v_mfma_f32_16x16x32_bf16 v[2:5], v[154:157], v[196:199], v[2:5]
	v_mfma_f32_16x16x32_bf16 v[54:57], v[150:153], v[166:169], v[54:57]
	v_mfma_f32_16x16x32_bf16 v[50:53], v[158:161], v[166:169], v[50:53]
	v_mfma_f32_16x16x32_bf16 v[38:41], v[150:153], v[174:177], v[38:41]
	v_mfma_f32_16x16x32_bf16 v[34:37], v[158:161], v[174:177], v[34:37]
	v_mfma_f32_16x16x32_bf16 v[22:25], v[150:153], v[192:195], v[22:25]
	v_mfma_f32_16x16x32_bf16 v[18:21], v[158:161], v[192:195], v[18:21]
	v_mfma_f32_16x16x32_bf16 v[6:9], v[150:153], v[204:207], v[6:9]
	v_mfma_f32_16x16x32_bf16 v[2:5], v[158:161], v[204:207], v[2:5]
	s_setprio 0
	s_barrier
; #define PG8_WAIT_V(n) asm volatile("s_waitcnt vmcnt(" #n ")" ::: "memory")
; #define PG8_BAR __builtin_amdgcn_s_barrier()
; template <class Epi, class Sched, bool ALIGN_EPI = true, bool SP2 = true, bool FULLLINE = false, bool NOSTAGE = false, bool FP8 = false>
; __device__ __forceinline__ void gemm_phase(PG8_LAS unsigned char* lds, const Gemm g, const Sched& S, const Epi& E) {
;     ...
;         static_assert(SP2, "only the SP2 loop is kept");
;         { const int t = 0; if constexpr (Epi::NST == 16) PG8_ITER(PG8_WAIT_V(24)); else if constexpr (Epi::NST == 8) PG8_ITER(PG8_WAIT_V(16)); else PG8_ITER(PG8_WAIT_V(8)); }
;         for (int t = 2; t < nt; t += 2) PG8_ITER(PG8_WAIT_V(8));
;     ...
;         if constexpr (ALIGN_EPI) { if (wr == 0) PG8_BAR; }
	ds_read_b128 v[86:89], v202
	ds_read_b128 v[94:97], v202 offset:1024
	ds_read_b128 v[102:105], v202 offset:2048
	ds_read_b128 v[106:109], v202 offset:3072
	ds_read_b128 v[146:149], v203
	ds_read_b128 v[150:153], v203 offset:1024
	ds_read_b128 v[154:157], v203 offset:2048
	ds_read_b128 v[158:161], v203 offset:3072
	s_mov_b32 m0, s52
	v_lshl_add_u64 v[212:213], v[210:211], 0, s[24:25]
	s_mov_b64 s[0:1], 0xc0000
	ds_read_b128 v[162:165], v201 offset:32768
	ds_read_b128 v[166:169], v201 offset:33792
	ds_read_b128 v[170:173], v201 offset:34816
	ds_read_b128 v[174:177], v201 offset:35840
	ds_read_b128 v[188:191], v201 offset:36864
	ds_read_b128 v[192:195], v201 offset:37888
	ds_read_b128 v[196:199], v201 offset:38912
	ds_read_b128 v[204:207], v201 offset:39936
	global_load_lds_dwordx4 v[212:213], off
	v_lshl_add_u64 v[212:213], v[210:211], 0, s[0:1]
	s_mov_b32 m0, s53
	s_nop 0
	global_load_lds_dwordx4 v[212:213], off
	s_waitcnt vmcnt(8)
	s_waitcnt lgkmcnt(0)
	s_barrier
	s_waitcnt lgkmcnt(0)
	s_setprio 1
	v_mfma_f32_16x16x32_bf16 v[134:137], v[86:89], v[162:165], v[134:137]
	v_mfma_f32_16x16x32_bf16 v[130:133], v[102:105], v[162:165], v[130:133]
	v_mfma_f32_16x16x32_bf16 v[126:129], v[86:89], v[170:173], v[126:129]
	v_mfma_f32_16x16x32_bf16 v[122:125], v[102:105], v[170:173], v[122:125]
	v_mfma_f32_16x16x32_bf16 v[110:113], v[86:89], v[188:191], v[110:113]
	v_mfma_f32_16x16x32_bf16 v[98:101], v[102:105], v[188:191], v[98:101]
	v_mfma_f32_16x16x32_bf16 v[78:81], v[86:89], v[196:199], v[78:81]
	v_mfma_f32_16x16x32_bf16 v[74:77], v[102:105], v[196:199], v[74:77]
	v_mfma_f32_16x16x32_bf16 v[134:137], v[94:97], v[166:169], v[134:137]
	v_mfma_f32_16x16x32_bf16 v[130:133], v[106:109], v[166:169], v[130:133]
	v_mfma_f32_16x16x32_bf16 v[126:129], v[94:97], v[174:177], v[126:129]
	v_mfma_f32_16x16x32_bf16 v[122:125], v[106:109], v[174:177], v[122:125]
	v_mfma_f32_16x16x32_bf16 v[110:113], v[94:97], v[192:195], v[110:113]
	v_mfma_f32_16x16x32_bf16 v[98:101], v[106:109], v[192:195], v[98:101]
	v_mfma_f32_16x16x32_bf16 v[78:81], v[94:97], v[204:207], v[78:81]
	v_mfma_f32_16x16x32_bf16 v[74:77], v[106:109], v[204:207], v[74:77]
	v_mfma_f32_16x16x32_bf16 v[142:145], v[146:149], v[162:165], v[142:145]
	v_mfma_f32_16x16x32_bf16 v[138:141], v[154:157], v[162:165], v[138:141]
	v_mfma_f32_16x16x32_bf16 v[118:121], v[146:149], v[170:173], v[118:121]
	v_mfma_f32_16x16x32_bf16 v[114:117], v[154:157], v[170:173], v[114:117]
	v_mfma_f32_16x16x32_bf16 v[90:93], v[146:149], v[188:191], v[90:93]
	v_mfma_f32_16x16x32_bf16 v[82:85], v[154:157], v[188:191], v[82:85]
	v_mfma_f32_16x16x32_bf16 v[70:73], v[146:149], v[196:199], v[70:73]
	v_mfma_f32_16x16x32_bf16 v[66:69], v[154:157], v[196:199], v[66:69]
	v_mfma_f32_16x16x32_bf16 v[142:145], v[150:153], v[166:169], v[142:145]
	v_mfma_f32_16x16x32_bf16 v[138:141], v[158:161], v[166:169], v[138:141]
	v_mfma_f32_16x16x32_bf16 v[118:121], v[150:153], v[174:177], v[118:121]
	v_mfma_f32_16x16x32_bf16 v[114:117], v[158:161], v[174:177], v[114:117]
	v_mfma_f32_16x16x32_bf16 v[90:93], v[150:153], v[192:195], v[90:93]
	v_mfma_f32_16x16x32_bf16 v[82:85], v[158:161], v[192:195], v[82:85]
	v_mfma_f32_16x16x32_bf16 v[70:73], v[150:153], v[204:207], v[70:73]
	v_mfma_f32_16x16x32_bf16 v[66:69], v[158:161], v[204:207], v[66:69]
	s_setprio 0
	s_barrier
	s_mov_b32 m0, s85
	v_lshl_add_u64 v[212:213], v[208:209], 0, s[26:27]
	s_mov_b64 s[0:1], 0x10080
	ds_read_b128 v[162:165], v201 offset:49152
	ds_read_b128 v[166:169], v201 offset:50176
	ds_read_b128 v[170:173], v201 offset:51200
	ds_read_b128 v[174:177], v201 offset:52224
	ds_read_b128 v[188:191], v201 offset:53248
	ds_read_b128 v[192:195], v201 offset:54272
	ds_read_b128 v[196:199], v201 offset:55296
	ds_read_b128 v[204:207], v201 offset:56320
	global_load_lds_dwordx4 v[212:213], off
	v_lshl_add_u64 v[212:213], v[208:209], 0, s[0:1]
	s_mov_b32 m0, s87
	s_mov_b64 s[0:1], 0x20080
	global_load_lds_dwordx4 v[212:213], off
	v_lshl_add_u64 v[212:213], v[208:209], 0, s[0:1]
	s_mov_b32 m0, s50
	s_mov_b64 s[0:1], 0x30080
	global_load_lds_dwordx4 v[212:213], off
	v_lshl_add_u64 v[208:209], v[208:209], 0, s[0:1]
	s_mov_b32 m0, s51
	s_mov_b64 s[0:1], 0x40080
	global_load_lds_dwordx4 v[208:209], off
	v_lshl_add_u64 v[208:209], v[210:211], 0, s[26:27]
	s_mov_b32 m0, s54
	s_nop 0
	global_load_lds_dwordx4 v[208:209], off
	v_lshl_add_u64 v[208:209], v[210:211], 0, s[0:1]
	s_mov_b32 m0, s55
	s_nop 0
	global_load_lds_dwordx4 v[208:209], off
	s_waitcnt vmcnt(8)
	s_waitcnt lgkmcnt(0)
	s_barrier
	s_waitcnt lgkmcnt(0)
	s_setprio 1
	v_mfma_f32_16x16x32_bf16 v[62:65], v[86:89], v[162:165], v[62:65]
	v_mfma_f32_16x16x32_bf16 v[58:61], v[102:105], v[162:165], v[58:61]
	v_mfma_f32_16x16x32_bf16 v[46:49], v[86:89], v[170:173], v[46:49]
	v_mfma_f32_16x16x32_bf16 v[42:45], v[102:105], v[170:173], v[42:45]
	v_mfma_f32_16x16x32_bf16 v[30:33], v[86:89], v[188:191], v[30:33]
	v_mfma_f32_16x16x32_bf16 v[26:29], v[102:105], v[188:191], v[26:29]
	v_mfma_f32_16x16x32_bf16 v[14:17], v[86:89], v[196:199], v[14:17]
	v_mfma_f32_16x16x32_bf16 v[10:13], v[102:105], v[196:199], v[10:13]
	v_mfma_f32_16x16x32_bf16 v[62:65], v[94:97], v[166:169], v[62:65]
	v_mfma_f32_16x16x32_bf16 v[58:61], v[106:109], v[166:169], v[58:61]
	v_mfma_f32_16x16x32_bf16 v[46:49], v[94:97], v[174:177], v[46:49]
	v_mfma_f32_16x16x32_bf16 v[42:45], v[106:109], v[174:177], v[42:45]
	v_mfma_f32_16x16x32_bf16 v[30:33], v[94:97], v[192:195], v[30:33]
	v_mfma_f32_16x16x32_bf16 v[26:29], v[106:109], v[192:195], v[26:29]
	v_mfma_f32_16x16x32_bf16 v[14:17], v[94:97], v[204:207], v[14:17]
	v_mfma_f32_16x16x32_bf16 v[10:13], v[106:109], v[204:207], v[10:13]
	v_mfma_f32_16x16x32_bf16 v[54:57], v[146:149], v[162:165], v[54:57]
	v_mfma_f32_16x16x32_bf16 v[50:53], v[154:157], v[162:165], v[50:53]
	v_mfma_f32_16x16x32_bf16 v[38:41], v[146:149], v[170:173], v[38:41]
	v_mfma_f32_16x16x32_bf16 v[34:37], v[154:157], v[170:173], v[34:37]
	v_mfma_f32_16x16x32_bf16 v[22:25], v[146:149], v[188:191], v[22:25]
	v_mfma_f32_16x16x32_bf16 v[18:21], v[154:157], v[188:191], v[18:21]
	v_mfma_f32_16x16x32_bf16 v[6:9], v[146:149], v[196:199], v[6:9]
	v_mfma_f32_16x16x32_bf16 v[2:5], v[154:157], v[196:199], v[2:5]
	v_mfma_f32_16x16x32_bf16 v[54:57], v[150:153], v[166:169], v[54:57]
	v_mfma_f32_16x16x32_bf16 v[50:53], v[158:161], v[166:169], v[50:53]
	v_mfma_f32_16x16x32_bf16 v[38:41], v[150:153], v[174:177], v[38:41]
	v_mfma_f32_16x16x32_bf16 v[34:37], v[158:161], v[174:177], v[34:37]
	v_mfma_f32_16x16x32_bf16 v[22:25], v[150:153], v[192:195], v[22:25]
	v_mfma_f32_16x16x32_bf16 v[18:21], v[158:161], v[192:195], v[18:21]
	v_mfma_f32_16x16x32_bf16 v[6:9], v[150:153], v[204:207], v[6:9]
	v_mfma_f32_16x16x32_bf16 v[2:5], v[158:161], v[204:207], v[2:5]
	s_setprio 0
	s_barrier
	s_add_i32 s57, s57, 2
	s_add_u32 s10, s10, 0x100
	s_addc_u32 s11, s11, 0
	s_add_u32 s33, s33, 0x100
	s_addc_u32 s56, s56, 0
	s_cmp_gt_u32 s57, 5
	s_cbranch_scc0 .LBB0_2682
	s_and_b64 vcc, exec, s[14:15]
	s_cbranch_vccz .LBB0_2685
	s_barrier

; #define PG8_STAGE(bufoff, gbase, voff) do { if constexpr (!NOSTAGE) _Pragma("unroll") for (int _i = 0; _i < 2; ++_i) \
;         __builtin_amdgcn_global_load_lds((const unsigned*)((const char*)(gbase) + (size_t)_i * pstep##voff + v##voff), (PG8_LAS unsigned*)(lds + (bufoff) + ldsw + _i * 8192), 16, 0, 0); } while (0)
; #define PG8_WAIT_V(n) asm volatile("s_waitcnt vmcnt(" #n ")" ::: "memory")
; #define PG8_BAR __builtin_amdgcn_s_barrier()
; template <class Epi, class Sched, bool ALIGN_EPI = true, bool SP2 = true, bool FULLLINE = false, bool NOSTAGE = false, bool FP8 = false>
; __device__ __forceinline__ void gemm_phase(PG8_LAS unsigned char* lds, const Gemm g, const Sched& S, const Epi& E) {
;     const int tid = threadIdx.x, wid = __builtin_amdgcn_readfirstlane(tid >> 6), lane = tid & 63, wr = wid >> 2, wc = wid & 3, fr = lane & 15, fq = lane >> 4;
;     const int K = g.K, nt = K / BK;
;     unsigned voffA_, voffB_;
;     { int R, C; stage_rc(tid * 16, R, C); const int Rb = Epi::PERM ? ((R & ~31) + perm32(R & 31)) : R;
;       voffA_ = (unsigned)(R * g.lda + C) * 2u; voffB_ = (unsigned)(Rb * g.ldb + C) * 2u; }
;     const unsigned voffA = voffA_, voffB = voffB_;
;     const size_t pstepoffA = (size_t)64 * g.lda * 2, pstepoffB = (size_t)64 * g.ldb * 2;
;     const size_t kstep = (size_t)(BK * 2);
;     const size_t hstepA = (size_t)HALF * g.lda * 2, hstepB = (size_t)HALF * g.ldb * 2;
;     const size_t tstepA = 2 * hstepA, tstepB = 2 * hstepB;
;     const unsigned ldsw = (unsigned)wid * 1024u;
;     const int aoff = lds_byte(wr * 64 + fr, fq * 8), boff = lds_byte(wc * 32 + fr, fq * 8);
;     ...
;     if (wr == 1) PG8_BAR;
;     PG8_WAIT_V(0); PG8_BAR;
;     PG8_BAR;
;     } else {
;     PG8_STAGE(PG8_SB(0, 0), cB, offB); PG8_STAGE(PG8_SA(0, 0), cA, offA); PG8_STAGE(PG8_SB(0, 1), cB + hstepB, offB); PG8_STAGE(PG8_SA(0, 1), cA + hstepA, offA);
;     if (wr == 1) PG8_BAR;
;     PG8_WAIT_V(4); PG8_BAR;
;     PG8_STAGE(PG8_SB(1, 0), cB + kstep, offB); PG8_STAGE(PG8_SA(1, 0), cA + kstep, offA); PG8_STAGE(PG8_SB(1, 1), cB + hstepB + kstep, offB);
;     PG8_WAIT_V(6); PG8_BAR;
;     }
;     if (wr == 1) __builtin_amdgcn_s_setprio(1);
.LBB0_2854:
	s_waitcnt vmcnt(0)
	v_cndmask_b32_e64 v4, 0, 1, s[10:11]
	v_cmp_ne_u32_e64 s[6:7], 1, v4
	s_andn2_b64 vcc, exec, s[10:11]
	s_barrier
	s_barrier
	s_cbranch_vccnz .LBB0_2856
.LBB0_2856:
	v_and_b32_e32 v4, 48, v0
	v_lshlrev_b32_e32 v5, 6, v0
	s_movk_i32 s1, 0x3c0
	v_and_or_b32 v4, v5, s1, v4
	v_lshlrev_b32_e32 v5, 2, v0
	s_lshl_b32 s0, s13, 13
	v_and_b32_e32 v5, 32, v5
	v_bitop3_b32 v6, v4, s0, v5 bitop3:0xde
	s_lshl_b32 s0, s12, 5
	s_and_b32 s75, s0, 0x60
	s_lshl_b32 s0, s75, 7
	s_lshl_b32 s74, s13, 6
	v_bitop3_b32 v4, s0, v4, v5 bitop3:0xf6
	v_lshlrev_b32_e32 v5, 9, v0
	s_cmpk_lt_u32 s9, 0x100
	v_and_b32_e32 v5, 0x30000, v5
	v_lshlrev_b32_e32 v3, 12, v3
	s_cselect_b64 s[10:11], -1, 0
	v_or3_b32 v1, v1, v5, v3
	s_add_i32 s81, 0, 0x10000
	s_add_i32 s78, 0, 0x14000
	s_add_i32 s82, 0, 0x18000
	s_add_i32 s83, 0, 0x1c000
	s_sext_i32_i16 s85, s8
	s_ashr_i32 s76, s86, 31
	v_add_u32_e32 v134, v1, v2
	v_mov_b32_e32 v135, 0
	s_mov_b32 s77, 0
	v_mov_b64_e32 v[136:137], 0xb00
	v_mov_b64_e32 v[138:139], 0xaff
	v_add_u32_e32 v1, s81, v4
	v_add_u32_e32 v142, s78, v4
	v_add_u32_e32 v143, 0, v6
	s_mov_b64 s[12:13], 0x80080
	s_add_i32 s79, s53, 0xc000
	s_mov_b64 s[14:15], 0xc0080
	s_add_i32 s80, s53, 0xe000
	s_mov_b64 s[16:17], 0x100
	s_add_i32 s81, s81, s43
	s_mov_b64 s[18:19], 0x40100
	s_mov_b64 s[20:21], 0x80100
	s_mov_b64 s[22:23], 0xc0100
	v_add_u32_e32 v144, s82, v4
	v_add_u32_e32 v145, s83, v4
	s_mov_b64 s[24:25], 0x180
	s_mov_b64 s[26:27], 0x40180
	s_mov_b64 s[28:29], 0x40000
	s_mov_b64 s[30:31], 0x80000
	s_mov_b64 s[34:35], 0xc0000
	s_mov_b64 s[36:37], 0x80
	s_mov_b64 s[38:39], 0x40080
	s_movk_i32 s84, 0x2c00
	s_branch .LBB0_2859

.LBB0_2861:
	s_ashr_i32 s45, s44, 31
	s_lshl_b64 s[0:1], s[44:45], 20
	s_add_u32 s46, s58, s0
	ds_read_b128 v[2:5], v1
	ds_read_b128 v[6:9], v1 offset:1024
	ds_read_b128 v[10:13], v1 offset:2048
	ds_read_b128 v[14:17], v1 offset:3072
	ds_read_b128 v[18:21], v142
	ds_read_b128 v[22:25], v142 offset:1024
	ds_read_b128 v[26:29], v142 offset:2048
	ds_read_b128 v[30:33], v142 offset:3072
	s_addc_u32 s47, s59, s1
	s_ashr_i32 s41, s40, 31
	s_lshl_b64 s[0:1], s[40:41], 20
	s_add_u32 s62, s3, s0
	s_addc_u32 s63, s42, s1
	s_and_b64 s[0:1], s[8:9], exec
	s_cselect_b32 s41, s47, s71
	s_cselect_b32 s45, s46, s70
	s_cselect_b32 s87, s63, s69
	s_cselect_b32 s88, s62, s68
	v_lshl_add_u64 v[140:141], s[70:71], 0, v[132:133]
	s_mov_b32 m0, s79
	v_lshl_add_u64 v[66:67], v[140:141], 0, s[12:13]
	ds_read_b128 v[34:37], v143
	ds_read_b128 v[38:41], v143 offset:1024
	ds_read_b128 v[42:45], v143 offset:2048
	ds_read_b128 v[46:49], v143 offset:3072
	ds_read_b128 v[50:53], v143 offset:4096
	ds_read_b128 v[54:57], v143 offset:5120
	ds_read_b128 v[58:61], v143 offset:6144
	ds_read_b128 v[62:65], v143 offset:7168
	global_load_lds_dwordx4 v[66:67], off
	v_lshl_add_u64 v[66:67], v[140:141], 0, s[14:15]
	s_mov_b32 m0, s80
	s_nop 0
	global_load_lds_dwordx4 v[66:67], off
	s_waitcnt vmcnt(16)
	s_waitcnt lgkmcnt(0)
	s_barrier
	s_waitcnt lgkmcnt(0)
	s_setprio 1
	v_mfma_f32_16x16x32_bf16 v[86:89], v[10:13], v[50:53], 0
	v_mfma_f32_16x16x32_bf16 v[90:93], v[14:17], v[54:57], v[86:89]
	v_mfma_f32_16x16x32_bf16 v[86:89], v[2:5], v[58:61], 0
	v_mfma_f32_16x16x32_bf16 v[66:69], v[2:5], v[34:37], 0
	v_mfma_f32_16x16x32_bf16 v[70:73], v[10:13], v[34:37], 0
	v_mfma_f32_16x16x32_bf16 v[74:77], v[2:5], v[42:45], 0
	v_mfma_f32_16x16x32_bf16 v[78:81], v[10:13], v[42:45], 0
	v_mfma_f32_16x16x32_bf16 v[82:85], v[2:5], v[50:53], 0
	v_mfma_f32_16x16x32_bf16 v[94:97], v[6:9], v[62:65], v[86:89]
	v_mfma_f32_16x16x32_bf16 v[86:89], v[10:13], v[58:61], 0
	v_mfma_f32_16x16x32_bf16 v[66:69], v[6:9], v[38:41], v[66:69]
	v_mfma_f32_16x16x32_bf16 v[70:73], v[14:17], v[38:41], v[70:73]
	v_mfma_f32_16x16x32_bf16 v[74:77], v[6:9], v[46:49], v[74:77]
	v_mfma_f32_16x16x32_bf16 v[78:81], v[14:17], v[46:49], v[78:81]
	v_mfma_f32_16x16x32_bf16 v[82:85], v[6:9], v[54:57], v[82:85]
	v_mfma_f32_16x16x32_bf16 v[106:109], v[14:17], v[62:65], v[86:89]
	v_mfma_f32_16x16x32_bf16 v[86:89], v[18:21], v[34:37], 0
	v_mfma_f32_16x16x32_bf16 v[34:37], v[26:29], v[34:37], 0
	v_mfma_f32_16x16x32_bf16 v[110:113], v[22:25], v[38:41], v[86:89]
	v_mfma_f32_16x16x32_bf16 v[34:37], v[30:33], v[38:41], v[34:37]
	v_mfma_f32_16x16x32_bf16 v[38:41], v[18:21], v[42:45], 0
	v_mfma_f32_16x16x32_bf16 v[42:45], v[26:29], v[42:45], 0
	v_mfma_f32_16x16x32_bf16 v[38:41], v[22:25], v[46:49], v[38:41]
	v_mfma_f32_16x16x32_bf16 v[42:45], v[30:33], v[46:49], v[42:45]
	v_mfma_f32_16x16x32_bf16 v[46:49], v[18:21], v[50:53], 0
	v_mfma_f32_16x16x32_bf16 v[50:53], v[26:29], v[50:53], 0
	v_mfma_f32_16x16x32_bf16 v[46:49], v[22:25], v[54:57], v[46:49]
	v_mfma_f32_16x16x32_bf16 v[50:53], v[30:33], v[54:57], v[50:53]
	v_mfma_f32_16x16x32_bf16 v[54:57], v[18:21], v[58:61], 0
	v_mfma_f32_16x16x32_bf16 v[58:61], v[26:29], v[58:61], 0
	v_mfma_f32_16x16x32_bf16 v[54:57], v[22:25], v[62:65], v[54:57]
	v_mfma_f32_16x16x32_bf16 v[58:61], v[30:33], v[62:65], v[58:61]
	s_setprio 0
	s_barrier
	v_lshl_add_u64 v[238:239], s[68:69], 0, v[130:131]
	s_mov_b32 m0, s81
	v_lshl_add_u64 v[146:147], v[238:239], 0, s[16:17]
	s_add_i32 s89, s81, 0x2000
	ds_read_b128 v[62:65], v143 offset:16384
	ds_read_b128 v[86:89], v143 offset:17408
	ds_read_b128 v[98:101], v143 offset:18432
	ds_read_b128 v[102:105], v143 offset:19456
	ds_read_b128 v[114:117], v143 offset:20480
	ds_read_b128 v[118:121], v143 offset:21504
	ds_read_b128 v[122:125], v143 offset:22528
	ds_read_b128 v[126:129], v143 offset:23552
	global_load_lds_dwordx4 v[146:147], off
	v_lshl_add_u64 v[146:147], v[238:239], 0, s[18:19]
	s_mov_b32 m0, s89
	s_add_i32 s90, s78, s43
	global_load_lds_dwordx4 v[146:147], off
	v_lshl_add_u64 v[146:147], v[238:239], 0, s[20:21]
	s_mov_b32 m0, s90
	s_add_i32 s91, s90, 0x2000
	global_load_lds_dwordx4 v[146:147], off
	v_lshl_add_u64 v[146:147], v[238:239], 0, s[22:23]
	s_mov_b32 m0, s91
	s_nop 0
	global_load_lds_dwordx4 v[146:147], off
	v_lshl_add_u64 v[146:147], v[140:141], 0, s[16:17]
	s_mov_b32 m0, s53
	s_nop 0
	global_load_lds_dwordx4 v[146:147], off
	v_lshl_add_u64 v[146:147], v[140:141], 0, s[18:19]
	s_mov_b32 m0, s54
	s_nop 0
	global_load_lds_dwordx4 v[146:147], off
	s_waitcnt vmcnt(16)
	s_waitcnt lgkmcnt(0)
	s_barrier
	s_waitcnt lgkmcnt(0)
	s_setprio 1
	v_mfma_f32_16x16x32_bf16 v[146:149], v[2:5], v[62:65], 0
	v_mfma_f32_16x16x32_bf16 v[154:157], v[2:5], v[98:101], 0
	v_mfma_f32_16x16x32_bf16 v[162:165], v[2:5], v[114:117], 0
	v_mfma_f32_16x16x32_bf16 v[2:5], v[2:5], v[122:125], 0
	v_mfma_f32_16x16x32_bf16 v[146:149], v[6:9], v[86:89], v[146:149]
	v_mfma_f32_16x16x32_bf16 v[154:157], v[6:9], v[102:105], v[154:157]
	v_mfma_f32_16x16x32_bf16 v[162:165], v[6:9], v[118:121], v[162:165]
	v_mfma_f32_16x16x32_bf16 v[2:5], v[6:9], v[126:129], v[2:5]
	v_mfma_f32_16x16x32_bf16 v[6:9], v[10:13], v[122:125], 0
	v_mfma_f32_16x16x32_bf16 v[150:153], v[10:13], v[62:65], 0
	v_mfma_f32_16x16x32_bf16 v[158:161], v[10:13], v[98:101], 0
	v_mfma_f32_16x16x32_bf16 v[166:169], v[10:13], v[114:117], 0
	v_mfma_f32_16x16x32_bf16 v[10:13], v[14:17], v[126:129], v[6:9]
	v_mfma_f32_16x16x32_bf16 v[150:153], v[14:17], v[86:89], v[150:153]
	v_mfma_f32_16x16x32_bf16 v[158:161], v[14:17], v[102:105], v[158:161]
	v_mfma_f32_16x16x32_bf16 v[166:169], v[14:17], v[118:121], v[166:169]
	v_mfma_f32_16x16x32_bf16 v[6:9], v[18:21], v[62:65], 0
	v_mfma_f32_16x16x32_bf16 v[14:17], v[22:25], v[86:89], v[6:9]
	v_mfma_f32_16x16x32_bf16 v[6:9], v[26:29], v[62:65], 0
	v_mfma_f32_16x16x32_bf16 v[170:173], v[30:33], v[86:89], v[6:9]
	v_mfma_f32_16x16x32_bf16 v[6:9], v[18:21], v[98:101], 0
	v_mfma_f32_16x16x32_bf16 v[174:177], v[22:25], v[102:105], v[6:9]
	v_mfma_f32_16x16x32_bf16 v[6:9], v[26:29], v[98:101], 0
	v_mfma_f32_16x16x32_bf16 v[178:181], v[30:33], v[102:105], v[6:9]
	v_mfma_f32_16x16x32_bf16 v[6:9], v[18:21], v[114:117], 0
	v_mfma_f32_16x16x32_bf16 v[182:185], v[22:25], v[118:121], v[6:9]
	v_mfma_f32_16x16x32_bf16 v[6:9], v[26:29], v[114:117], 0
	v_mfma_f32_16x16x32_bf16 v[186:189], v[30:33], v[118:121], v[6:9]
	v_mfma_f32_16x16x32_bf16 v[6:9], v[18:21], v[122:125], 0
	v_mfma_f32_16x16x32_bf16 v[190:193], v[22:25], v[126:129], v[6:9]
	v_mfma_f32_16x16x32_bf16 v[6:9], v[26:29], v[122:125], 0
	v_mfma_f32_16x16x32_bf16 v[194:197], v[30:33], v[126:129], v[6:9]
	s_setprio 0
	s_barrier
; #define PG8_WAIT_V(n) asm volatile("s_waitcnt vmcnt(" #n ")" ::: "memory")
; template <class Epi, class Sched, bool ALIGN_EPI = true, bool SP2 = true, bool FULLLINE = false, bool NOSTAGE = false, bool FP8 = false>
; __device__ __forceinline__ void gemm_phase(PG8_LAS unsigned char* lds, const Gemm g, const Sched& S, const Epi& E) {
;     ...
;         static_assert(SP2, "only the SP2 loop is kept");
;         { const int t = 0; if constexpr (Epi::NST == 16) PG8_ITER(PG8_WAIT_V(24)); else if constexpr (Epi::NST == 8) PG8_ITER(PG8_WAIT_V(16)); else PG8_ITER(PG8_WAIT_V(8)); }
;         for (int t = 2; t < nt; t += 2) PG8_ITER(PG8_WAIT_V(8));
	s_nop 5
	ds_read_b128 v[6:9], v144
	ds_read_b128 v[26:29], v144 offset:1024
	ds_read_b128 v[30:33], v144 offset:2048
	ds_read_b128 v[62:65], v144 offset:3072
	ds_read_b128 v[198:201], v145
	ds_read_b128 v[202:205], v145 offset:1024
	ds_read_b128 v[206:209], v145 offset:2048
	ds_read_b128 v[210:213], v145 offset:3072
	s_mov_b32 m0, s55
	v_lshl_add_u64 v[86:87], v[140:141], 0, s[20:21]
	ds_read_b128 v[18:21], v143 offset:32768
	ds_read_b128 v[22:25], v143 offset:33792
	ds_read_b128 v[214:217], v143 offset:34816
	ds_read_b128 v[218:221], v143 offset:35840
	ds_read_b128 v[222:225], v143 offset:36864
	ds_read_b128 v[226:229], v143 offset:37888
	ds_read_b128 v[230:233], v143 offset:38912
	ds_read_b128 v[234:237], v143 offset:39936
	global_load_lds_dwordx4 v[86:87], off
	v_lshl_add_u64 v[86:87], v[140:141], 0, s[22:23]
	s_mov_b32 m0, s67
	s_nop 0
	global_load_lds_dwordx4 v[86:87], off
	s_waitcnt vmcnt(8)
	s_waitcnt lgkmcnt(0)
	s_barrier
	s_waitcnt lgkmcnt(0)
	s_setprio 1
	v_mfma_f32_16x16x32_bf16 v[66:69], v[6:9], v[18:21], v[66:69]
	v_mfma_f32_16x16x32_bf16 v[118:121], v[26:29], v[22:25], v[66:69]
	v_mfma_f32_16x16x32_bf16 v[66:69], v[30:33], v[18:21], v[70:73]
	v_mfma_f32_16x16x32_bf16 v[114:117], v[62:65], v[22:25], v[66:69]
	v_mfma_f32_16x16x32_bf16 v[66:69], v[6:9], v[214:217], v[74:77]
	v_mfma_f32_16x16x32_bf16 v[102:105], v[26:29], v[218:221], v[66:69]
	v_mfma_f32_16x16x32_bf16 v[66:69], v[30:33], v[214:217], v[78:81]
	v_mfma_f32_16x16x32_bf16 v[98:101], v[62:65], v[218:221], v[66:69]
	v_mfma_f32_16x16x32_bf16 v[66:69], v[6:9], v[222:225], v[82:85]
	v_mfma_f32_16x16x32_bf16 v[86:89], v[26:29], v[226:229], v[66:69]
	v_mfma_f32_16x16x32_bf16 v[66:69], v[30:33], v[222:225], v[90:93]
	v_mfma_f32_16x16x32_bf16 v[82:85], v[62:65], v[226:229], v[66:69]
	v_mfma_f32_16x16x32_bf16 v[66:69], v[6:9], v[230:233], v[94:97]
	v_mfma_f32_16x16x32_bf16 v[70:73], v[26:29], v[234:237], v[66:69]
	v_mfma_f32_16x16x32_bf16 v[66:69], v[30:33], v[230:233], v[106:109]
	v_mfma_f32_16x16x32_bf16 v[66:69], v[62:65], v[234:237], v[66:69]
	v_mfma_f32_16x16x32_bf16 v[74:77], v[198:201], v[18:21], v[110:113]
	v_mfma_f32_16x16x32_bf16 v[18:21], v[206:209], v[18:21], v[34:37]
	v_mfma_f32_16x16x32_bf16 v[122:125], v[210:213], v[22:25], v[18:21]
	v_mfma_f32_16x16x32_bf16 v[18:21], v[198:201], v[214:217], v[38:41]
	v_mfma_f32_16x16x32_bf16 v[110:113], v[202:205], v[218:221], v[18:21]
	v_mfma_f32_16x16x32_bf16 v[18:21], v[206:209], v[214:217], v[42:45]
	v_mfma_f32_16x16x32_bf16 v[106:109], v[210:213], v[218:221], v[18:21]
	v_mfma_f32_16x16x32_bf16 v[18:21], v[198:201], v[222:225], v[46:49]
	v_mfma_f32_16x16x32_bf16 v[94:97], v[202:205], v[226:229], v[18:21]
	v_mfma_f32_16x16x32_bf16 v[18:21], v[206:209], v[222:225], v[50:53]
	v_mfma_f32_16x16x32_bf16 v[90:93], v[210:213], v[226:229], v[18:21]
	v_mfma_f32_16x16x32_bf16 v[18:21], v[198:201], v[230:233], v[54:57]
	v_mfma_f32_16x16x32_bf16 v[78:81], v[202:205], v[234:237], v[18:21]
	v_mfma_f32_16x16x32_bf16 v[18:21], v[206:209], v[230:233], v[58:61]
	v_mfma_f32_16x16x32_bf16 v[126:129], v[202:205], v[22:25], v[74:77]
	v_mfma_f32_16x16x32_bf16 v[74:77], v[210:213], v[234:237], v[18:21]
	s_setprio 0
	s_barrier
	s_add_i32 s50, s82, s43
	s_nop 3
	v_lshl_add_u64 v[18:19], v[238:239], 0, s[24:25]
	s_mov_b32 m0, s50
	s_add_i32 s51, s50, 0x2000
	ds_read_b128 v[42:45], v143 offset:49152
	ds_read_b128 v[46:49], v143 offset:50176
	ds_read_b128 v[214:217], v143 offset:51200
	ds_read_b128 v[218:221], v143 offset:52224
	ds_read_b128 v[222:225], v143 offset:53248
	ds_read_b128 v[226:229], v143 offset:54272
	ds_read_b128 v[230:233], v143 offset:55296
	ds_read_b128 v[234:237], v143 offset:56320
	global_load_lds_dwordx4 v[18:19], off
	v_lshl_add_u64 v[18:19], v[238:239], 0, s[26:27]
	s_mov_b32 m0, s51
	s_mov_b64 s[0:1], 0x80180
	s_add_i32 s33, s83, s43
	global_load_lds_dwordx4 v[18:19], off
	v_lshl_add_u64 v[18:19], v[238:239], 0, s[0:1]
	s_mov_b32 m0, s33
	s_mov_b64 s[0:1], 0xc0180
	s_add_i32 s56, s33, 0x2000
	global_load_lds_dwordx4 v[18:19], off
	v_lshl_add_u64 v[18:19], v[238:239], 0, s[0:1]
	s_mov_b32 m0, s56
	s_nop 0
	global_load_lds_dwordx4 v[18:19], off
	v_lshl_add_u64 v[18:19], v[140:141], 0, s[24:25]
	s_mov_b32 m0, s72
	s_nop 0
	global_load_lds_dwordx4 v[18:19], off
	v_lshl_add_u64 v[18:19], v[140:141], 0, s[26:27]
	s_mov_b32 m0, s73
	s_nop 0
	global_load_lds_dwordx4 v[18:19], off
	s_waitcnt vmcnt(8)
	s_waitcnt lgkmcnt(0)
	s_barrier
	s_waitcnt lgkmcnt(0)
	s_setprio 1
	v_mfma_f32_16x16x32_bf16 v[18:21], v[6:9], v[42:45], v[146:149]
	v_mfma_f32_16x16x32_bf16 v[54:57], v[26:29], v[46:49], v[18:21]
	v_mfma_f32_16x16x32_bf16 v[18:21], v[30:33], v[42:45], v[150:153]
	v_mfma_f32_16x16x32_bf16 v[50:53], v[62:65], v[46:49], v[18:21]
	v_mfma_f32_16x16x32_bf16 v[18:21], v[6:9], v[214:217], v[154:157]
	v_mfma_f32_16x16x32_bf16 v[38:41], v[26:29], v[218:221], v[18:21]
	v_mfma_f32_16x16x32_bf16 v[18:21], v[30:33], v[214:217], v[158:161]
	v_mfma_f32_16x16x32_bf16 v[34:37], v[62:65], v[218:221], v[18:21]
	v_mfma_f32_16x16x32_bf16 v[18:21], v[6:9], v[222:225], v[162:165]
	v_mfma_f32_16x16x32_bf16 v[2:5], v[6:9], v[230:233], v[2:5]
	v_mfma_f32_16x16x32_bf16 v[22:25], v[26:29], v[226:229], v[18:21]
	v_mfma_f32_16x16x32_bf16 v[18:21], v[30:33], v[222:225], v[166:169]
	v_mfma_f32_16x16x32_bf16 v[6:9], v[26:29], v[234:237], v[2:5]
	v_mfma_f32_16x16x32_bf16 v[2:5], v[30:33], v[230:233], v[10:13]
	v_mfma_f32_16x16x32_bf16 v[18:21], v[62:65], v[226:229], v[18:21]
	v_mfma_f32_16x16x32_bf16 v[2:5], v[62:65], v[234:237], v[2:5]
	v_mfma_f32_16x16x32_bf16 v[10:13], v[198:201], v[42:45], v[14:17]
	v_mfma_f32_16x16x32_bf16 v[62:65], v[202:205], v[46:49], v[10:13]
	v_mfma_f32_16x16x32_bf16 v[10:13], v[206:209], v[42:45], v[170:173]
	v_mfma_f32_16x16x32_bf16 v[58:61], v[210:213], v[46:49], v[10:13]
	v_mfma_f32_16x16x32_bf16 v[10:13], v[198:201], v[214:217], v[174:177]
	v_mfma_f32_16x16x32_bf16 v[46:49], v[202:205], v[218:221], v[10:13]
	v_mfma_f32_16x16x32_bf16 v[10:13], v[206:209], v[214:217], v[178:181]
	v_mfma_f32_16x16x32_bf16 v[42:45], v[210:213], v[218:221], v[10:13]
	v_mfma_f32_16x16x32_bf16 v[10:13], v[198:201], v[222:225], v[182:185]
	v_mfma_f32_16x16x32_bf16 v[30:33], v[202:205], v[226:229], v[10:13]
	v_mfma_f32_16x16x32_bf16 v[10:13], v[206:209], v[222:225], v[186:189]
	v_mfma_f32_16x16x32_bf16 v[26:29], v[210:213], v[226:229], v[10:13]
	v_mfma_f32_16x16x32_bf16 v[10:13], v[198:201], v[230:233], v[190:193]
	v_mfma_f32_16x16x32_bf16 v[14:17], v[202:205], v[234:237], v[10:13]
	v_mfma_f32_16x16x32_bf16 v[10:13], v[206:209], v[230:233], v[194:197]
	v_mfma_f32_16x16x32_bf16 v[10:13], v[210:213], v[234:237], v[10:13]
	s_setprio 0
	s_barrier
	s_add_u32 s70, s70, 0x80180
	s_addc_u32 s71, s71, 0
	s_add_u32 s57, s68, 0x200
	s_addc_u32 s68, s69, 0
	s_mov_b32 s69, 0
.LBB0_2862:
	ds_read_b128 v[146:149], v1
	ds_read_b128 v[150:153], v1 offset:1024
	ds_read_b128 v[154:157], v1 offset:2048
	ds_read_b128 v[158:161], v1 offset:3072
	ds_read_b128 v[162:165], v142
	ds_read_b128 v[166:169], v142 offset:1024
	ds_read_b128 v[170:173], v142 offset:2048
	ds_read_b128 v[174:177], v142 offset:3072
	s_add_u32 s0, s70, 0xfff80080
	s_addc_u32 s1, s71, -1
	s_cmp_eq_u32 s69, 28
	s_cselect_b32 s1, s41, s1
	s_cselect_b32 s0, s45, s0
	s_cselect_b32 s65, s87, s68
	s_cselect_b32 s64, s88, s57
	s_mov_b32 m0, s79
	v_lshl_add_u64 v[140:141], s[70:71], 0, v[134:135]
	ds_read_b128 v[178:181], v143
	ds_read_b128 v[182:185], v143 offset:1024
	ds_read_b128 v[186:189], v143 offset:2048
	ds_read_b128 v[190:193], v143 offset:3072
	ds_read_b128 v[194:197], v143 offset:4096
	ds_read_b128 v[198:201], v143 offset:5120
	ds_read_b128 v[202:205], v143 offset:6144
	ds_read_b128 v[206:209], v143 offset:7168
	global_load_lds_dwordx4 v[140:141], off
	v_lshl_add_u64 v[140:141], v[140:141], 0, s[28:29]
	s_mov_b32 m0, s80
	s_nop 0
	global_load_lds_dwordx4 v[140:141], off
	s_waitcnt vmcnt(8)
	s_waitcnt lgkmcnt(0)
	s_barrier
	s_waitcnt lgkmcnt(0)
	s_setprio 1
	v_mfma_f32_16x16x32_bf16 v[118:121], v[146:149], v[178:181], v[118:121]
	v_mfma_f32_16x16x32_bf16 v[114:117], v[154:157], v[178:181], v[114:117]
	v_mfma_f32_16x16x32_bf16 v[102:105], v[146:149], v[186:189], v[102:105]
	v_mfma_f32_16x16x32_bf16 v[98:101], v[154:157], v[186:189], v[98:101]
	v_mfma_f32_16x16x32_bf16 v[86:89], v[146:149], v[194:197], v[86:89]
	v_mfma_f32_16x16x32_bf16 v[82:85], v[154:157], v[194:197], v[82:85]
	v_mfma_f32_16x16x32_bf16 v[70:73], v[146:149], v[202:205], v[70:73]
	v_mfma_f32_16x16x32_bf16 v[66:69], v[154:157], v[202:205], v[66:69]
	v_mfma_f32_16x16x32_bf16 v[118:121], v[150:153], v[182:185], v[118:121]
	v_mfma_f32_16x16x32_bf16 v[114:117], v[158:161], v[182:185], v[114:117]
	v_mfma_f32_16x16x32_bf16 v[102:105], v[150:153], v[190:193], v[102:105]
	v_mfma_f32_16x16x32_bf16 v[98:101], v[158:161], v[190:193], v[98:101]
	v_mfma_f32_16x16x32_bf16 v[86:89], v[150:153], v[198:201], v[86:89]
	v_mfma_f32_16x16x32_bf16 v[82:85], v[158:161], v[198:201], v[82:85]
	v_mfma_f32_16x16x32_bf16 v[70:73], v[150:153], v[206:209], v[70:73]
	v_mfma_f32_16x16x32_bf16 v[66:69], v[158:161], v[206:209], v[66:69]
	v_mfma_f32_16x16x32_bf16 v[126:129], v[162:165], v[178:181], v[126:129]
	v_mfma_f32_16x16x32_bf16 v[122:125], v[170:173], v[178:181], v[122:125]
	v_mfma_f32_16x16x32_bf16 v[110:113], v[162:165], v[186:189], v[110:113]
	v_mfma_f32_16x16x32_bf16 v[106:109], v[170:173], v[186:189], v[106:109]
	v_mfma_f32_16x16x32_bf16 v[94:97], v[162:165], v[194:197], v[94:97]
	v_mfma_f32_16x16x32_bf16 v[90:93], v[170:173], v[194:197], v[90:93]
	v_mfma_f32_16x16x32_bf16 v[78:81], v[162:165], v[202:205], v[78:81]
	v_mfma_f32_16x16x32_bf16 v[74:77], v[170:173], v[202:205], v[74:77]
	v_mfma_f32_16x16x32_bf16 v[126:129], v[166:169], v[182:185], v[126:129]
	v_mfma_f32_16x16x32_bf16 v[122:125], v[174:177], v[182:185], v[122:125]
	v_mfma_f32_16x16x32_bf16 v[110:113], v[166:169], v[190:193], v[110:113]
	v_mfma_f32_16x16x32_bf16 v[106:109], v[174:177], v[190:193], v[106:109]
	v_mfma_f32_16x16x32_bf16 v[94:97], v[166:169], v[198:201], v[94:97]
	v_mfma_f32_16x16x32_bf16 v[90:93], v[174:177], v[198:201], v[90:93]
	v_mfma_f32_16x16x32_bf16 v[78:81], v[166:169], v[206:209], v[78:81]
	v_mfma_f32_16x16x32_bf16 v[74:77], v[174:177], v[206:209], v[74:77]
	s_setprio 0
	s_barrier
	s_mov_b32 m0, s81
	v_lshl_add_u64 v[140:141], s[64:65], 0, v[130:131]
	ds_read_b128 v[178:181], v143 offset:16384
	ds_read_b128 v[182:185], v143 offset:17408
	ds_read_b128 v[186:189], v143 offset:18432
	ds_read_b128 v[190:193], v143 offset:19456
	ds_read_b128 v[194:197], v143 offset:20480
	ds_read_b128 v[198:201], v143 offset:21504
	ds_read_b128 v[202:205], v143 offset:22528
	ds_read_b128 v[206:209], v143 offset:23552
	global_load_lds_dwordx4 v[140:141], off
	v_lshl_add_u64 v[210:211], v[140:141], 0, s[28:29]
	s_mov_b32 m0, s89
	s_nop 0
	global_load_lds_dwordx4 v[210:211], off
	v_lshl_add_u64 v[210:211], v[140:141], 0, s[30:31]
	s_mov_b32 m0, s90
	s_nop 0
	global_load_lds_dwordx4 v[210:211], off
	v_lshl_add_u64 v[210:211], v[140:141], 0, s[34:35]
	s_mov_b32 m0, s91
	s_nop 0
	global_load_lds_dwordx4 v[210:211], off
	v_lshl_add_u64 v[210:211], s[0:1], 0, v[132:133]
	s_mov_b32 m0, s53
	v_lshl_add_u64 v[212:213], v[210:211], 0, s[28:29]
	global_load_lds_dwordx4 v[210:211], off
	s_mov_b32 m0, s54
	s_nop 0
	global_load_lds_dwordx4 v[212:213], off
	s_waitcnt vmcnt(8)
	s_waitcnt lgkmcnt(0)
	s_barrier
	s_waitcnt lgkmcnt(0)
	s_setprio 1
	v_mfma_f32_16x16x32_bf16 v[54:57], v[146:149], v[178:181], v[54:57]
	v_mfma_f32_16x16x32_bf16 v[50:53], v[154:157], v[178:181], v[50:53]
	v_mfma_f32_16x16x32_bf16 v[38:41], v[146:149], v[186:189], v[38:41]
	v_mfma_f32_16x16x32_bf16 v[34:37], v[154:157], v[186:189], v[34:37]
	v_mfma_f32_16x16x32_bf16 v[22:25], v[146:149], v[194:197], v[22:25]
	v_mfma_f32_16x16x32_bf16 v[18:21], v[154:157], v[194:197], v[18:21]
	v_mfma_f32_16x16x32_bf16 v[6:9], v[146:149], v[202:205], v[6:9]
	v_mfma_f32_16x16x32_bf16 v[2:5], v[154:157], v[202:205], v[2:5]
	v_mfma_f32_16x16x32_bf16 v[54:57], v[150:153], v[182:185], v[54:57]
	v_mfma_f32_16x16x32_bf16 v[50:53], v[158:161], v[182:185], v[50:53]
	v_mfma_f32_16x16x32_bf16 v[38:41], v[150:153], v[190:193], v[38:41]
	v_mfma_f32_16x16x32_bf16 v[34:37], v[158:161], v[190:193], v[34:37]
	v_mfma_f32_16x16x32_bf16 v[22:25], v[150:153], v[198:201], v[22:25]
	v_mfma_f32_16x16x32_bf16 v[18:21], v[158:161], v[198:201], v[18:21]
	v_mfma_f32_16x16x32_bf16 v[6:9], v[150:153], v[206:209], v[6:9]
	v_mfma_f32_16x16x32_bf16 v[2:5], v[158:161], v[206:209], v[2:5]
	v_mfma_f32_16x16x32_bf16 v[62:65], v[162:165], v[178:181], v[62:65]
	v_mfma_f32_16x16x32_bf16 v[58:61], v[170:173], v[178:181], v[58:61]
	v_mfma_f32_16x16x32_bf16 v[46:49], v[162:165], v[186:189], v[46:49]
	v_mfma_f32_16x16x32_bf16 v[42:45], v[170:173], v[186:189], v[42:45]
	v_mfma_f32_16x16x32_bf16 v[30:33], v[162:165], v[194:197], v[30:33]
	v_mfma_f32_16x16x32_bf16 v[26:29], v[170:173], v[194:197], v[26:29]
	v_mfma_f32_16x16x32_bf16 v[14:17], v[162:165], v[202:205], v[14:17]
	v_mfma_f32_16x16x32_bf16 v[10:13], v[170:173], v[202:205], v[10:13]
	v_mfma_f32_16x16x32_bf16 v[62:65], v[166:169], v[182:185], v[62:65]
	v_mfma_f32_16x16x32_bf16 v[58:61], v[174:177], v[182:185], v[58:61]
	v_mfma_f32_16x16x32_bf16 v[46:49], v[166:169], v[190:193], v[46:49]
	v_mfma_f32_16x16x32_bf16 v[42:45], v[174:177], v[190:193], v[42:45]
	v_mfma_f32_16x16x32_bf16 v[30:33], v[166:169], v[198:201], v[30:33]
	v_mfma_f32_16x16x32_bf16 v[26:29], v[174:177], v[198:201], v[26:29]
	v_mfma_f32_16x16x32_bf16 v[14:17], v[166:169], v[206:209], v[14:17]
	v_mfma_f32_16x16x32_bf16 v[10:13], v[174:177], v[206:209], v[10:13]
	s_setprio 0
	s_barrier
	ds_read_b128 v[146:149], v144
	ds_read_b128 v[150:153], v144 offset:1024
	ds_read_b128 v[154:157], v144 offset:2048
	ds_read_b128 v[158:161], v144 offset:3072
	ds_read_b128 v[162:165], v145
	ds_read_b128 v[166:169], v145 offset:1024
	ds_read_b128 v[170:173], v145 offset:2048
	ds_read_b128 v[174:177], v145 offset:3072
	s_mov_b32 m0, s55
	v_lshl_add_u64 v[212:213], v[210:211], 0, s[30:31]
	ds_read_b128 v[178:181], v143 offset:32768
	ds_read_b128 v[182:185], v143 offset:33792
	ds_read_b128 v[186:189], v143 offset:34816
	ds_read_b128 v[190:193], v143 offset:35840
	ds_read_b128 v[194:197], v143 offset:36864
	ds_read_b128 v[198:201], v143 offset:37888
	ds_read_b128 v[202:205], v143 offset:38912
	ds_read_b128 v[206:209], v143 offset:39936
	global_load_lds_dwordx4 v[212:213], off
	v_lshl_add_u64 v[212:213], v[210:211], 0, s[34:35]
	s_mov_b32 m0, s67
	s_nop 0
	global_load_lds_dwordx4 v[212:213], off
	s_waitcnt vmcnt(8)
	s_waitcnt lgkmcnt(0)
	s_barrier
	s_waitcnt lgkmcnt(0)
	s_setprio 1
	v_mfma_f32_16x16x32_bf16 v[118:121], v[146:149], v[178:181], v[118:121]
	v_mfma_f32_16x16x32_bf16 v[114:117], v[154:157], v[178:181], v[114:117]
	v_mfma_f32_16x16x32_bf16 v[102:105], v[146:149], v[186:189], v[102:105]
	v_mfma_f32_16x16x32_bf16 v[98:101], v[154:157], v[186:189], v[98:101]
	v_mfma_f32_16x16x32_bf16 v[86:89], v[146:149], v[194:197], v[86:89]
	v_mfma_f32_16x16x32_bf16 v[82:85], v[154:157], v[194:197], v[82:85]
	v_mfma_f32_16x16x32_bf16 v[70:73], v[146:149], v[202:205], v[70:73]
	v_mfma_f32_16x16x32_bf16 v[66:69], v[154:157], v[202:205], v[66:69]
	v_mfma_f32_16x16x32_bf16 v[118:121], v[150:153], v[182:185], v[118:121]
	v_mfma_f32_16x16x32_bf16 v[114:117], v[158:161], v[182:185], v[114:117]
	v_mfma_f32_16x16x32_bf16 v[102:105], v[150:153], v[190:193], v[102:105]
	v_mfma_f32_16x16x32_bf16 v[98:101], v[158:161], v[190:193], v[98:101]
	v_mfma_f32_16x16x32_bf16 v[86:89], v[150:153], v[198:201], v[86:89]
	v_mfma_f32_16x16x32_bf16 v[82:85], v[158:161], v[198:201], v[82:85]
	v_mfma_f32_16x16x32_bf16 v[70:73], v[150:153], v[206:209], v[70:73]
	v_mfma_f32_16x16x32_bf16 v[66:69], v[158:161], v[206:209], v[66:69]
	v_mfma_f32_16x16x32_bf16 v[126:129], v[162:165], v[178:181], v[126:129]
	v_mfma_f32_16x16x32_bf16 v[122:125], v[170:173], v[178:181], v[122:125]
	v_mfma_f32_16x16x32_bf16 v[110:113], v[162:165], v[186:189], v[110:113]
	v_mfma_f32_16x16x32_bf16 v[106:109], v[170:173], v[186:189], v[106:109]
	v_mfma_f32_16x16x32_bf16 v[94:97], v[162:165], v[194:197], v[94:97]
	v_mfma_f32_16x16x32_bf16 v[90:93], v[170:173], v[194:197], v[90:93]
	v_mfma_f32_16x16x32_bf16 v[78:81], v[162:165], v[202:205], v[78:81]
	v_mfma_f32_16x16x32_bf16 v[74:77], v[170:173], v[202:205], v[74:77]
	v_mfma_f32_16x16x32_bf16 v[126:129], v[166:169], v[182:185], v[126:129]
	v_mfma_f32_16x16x32_bf16 v[122:125], v[174:177], v[182:185], v[122:125]
	v_mfma_f32_16x16x32_bf16 v[110:113], v[166:169], v[190:193], v[110:113]
	v_mfma_f32_16x16x32_bf16 v[106:109], v[174:177], v[190:193], v[106:109]
	v_mfma_f32_16x16x32_bf16 v[94:97], v[166:169], v[198:201], v[94:97]
	v_mfma_f32_16x16x32_bf16 v[90:93], v[174:177], v[198:201], v[90:93]
	v_mfma_f32_16x16x32_bf16 v[78:81], v[166:169], v[206:209], v[78:81]
	v_mfma_f32_16x16x32_bf16 v[74:77], v[174:177], v[206:209], v[74:77]
	s_setprio 0
	s_barrier
; #define PG8_WAIT_V(n) asm volatile("s_waitcnt vmcnt(" #n ")" ::: "memory")
; #define PG8_BAR __builtin_amdgcn_s_barrier()
; template <class Epi, class Sched, bool ALIGN_EPI = true, bool SP2 = true, bool FULLLINE = false, bool NOSTAGE = false, bool FP8 = false>
; __device__ __forceinline__ void gemm_phase(PG8_LAS unsigned char* lds, const Gemm g, const Sched& S, const Epi& E) {
;     ...
;         static_assert(SP2, "only the SP2 loop is kept");
;         { const int t = 0; if constexpr (Epi::NST == 16) PG8_ITER(PG8_WAIT_V(24)); else if constexpr (Epi::NST == 8) PG8_ITER(PG8_WAIT_V(16)); else PG8_ITER(PG8_WAIT_V(8)); }
;         for (int t = 2; t < nt; t += 2) PG8_ITER(PG8_WAIT_V(8));
;     ...
;         if constexpr (ALIGN_EPI) { if (wr == 0) PG8_BAR; }
	s_mov_b32 m0, s50
	v_lshl_add_u64 v[212:213], v[140:141], 0, s[36:37]
	ds_read_b128 v[178:181], v143 offset:49152
	ds_read_b128 v[182:185], v143 offset:50176
	ds_read_b128 v[186:189], v143 offset:51200
	ds_read_b128 v[190:193], v143 offset:52224
	ds_read_b128 v[194:197], v143 offset:53248
	ds_read_b128 v[198:201], v143 offset:54272
	ds_read_b128 v[202:205], v143 offset:55296
	ds_read_b128 v[206:209], v143 offset:56320
	global_load_lds_dwordx4 v[212:213], off
	v_lshl_add_u64 v[212:213], v[140:141], 0, s[38:39]
	s_mov_b32 m0, s51
	s_nop 0
	global_load_lds_dwordx4 v[212:213], off
	v_lshl_add_u64 v[212:213], v[140:141], 0, s[12:13]
	s_mov_b32 m0, s33
	v_lshl_add_u64 v[140:141], v[140:141], 0, s[14:15]
	global_load_lds_dwordx4 v[212:213], off
	s_mov_b32 m0, s56
	s_nop 0
	global_load_lds_dwordx4 v[140:141], off
	v_lshl_add_u64 v[140:141], v[210:211], 0, s[36:37]
	s_mov_b32 m0, s72
	s_nop 0
	global_load_lds_dwordx4 v[140:141], off
	v_lshl_add_u64 v[140:141], v[210:211], 0, s[38:39]
	s_mov_b32 m0, s73
	s_nop 0
	global_load_lds_dwordx4 v[140:141], off
	s_waitcnt vmcnt(8)
	s_waitcnt lgkmcnt(0)
	s_barrier
	s_waitcnt lgkmcnt(0)
	s_setprio 1
	v_mfma_f32_16x16x32_bf16 v[54:57], v[146:149], v[178:181], v[54:57]
	v_mfma_f32_16x16x32_bf16 v[50:53], v[154:157], v[178:181], v[50:53]
	v_mfma_f32_16x16x32_bf16 v[38:41], v[146:149], v[186:189], v[38:41]
	v_mfma_f32_16x16x32_bf16 v[34:37], v[154:157], v[186:189], v[34:37]
	v_mfma_f32_16x16x32_bf16 v[22:25], v[146:149], v[194:197], v[22:25]
	v_mfma_f32_16x16x32_bf16 v[18:21], v[154:157], v[194:197], v[18:21]
	v_mfma_f32_16x16x32_bf16 v[6:9], v[146:149], v[202:205], v[6:9]
	v_mfma_f32_16x16x32_bf16 v[2:5], v[154:157], v[202:205], v[2:5]
	v_mfma_f32_16x16x32_bf16 v[54:57], v[150:153], v[182:185], v[54:57]
	v_mfma_f32_16x16x32_bf16 v[50:53], v[158:161], v[182:185], v[50:53]
	v_mfma_f32_16x16x32_bf16 v[38:41], v[150:153], v[190:193], v[38:41]
	v_mfma_f32_16x16x32_bf16 v[34:37], v[158:161], v[190:193], v[34:37]
	v_mfma_f32_16x16x32_bf16 v[22:25], v[150:153], v[198:201], v[22:25]
	v_mfma_f32_16x16x32_bf16 v[18:21], v[158:161], v[198:201], v[18:21]
	v_mfma_f32_16x16x32_bf16 v[6:9], v[150:153], v[206:209], v[6:9]
	v_mfma_f32_16x16x32_bf16 v[2:5], v[158:161], v[206:209], v[2:5]
	v_mfma_f32_16x16x32_bf16 v[62:65], v[162:165], v[178:181], v[62:65]
	v_mfma_f32_16x16x32_bf16 v[58:61], v[170:173], v[178:181], v[58:61]
	v_mfma_f32_16x16x32_bf16 v[46:49], v[162:165], v[186:189], v[46:49]
	v_mfma_f32_16x16x32_bf16 v[42:45], v[170:173], v[186:189], v[42:45]
	v_mfma_f32_16x16x32_bf16 v[30:33], v[162:165], v[194:197], v[30:33]
	v_mfma_f32_16x16x32_bf16 v[26:29], v[170:173], v[194:197], v[26:29]
	v_mfma_f32_16x16x32_bf16 v[14:17], v[162:165], v[202:205], v[14:17]
	v_mfma_f32_16x16x32_bf16 v[10:13], v[170:173], v[202:205], v[10:13]
	v_mfma_f32_16x16x32_bf16 v[62:65], v[166:169], v[182:185], v[62:65]
	v_mfma_f32_16x16x32_bf16 v[58:61], v[174:177], v[182:185], v[58:61]
	v_mfma_f32_16x16x32_bf16 v[46:49], v[166:169], v[190:193], v[46:49]
	v_mfma_f32_16x16x32_bf16 v[42:45], v[174:177], v[190:193], v[42:45]
	v_mfma_f32_16x16x32_bf16 v[30:33], v[166:169], v[198:201], v[30:33]
	v_mfma_f32_16x16x32_bf16 v[26:29], v[174:177], v[198:201], v[26:29]
	v_mfma_f32_16x16x32_bf16 v[14:17], v[166:169], v[206:209], v[14:17]
	v_mfma_f32_16x16x32_bf16 v[10:13], v[174:177], v[206:209], v[10:13]
	s_setprio 0
	s_barrier
	s_add_i32 s69, s69, 2
	s_add_u32 s70, s70, 0x100
	s_addc_u32 s71, s71, 0
	s_add_u32 s57, s57, 0x100
	s_addc_u32 s68, s68, 0
	s_cmp_gt_u32 s69, 29
	s_cbranch_scc0 .LBB0_2862
	s_and_b64 vcc, exec, s[10:11]
	s_cbranch_vccz .LBB0_2865
	s_barrier

; #define PG8_STAGE(bufoff, gbase, voff) do { if constexpr (!NOSTAGE) _Pragma("unroll") for (int _i = 0; _i < 2; ++_i) \
;         __builtin_amdgcn_global_load_lds((const unsigned*)((const char*)(gbase) + (size_t)_i * pstep##voff + v##voff), (PG8_LAS unsigned*)(lds + (bufoff) + ldsw + _i * 8192), 16, 0, 0); } while (0)
; #define PG8_WAIT_V(n) asm volatile("s_waitcnt vmcnt(" #n ")" ::: "memory")
; #define PG8_BAR __builtin_amdgcn_s_barrier()
; template <class Epi, class Sched, bool ALIGN_EPI = true, bool SP2 = true, bool FULLLINE = false, bool NOSTAGE = false, bool FP8 = false>
; __device__ __forceinline__ void gemm_phase(PG8_LAS unsigned char* lds, const Gemm g, const Sched& S, const Epi& E) {
;     const int tid = threadIdx.x, wid = __builtin_amdgcn_readfirstlane(tid >> 6), lane = tid & 63, wr = wid >> 2, wc = wid & 3, fr = lane & 15, fq = lane >> 4;
;     const int K = g.K, nt = K / BK;
;     unsigned voffA_, voffB_;
;     { int R, C; stage_rc(tid * 16, R, C); const int Rb = Epi::PERM ? ((R & ~31) + perm32(R & 31)) : R;
;       voffA_ = (unsigned)(R * g.lda + C) * 2u; voffB_ = (unsigned)(Rb * g.ldb + C) * 2u; }
;     const unsigned voffA = voffA_, voffB = voffB_;
;     const size_t pstepoffA = (size_t)64 * g.lda * 2, pstepoffB = (size_t)64 * g.ldb * 2;
;     const size_t kstep = (size_t)(BK * 2);
;     const size_t hstepA = (size_t)HALF * g.lda * 2, hstepB = (size_t)HALF * g.ldb * 2;
;     const size_t tstepA = 2 * hstepA, tstepB = 2 * hstepB;
;     const unsigned ldsw = (unsigned)wid * 1024u;
;     const int aoff = lds_byte(wr * 64 + fr, fq * 8), boff = lds_byte(wc * 32 + fr, fq * 8);
;     ...
;     if (wr == 1) PG8_BAR;
;     PG8_WAIT_V(0); PG8_BAR;
;     PG8_BAR;
;     } else {
;     PG8_STAGE(PG8_SB(0, 0), cB, offB); PG8_STAGE(PG8_SA(0, 0), cA, offA); PG8_STAGE(PG8_SB(0, 1), cB + hstepB, offB); PG8_STAGE(PG8_SA(0, 1), cA + hstepA, offA);
;     if (wr == 1) PG8_BAR;
;     PG8_WAIT_V(4); PG8_BAR;
;     PG8_STAGE(PG8_SB(1, 0), cB + kstep, offB); PG8_STAGE(PG8_SA(1, 0), cA + kstep, offA); PG8_STAGE(PG8_SB(1, 1), cB + hstepB + kstep, offB);
;     PG8_WAIT_V(6); PG8_BAR;
;     }
;     if (wr == 1) __builtin_amdgcn_s_setprio(1);
.LBB0_2949:
	s_waitcnt vmcnt(0)
	v_cndmask_b32_e64 v4, 0, 1, s[8:9]
	s_lshr_b32 s13, s6, 3
	v_cmp_ne_u32_e64 s[6:7], 1, v4
	s_andn2_b64 vcc, exec, s[8:9]
	s_barrier
	s_barrier
	s_cbranch_vccnz .LBB0_2951
.LBB0_2951:
	v_and_b32_e32 v4, 48, v0
	v_lshlrev_b32_e32 v5, 6, v0
	s_movk_i32 s1, 0x3c0
	s_add_u32 s67, s48, 0x22a000
	v_and_or_b32 v4, v5, s1, v4
	v_lshlrev_b32_e32 v5, 2, v0
	s_addc_u32 s68, s49, 0
	s_lshl_b32 s0, s12, 13
	v_and_b32_e32 v5, 32, v5
	v_bitop3_b32 v6, v4, s0, v5 bitop3:0xde
	s_lshl_b32 s0, s11, 5
	s_and_b32 s70, s0, 0x60
	s_lshl_b32 s69, s12, 6
	s_lshl_b32 s0, s70, 7
	s_cmpk_lt_u32 s10, 0x100
	v_add_u16_e32 v1, v1, v2
	s_sext_i32_i8 s80, s13
	v_bitop3_b32 v4, s0, v4, v5 bitop3:0xf6
	s_cselect_b64 s[12:13], -1, 0
	v_lshrrev_b16_e32 v1, 1, v1
	s_add_i32 s73, 0, 0x10000
	s_add_i32 s74, 0, 0x14000
	s_add_i32 s75, 0, 0x18000
	s_add_i32 s76, 0, 0x1c000
	s_ashr_i32 s71, s86, 31
	v_add_lshl_u32 v154, v3, v1, 1
	v_mov_b32_e32 v155, 0
	s_mov_b32 s72, 0
	v_mov_b64_e32 v[156:157], 0x200
	v_mov_b64_e32 v[158:159], 0x1ff
	v_add_u32_e32 v1, s73, v4
	v_add_u32_e32 v168, s74, v4
	v_add_u32_e32 v169, 0, v6
	s_mov_b64 s[14:15], 0x160080
	s_mov_b64 s[16:17], 0x210080
	s_mov_b64 s[18:19], 0x100
	s_mov_b64 s[20:21], 0xb0100
	s_mov_b64 s[22:23], 0x160100
	s_mov_b64 s[24:25], 0x210100
	v_add_u32_e32 v170, s75, v4
	v_add_u32_e32 v171, s76, v4
	s_mov_b64 s[26:27], 0x180
	s_mov_b64 s[28:29], 0xb0180
	s_mov_b64 s[30:31], 0xb0000
	s_mov_b64 s[34:35], 0x160000
	s_mov_b64 s[36:37], 0x210000
	s_mov_b64 s[38:39], 0x80
	s_mov_b64 s[40:41], 0xb0080
	s_branch .LBB0_2954

.LBB0_2964:
	ds_read_b128 v[2:5], v1
	ds_read_b128 v[6:9], v1 offset:1024
	ds_read_b128 v[10:13], v1 offset:2048
	ds_read_b128 v[14:17], v1 offset:3072
	ds_read_b128 v[18:21], v168
	ds_read_b128 v[22:25], v168 offset:1024
	ds_read_b128 v[26:29], v168 offset:2048
	ds_read_b128 v[30:33], v168 offset:3072
	v_lshl_add_u64 v[244:245], s[46:47], 0, v[150:151]
	s_add_i32 s81, s53, 0xc000
	v_lshl_add_u64 v[66:67], v[244:245], 0, s[14:15]
	s_mov_b32 m0, s81
	s_add_i32 s82, s53, 0xe000
	ds_read_b128 v[34:37], v169
	ds_read_b128 v[38:41], v169 offset:1024
	ds_read_b128 v[42:45], v169 offset:2048
	ds_read_b128 v[46:49], v169 offset:3072
	ds_read_b128 v[50:53], v169 offset:4096
	ds_read_b128 v[54:57], v169 offset:5120
	ds_read_b128 v[58:61], v169 offset:6144
	ds_read_b128 v[62:65], v169 offset:7168
	global_load_lds_dwordx4 v[66:67], off
	v_lshl_add_u64 v[66:67], v[244:245], 0, s[16:17]
	s_mov_b32 m0, s82
	s_nop 0
	global_load_lds_dwordx4 v[66:67], off
	s_waitcnt vmcnt(24)
	s_waitcnt lgkmcnt(0)
	s_barrier
	s_waitcnt lgkmcnt(0)
	s_setprio 1
	v_mfma_f32_16x16x32_bf16 v[66:69], v[2:5], v[34:37], 0
	v_mfma_f32_16x16x32_bf16 v[70:73], v[10:13], v[34:37], 0
	v_mfma_f32_16x16x32_bf16 v[74:77], v[2:5], v[42:45], 0
	v_mfma_f32_16x16x32_bf16 v[78:81], v[10:13], v[42:45], 0
	v_mfma_f32_16x16x32_bf16 v[90:93], v[2:5], v[58:61], 0
	v_mfma_f32_16x16x32_bf16 v[66:69], v[6:9], v[38:41], v[66:69]
	v_mfma_f32_16x16x32_bf16 v[70:73], v[14:17], v[38:41], v[70:73]
	v_mfma_f32_16x16x32_bf16 v[74:77], v[6:9], v[46:49], v[74:77]
	v_mfma_f32_16x16x32_bf16 v[78:81], v[14:17], v[46:49], v[78:81]
	v_mfma_f32_16x16x32_bf16 v[82:85], v[2:5], v[50:53], 0
	v_mfma_f32_16x16x32_bf16 v[86:89], v[10:13], v[50:53], 0
	v_mfma_f32_16x16x32_bf16 v[90:93], v[6:9], v[62:65], v[90:93]
	v_mfma_f32_16x16x32_bf16 v[94:97], v[10:13], v[58:61], 0
	v_mfma_f32_16x16x32_bf16 v[82:85], v[6:9], v[54:57], v[82:85]
	v_mfma_f32_16x16x32_bf16 v[86:89], v[14:17], v[54:57], v[86:89]
	v_mfma_f32_16x16x32_bf16 v[94:97], v[14:17], v[62:65], v[94:97]
	v_mfma_f32_16x16x32_bf16 v[98:101], v[18:21], v[34:37], 0
	v_mfma_f32_16x16x32_bf16 v[34:37], v[26:29], v[34:37], 0
	v_mfma_f32_16x16x32_bf16 v[98:101], v[22:25], v[38:41], v[98:101]
	v_mfma_f32_16x16x32_bf16 v[34:37], v[30:33], v[38:41], v[34:37]
	v_mfma_f32_16x16x32_bf16 v[38:41], v[18:21], v[42:45], 0
	v_mfma_f32_16x16x32_bf16 v[42:45], v[26:29], v[42:45], 0
	v_mfma_f32_16x16x32_bf16 v[38:41], v[22:25], v[46:49], v[38:41]
	v_mfma_f32_16x16x32_bf16 v[42:45], v[30:33], v[46:49], v[42:45]
	v_mfma_f32_16x16x32_bf16 v[46:49], v[18:21], v[50:53], 0
	v_mfma_f32_16x16x32_bf16 v[50:53], v[26:29], v[50:53], 0
	v_mfma_f32_16x16x32_bf16 v[46:49], v[22:25], v[54:57], v[46:49]
	v_mfma_f32_16x16x32_bf16 v[50:53], v[30:33], v[54:57], v[50:53]
	v_mfma_f32_16x16x32_bf16 v[54:57], v[18:21], v[58:61], 0
	v_mfma_f32_16x16x32_bf16 v[58:61], v[26:29], v[58:61], 0
	v_mfma_f32_16x16x32_bf16 v[54:57], v[22:25], v[62:65], v[54:57]
	v_mfma_f32_16x16x32_bf16 v[58:61], v[30:33], v[62:65], v[58:61]
	s_setprio 0
	s_barrier
	v_lshl_add_u64 v[246:247], s[58:59], 0, v[152:153]
	s_add_i32 s83, s73, s52
	v_lshl_add_u64 v[130:131], v[246:247], 0, s[18:19]
	s_mov_b32 m0, s83
	s_add_i32 s84, s83, 0x2000
	ds_read_b128 v[62:65], v169 offset:16384
	ds_read_b128 v[102:105], v169 offset:17408
	ds_read_b128 v[106:109], v169 offset:18432
	ds_read_b128 v[110:113], v169 offset:19456
	ds_read_b128 v[114:117], v169 offset:20480
	ds_read_b128 v[118:121], v169 offset:21504
	ds_read_b128 v[122:125], v169 offset:22528
	ds_read_b128 v[126:129], v169 offset:23552
	global_load_lds_dwordx4 v[130:131], off
	v_lshl_add_u64 v[130:131], v[246:247], 0, s[20:21]
	s_mov_b32 m0, s84
	s_add_i32 s85, s74, s52
	global_load_lds_dwordx4 v[130:131], off
	v_lshl_add_u64 v[130:131], v[246:247], 0, s[22:23]
	s_mov_b32 m0, s85
	s_add_i32 s87, s85, 0x2000
	global_load_lds_dwordx4 v[130:131], off
	v_lshl_add_u64 v[130:131], v[246:247], 0, s[24:25]
	s_mov_b32 m0, s87
	s_nop 0
	global_load_lds_dwordx4 v[130:131], off
	v_lshl_add_u64 v[130:131], v[244:245], 0, s[18:19]
	s_mov_b32 m0, s53
	s_nop 0
	global_load_lds_dwordx4 v[130:131], off
	v_lshl_add_u64 v[130:131], v[244:245], 0, s[20:21]
	s_mov_b32 m0, s54
	s_nop 0
	global_load_lds_dwordx4 v[130:131], off
	s_waitcnt vmcnt(24)
	s_waitcnt lgkmcnt(0)
	s_barrier
	s_waitcnt lgkmcnt(0)
	s_setprio 1
	v_mfma_f32_16x16x32_bf16 v[130:133], v[2:5], v[62:65], 0
	v_mfma_f32_16x16x32_bf16 v[146:149], v[6:9], v[102:105], v[130:133]
	v_mfma_f32_16x16x32_bf16 v[130:133], v[10:13], v[62:65], 0
	v_mfma_f32_16x16x32_bf16 v[160:163], v[14:17], v[102:105], v[130:133]
	v_mfma_f32_16x16x32_bf16 v[130:133], v[2:5], v[106:109], 0
	v_mfma_f32_16x16x32_bf16 v[164:167], v[6:9], v[110:113], v[130:133]
	v_mfma_f32_16x16x32_bf16 v[130:133], v[10:13], v[106:109], 0
	v_mfma_f32_16x16x32_bf16 v[172:175], v[14:17], v[110:113], v[130:133]
	v_mfma_f32_16x16x32_bf16 v[130:133], v[2:5], v[114:117], 0
	v_mfma_f32_16x16x32_bf16 v[2:5], v[2:5], v[122:125], 0
	v_mfma_f32_16x16x32_bf16 v[176:179], v[6:9], v[118:121], v[130:133]
	v_mfma_f32_16x16x32_bf16 v[2:5], v[6:9], v[126:129], v[2:5]
	v_mfma_f32_16x16x32_bf16 v[6:9], v[10:13], v[122:125], 0
	v_mfma_f32_16x16x32_bf16 v[130:133], v[10:13], v[114:117], 0
	v_mfma_f32_16x16x32_bf16 v[6:9], v[14:17], v[126:129], v[6:9]
	v_mfma_f32_16x16x32_bf16 v[180:183], v[14:17], v[118:121], v[130:133]
	v_mfma_f32_16x16x32_bf16 v[10:13], v[18:21], v[62:65], 0
	v_mfma_f32_16x16x32_bf16 v[184:187], v[22:25], v[102:105], v[10:13]
	v_mfma_f32_16x16x32_bf16 v[10:13], v[26:29], v[62:65], 0
	v_mfma_f32_16x16x32_bf16 v[102:105], v[30:33], v[102:105], v[10:13]
	v_mfma_f32_16x16x32_bf16 v[10:13], v[18:21], v[106:109], 0
	v_mfma_f32_16x16x32_bf16 v[188:191], v[22:25], v[110:113], v[10:13]
	v_mfma_f32_16x16x32_bf16 v[10:13], v[26:29], v[106:109], 0
	v_mfma_f32_16x16x32_bf16 v[192:195], v[30:33], v[110:113], v[10:13]
	v_mfma_f32_16x16x32_bf16 v[10:13], v[18:21], v[114:117], 0
	v_mfma_f32_16x16x32_bf16 v[196:199], v[22:25], v[118:121], v[10:13]
	v_mfma_f32_16x16x32_bf16 v[10:13], v[26:29], v[114:117], 0
	v_mfma_f32_16x16x32_bf16 v[200:203], v[30:33], v[118:121], v[10:13]
	v_mfma_f32_16x16x32_bf16 v[10:13], v[18:21], v[122:125], 0
	v_mfma_f32_16x16x32_bf16 v[204:207], v[22:25], v[126:129], v[10:13]
	v_mfma_f32_16x16x32_bf16 v[10:13], v[26:29], v[122:125], 0
	v_mfma_f32_16x16x32_bf16 v[208:211], v[30:33], v[126:129], v[10:13]
	s_setprio 0
	s_barrier
; #define PG8_WAIT_V(n) asm volatile("s_waitcnt vmcnt(" #n ")" ::: "memory")
; template <class Epi, class Sched, bool ALIGN_EPI = true, bool SP2 = true, bool FULLLINE = false, bool NOSTAGE = false, bool FP8 = false>
; __device__ __forceinline__ void gemm_phase(PG8_LAS unsigned char* lds, const Gemm g, const Sched& S, const Epi& E) {
;     ...
;         static_assert(SP2, "only the SP2 loop is kept");
;         { const int t = 0; if constexpr (Epi::NST == 16) PG8_ITER(PG8_WAIT_V(24)); else if constexpr (Epi::NST == 8) PG8_ITER(PG8_WAIT_V(16)); else PG8_ITER(PG8_WAIT_V(8)); }
;         for (int t = 2; t < nt; t += 2) PG8_ITER(PG8_WAIT_V(8));
	s_nop 5
	ds_read_b128 v[10:13], v170
	ds_read_b128 v[14:17], v170 offset:1024
	ds_read_b128 v[18:21], v170 offset:2048
	ds_read_b128 v[22:25], v170 offset:3072
	ds_read_b128 v[212:215], v171
	ds_read_b128 v[216:219], v171 offset:1024
	ds_read_b128 v[220:223], v171 offset:2048
	ds_read_b128 v[224:227], v171 offset:3072
	s_mov_b32 m0, s55
	v_lshl_add_u64 v[106:107], v[244:245], 0, s[22:23]
	ds_read_b128 v[26:29], v169 offset:32768
	ds_read_b128 v[30:33], v169 offset:33792
	ds_read_b128 v[62:65], v169 offset:34816
	ds_read_b128 v[114:117], v169 offset:35840
	ds_read_b128 v[228:231], v169 offset:36864
	ds_read_b128 v[232:235], v169 offset:37888
	ds_read_b128 v[236:239], v169 offset:38912
	ds_read_b128 v[240:243], v169 offset:39936
	global_load_lds_dwordx4 v[106:107], off
	v_lshl_add_u64 v[106:107], v[244:245], 0, s[24:25]
	s_mov_b32 m0, s62
	s_nop 0
	global_load_lds_dwordx4 v[106:107], off
	s_waitcnt vmcnt(8)
	s_waitcnt lgkmcnt(0)
	s_barrier
	s_waitcnt lgkmcnt(0)
	s_setprio 1
	v_mfma_f32_16x16x32_bf16 v[66:69], v[10:13], v[26:29], v[66:69]
	v_mfma_f32_16x16x32_bf16 v[138:141], v[14:17], v[30:33], v[66:69]
	v_mfma_f32_16x16x32_bf16 v[66:69], v[18:21], v[26:29], v[70:73]
	v_mfma_f32_16x16x32_bf16 v[134:137], v[22:25], v[30:33], v[66:69]
	v_mfma_f32_16x16x32_bf16 v[66:69], v[10:13], v[62:65], v[74:77]
	v_mfma_f32_16x16x32_bf16 v[126:129], v[14:17], v[114:117], v[66:69]
	v_mfma_f32_16x16x32_bf16 v[66:69], v[18:21], v[62:65], v[78:81]
	v_mfma_f32_16x16x32_bf16 v[122:125], v[22:25], v[114:117], v[66:69]
	v_mfma_f32_16x16x32_bf16 v[66:69], v[10:13], v[228:231], v[82:85]
	v_mfma_f32_16x16x32_bf16 v[110:113], v[14:17], v[232:235], v[66:69]
	v_mfma_f32_16x16x32_bf16 v[66:69], v[18:21], v[228:231], v[86:89]
	v_mfma_f32_16x16x32_bf16 v[106:109], v[22:25], v[232:235], v[66:69]
	v_mfma_f32_16x16x32_bf16 v[66:69], v[10:13], v[236:239], v[90:93]
	v_mfma_f32_16x16x32_bf16 v[78:81], v[14:17], v[240:243], v[66:69]
	v_mfma_f32_16x16x32_bf16 v[66:69], v[18:21], v[236:239], v[94:97]
	v_mfma_f32_16x16x32_bf16 v[74:77], v[22:25], v[240:243], v[66:69]
	v_mfma_f32_16x16x32_bf16 v[66:69], v[212:215], v[26:29], v[98:101]
	v_mfma_f32_16x16x32_bf16 v[26:29], v[220:223], v[26:29], v[34:37]
	v_mfma_f32_16x16x32_bf16 v[130:133], v[224:227], v[30:33], v[26:29]
	v_mfma_f32_16x16x32_bf16 v[26:29], v[212:215], v[62:65], v[38:41]
	v_mfma_f32_16x16x32_bf16 v[118:121], v[216:219], v[114:117], v[26:29]
	v_mfma_f32_16x16x32_bf16 v[26:29], v[220:223], v[62:65], v[42:45]
	v_mfma_f32_16x16x32_bf16 v[114:117], v[224:227], v[114:117], v[26:29]
	v_mfma_f32_16x16x32_bf16 v[26:29], v[212:215], v[228:231], v[46:49]
	v_mfma_f32_16x16x32_bf16 v[98:101], v[216:219], v[232:235], v[26:29]
	v_mfma_f32_16x16x32_bf16 v[26:29], v[220:223], v[228:231], v[50:53]
	v_mfma_f32_16x16x32_bf16 v[90:93], v[224:227], v[232:235], v[26:29]
	v_mfma_f32_16x16x32_bf16 v[26:29], v[212:215], v[236:239], v[54:57]
	v_mfma_f32_16x16x32_bf16 v[70:73], v[216:219], v[240:243], v[26:29]
	v_mfma_f32_16x16x32_bf16 v[26:29], v[220:223], v[236:239], v[58:61]
	v_mfma_f32_16x16x32_bf16 v[142:145], v[216:219], v[30:33], v[66:69]
	v_mfma_f32_16x16x32_bf16 v[66:69], v[224:227], v[240:243], v[26:29]
	s_setprio 0
	s_barrier
	s_add_i32 s50, s75, s52
	s_nop 3
	v_lshl_add_u64 v[26:27], v[246:247], 0, s[26:27]
	s_mov_b32 m0, s50
	s_add_i32 s51, s50, 0x2000
	ds_read_b128 v[34:37], v169 offset:49152
	ds_read_b128 v[38:41], v169 offset:50176
	ds_read_b128 v[82:85], v169 offset:51200
	ds_read_b128 v[86:89], v169 offset:52224
	ds_read_b128 v[94:97], v169 offset:53248
	ds_read_b128 v[228:231], v169 offset:54272
	ds_read_b128 v[232:235], v169 offset:55296
	ds_read_b128 v[236:239], v169 offset:56320
	global_load_lds_dwordx4 v[26:27], off
	v_lshl_add_u64 v[26:27], v[246:247], 0, s[28:29]
	s_mov_b32 m0, s51
	s_mov_b64 s[0:1], 0x160180
	s_add_i32 s33, s76, s52
	global_load_lds_dwordx4 v[26:27], off
	v_lshl_add_u64 v[26:27], v[246:247], 0, s[0:1]
	s_mov_b32 m0, s33
	s_mov_b64 s[0:1], 0x210180
	s_add_i32 s56, s33, 0x2000
	global_load_lds_dwordx4 v[26:27], off
	v_lshl_add_u64 v[26:27], v[246:247], 0, s[0:1]
	s_mov_b32 m0, s56
	s_nop 0
	global_load_lds_dwordx4 v[26:27], off
	v_lshl_add_u64 v[26:27], v[244:245], 0, s[26:27]
	s_mov_b32 m0, s63
	s_nop 0
	global_load_lds_dwordx4 v[26:27], off
	v_lshl_add_u64 v[26:27], v[244:245], 0, s[28:29]
	s_mov_b32 m0, s66
	s_nop 0
	global_load_lds_dwordx4 v[26:27], off
	s_waitcnt vmcnt(8)
	s_waitcnt lgkmcnt(0)
	s_barrier
	s_waitcnt lgkmcnt(0)
	s_setprio 1
	v_mfma_f32_16x16x32_bf16 v[26:29], v[10:13], v[34:37], v[146:149]
	v_mfma_f32_16x16x32_bf16 v[62:65], v[14:17], v[38:41], v[26:29]
	v_mfma_f32_16x16x32_bf16 v[26:29], v[18:21], v[34:37], v[160:163]
	v_mfma_f32_16x16x32_bf16 v[58:61], v[22:25], v[38:41], v[26:29]
	v_mfma_f32_16x16x32_bf16 v[26:29], v[10:13], v[82:85], v[164:167]
	v_mfma_f32_16x16x32_bf16 v[46:49], v[14:17], v[86:89], v[26:29]
	v_mfma_f32_16x16x32_bf16 v[26:29], v[18:21], v[82:85], v[172:175]
	v_mfma_f32_16x16x32_bf16 v[42:45], v[22:25], v[86:89], v[26:29]
	v_mfma_f32_16x16x32_bf16 v[26:29], v[10:13], v[94:97], v[176:179]
	v_mfma_f32_16x16x32_bf16 v[2:5], v[10:13], v[232:235], v[2:5]
	v_mfma_f32_16x16x32_bf16 v[30:33], v[14:17], v[228:231], v[26:29]
	v_mfma_f32_16x16x32_bf16 v[26:29], v[18:21], v[94:97], v[180:183]
	v_mfma_f32_16x16x32_bf16 v[14:17], v[14:17], v[236:239], v[2:5]
	v_mfma_f32_16x16x32_bf16 v[2:5], v[18:21], v[232:235], v[6:9]
	v_mfma_f32_16x16x32_bf16 v[26:29], v[22:25], v[228:231], v[26:29]
	v_mfma_f32_16x16x32_bf16 v[10:13], v[22:25], v[236:239], v[2:5]
	v_mfma_f32_16x16x32_bf16 v[2:5], v[212:215], v[34:37], v[184:187]
	v_mfma_f32_16x16x32_bf16 v[54:57], v[216:219], v[38:41], v[2:5]
	v_mfma_f32_16x16x32_bf16 v[2:5], v[220:223], v[34:37], v[102:105]
	v_mfma_f32_16x16x32_bf16 v[50:53], v[224:227], v[38:41], v[2:5]
	v_mfma_f32_16x16x32_bf16 v[2:5], v[212:215], v[82:85], v[188:191]
	v_mfma_f32_16x16x32_bf16 v[38:41], v[216:219], v[86:89], v[2:5]
	v_mfma_f32_16x16x32_bf16 v[2:5], v[220:223], v[82:85], v[192:195]
	v_mfma_f32_16x16x32_bf16 v[34:37], v[224:227], v[86:89], v[2:5]
	v_mfma_f32_16x16x32_bf16 v[2:5], v[212:215], v[94:97], v[196:199]
	v_mfma_f32_16x16x32_bf16 v[22:25], v[216:219], v[228:231], v[2:5]
	v_mfma_f32_16x16x32_bf16 v[2:5], v[220:223], v[94:97], v[200:203]
	v_mfma_f32_16x16x32_bf16 v[18:21], v[224:227], v[228:231], v[2:5]
	v_mfma_f32_16x16x32_bf16 v[2:5], v[212:215], v[232:235], v[204:207]
	v_mfma_f32_16x16x32_bf16 v[6:9], v[216:219], v[236:239], v[2:5]
	v_mfma_f32_16x16x32_bf16 v[2:5], v[220:223], v[232:235], v[208:211]
	v_mfma_f32_16x16x32_bf16 v[2:5], v[224:227], v[236:239], v[2:5]
	s_setprio 0
	s_barrier
	s_add_u32 s46, s46, 0x160180
	s_addc_u32 s47, s47, 0
	s_add_u32 s57, s58, 0x200
	s_addc_u32 s58, s59, 0
	s_mov_b32 s59, 0
.LBB0_2965:
	ds_read_b128 v[82:85], v1
	ds_read_b128 v[86:89], v1 offset:1024
	ds_read_b128 v[94:97], v1 offset:2048
	ds_read_b128 v[102:105], v1 offset:3072
	ds_read_b128 v[146:149], v168
	ds_read_b128 v[160:163], v168 offset:1024
	ds_read_b128 v[164:167], v168 offset:2048
	ds_read_b128 v[172:175], v168 offset:3072
	s_add_u32 s0, s46, 0xffea0080
	s_addc_u32 s1, s47, -1
	s_cmpk_eq_i32 s59, 0x54
	s_cselect_b32 s1, s11, s1
	s_cselect_b32 s0, s10, s0
	s_cselect_b32 s65, s45, s58
	s_cselect_b32 s64, s44, s57
	s_mov_b32 m0, s81
	v_lshl_add_u64 v[208:209], s[46:47], 0, v[154:155]
	ds_read_b128 v[176:179], v169
	ds_read_b128 v[180:183], v169 offset:1024
	ds_read_b128 v[184:187], v169 offset:2048
	ds_read_b128 v[188:191], v169 offset:3072
	ds_read_b128 v[192:195], v169 offset:4096
	ds_read_b128 v[196:199], v169 offset:5120
	ds_read_b128 v[200:203], v169 offset:6144
	ds_read_b128 v[204:207], v169 offset:7168
	global_load_lds_dwordx4 v[208:209], off
	v_lshl_add_u64 v[208:209], v[208:209], 0, s[30:31]
	s_mov_b32 m0, s82
	s_nop 0
	global_load_lds_dwordx4 v[208:209], off
	s_waitcnt vmcnt(8)
	s_waitcnt lgkmcnt(0)
	s_barrier
	s_waitcnt lgkmcnt(0)
	s_setprio 1
	v_mfma_f32_16x16x32_bf16 v[138:141], v[82:85], v[176:179], v[138:141]
	v_mfma_f32_16x16x32_bf16 v[134:137], v[94:97], v[176:179], v[134:137]
	v_mfma_f32_16x16x32_bf16 v[126:129], v[82:85], v[184:187], v[126:129]
	v_mfma_f32_16x16x32_bf16 v[122:125], v[94:97], v[184:187], v[122:125]
	v_mfma_f32_16x16x32_bf16 v[110:113], v[82:85], v[192:195], v[110:113]
	v_mfma_f32_16x16x32_bf16 v[106:109], v[94:97], v[192:195], v[106:109]
	v_mfma_f32_16x16x32_bf16 v[78:81], v[82:85], v[200:203], v[78:81]
	v_mfma_f32_16x16x32_bf16 v[74:77], v[94:97], v[200:203], v[74:77]
	v_mfma_f32_16x16x32_bf16 v[138:141], v[86:89], v[180:183], v[138:141]
	v_mfma_f32_16x16x32_bf16 v[134:137], v[102:105], v[180:183], v[134:137]
	v_mfma_f32_16x16x32_bf16 v[126:129], v[86:89], v[188:191], v[126:129]
	v_mfma_f32_16x16x32_bf16 v[122:125], v[102:105], v[188:191], v[122:125]
	v_mfma_f32_16x16x32_bf16 v[110:113], v[86:89], v[196:199], v[110:113]
	v_mfma_f32_16x16x32_bf16 v[106:109], v[102:105], v[196:199], v[106:109]
	v_mfma_f32_16x16x32_bf16 v[78:81], v[86:89], v[204:207], v[78:81]
	v_mfma_f32_16x16x32_bf16 v[74:77], v[102:105], v[204:207], v[74:77]
	v_mfma_f32_16x16x32_bf16 v[142:145], v[146:149], v[176:179], v[142:145]
	v_mfma_f32_16x16x32_bf16 v[130:133], v[164:167], v[176:179], v[130:133]
	v_mfma_f32_16x16x32_bf16 v[118:121], v[146:149], v[184:187], v[118:121]
	v_mfma_f32_16x16x32_bf16 v[114:117], v[164:167], v[184:187], v[114:117]
	v_mfma_f32_16x16x32_bf16 v[98:101], v[146:149], v[192:195], v[98:101]
	v_mfma_f32_16x16x32_bf16 v[90:93], v[164:167], v[192:195], v[90:93]
	v_mfma_f32_16x16x32_bf16 v[70:73], v[146:149], v[200:203], v[70:73]
	v_mfma_f32_16x16x32_bf16 v[66:69], v[164:167], v[200:203], v[66:69]
	v_mfma_f32_16x16x32_bf16 v[142:145], v[160:163], v[180:183], v[142:145]
	v_mfma_f32_16x16x32_bf16 v[130:133], v[172:175], v[180:183], v[130:133]
	v_mfma_f32_16x16x32_bf16 v[118:121], v[160:163], v[188:191], v[118:121]
	v_mfma_f32_16x16x32_bf16 v[114:117], v[172:175], v[188:191], v[114:117]
	v_mfma_f32_16x16x32_bf16 v[98:101], v[160:163], v[196:199], v[98:101]
	v_mfma_f32_16x16x32_bf16 v[90:93], v[172:175], v[196:199], v[90:93]
	v_mfma_f32_16x16x32_bf16 v[70:73], v[160:163], v[204:207], v[70:73]
	v_mfma_f32_16x16x32_bf16 v[66:69], v[172:175], v[204:207], v[66:69]
	s_setprio 0
	s_barrier
	s_mov_b32 m0, s83
	v_lshl_add_u64 v[208:209], s[64:65], 0, v[152:153]
	ds_read_b128 v[176:179], v169 offset:16384
	ds_read_b128 v[180:183], v169 offset:17408
	ds_read_b128 v[184:187], v169 offset:18432
	ds_read_b128 v[188:191], v169 offset:19456
	ds_read_b128 v[192:195], v169 offset:20480
	ds_read_b128 v[196:199], v169 offset:21504
	ds_read_b128 v[200:203], v169 offset:22528
	ds_read_b128 v[204:207], v169 offset:23552
	global_load_lds_dwordx4 v[208:209], off
	v_lshl_add_u64 v[210:211], v[208:209], 0, s[30:31]
	s_mov_b32 m0, s84
	s_nop 0
	global_load_lds_dwordx4 v[210:211], off
	v_lshl_add_u64 v[210:211], v[208:209], 0, s[34:35]
	s_mov_b32 m0, s85
	s_nop 0
	global_load_lds_dwordx4 v[210:211], off
	v_lshl_add_u64 v[210:211], v[208:209], 0, s[36:37]
	s_mov_b32 m0, s87
	s_nop 0
	global_load_lds_dwordx4 v[210:211], off
	v_lshl_add_u64 v[210:211], s[0:1], 0, v[150:151]
	s_mov_b32 m0, s53
	v_lshl_add_u64 v[212:213], v[210:211], 0, s[30:31]
	global_load_lds_dwordx4 v[210:211], off
	s_mov_b32 m0, s54
	s_nop 0
	global_load_lds_dwordx4 v[212:213], off
	s_waitcnt vmcnt(8)
	s_waitcnt lgkmcnt(0)
	s_barrier
	s_waitcnt lgkmcnt(0)
	s_setprio 1
	v_mfma_f32_16x16x32_bf16 v[62:65], v[82:85], v[176:179], v[62:65]
	v_mfma_f32_16x16x32_bf16 v[58:61], v[94:97], v[176:179], v[58:61]
	v_mfma_f32_16x16x32_bf16 v[46:49], v[82:85], v[184:187], v[46:49]
	v_mfma_f32_16x16x32_bf16 v[42:45], v[94:97], v[184:187], v[42:45]
	v_mfma_f32_16x16x32_bf16 v[30:33], v[82:85], v[192:195], v[30:33]
	v_mfma_f32_16x16x32_bf16 v[26:29], v[94:97], v[192:195], v[26:29]
	v_mfma_f32_16x16x32_bf16 v[14:17], v[82:85], v[200:203], v[14:17]
	v_mfma_f32_16x16x32_bf16 v[10:13], v[94:97], v[200:203], v[10:13]
	v_mfma_f32_16x16x32_bf16 v[62:65], v[86:89], v[180:183], v[62:65]
	v_mfma_f32_16x16x32_bf16 v[58:61], v[102:105], v[180:183], v[58:61]
	v_mfma_f32_16x16x32_bf16 v[46:49], v[86:89], v[188:191], v[46:49]
	v_mfma_f32_16x16x32_bf16 v[42:45], v[102:105], v[188:191], v[42:45]
	v_mfma_f32_16x16x32_bf16 v[30:33], v[86:89], v[196:199], v[30:33]
	v_mfma_f32_16x16x32_bf16 v[26:29], v[102:105], v[196:199], v[26:29]
	v_mfma_f32_16x16x32_bf16 v[14:17], v[86:89], v[204:207], v[14:17]
	v_mfma_f32_16x16x32_bf16 v[10:13], v[102:105], v[204:207], v[10:13]
	v_mfma_f32_16x16x32_bf16 v[54:57], v[146:149], v[176:179], v[54:57]
	v_mfma_f32_16x16x32_bf16 v[50:53], v[164:167], v[176:179], v[50:53]
	v_mfma_f32_16x16x32_bf16 v[38:41], v[146:149], v[184:187], v[38:41]
	v_mfma_f32_16x16x32_bf16 v[34:37], v[164:167], v[184:187], v[34:37]
	v_mfma_f32_16x16x32_bf16 v[22:25], v[146:149], v[192:195], v[22:25]
	v_mfma_f32_16x16x32_bf16 v[18:21], v[164:167], v[192:195], v[18:21]
	v_mfma_f32_16x16x32_bf16 v[6:9], v[146:149], v[200:203], v[6:9]
	v_mfma_f32_16x16x32_bf16 v[2:5], v[164:167], v[200:203], v[2:5]
	v_mfma_f32_16x16x32_bf16 v[54:57], v[160:163], v[180:183], v[54:57]
	v_mfma_f32_16x16x32_bf16 v[50:53], v[172:175], v[180:183], v[50:53]
	v_mfma_f32_16x16x32_bf16 v[38:41], v[160:163], v[188:191], v[38:41]
	v_mfma_f32_16x16x32_bf16 v[34:37], v[172:175], v[188:191], v[34:37]
	v_mfma_f32_16x16x32_bf16 v[22:25], v[160:163], v[196:199], v[22:25]
	v_mfma_f32_16x16x32_bf16 v[18:21], v[172:175], v[196:199], v[18:21]
	v_mfma_f32_16x16x32_bf16 v[6:9], v[160:163], v[204:207], v[6:9]
	v_mfma_f32_16x16x32_bf16 v[2:5], v[172:175], v[204:207], v[2:5]
	s_setprio 0
	s_barrier
	ds_read_b128 v[82:85], v170
	ds_read_b128 v[86:89], v170 offset:1024
	ds_read_b128 v[94:97], v170 offset:2048
	ds_read_b128 v[102:105], v170 offset:3072
	ds_read_b128 v[146:149], v171
	ds_read_b128 v[160:163], v171 offset:1024
	ds_read_b128 v[164:167], v171 offset:2048
	ds_read_b128 v[172:175], v171 offset:3072
	s_mov_b32 m0, s55
	v_lshl_add_u64 v[212:213], v[210:211], 0, s[34:35]
	ds_read_b128 v[176:179], v169 offset:32768
	ds_read_b128 v[180:183], v169 offset:33792
	ds_read_b128 v[184:187], v169 offset:34816
	ds_read_b128 v[188:191], v169 offset:35840
	ds_read_b128 v[192:195], v169 offset:36864
	ds_read_b128 v[196:199], v169 offset:37888
	ds_read_b128 v[200:203], v169 offset:38912
	ds_read_b128 v[204:207], v169 offset:39936
	global_load_lds_dwordx4 v[212:213], off
	v_lshl_add_u64 v[212:213], v[210:211], 0, s[36:37]
	s_mov_b32 m0, s62
	s_nop 0
	global_load_lds_dwordx4 v[212:213], off
	s_waitcnt vmcnt(8)
	s_waitcnt lgkmcnt(0)
	s_barrier
	s_waitcnt lgkmcnt(0)
	s_setprio 1
	v_mfma_f32_16x16x32_bf16 v[138:141], v[82:85], v[176:179], v[138:141]
	v_mfma_f32_16x16x32_bf16 v[134:137], v[94:97], v[176:179], v[134:137]
	v_mfma_f32_16x16x32_bf16 v[126:129], v[82:85], v[184:187], v[126:129]
	v_mfma_f32_16x16x32_bf16 v[122:125], v[94:97], v[184:187], v[122:125]
	v_mfma_f32_16x16x32_bf16 v[110:113], v[82:85], v[192:195], v[110:113]
	v_mfma_f32_16x16x32_bf16 v[106:109], v[94:97], v[192:195], v[106:109]
	v_mfma_f32_16x16x32_bf16 v[78:81], v[82:85], v[200:203], v[78:81]
	v_mfma_f32_16x16x32_bf16 v[74:77], v[94:97], v[200:203], v[74:77]
	v_mfma_f32_16x16x32_bf16 v[138:141], v[86:89], v[180:183], v[138:141]
	v_mfma_f32_16x16x32_bf16 v[134:137], v[102:105], v[180:183], v[134:137]
	v_mfma_f32_16x16x32_bf16 v[126:129], v[86:89], v[188:191], v[126:129]
	v_mfma_f32_16x16x32_bf16 v[122:125], v[102:105], v[188:191], v[122:125]
	v_mfma_f32_16x16x32_bf16 v[110:113], v[86:89], v[196:199], v[110:113]
	v_mfma_f32_16x16x32_bf16 v[106:109], v[102:105], v[196:199], v[106:109]
	v_mfma_f32_16x16x32_bf16 v[78:81], v[86:89], v[204:207], v[78:81]
	v_mfma_f32_16x16x32_bf16 v[74:77], v[102:105], v[204:207], v[74:77]
	v_mfma_f32_16x16x32_bf16 v[142:145], v[146:149], v[176:179], v[142:145]
	v_mfma_f32_16x16x32_bf16 v[130:133], v[164:167], v[176:179], v[130:133]
	v_mfma_f32_16x16x32_bf16 v[118:121], v[146:149], v[184:187], v[118:121]
	v_mfma_f32_16x16x32_bf16 v[114:117], v[164:167], v[184:187], v[114:117]
	v_mfma_f32_16x16x32_bf16 v[98:101], v[146:149], v[192:195], v[98:101]
	v_mfma_f32_16x16x32_bf16 v[90:93], v[164:167], v[192:195], v[90:93]
	v_mfma_f32_16x16x32_bf16 v[70:73], v[146:149], v[200:203], v[70:73]
	v_mfma_f32_16x16x32_bf16 v[66:69], v[164:167], v[200:203], v[66:69]
	v_mfma_f32_16x16x32_bf16 v[142:145], v[160:163], v[180:183], v[142:145]
	v_mfma_f32_16x16x32_bf16 v[130:133], v[172:175], v[180:183], v[130:133]
	v_mfma_f32_16x16x32_bf16 v[118:121], v[160:163], v[188:191], v[118:121]
	v_mfma_f32_16x16x32_bf16 v[114:117], v[172:175], v[188:191], v[114:117]
	v_mfma_f32_16x16x32_bf16 v[98:101], v[160:163], v[196:199], v[98:101]
	v_mfma_f32_16x16x32_bf16 v[90:93], v[172:175], v[196:199], v[90:93]
	v_mfma_f32_16x16x32_bf16 v[70:73], v[160:163], v[204:207], v[70:73]
	v_mfma_f32_16x16x32_bf16 v[66:69], v[172:175], v[204:207], v[66:69]
	s_setprio 0
	s_barrier
; #define PG8_WAIT_V(n) asm volatile("s_waitcnt vmcnt(" #n ")" ::: "memory")
; #define PG8_BAR __builtin_amdgcn_s_barrier()
; template <class Epi, class Sched, bool ALIGN_EPI = true, bool SP2 = true, bool FULLLINE = false, bool NOSTAGE = false, bool FP8 = false>
; __device__ __forceinline__ void gemm_phase(PG8_LAS unsigned char* lds, const Gemm g, const Sched& S, const Epi& E) {
;     ...
;         static_assert(SP2, "only the SP2 loop is kept");
;         { const int t = 0; if constexpr (Epi::NST == 16) PG8_ITER(PG8_WAIT_V(24)); else if constexpr (Epi::NST == 8) PG8_ITER(PG8_WAIT_V(16)); else PG8_ITER(PG8_WAIT_V(8)); }
;         for (int t = 2; t < nt; t += 2) PG8_ITER(PG8_WAIT_V(8));
;     ...
;         if constexpr (ALIGN_EPI) { if (wr == 0) PG8_BAR; }
	s_mov_b32 m0, s50
	v_lshl_add_u64 v[212:213], v[208:209], 0, s[38:39]
	ds_read_b128 v[176:179], v169 offset:49152
	ds_read_b128 v[180:183], v169 offset:50176
	ds_read_b128 v[184:187], v169 offset:51200
	ds_read_b128 v[188:191], v169 offset:52224
	ds_read_b128 v[192:195], v169 offset:53248
	ds_read_b128 v[196:199], v169 offset:54272
	ds_read_b128 v[200:203], v169 offset:55296
	ds_read_b128 v[204:207], v169 offset:56320
	global_load_lds_dwordx4 v[212:213], off
	v_lshl_add_u64 v[212:213], v[208:209], 0, s[40:41]
	s_mov_b32 m0, s51
	s_nop 0
	global_load_lds_dwordx4 v[212:213], off
	v_lshl_add_u64 v[212:213], v[208:209], 0, s[14:15]
	s_mov_b32 m0, s33
	v_lshl_add_u64 v[208:209], v[208:209], 0, s[16:17]
	global_load_lds_dwordx4 v[212:213], off
	s_mov_b32 m0, s56
	s_nop 0
	global_load_lds_dwordx4 v[208:209], off
	v_lshl_add_u64 v[208:209], v[210:211], 0, s[38:39]
	s_mov_b32 m0, s63
	s_nop 0
	global_load_lds_dwordx4 v[208:209], off
	v_lshl_add_u64 v[208:209], v[210:211], 0, s[40:41]
	s_mov_b32 m0, s66
	s_nop 0
	global_load_lds_dwordx4 v[208:209], off
	s_waitcnt vmcnt(8)
	s_waitcnt lgkmcnt(0)
	s_barrier
	s_waitcnt lgkmcnt(0)
	s_setprio 1
	v_mfma_f32_16x16x32_bf16 v[62:65], v[82:85], v[176:179], v[62:65]
	v_mfma_f32_16x16x32_bf16 v[58:61], v[94:97], v[176:179], v[58:61]
	v_mfma_f32_16x16x32_bf16 v[46:49], v[82:85], v[184:187], v[46:49]
	v_mfma_f32_16x16x32_bf16 v[42:45], v[94:97], v[184:187], v[42:45]
	v_mfma_f32_16x16x32_bf16 v[30:33], v[82:85], v[192:195], v[30:33]
	v_mfma_f32_16x16x32_bf16 v[26:29], v[94:97], v[192:195], v[26:29]
	v_mfma_f32_16x16x32_bf16 v[14:17], v[82:85], v[200:203], v[14:17]
	v_mfma_f32_16x16x32_bf16 v[10:13], v[94:97], v[200:203], v[10:13]
	v_mfma_f32_16x16x32_bf16 v[62:65], v[86:89], v[180:183], v[62:65]
	v_mfma_f32_16x16x32_bf16 v[58:61], v[102:105], v[180:183], v[58:61]
	v_mfma_f32_16x16x32_bf16 v[46:49], v[86:89], v[188:191], v[46:49]
	v_mfma_f32_16x16x32_bf16 v[42:45], v[102:105], v[188:191], v[42:45]
	v_mfma_f32_16x16x32_bf16 v[30:33], v[86:89], v[196:199], v[30:33]
	v_mfma_f32_16x16x32_bf16 v[26:29], v[102:105], v[196:199], v[26:29]
	v_mfma_f32_16x16x32_bf16 v[14:17], v[86:89], v[204:207], v[14:17]
	v_mfma_f32_16x16x32_bf16 v[10:13], v[102:105], v[204:207], v[10:13]
	v_mfma_f32_16x16x32_bf16 v[54:57], v[146:149], v[176:179], v[54:57]
	v_mfma_f32_16x16x32_bf16 v[50:53], v[164:167], v[176:179], v[50:53]
	v_mfma_f32_16x16x32_bf16 v[38:41], v[146:149], v[184:187], v[38:41]
	v_mfma_f32_16x16x32_bf16 v[34:37], v[164:167], v[184:187], v[34:37]
	v_mfma_f32_16x16x32_bf16 v[22:25], v[146:149], v[192:195], v[22:25]
	v_mfma_f32_16x16x32_bf16 v[18:21], v[164:167], v[192:195], v[18:21]
	v_mfma_f32_16x16x32_bf16 v[6:9], v[146:149], v[200:203], v[6:9]
	v_mfma_f32_16x16x32_bf16 v[2:5], v[164:167], v[200:203], v[2:5]
	v_mfma_f32_16x16x32_bf16 v[54:57], v[160:163], v[180:183], v[54:57]
	v_mfma_f32_16x16x32_bf16 v[50:53], v[172:175], v[180:183], v[50:53]
	v_mfma_f32_16x16x32_bf16 v[38:41], v[160:163], v[188:191], v[38:41]
	v_mfma_f32_16x16x32_bf16 v[34:37], v[172:175], v[188:191], v[34:37]
	v_mfma_f32_16x16x32_bf16 v[22:25], v[160:163], v[196:199], v[22:25]
	v_mfma_f32_16x16x32_bf16 v[18:21], v[172:175], v[196:199], v[18:21]
	v_mfma_f32_16x16x32_bf16 v[6:9], v[160:163], v[204:207], v[6:9]
	v_mfma_f32_16x16x32_bf16 v[2:5], v[172:175], v[204:207], v[2:5]
	s_setprio 0
	s_barrier
	s_add_i32 s59, s59, 2
	s_add_u32 s46, s46, 0x100
	s_addc_u32 s47, s47, 0
	s_add_u32 s57, s57, 0x100
	s_addc_u32 s58, s58, 0
	s_cmpk_gt_u32 s59, 0x55
	s_cbranch_scc0 .LBB0_2965
	s_and_b64 vcc, exec, s[12:13]
	s_cbranch_vccz .LBB0_2968
	s_barrier
